# all flat_load/flat_store (655) rewritten as global_load/global_store: no LDS-side issue or lgkmcnt coupling for global-memory accesses
# speedup vs baseline: 1.0074x; 1.0074x over previous
; #define LAS __attribute__((address_space(3)))
; template <int MAP>
; __device__ __forceinline__ void transpose_item(const float* W, int K, int N, int Npad, bf16_t* WT, const float* gk, LAS float* scr, int item, int lane) {
;     const int nblk = Npad / 32, kb = item / nblk, nb = item % nblk, k0 = 64 * kb, n0 = 32 * nb;
;     float sc; const int ns = srcmap<MAP>(n0 + (lane & 31), sc);
;     float wv[32];
;     const float* Wp = W + (size_t)(k0 + (lane >> 5)) * N + (ns >= 0 ? ns : 0);
; #pragma unroll
;     for (int i = 0; i < 32; ++i) wv[i] = Wp[(size_t)(2 * i) * N];
; #pragma unroll
;     for (int i = 0; i < 32; ++i) { const int kk = 2 * i + (lane >> 5); float v = ns >= 0 ? wv[i] : 0.f; if (gk) v *= gk[k0 + kk]; scr[kk * 33 + (lane & 31)] = v * sc; }
.LBB0_5:
	s_or_b64 exec, exec, s[0:1]
	v_readlane_b32 s72, v254, 12
	s_mul_i32 s0, s36, 0x2180000
	v_readlane_b32 s82, v254, 22
	s_mul_hi_i32 s1, s36, 0x2180000
	v_readlane_b32 s83, v254, 23
	s_add_u32 s0, s82, s0
	s_addc_u32 s1, s83, s1
	s_mul_hi_i32 s41, s36, 0x1100000
	s_mul_i32 s36, s36, 0x1100000
	s_add_u32 s40, s51, s36
	s_sext_i32_i16 s36, s37
	s_addc_u32 s41, s52, s41
	s_lshl_b32 s36, s36, 6
	v_or_b32_e32 v2, s36, v27
	v_mul_i32_i24_e32 v8, 0x4300, v2
	v_ashrrev_i32_e32 v9, 31, v8
	v_cmp_lt_i32_e32 vcc, -1, v6
	v_lshl_add_u64 v[8:9], s[0:1], 0, v[8:9]
	s_ashr_i32 s37, s36, 31
	v_cndmask_b32_e32 v2, 0, v6, vcc
	v_lshl_add_u64 v[6:7], v[2:3], 2, v[8:9]
	v_add_co_u32_e64 v8, s[0:1], s54, v6
	v_readlane_b32 s73, v254, 13
	s_nop 0
	v_addc_co_u32_e64 v9, s[0:1], 0, v7, s[0:1]
	v_add_co_u32_e64 v10, s[0:1], s68, v6
	v_readlane_b32 s74, v254, 14
	s_nop 0
	v_addc_co_u32_e64 v11, s[0:1], 0, v7, s[0:1]
	v_add_co_u32_e64 v12, s[0:1], s24, v6
	v_readlane_b32 s75, v254, 15
	s_nop 0
	v_addc_co_u32_e64 v13, s[0:1], 0, v7, s[0:1]
	v_add_co_u32_e64 v14, s[0:1], s90, v6
	v_readlane_b32 s76, v254, 16
	s_nop 0
	v_addc_co_u32_e64 v15, s[0:1], 0, v7, s[0:1]
	s_mov_b32 s0, 0x29000
	s_nop 0
	v_add_co_u32_e64 v16, s[0:1], s0, v6
	v_readlane_b32 s77, v254, 17
	s_nop 0
	v_addc_co_u32_e64 v17, s[0:1], 0, v7, s[0:1]
	v_add_co_u32_e64 v18, s[0:1], s23, v6
	v_readlane_b32 s78, v254, 18
	s_nop 0
	v_addc_co_u32_e64 v19, s[0:1], 0, v7, s[0:1]
	s_mov_b32 s0, 0x3a000
	s_nop 0
	v_add_co_u32_e64 v20, s[0:1], s0, v6
	v_readlane_b32 s79, v254, 19
	s_nop 0
	v_addc_co_u32_e64 v21, s[0:1], 0, v7, s[0:1]
	s_mov_b32 s0, 0x43000
	global_load_dword v2, v[6:7], off
	global_load_dword v55, v[8:9], off offset:1536
	global_load_dword v56, v[10:11], off offset:3072
	global_load_dword v57, v[12:13], off offset:512
	global_load_dword v58, v[14:15], off offset:2048
	global_load_dword v59, v[16:17], off offset:3584
	global_load_dword v60, v[18:19], off offset:1024
	global_load_dword v61, v[20:21], off offset:2560
	v_add_co_u32_e64 v8, s[0:1], s0, v6
	v_readlane_b32 s80, v254, 20
	s_nop 0
	v_addc_co_u32_e64 v9, s[0:1], 0, v7, s[0:1]
	s_mov_b32 s0, 0x4b000
	s_nop 0
	v_add_co_u32_e64 v10, s[0:1], s0, v6
	v_readlane_b32 s81, v254, 21
	s_nop 0
	v_addc_co_u32_e64 v11, s[0:1], 0, v7, s[0:1]
	s_mov_b32 s0, 0x53000
	s_nop 0
	v_add_co_u32_e64 v12, s[0:1], s0, v6
	v_readlane_b32 s84, v254, 24
	s_nop 0
	v_addc_co_u32_e64 v13, s[0:1], 0, v7, s[0:1]
	v_add_co_u32_e64 v14, s[0:1], s47, v6
	v_readlane_b32 s85, v254, 25
	s_nop 0
	v_addc_co_u32_e64 v15, s[0:1], 0, v7, s[0:1]
	v_add_co_u32_e64 v16, s[0:1], s89, v6
	v_readlane_b32 s86, v254, 26
	s_nop 0
	v_addc_co_u32_e64 v17, s[0:1], 0, v7, s[0:1]
	v_add_co_u32_e64 v18, s[0:1], s91, v6
	v_readlane_b32 s87, v254, 27
	s_nop 0
	v_addc_co_u32_e64 v19, s[0:1], 0, v7, s[0:1]
	s_mov_b32 s0, 0x75000
	s_nop 0
	v_add_co_u32_e64 v20, s[0:1], s0, v6
	s_waitcnt vmcnt(0)
	v_cndmask_b32_e32 v2, 0, v2, vcc
	v_addc_co_u32_e64 v21, s[0:1], 0, v7, s[0:1]
	s_mov_b32 s0, 0x7d000
	s_nop 0
	v_add_co_u32_e64 v22, s[0:1], s0, v6
	v_mul_f32_e32 v2, v5, v2
	s_nop 0
	v_addc_co_u32_e64 v23, s[0:1], 0, v7, s[0:1]
	s_mov_b32 s0, 0x86000
	global_load_dword v62, v[8:9], off
	global_load_dword v63, v[10:11], off offset:1536
	global_load_dword v64, v[12:13], off offset:3072
	global_load_dword v65, v[14:15], off offset:512
	global_load_dword v66, v[16:17], off offset:2048
	global_load_dword v67, v[18:19], off offset:3584
	global_load_dword v68, v[20:21], off offset:1024
	global_load_dword v69, v[22:23], off offset:2560
	v_add_co_u32_e64 v8, s[0:1], s0, v6
	s_nop 1
	v_addc_co_u32_e64 v9, s[0:1], 0, v7, s[0:1]
	s_mov_b32 s0, 0x8e000
	s_nop 0
	v_add_co_u32_e64 v10, s[0:1], s0, v6
	s_nop 1
	v_addc_co_u32_e64 v11, s[0:1], 0, v7, s[0:1]
	s_mov_b32 s0, 0x96000
	s_nop 0
	v_add_co_u32_e64 v12, s[0:1], s0, v6
	s_nop 1
	v_addc_co_u32_e64 v13, s[0:1], 0, v7, s[0:1]
	s_mov_b32 s0, 0x9f000
	s_nop 0
	v_add_co_u32_e64 v14, s[0:1], s0, v6
	s_nop 1
	v_addc_co_u32_e64 v15, s[0:1], 0, v7, s[0:1]
	s_mov_b32 s0, 0xa7000
	s_nop 0
	v_add_co_u32_e64 v16, s[0:1], s0, v6
	s_nop 1
	v_addc_co_u32_e64 v17, s[0:1], 0, v7, s[0:1]
	s_mov_b32 s0, 0xaf000
	s_nop 0
	v_add_co_u32_e64 v18, s[0:1], s0, v6
	s_nop 1
	v_addc_co_u32_e64 v19, s[0:1], 0, v7, s[0:1]
	s_mov_b32 s0, 0xb8000
	s_nop 0
	v_add_co_u32_e64 v20, s[0:1], s0, v6
	s_nop 1
	v_addc_co_u32_e64 v21, s[0:1], 0, v7, s[0:1]
	v_add_co_u32_e64 v22, s[0:1], s33, v6
	s_nop 1
	v_addc_co_u32_e64 v23, s[0:1], 0, v7, s[0:1]
	s_mov_b32 s0, 0xc9000
	global_load_dword v70, v[8:9], off
	global_load_dword v71, v[10:11], off offset:1536
	global_load_dword v72, v[12:13], off offset:3072
	global_load_dword v73, v[14:15], off offset:512
	s_nop 0
	global_load_dword v16, v[16:17], off offset:2048
	s_nop 0
	global_load_dword v17, v[18:19], off offset:3584
	s_nop 0
	global_load_dword v18, v[20:21], off offset:1024
	global_load_dword v19, v[22:23], off offset:2560
	v_add_co_u32_e64 v8, s[0:1], s0, v6
	s_nop 1
	v_addc_co_u32_e64 v9, s[0:1], 0, v7, s[0:1]
	s_mov_b32 s0, 0xd1000
	s_nop 0
	v_add_co_u32_e64 v10, s[0:1], s0, v6
	s_nop 1
	v_addc_co_u32_e64 v11, s[0:1], 0, v7, s[0:1]
	s_mov_b32 s0, 0xd9000
	s_nop 0
	v_add_co_u32_e64 v12, s[0:1], s0, v6
	s_nop 1
	v_addc_co_u32_e64 v13, s[0:1], 0, v7, s[0:1]
	s_mov_b32 s0, 0xe2000
	s_nop 0
	v_add_co_u32_e64 v14, s[0:1], s0, v6
	s_nop 1
	v_addc_co_u32_e64 v15, s[0:1], 0, v7, s[0:1]
	s_mov_b32 s0, 0xea000
	global_load_dword v20, v[8:9], off
	global_load_dword v21, v[10:11], off offset:1536
	global_load_dword v22, v[12:13], off offset:3072
	s_nop 0
	global_load_dword v14, v[14:15], off offset:512
	v_add_co_u32_e64 v8, s[0:1], s0, v6
	s_nop 1
	v_addc_co_u32_e64 v9, s[0:1], 0, v7, s[0:1]
	s_mov_b32 s0, 0xf2000
	s_nop 0
	v_add_co_u32_e64 v10, s[0:1], s0, v6
	s_nop 1
	v_addc_co_u32_e64 v11, s[0:1], 0, v7, s[0:1]
	s_mov_b32 s0, 0xfb000
	s_nop 0
	v_add_co_u32_e64 v12, s[0:1], s0, v6
	s_nop 1
	v_addc_co_u32_e64 v13, s[0:1], 0, v7, s[0:1]
	s_mov_b32 s0, 0x103000
	s_nop 0
	v_add_co_u32_e64 v6, s[0:1], s0, v6
	global_load_dword v8, v[8:9], off offset:2048
	s_nop 0
	global_load_dword v9, v[10:11], off offset:3584
	s_nop 0
	global_load_dword v10, v[12:13], off offset:1024
	v_addc_co_u32_e64 v7, s[0:1], 0, v7, s[0:1]
	global_load_dword v6, v[6:7], off offset:2560
	v_cndmask_b32_e32 v7, 0, v55, vcc
	v_mul_f32_e32 v7, v5, v7
	ds_write2_b32 v29, v2, v7 offset1:66
	v_cndmask_b32_e32 v2, 0, v56, vcc
	v_cndmask_b32_e32 v7, 0, v57, vcc
	v_mul_f32_e32 v2, v5, v2
	v_mul_f32_e32 v7, v5, v7
	ds_write2_b32 v29, v2, v7 offset0:132 offset1:198
	v_cndmask_b32_e32 v2, 0, v58, vcc
	v_cndmask_b32_e32 v7, 0, v59, vcc
	v_mul_f32_e32 v2, v5, v2
	v_mul_f32_e32 v7, v5, v7
	ds_write2_b32 v46, v2, v7 offset0:8 offset1:74
	v_cndmask_b32_e32 v2, 0, v60, vcc
	v_cndmask_b32_e32 v7, 0, v61, vcc
	v_mul_f32_e32 v2, v5, v2
	v_mul_f32_e32 v7, v5, v7
	ds_write2_b32 v46, v2, v7 offset0:140 offset1:206
	s_waitcnt vmcnt(0)
; #define LAS __attribute__((address_space(3)))
; __device__ __forceinline__ unsigned pk2(float lo, float hi) { return f2bf(lo) | (f2bf(hi) << 16); }
; template <int MAP>
; __device__ __forceinline__ void transpose_item(const float* W, int K, int N, int Npad, bf16_t* WT, const float* gk, LAS float* scr, int item, int lane) {
;     ...
;     for (int i = 0; i < 32; ++i) { const int kk = 2 * i + (lane >> 5); float v = ns >= 0 ? wv[i] : 0.f; if (gk) v *= gk[k0 + kk]; scr[kk * 33 + (lane & 31)] = v * sc; }
;     asm volatile("s_waitcnt lgkmcnt(0)" ::: "memory");
;     const int c = lane & 7;
; #pragma unroll
;     for (int j = 0; j < 4; ++j) { const int n = (lane >> 3) + 8 * j; const LAS float* s = scr + (8 * c) * 33 + n;
;         u32x4 o; o.x = pk2(s[0 * 33], s[1 * 33]); o.y = pk2(s[2 * 33], s[3 * 33]); o.z = pk2(s[4 * 33], s[5 * 33]); o.w = pk2(s[6 * 33], s[7 * 33]);
;         *(u32x4*)(WT + (size_t)(n0 + n) * K + k0 + 8 * c) = o; }
;     asm volatile("s_waitcnt lgkmcnt(0)" ::: "memory");
	v_cndmask_b32_e32 v2, 0, v62, vcc
	v_cndmask_b32_e32 v7, 0, v63, vcc
	v_mul_f32_e32 v2, v5, v2
	v_mul_f32_e32 v7, v5, v7
	ds_write2_b32 v47, v2, v7 offset0:16 offset1:82
	v_cndmask_b32_e32 v2, 0, v64, vcc
	v_cndmask_b32_e32 v7, 0, v65, vcc
	v_mul_f32_e32 v2, v5, v2
	v_mul_f32_e32 v7, v5, v7
	ds_write2_b32 v47, v2, v7 offset0:148 offset1:214
	v_cndmask_b32_e32 v2, 0, v66, vcc
	v_cndmask_b32_e32 v7, 0, v67, vcc
	v_mul_f32_e32 v2, v5, v2
	v_mul_f32_e32 v7, v5, v7
	ds_write2_b32 v48, v2, v7 offset0:24 offset1:90
	v_cndmask_b32_e32 v2, 0, v68, vcc
	v_cndmask_b32_e32 v7, 0, v69, vcc
	v_mul_f32_e32 v2, v5, v2
	v_mul_f32_e32 v7, v5, v7
	ds_write2_b32 v48, v2, v7 offset0:156 offset1:222
	v_cndmask_b32_e32 v2, 0, v70, vcc
	v_cndmask_b32_e32 v7, 0, v71, vcc
	v_mul_f32_e32 v2, v5, v2
	v_mul_f32_e32 v7, v5, v7
	ds_write2_b32 v49, v2, v7 offset0:32 offset1:98
	v_cndmask_b32_e32 v2, 0, v72, vcc
	v_cndmask_b32_e32 v7, 0, v73, vcc
	v_mul_f32_e32 v2, v5, v2
	v_mul_f32_e32 v7, v5, v7
	ds_write2_b32 v49, v2, v7 offset0:164 offset1:230
	v_cndmask_b32_e32 v2, 0, v16, vcc
	v_cndmask_b32_e32 v7, 0, v17, vcc
	v_mul_f32_e32 v2, v5, v2
	v_mul_f32_e32 v7, v5, v7
	ds_write2_b32 v50, v2, v7 offset0:40 offset1:106
	v_cndmask_b32_e32 v2, 0, v18, vcc
	v_cndmask_b32_e32 v7, 0, v19, vcc
	v_mul_f32_e32 v2, v5, v2
	v_mul_f32_e32 v7, v5, v7
	ds_write2_b32 v50, v2, v7 offset0:172 offset1:238
	v_cndmask_b32_e32 v2, 0, v20, vcc
	v_cndmask_b32_e32 v7, 0, v21, vcc
	v_mul_f32_e32 v2, v5, v2
	v_mul_f32_e32 v7, v5, v7
	ds_write2_b32 v51, v2, v7 offset0:48 offset1:114
	v_cndmask_b32_e32 v2, 0, v22, vcc
	v_cndmask_b32_e32 v7, 0, v14, vcc
	v_mul_f32_e32 v2, v5, v2
	v_mul_f32_e32 v7, v5, v7
	ds_write2_b32 v51, v2, v7 offset0:180 offset1:246
	s_lshl_b64 s[0:1], s[36:37], 1
	s_add_u32 s0, s40, s0
	s_addc_u32 s1, s41, s1
	v_cndmask_b32_e32 v2, 0, v8, vcc
	v_cndmask_b32_e32 v7, 0, v9, vcc
	v_mul_f32_e32 v2, v5, v2
	v_mul_f32_e32 v7, v5, v7
	ds_write2_b32 v52, v2, v7 offset0:56 offset1:122
	v_cndmask_b32_e32 v2, 0, v10, vcc
	v_cndmask_b32_e32 v6, 0, v6, vcc
	v_mul_f32_e32 v2, v5, v2
	v_mul_f32_e32 v5, v5, v6
	ds_write2_b32 v52, v2, v5 offset0:188 offset1:254
	s_waitcnt lgkmcnt(0)
	v_mov_b32_e32 v5, v3
	v_lshl_add_u64 v[10:11], s[0:1], 0, v[4:5]
	ds_read_b32 v2, v31
	ds_read_b32 v5, v31 offset:132
	ds_read_b32 v7, v31 offset:264
	ds_read_b32 v8, v31 offset:396
	ds_read_b32 v9, v31 offset:528
	ds_read_b32 v12, v31 offset:660
	ds_read_b32 v13, v31 offset:792
	ds_read_b32 v14, v31 offset:924
	s_waitcnt lgkmcnt(0)
	v_bfe_u32 v6, v2, 16, 1
	v_add3_u32 v2, v2, v6, s96
	v_bfe_u32 v6, v5, 16, 1
	v_lshrrev_b32_e32 v2, 16, v2
	v_add3_u32 v5, v5, v6, s96
	v_and_or_b32 v6, v5, s97, v2
	v_bfe_u32 v2, v7, 16, 1
	v_add3_u32 v2, v7, v2, s96
	v_bfe_u32 v5, v8, 16, 1
	v_lshrrev_b32_e32 v2, 16, v2
	v_add3_u32 v5, v8, v5, s96
	v_and_or_b32 v7, v5, s97, v2
	v_bfe_u32 v2, v9, 16, 1
	v_add3_u32 v2, v9, v2, s96
	v_bfe_u32 v5, v12, 16, 1
	v_lshrrev_b32_e32 v2, 16, v2
	v_add3_u32 v5, v12, v5, s96
	v_and_or_b32 v8, v5, s97, v2
	v_bfe_u32 v2, v13, 16, 1
	v_or_b32_e32 v12, s66, v30
	v_add3_u32 v2, v13, v2, s96
	v_bfe_u32 v5, v14, 16, 1
	v_ashrrev_i32_e32 v13, 31, v12
	v_lshrrev_b32_e32 v2, 16, v2
	v_add3_u32 v5, v14, v5, s96
	v_lshlrev_b64 v[12:13], 12, v[12:13]
	v_and_or_b32 v9, v5, s97, v2
	v_lshl_add_u64 v[12:13], v[10:11], 0, v[12:13]
	global_store_dwordx4 v[12:13], v[6:9], off
	ds_read_b32 v2, v31 offset:32
	ds_read_b32 v5, v31 offset:164
	ds_read_b32 v7, v31 offset:296
	ds_read_b32 v8, v31 offset:428
	ds_read_b32 v9, v31 offset:560
	ds_read_b32 v12, v31 offset:692
	ds_read_b32 v13, v31 offset:824
	ds_read_b32 v14, v31 offset:956
	s_waitcnt lgkmcnt(0)
	v_bfe_u32 v6, v2, 16, 1
	v_add3_u32 v2, v2, v6, s96
	v_bfe_u32 v6, v5, 16, 1
	v_lshrrev_b32_e32 v2, 16, v2
	v_add3_u32 v5, v5, v6, s96
	v_and_or_b32 v6, v5, s97, v2
	v_bfe_u32 v2, v7, 16, 1
	v_add3_u32 v2, v7, v2, s96
	v_bfe_u32 v5, v8, 16, 1
	v_lshrrev_b32_e32 v2, 16, v2
	v_add3_u32 v5, v8, v5, s96
	v_and_or_b32 v7, v5, s97, v2
	v_bfe_u32 v2, v9, 16, 1
	v_add3_u32 v2, v9, v2, s96
	v_bfe_u32 v5, v12, 16, 1
	v_lshrrev_b32_e32 v2, 16, v2
	v_add3_u32 v5, v12, v5, s96
	v_and_or_b32 v8, v5, s97, v2
	v_bfe_u32 v2, v13, 16, 1
	v_or_b32_e32 v12, s66, v32
	v_add3_u32 v2, v13, v2, s96
	v_bfe_u32 v5, v14, 16, 1
	v_ashrrev_i32_e32 v13, 31, v12
	v_lshrrev_b32_e32 v2, 16, v2
	v_add3_u32 v5, v14, v5, s96
	v_lshlrev_b64 v[12:13], 12, v[12:13]
	v_and_or_b32 v9, v5, s97, v2
	v_lshl_add_u64 v[12:13], v[10:11], 0, v[12:13]
	global_store_dwordx4 v[12:13], v[6:9], off
	ds_read_b32 v2, v31 offset:64
	ds_read_b32 v5, v31 offset:196
	ds_read_b32 v7, v31 offset:328
	ds_read_b32 v8, v31 offset:460
	ds_read_b32 v9, v31 offset:592
	ds_read_b32 v12, v31 offset:724
	ds_read_b32 v13, v31 offset:856
	ds_read_b32 v14, v31 offset:988
	s_waitcnt lgkmcnt(0)
	v_bfe_u32 v6, v2, 16, 1
	v_add3_u32 v2, v2, v6, s96
	v_bfe_u32 v6, v5, 16, 1
	v_lshrrev_b32_e32 v2, 16, v2
	v_add3_u32 v5, v5, v6, s96
	v_and_or_b32 v6, v5, s97, v2
	v_bfe_u32 v2, v7, 16, 1
	v_add3_u32 v2, v7, v2, s96
	v_bfe_u32 v5, v8, 16, 1
	v_lshrrev_b32_e32 v2, 16, v2
	v_add3_u32 v5, v8, v5, s96
	v_and_or_b32 v7, v5, s97, v2
	v_bfe_u32 v2, v9, 16, 1
	v_add3_u32 v2, v9, v2, s96
	v_bfe_u32 v5, v12, 16, 1
	v_lshrrev_b32_e32 v2, 16, v2
	v_add3_u32 v5, v12, v5, s96
	v_and_or_b32 v8, v5, s97, v2
	v_bfe_u32 v2, v13, 16, 1
	v_or_b32_e32 v12, s66, v33
	v_add3_u32 v2, v13, v2, s96
	v_bfe_u32 v5, v14, 16, 1
	v_ashrrev_i32_e32 v13, 31, v12
	v_lshrrev_b32_e32 v2, 16, v2
	v_add3_u32 v5, v14, v5, s96
	v_lshlrev_b64 v[12:13], 12, v[12:13]
	v_and_or_b32 v9, v5, s97, v2
	v_lshl_add_u64 v[12:13], v[10:11], 0, v[12:13]
	global_store_dwordx4 v[12:13], v[6:9], off
	ds_read_b32 v2, v31 offset:96
	ds_read_b32 v5, v31 offset:228
	ds_read_b32 v7, v31 offset:360
	ds_read_b32 v8, v31 offset:492
	ds_read_b32 v9, v31 offset:624
	ds_read_b32 v12, v31 offset:756
	ds_read_b32 v13, v31 offset:888
	ds_read_b32 v14, v31 offset:1020
	s_waitcnt lgkmcnt(0)
	v_bfe_u32 v6, v2, 16, 1
	v_add3_u32 v2, v2, v6, s96
	v_bfe_u32 v6, v5, 16, 1
	v_lshrrev_b32_e32 v2, 16, v2
	v_add3_u32 v5, v5, v6, s96
	v_and_or_b32 v6, v5, s97, v2
	v_bfe_u32 v2, v7, 16, 1
	v_add3_u32 v2, v7, v2, s96
	v_bfe_u32 v5, v8, 16, 1
	v_lshrrev_b32_e32 v2, 16, v2
	v_add3_u32 v5, v8, v5, s96
	v_and_or_b32 v7, v5, s97, v2
	v_bfe_u32 v2, v9, 16, 1
	v_add3_u32 v2, v9, v2, s96
	v_bfe_u32 v5, v12, 16, 1
	v_lshrrev_b32_e32 v2, 16, v2
	v_add3_u32 v5, v12, v5, s96
	v_and_or_b32 v8, v5, s97, v2
	v_bfe_u32 v2, v13, 16, 1
	v_or_b32_e32 v12, s66, v34
	v_add3_u32 v2, v13, v2, s96
	v_bfe_u32 v5, v14, 16, 1
	v_ashrrev_i32_e32 v13, 31, v12
	v_lshrrev_b32_e32 v2, 16, v2
	v_add3_u32 v5, v14, v5, s96
	v_lshlrev_b64 v[12:13], 12, v[12:13]
	v_and_or_b32 v9, v5, s97, v2
	v_lshl_add_u64 v[10:11], v[10:11], 0, v[12:13]
	global_store_dwordx4 v[10:11], v[6:9], off
	s_waitcnt lgkmcnt(0)

; #define LAS __attribute__((address_space(3)))
; template <int MAP>
; __device__ __forceinline__ void transpose_item(const float* W, int K, int N, int Npad, bf16_t* WT, const float* gk, LAS float* scr, int item, int lane) {
;     const int nblk = Npad / 32, kb = item / nblk, nb = item % nblk, k0 = 64 * kb, n0 = 32 * nb;
;     float sc; const int ns = srcmap<MAP>(n0 + (lane & 31), sc);
;     float wv[32];
;     const float* Wp = W + (size_t)(k0 + (lane >> 5)) * N + (ns >= 0 ? ns : 0);
; #pragma unroll
;     for (int i = 0; i < 32; ++i) wv[i] = Wp[(size_t)(2 * i) * N];
; __global__ void __launch_bounds__(NTHR, 2) mega_fwd(Args a) {
;     ...
;             const int l = it / I_L; int r = it % I_L;
;             if (r < I_IN) { transpose_item<1>(a.w_in + (size_t)l * DM * INC, DM, INC, INP, WIN + (size_t)l * INP * DM, nullptr, scr, r, lane); continue; } r -= I_IN;
;             if (r < I_UQ) { transpose_item<2>(a.b_w_uq + (size_t)l * 384 * 768, 384, 768, 768, WUQ + (size_t)l * 768 * 384, a.b_q_norm + l * 384, scr, r, lane); continue; } r -= I_UQ;
;             if (r < I_UKV) { transpose_item<0>(a.b_w_ukv + (size_t)l * 256 * 1024, 256, 1024, 1024, WUKV + (size_t)l * 1024 * 256, a.b_kv_norm + l * 256, scr, r, lane); continue; } r -= I_UKV;
;             if (r < I_OUT) { transpose_item<0>(a.w_out + (size_t)l * DM * DM, DM, DM, DM, WOUT + (size_t)l * DM * DM, nullptr, scr, r, lane); continue; } r -= I_OUT;
;             if (r < I_F1) { transpose_item<0>(a.w_ff1 + (size_t)l * DM * DFF, DM, DFF, DFF, WFF1 + (size_t)l * DFF * DM, nullptr, scr, r, lane); continue; } r -= I_F1;
;             transpose_item<0>(a.w_ff2 + (size_t)l * DFF * DM, DFF, DM, DM, WFF2 + (size_t)l * DM * DFF, nullptr, scr, r, lane);
.LBB0_9:
	s_cmpk_gt_u32 s64, 0x118f
	s_cbranch_scc0 .LBB0_47
	s_cmpk_gt_u32 s64, 0x120f
	s_cbranch_scc0 .LBB0_20
	s_cmpk_gt_u32 s64, 0x1a0f
	s_cbranch_scc0 .LBB0_17
	s_ashr_i32 s37, s36, 31
	s_lshl_b64 s[66:67], s[36:37], 26
	s_lshl_b64 s[0:1], s[36:37], 25
	s_cmpk_gt_u32 s64, 0x3a0f
	s_mov_b64 s[40:41], -1
	s_cbranch_scc0 .LBB0_14
	v_readlane_b32 s72, v254, 0
	v_readlane_b32 s76, v254, 4
	v_readlane_b32 s77, v254, 5
	s_add_u32 vcc_lo, s76, s66
	s_addc_u32 vcc_hi, s77, s67
	s_add_u32 s40, s25, s0
	s_addc_u32 s41, s26, s1
	s_add_i32 s37, s64, 0xc5f0
	s_and_b32 s65, s37, 0xffc0
	s_lshl_b32 s37, s37, 5
	s_and_b32 s37, s37, 0x7e0
	v_or_b32_e32 v2, s65, v27
	v_or_b32_e32 v5, s37, v26
	v_lshlrev_b32_e32 v2, 13, v2
	v_lshl_add_u64 v[6:7], vcc, 0, v[2:3]
	v_lshlrev_b32_e32 v2, 2, v5
	v_lshl_add_u64 v[6:7], v[6:7], 0, v[2:3]
	v_add_co_u32_e32 v8, vcc, s53, v6
	s_mov_b32 s72, 0x14000
	s_nop 0
	v_addc_co_u32_e32 v9, vcc, 0, v7, vcc
	v_add_co_u32_e32 v10, vcc, s54, v6
	s_lshl_b32 s65, s65, 1
	s_nop 0
	v_addc_co_u32_e32 v11, vcc, 0, v7, vcc
	v_add_co_u32_e32 v12, vcc, s55, v6
	s_add_u32 s40, s40, s65
	s_nop 0
	v_addc_co_u32_e32 v13, vcc, 0, v7, vcc
	v_add_co_u32_e32 v14, vcc, s68, v6
	s_addc_u32 s41, s41, 0
	s_nop 0
	v_addc_co_u32_e32 v15, vcc, 0, v7, vcc
	v_add_co_u32_e32 v16, vcc, s72, v6
	s_mov_b32 s72, 0x3c000
	s_nop 0
	v_addc_co_u32_e32 v17, vcc, 0, v7, vcc
	v_add_co_u32_e32 v18, vcc, s70, v6
	v_readlane_b32 s73, v254, 1
	s_nop 0
	v_addc_co_u32_e32 v19, vcc, 0, v7, vcc
	v_add_co_u32_e32 v20, vcc, s71, v6
	v_readlane_b32 s74, v254, 2
	s_nop 0
	v_addc_co_u32_e32 v21, vcc, 0, v7, vcc
	global_load_dword v2, v[6:7], off
	global_load_dword v5, v[8:9], off
	global_load_dword v55, v[10:11], off
	global_load_dword v56, v[12:13], off
	global_load_dword v57, v[14:15], off
	global_load_dword v58, v[16:17], off
	global_load_dword v59, v[18:19], off
	global_load_dword v60, v[20:21], off
	v_add_co_u32_e32 v8, vcc, s95, v6
	v_readlane_b32 s75, v254, 3
	s_nop 0
	v_addc_co_u32_e32 v9, vcc, 0, v7, vcc
	v_add_co_u32_e32 v10, vcc, s3, v6
	v_readlane_b32 s78, v254, 6
	s_nop 0
	v_addc_co_u32_e32 v11, vcc, 0, v7, vcc
	v_add_co_u32_e32 v12, vcc, s88, v6
	v_readlane_b32 s79, v254, 7
	s_nop 0
	v_addc_co_u32_e32 v13, vcc, 0, v7, vcc
	v_add_co_u32_e32 v14, vcc, s92, v6
	s_nop 1
	v_addc_co_u32_e32 v15, vcc, 0, v7, vcc
	v_add_co_u32_e32 v16, vcc, s45, v6
	s_nop 1
	v_addc_co_u32_e32 v17, vcc, 0, v7, vcc
	v_add_co_u32_e32 v18, vcc, s46, v6
	s_nop 1
	v_addc_co_u32_e32 v19, vcc, 0, v7, vcc
	v_add_co_u32_e32 v20, vcc, s69, v6
	s_nop 1
	v_addc_co_u32_e32 v21, vcc, 0, v7, vcc
	v_add_co_u32_e32 v22, vcc, s72, v6
	s_mov_b32 s72, 0x40000
	s_nop 0
	v_addc_co_u32_e32 v23, vcc, 0, v7, vcc
	global_load_dword v61, v[8:9], off
	global_load_dword v62, v[10:11], off
	global_load_dword v63, v[12:13], off
	global_load_dword v64, v[14:15], off
	global_load_dword v65, v[16:17], off
	global_load_dword v66, v[18:19], off
	global_load_dword v67, v[20:21], off
	global_load_dword v68, v[22:23], off
	v_add_co_u32_e32 v8, vcc, s72, v6
	s_mov_b32 s72, 0x44000
	s_nop 0
	v_addc_co_u32_e32 v9, vcc, 0, v7, vcc
	v_add_co_u32_e32 v10, vcc, s72, v6
	s_mov_b32 s72, 0x48000
	s_nop 0
	v_addc_co_u32_e32 v11, vcc, 0, v7, vcc
	v_add_co_u32_e32 v12, vcc, s72, v6
	s_mov_b32 s72, 0x4c000
	s_nop 0
	v_addc_co_u32_e32 v13, vcc, 0, v7, vcc
	v_add_co_u32_e32 v14, vcc, s72, v6
	s_mov_b32 s72, 0x50000
	s_nop 0
	v_addc_co_u32_e32 v15, vcc, 0, v7, vcc
	v_add_co_u32_e32 v16, vcc, s72, v6
	s_mov_b32 s72, 0x54000
	s_nop 0
	v_addc_co_u32_e32 v17, vcc, 0, v7, vcc
	v_add_co_u32_e32 v18, vcc, s72, v6
	s_mov_b32 s72, 0x58000
	s_nop 0
	v_addc_co_u32_e32 v19, vcc, 0, v7, vcc
	v_add_co_u32_e32 v20, vcc, s72, v6
	s_mov_b32 s72, 0x60000
	s_nop 0
	v_addc_co_u32_e32 v21, vcc, 0, v7, vcc
	v_add_co_u32_e32 v22, vcc, s47, v6
	s_nop 1
	v_addc_co_u32_e32 v23, vcc, 0, v7, vcc
	global_load_dword v69, v[8:9], off
	global_load_dword v70, v[10:11], off
	global_load_dword v71, v[12:13], off
	global_load_dword v72, v[14:15], off
	global_load_dword v73, v[16:17], off
	global_load_dword v74, v[18:19], off
	global_load_dword v75, v[20:21], off
	s_nop 0
	global_load_dword v22, v[22:23], off
	v_add_co_u32_e32 v8, vcc, s72, v6
	s_mov_b32 s72, 0x68000
	s_nop 0
	v_addc_co_u32_e32 v9, vcc, 0, v7, vcc
	v_add_co_u32_e32 v10, vcc, s89, v6
	s_nop 1
	v_addc_co_u32_e32 v11, vcc, 0, v7, vcc
	v_add_co_u32_e32 v12, vcc, s72, v6
	s_mov_b32 s72, 0x70000
	s_nop 0
	v_addc_co_u32_e32 v13, vcc, 0, v7, vcc
	v_add_co_u32_e32 v14, vcc, s91, v6
	s_nop 1
	v_addc_co_u32_e32 v15, vcc, 0, v7, vcc
	v_add_co_u32_e32 v16, vcc, s72, v6
	s_mov_b32 s72, 0x74000
	s_nop 0
	v_addc_co_u32_e32 v17, vcc, 0, v7, vcc
	v_add_co_u32_e32 v18, vcc, s72, v6
	s_mov_b32 s72, 0x78000
	s_nop 0
	v_addc_co_u32_e32 v19, vcc, 0, v7, vcc
	v_add_co_u32_e32 v20, vcc, s72, v6
	s_mov_b32 s72, 0x7c000
	s_nop 0
	v_addc_co_u32_e32 v21, vcc, 0, v7, vcc
	v_add_co_u32_e32 v6, vcc, s72, v6
	s_nop 1
	v_addc_co_u32_e32 v7, vcc, 0, v7, vcc
	global_load_dword v8, v[8:9], off
	s_nop 0
	global_load_dword v9, v[10:11], off
	s_nop 0
	global_load_dword v10, v[12:13], off
	global_load_dword v11, v[14:15], off
	s_nop 0
	global_load_dword v12, v[16:17], off
	global_load_dword v13, v[18:19], off
	global_load_dword v14, v[20:21], off
	s_nop 0
	global_load_dword v6, v[6:7], off
	s_waitcnt vmcnt(0)
	ds_write2_b32 v29, v2, v5 offset1:66
	s_waitcnt vmcnt(28)
	ds_write2_b32 v29, v55, v56 offset0:132 offset1:198
	s_waitcnt vmcnt(26)
	ds_write2_b32 v46, v57, v58 offset0:8 offset1:74
	s_waitcnt vmcnt(24)
	ds_write2_b32 v46, v59, v60 offset0:140 offset1:206
	s_waitcnt vmcnt(22)
	ds_write2_b32 v47, v61, v62 offset0:16 offset1:82
	s_waitcnt vmcnt(20)
; #define LAS __attribute__((address_space(3)))
; __device__ __forceinline__ unsigned pk2(float lo, float hi) { return f2bf(lo) | (f2bf(hi) << 16); }
; template <int MAP>
; __device__ __forceinline__ void transpose_item(const float* W, int K, int N, int Npad, bf16_t* WT, const float* gk, LAS float* scr, int item, int lane) {
;     ...
; #pragma unroll
;     for (int i = 0; i < 32; ++i) { const int kk = 2 * i + (lane >> 5); float v = ns >= 0 ? wv[i] : 0.f; if (gk) v *= gk[k0 + kk]; scr[kk * 33 + (lane & 31)] = v * sc; }
;     asm volatile("s_waitcnt lgkmcnt(0)" ::: "memory");
;     const int c = lane & 7;
; #pragma unroll
;     for (int j = 0; j < 4; ++j) { const int n = (lane >> 3) + 8 * j; const LAS float* s = scr + (8 * c) * 33 + n;
;         u32x4 o; o.x = pk2(s[0 * 33], s[1 * 33]); o.y = pk2(s[2 * 33], s[3 * 33]); o.z = pk2(s[4 * 33], s[5 * 33]); o.w = pk2(s[6 * 33], s[7 * 33]);
;         *(u32x4*)(WT + (size_t)(n0 + n) * K + k0 + 8 * c) = o; }
;     asm volatile("s_waitcnt lgkmcnt(0)" ::: "memory");
	ds_write2_b32 v47, v63, v64 offset0:148 offset1:214
	s_waitcnt vmcnt(18)
	ds_write2_b32 v48, v65, v66 offset0:24 offset1:90
	s_waitcnt vmcnt(16)
	ds_write2_b32 v48, v67, v68 offset0:156 offset1:222
	s_waitcnt vmcnt(14)
	ds_write2_b32 v49, v69, v70 offset0:32 offset1:98
	s_waitcnt vmcnt(12)
	ds_write2_b32 v49, v71, v72 offset0:164 offset1:230
	s_waitcnt vmcnt(10)
	ds_write2_b32 v50, v73, v74 offset0:40 offset1:106
	s_waitcnt vmcnt(8)
	ds_write2_b32 v50, v75, v22 offset0:172 offset1:238
	s_waitcnt vmcnt(6)
	ds_write2_b32 v51, v8, v9 offset0:48 offset1:114
	s_waitcnt vmcnt(4)
	ds_write2_b32 v51, v10, v11 offset0:180 offset1:246
	s_waitcnt vmcnt(2)
	ds_write2_b32 v52, v12, v13 offset0:56 offset1:122
	s_waitcnt vmcnt(0)
	ds_write2_b32 v52, v14, v6 offset0:188 offset1:254
	s_waitcnt lgkmcnt(0)
	v_mov_b32_e32 v5, v3
	v_lshl_add_u64 v[10:11], s[40:41], 0, v[4:5]
	ds_read_b32 v2, v31
	ds_read_b32 v5, v31 offset:132
	ds_read_b32 v7, v31 offset:264
	ds_read_b32 v8, v31 offset:396
	ds_read_b32 v9, v31 offset:528
	ds_read_b32 v12, v31 offset:660
	ds_read_b32 v13, v31 offset:792
	ds_read_b32 v14, v31 offset:924
	s_waitcnt lgkmcnt(7)
	v_bfe_u32 v6, v2, 16, 1
	v_add3_u32 v2, v2, v6, s96
	s_waitcnt lgkmcnt(6)
	v_bfe_u32 v6, v5, 16, 1
	v_lshrrev_b32_e32 v2, 16, v2
	v_add3_u32 v5, v5, v6, s96
	v_and_or_b32 v6, v5, s97, v2
	s_waitcnt lgkmcnt(5)
	v_bfe_u32 v2, v7, 16, 1
	v_add3_u32 v2, v7, v2, s96
	s_waitcnt lgkmcnt(4)
	v_bfe_u32 v5, v8, 16, 1
	v_lshrrev_b32_e32 v2, 16, v2
	v_add3_u32 v5, v8, v5, s96
	v_and_or_b32 v7, v5, s97, v2
	s_waitcnt lgkmcnt(3)
	v_bfe_u32 v2, v9, 16, 1
	v_add3_u32 v2, v9, v2, s96
	s_waitcnt lgkmcnt(2)
	v_bfe_u32 v5, v12, 16, 1
	v_lshrrev_b32_e32 v2, 16, v2
	v_add3_u32 v5, v12, v5, s96
	v_and_or_b32 v8, v5, s97, v2
	s_waitcnt lgkmcnt(1)
	v_bfe_u32 v2, v13, 16, 1
	v_add3_u32 v2, v13, v2, s96
	s_waitcnt lgkmcnt(0)
	v_bfe_u32 v5, v14, 16, 1
	v_lshrrev_b32_e32 v2, 16, v2
	v_add3_u32 v5, v14, v5, s96
	v_and_or_b32 v9, v5, s97, v2
	v_or_b32_e32 v2, s37, v30
	v_lshlrev_b32_e32 v2, 14, v2
	v_lshl_add_u64 v[12:13], v[10:11], 0, v[2:3]
	global_store_dwordx4 v[12:13], v[6:9], off
	ds_read_b32 v2, v31 offset:32
	ds_read_b32 v5, v31 offset:164
	ds_read_b32 v7, v31 offset:296
	ds_read_b32 v8, v31 offset:428
	ds_read_b32 v9, v31 offset:560
	ds_read_b32 v12, v31 offset:692
	ds_read_b32 v13, v31 offset:824
	ds_read_b32 v14, v31 offset:956
	s_waitcnt lgkmcnt(0)
	v_bfe_u32 v6, v2, 16, 1
	v_add3_u32 v2, v2, v6, s96
	v_bfe_u32 v6, v5, 16, 1
	v_lshrrev_b32_e32 v2, 16, v2
	v_add3_u32 v5, v5, v6, s96
	v_and_or_b32 v6, v5, s97, v2
	v_bfe_u32 v2, v7, 16, 1
	v_add3_u32 v2, v7, v2, s96
	v_bfe_u32 v5, v8, 16, 1
	v_lshrrev_b32_e32 v2, 16, v2
	v_add3_u32 v5, v8, v5, s96
	v_and_or_b32 v7, v5, s97, v2
	v_bfe_u32 v2, v9, 16, 1
	v_add3_u32 v2, v9, v2, s96
	v_bfe_u32 v5, v12, 16, 1
	v_lshrrev_b32_e32 v2, 16, v2
	v_add3_u32 v5, v12, v5, s96
	v_and_or_b32 v8, v5, s97, v2
	v_bfe_u32 v2, v13, 16, 1
	v_add3_u32 v2, v13, v2, s96
	v_bfe_u32 v5, v14, 16, 1
	v_lshrrev_b32_e32 v2, 16, v2
	v_add3_u32 v5, v14, v5, s96
	v_and_or_b32 v9, v5, s97, v2
	v_or_b32_e32 v2, s37, v32
	v_lshlrev_b32_e32 v2, 14, v2
	v_lshl_add_u64 v[12:13], v[10:11], 0, v[2:3]
	global_store_dwordx4 v[12:13], v[6:9], off
	ds_read_b32 v2, v31 offset:64
	ds_read_b32 v5, v31 offset:196
	ds_read_b32 v7, v31 offset:328
	ds_read_b32 v8, v31 offset:460
	ds_read_b32 v9, v31 offset:592
	ds_read_b32 v12, v31 offset:724
	ds_read_b32 v13, v31 offset:856
	ds_read_b32 v14, v31 offset:988
	s_waitcnt lgkmcnt(0)
	v_bfe_u32 v6, v2, 16, 1
	v_add3_u32 v2, v2, v6, s96
	v_bfe_u32 v6, v5, 16, 1
	v_lshrrev_b32_e32 v2, 16, v2
	v_add3_u32 v5, v5, v6, s96
	v_and_or_b32 v6, v5, s97, v2
	v_bfe_u32 v2, v7, 16, 1
	v_add3_u32 v2, v7, v2, s96
	v_bfe_u32 v5, v8, 16, 1
	v_lshrrev_b32_e32 v2, 16, v2
	v_add3_u32 v5, v8, v5, s96
	v_and_or_b32 v7, v5, s97, v2
	v_bfe_u32 v2, v9, 16, 1
	v_add3_u32 v2, v9, v2, s96
	v_bfe_u32 v5, v12, 16, 1
	v_lshrrev_b32_e32 v2, 16, v2
	v_add3_u32 v5, v12, v5, s96
	v_and_or_b32 v8, v5, s97, v2
	v_bfe_u32 v2, v13, 16, 1
	v_add3_u32 v2, v13, v2, s96
	v_bfe_u32 v5, v14, 16, 1
	v_lshrrev_b32_e32 v2, 16, v2
	v_add3_u32 v5, v14, v5, s96
	v_and_or_b32 v9, v5, s97, v2
	v_or_b32_e32 v2, s37, v33
	v_lshlrev_b32_e32 v2, 14, v2
	v_lshl_add_u64 v[12:13], v[10:11], 0, v[2:3]
	global_store_dwordx4 v[12:13], v[6:9], off
	ds_read_b32 v2, v31 offset:96
	ds_read_b32 v5, v31 offset:228
	ds_read_b32 v7, v31 offset:360
	ds_read_b32 v8, v31 offset:492
	ds_read_b32 v9, v31 offset:624
	ds_read_b32 v12, v31 offset:756
	ds_read_b32 v13, v31 offset:888
	ds_read_b32 v14, v31 offset:1020
	s_waitcnt lgkmcnt(0)
	v_bfe_u32 v6, v2, 16, 1
	v_add3_u32 v2, v2, v6, s96
	v_bfe_u32 v6, v5, 16, 1
	v_lshrrev_b32_e32 v2, 16, v2
	v_add3_u32 v5, v5, v6, s96
	v_and_or_b32 v6, v5, s97, v2
	v_bfe_u32 v2, v7, 16, 1
	v_add3_u32 v2, v7, v2, s96
	v_bfe_u32 v5, v8, 16, 1
	v_lshrrev_b32_e32 v2, 16, v2
	v_add3_u32 v5, v8, v5, s96
	v_and_or_b32 v7, v5, s97, v2
	v_bfe_u32 v2, v9, 16, 1
	v_add3_u32 v2, v9, v2, s96
	v_bfe_u32 v5, v12, 16, 1
	v_lshrrev_b32_e32 v2, 16, v2
	v_add3_u32 v5, v12, v5, s96
	v_and_or_b32 v8, v5, s97, v2
	v_bfe_u32 v2, v13, 16, 1
	v_add3_u32 v2, v13, v2, s96
	v_bfe_u32 v5, v14, 16, 1
	v_lshrrev_b32_e32 v2, 16, v2
	v_add3_u32 v5, v14, v5, s96
	v_and_or_b32 v9, v5, s97, v2
	v_or_b32_e32 v2, s37, v34
	v_lshlrev_b32_e32 v2, 14, v2
	v_lshl_add_u64 v[10:11], v[10:11], 0, v[2:3]
	global_store_dwordx4 v[10:11], v[6:9], off
	s_waitcnt lgkmcnt(0)
	s_mov_b64 s[40:41], 0
; #define LAS __attribute__((address_space(3)))
; template <int MAP>
; __device__ __forceinline__ void transpose_item(const float* W, int K, int N, int Npad, bf16_t* WT, const float* gk, LAS float* scr, int item, int lane) {
;     const int nblk = Npad / 32, kb = item / nblk, nb = item % nblk, k0 = 64 * kb, n0 = 32 * nb;
;     float sc; const int ns = srcmap<MAP>(n0 + (lane & 31), sc);
;     float wv[32];
;     const float* Wp = W + (size_t)(k0 + (lane >> 5)) * N + (ns >= 0 ? ns : 0);
; #pragma unroll
;     for (int i = 0; i < 32; ++i) wv[i] = Wp[(size_t)(2 * i) * N];
.LBB0_14:
	s_andn2_b64 vcc, exec, s[40:41]
	s_cbranch_vccnz .LBB0_16
	v_readlane_b32 s72, v254, 0
	v_readlane_b32 s74, v254, 2
	v_readlane_b32 s75, v254, 3
	s_add_u32 s66, s74, s66
	s_addc_u32 s67, s75, s67
	s_add_u32 s37, s27, s0
	v_readlane_b32 s0, v254, 31
	s_addc_u32 s1, s0, s1
	s_add_i32 s0, s64, 0xe5f0
	s_bfe_u32 s40, s0, 0x80008
	s_lshl_b32 s0, s0, 5
	s_and_b32 s0, s0, 0x1fe0
	v_lshl_or_b32 v2, s40, 6, v27
	v_or_b32_e32 v5, s0, v26
	v_lshlrev_b32_e32 v2, 15, v2
	v_lshl_add_u64 v[6:7], s[66:67], 0, v[2:3]
	v_lshlrev_b32_e32 v2, 2, v5
	v_lshl_add_u64 v[6:7], v[6:7], 0, v[2:3]
	v_add_co_u32_e32 v8, vcc, s68, v6
	s_mov_b32 s41, 0x40000
	s_nop 0
	v_addc_co_u32_e32 v9, vcc, 0, v7, vcc
	v_add_co_u32_e32 v10, vcc, s95, v6
	s_lshl_b32 s40, s40, 7
	s_nop 0
	v_addc_co_u32_e32 v11, vcc, 0, v7, vcc
	v_add_co_u32_e32 v12, vcc, s45, v6
	s_add_u32 s40, s37, s40
	s_nop 0
	v_addc_co_u32_e32 v13, vcc, 0, v7, vcc
	v_add_co_u32_e32 v14, vcc, s41, v6
	s_mov_b32 s41, 0x50000
	s_nop 0
	v_addc_co_u32_e32 v15, vcc, 0, v7, vcc
	v_add_co_u32_e32 v16, vcc, s41, v6
	s_mov_b32 s41, 0x60000
	s_nop 0
	v_addc_co_u32_e32 v17, vcc, 0, v7, vcc
	v_add_co_u32_e32 v18, vcc, s41, v6
	s_mov_b32 s41, 0x70000
	s_nop 0
	v_addc_co_u32_e32 v19, vcc, 0, v7, vcc
	v_add_co_u32_e32 v20, vcc, s41, v6
	s_mov_b32 s41, 0x80000
	s_nop 0
	v_addc_co_u32_e32 v21, vcc, 0, v7, vcc
	global_load_dword v2, v[6:7], off
	global_load_dword v5, v[8:9], off
	global_load_dword v55, v[10:11], off
	global_load_dword v56, v[12:13], off
	global_load_dword v57, v[14:15], off
	global_load_dword v58, v[16:17], off
	global_load_dword v59, v[18:19], off
	global_load_dword v60, v[20:21], off
	v_add_co_u32_e32 v8, vcc, s41, v6
	s_mov_b32 s41, 0x90000
	s_nop 0
	v_addc_co_u32_e32 v9, vcc, 0, v7, vcc
	v_add_co_u32_e32 v10, vcc, s41, v6
	s_mov_b32 s41, 0xa0000
	s_nop 0
	v_addc_co_u32_e32 v11, vcc, 0, v7, vcc
	v_add_co_u32_e32 v12, vcc, s41, v6
	s_mov_b32 s41, 0xb0000
	s_nop 0
	v_addc_co_u32_e32 v13, vcc, 0, v7, vcc
	v_add_co_u32_e32 v14, vcc, s41, v6
	s_mov_b32 s41, 0xd0000
	s_nop 0
	v_addc_co_u32_e32 v15, vcc, 0, v7, vcc
	v_add_co_u32_e32 v16, vcc, s33, v6
	v_readlane_b32 s73, v254, 1
	s_nop 0
	v_addc_co_u32_e32 v17, vcc, 0, v7, vcc
	v_add_co_u32_e32 v18, vcc, s41, v6
	s_mov_b32 s41, 0xe0000
	s_nop 0
	v_addc_co_u32_e32 v19, vcc, 0, v7, vcc
	v_add_co_u32_e32 v20, vcc, s41, v6
	s_mov_b32 s41, 0xf0000
	s_nop 0
	v_addc_co_u32_e32 v21, vcc, 0, v7, vcc
	v_add_co_u32_e32 v22, vcc, s41, v6
	s_mov_b32 s41, 0x100000
	s_nop 0
	v_addc_co_u32_e32 v23, vcc, 0, v7, vcc
	global_load_dword v61, v[8:9], off
	global_load_dword v62, v[10:11], off
	global_load_dword v63, v[12:13], off
	global_load_dword v64, v[14:15], off
	global_load_dword v65, v[16:17], off
	global_load_dword v66, v[18:19], off
	global_load_dword v67, v[20:21], off
	global_load_dword v68, v[22:23], off
	v_add_co_u32_e32 v8, vcc, s41, v6
	s_mov_b32 s41, 0x110000
	s_nop 0
	v_addc_co_u32_e32 v9, vcc, 0, v7, vcc
	v_add_co_u32_e32 v10, vcc, s41, v6
	s_mov_b32 s41, 0x120000
	s_nop 0
	v_addc_co_u32_e32 v11, vcc, 0, v7, vcc
	v_add_co_u32_e32 v12, vcc, s41, v6
	s_mov_b32 s41, 0x130000
	s_nop 0
	v_addc_co_u32_e32 v13, vcc, 0, v7, vcc
	v_add_co_u32_e32 v14, vcc, s41, v6
	s_mov_b32 s41, 0x140000
	s_nop 0
	v_addc_co_u32_e32 v15, vcc, 0, v7, vcc
	v_add_co_u32_e32 v16, vcc, s41, v6
	s_mov_b32 s41, 0x150000
	s_nop 0
	v_addc_co_u32_e32 v17, vcc, 0, v7, vcc
	v_add_co_u32_e32 v18, vcc, s41, v6
	s_mov_b32 s41, 0x160000
	s_nop 0
	v_addc_co_u32_e32 v19, vcc, 0, v7, vcc
	v_add_co_u32_e32 v20, vcc, s41, v6
	s_mov_b32 s41, 0x170000
	s_nop 0
	v_addc_co_u32_e32 v21, vcc, 0, v7, vcc
	v_add_co_u32_e32 v22, vcc, s41, v6
	s_mov_b32 s41, 0x180000
	s_nop 0
	v_addc_co_u32_e32 v23, vcc, 0, v7, vcc
	global_load_dword v69, v[8:9], off
	global_load_dword v70, v[10:11], off
	global_load_dword v71, v[12:13], off
	global_load_dword v72, v[14:15], off
	global_load_dword v73, v[16:17], off
	global_load_dword v74, v[18:19], off
	global_load_dword v75, v[20:21], off
	s_nop 0
	global_load_dword v22, v[22:23], off
	v_add_co_u32_e32 v8, vcc, s41, v6
	s_mov_b32 s41, 0x190000
	s_nop 0
	v_addc_co_u32_e32 v9, vcc, 0, v7, vcc
	v_add_co_u32_e32 v10, vcc, s41, v6
	s_mov_b32 s41, 0x1a0000
	s_nop 0
	v_addc_co_u32_e32 v11, vcc, 0, v7, vcc
	v_add_co_u32_e32 v12, vcc, s41, v6
	s_mov_b32 s41, 0x1b0000
	s_nop 0
	v_addc_co_u32_e32 v13, vcc, 0, v7, vcc
	v_add_co_u32_e32 v14, vcc, s41, v6
	s_mov_b32 s41, 0x1c0000
	s_nop 0
	v_addc_co_u32_e32 v15, vcc, 0, v7, vcc
	v_add_co_u32_e32 v16, vcc, s41, v6
	s_mov_b32 s41, 0x1d0000
	s_nop 0
	v_addc_co_u32_e32 v17, vcc, 0, v7, vcc
	v_add_co_u32_e32 v18, vcc, s41, v6
	s_mov_b32 s41, 0x1e0000
	s_nop 0
	v_addc_co_u32_e32 v19, vcc, 0, v7, vcc
	v_add_co_u32_e32 v20, vcc, s41, v6
	s_mov_b32 s41, 0x1f0000
	s_nop 0
	v_addc_co_u32_e32 v21, vcc, 0, v7, vcc
	v_add_co_u32_e32 v6, vcc, s41, v6
	s_addc_u32 s41, s1, 0
	s_nop 0
	v_addc_co_u32_e32 v7, vcc, 0, v7, vcc
	global_load_dword v8, v[8:9], off
	s_nop 0
	global_load_dword v9, v[10:11], off
	s_nop 0
	global_load_dword v10, v[12:13], off
	global_load_dword v11, v[14:15], off
	s_nop 0
	global_load_dword v12, v[16:17], off
	global_load_dword v13, v[18:19], off
	global_load_dword v14, v[20:21], off
	s_nop 0
	global_load_dword v6, v[6:7], off
	s_waitcnt vmcnt(0)
; #define LAS __attribute__((address_space(3)))
; __device__ __forceinline__ unsigned pk2(float lo, float hi) { return f2bf(lo) | (f2bf(hi) << 16); }
; template <int MAP>
; __device__ __forceinline__ void transpose_item(const float* W, int K, int N, int Npad, bf16_t* WT, const float* gk, LAS float* scr, int item, int lane) {
;     ...
; #pragma unroll
;     for (int i = 0; i < 32; ++i) { const int kk = 2 * i + (lane >> 5); float v = ns >= 0 ? wv[i] : 0.f; if (gk) v *= gk[k0 + kk]; scr[kk * 33 + (lane & 31)] = v * sc; }
;     asm volatile("s_waitcnt lgkmcnt(0)" ::: "memory");
;     const int c = lane & 7;
; #pragma unroll
;     for (int j = 0; j < 4; ++j) { const int n = (lane >> 3) + 8 * j; const LAS float* s = scr + (8 * c) * 33 + n;
;         u32x4 o; o.x = pk2(s[0 * 33], s[1 * 33]); o.y = pk2(s[2 * 33], s[3 * 33]); o.z = pk2(s[4 * 33], s[5 * 33]); o.w = pk2(s[6 * 33], s[7 * 33]);
;         *(u32x4*)(WT + (size_t)(n0 + n) * K + k0 + 8 * c) = o; }
;     asm volatile("s_waitcnt lgkmcnt(0)" ::: "memory");
	ds_write2_b32 v29, v2, v5 offset1:66
	ds_write2_b32 v29, v55, v56 offset0:132 offset1:198
	ds_write2_b32 v46, v57, v58 offset0:8 offset1:74
	ds_write2_b32 v46, v59, v60 offset0:140 offset1:206
	ds_write2_b32 v47, v61, v62 offset0:16 offset1:82
	ds_write2_b32 v47, v63, v64 offset0:148 offset1:214
	ds_write2_b32 v48, v65, v66 offset0:24 offset1:90
	ds_write2_b32 v48, v67, v68 offset0:156 offset1:222
	ds_write2_b32 v49, v69, v70 offset0:32 offset1:98
	ds_write2_b32 v49, v71, v72 offset0:164 offset1:230
	ds_write2_b32 v50, v73, v74 offset0:40 offset1:106
	ds_write2_b32 v50, v75, v22 offset0:172 offset1:238
	ds_write2_b32 v51, v8, v9 offset0:48 offset1:114
	ds_write2_b32 v51, v10, v11 offset0:180 offset1:246
	ds_write2_b32 v52, v12, v13 offset0:56 offset1:122
	ds_write2_b32 v52, v14, v6 offset0:188 offset1:254
	s_waitcnt lgkmcnt(0)
	v_mov_b32_e32 v5, v3
	v_lshl_add_u64 v[10:11], s[40:41], 0, v[4:5]
	ds_read_b32 v2, v31
	ds_read_b32 v5, v31 offset:132
	ds_read_b32 v7, v31 offset:264
	ds_read_b32 v8, v31 offset:396
	ds_read_b32 v9, v31 offset:528
	ds_read_b32 v12, v31 offset:660
	ds_read_b32 v13, v31 offset:792
	ds_read_b32 v14, v31 offset:924
	s_waitcnt lgkmcnt(0)
	v_bfe_u32 v6, v2, 16, 1
	v_add3_u32 v2, v2, v6, s96
	v_bfe_u32 v6, v5, 16, 1
	v_lshrrev_b32_e32 v2, 16, v2
	v_add3_u32 v5, v5, v6, s96
	v_and_or_b32 v6, v5, s97, v2
	v_bfe_u32 v2, v7, 16, 1
	v_add3_u32 v2, v7, v2, s96
	v_bfe_u32 v5, v8, 16, 1
	v_lshrrev_b32_e32 v2, 16, v2
	v_add3_u32 v5, v8, v5, s96
	v_and_or_b32 v7, v5, s97, v2
	v_bfe_u32 v2, v9, 16, 1
	v_add3_u32 v2, v9, v2, s96
	v_bfe_u32 v5, v12, 16, 1
	v_lshrrev_b32_e32 v2, 16, v2
	v_add3_u32 v5, v12, v5, s96
	v_and_or_b32 v8, v5, s97, v2
	v_bfe_u32 v2, v13, 16, 1
	v_add3_u32 v2, v13, v2, s96
	v_bfe_u32 v5, v14, 16, 1
	v_lshrrev_b32_e32 v2, 16, v2
	v_add3_u32 v5, v14, v5, s96
	v_and_or_b32 v9, v5, s97, v2
	v_or_b32_e32 v2, s0, v30
	v_lshlrev_b32_e32 v2, 12, v2
	v_lshl_add_u64 v[12:13], v[10:11], 0, v[2:3]
	global_store_dwordx4 v[12:13], v[6:9], off
	ds_read_b32 v2, v31 offset:32
	ds_read_b32 v5, v31 offset:164
	ds_read_b32 v7, v31 offset:296
	ds_read_b32 v8, v31 offset:428
	ds_read_b32 v9, v31 offset:560
	ds_read_b32 v12, v31 offset:692
	ds_read_b32 v13, v31 offset:824
	ds_read_b32 v14, v31 offset:956
	s_waitcnt lgkmcnt(0)
	v_bfe_u32 v6, v2, 16, 1
	v_add3_u32 v2, v2, v6, s96
	v_bfe_u32 v6, v5, 16, 1
	v_lshrrev_b32_e32 v2, 16, v2
	v_add3_u32 v5, v5, v6, s96
	v_and_or_b32 v6, v5, s97, v2
	v_bfe_u32 v2, v7, 16, 1
	v_add3_u32 v2, v7, v2, s96
	v_bfe_u32 v5, v8, 16, 1
	v_lshrrev_b32_e32 v2, 16, v2
	v_add3_u32 v5, v8, v5, s96
	v_and_or_b32 v7, v5, s97, v2
	v_bfe_u32 v2, v9, 16, 1
	v_add3_u32 v2, v9, v2, s96
	v_bfe_u32 v5, v12, 16, 1
	v_lshrrev_b32_e32 v2, 16, v2
	v_add3_u32 v5, v12, v5, s96
	v_and_or_b32 v8, v5, s97, v2
	v_bfe_u32 v2, v13, 16, 1
	v_add3_u32 v2, v13, v2, s96
	v_bfe_u32 v5, v14, 16, 1
	v_lshrrev_b32_e32 v2, 16, v2
	v_add3_u32 v5, v14, v5, s96
	v_and_or_b32 v9, v5, s97, v2
	v_or_b32_e32 v2, s0, v32
	v_lshlrev_b32_e32 v2, 12, v2
	v_lshl_add_u64 v[12:13], v[10:11], 0, v[2:3]
	global_store_dwordx4 v[12:13], v[6:9], off
	ds_read_b32 v2, v31 offset:64
	ds_read_b32 v5, v31 offset:196
	ds_read_b32 v7, v31 offset:328
	ds_read_b32 v8, v31 offset:460
	ds_read_b32 v9, v31 offset:592
	ds_read_b32 v12, v31 offset:724
	ds_read_b32 v13, v31 offset:856
	ds_read_b32 v14, v31 offset:988
	s_waitcnt lgkmcnt(0)
	v_bfe_u32 v6, v2, 16, 1
	v_add3_u32 v2, v2, v6, s96
	v_bfe_u32 v6, v5, 16, 1
	v_lshrrev_b32_e32 v2, 16, v2
	v_add3_u32 v5, v5, v6, s96
	v_and_or_b32 v6, v5, s97, v2
	v_bfe_u32 v2, v7, 16, 1
	v_add3_u32 v2, v7, v2, s96
	v_bfe_u32 v5, v8, 16, 1
	v_lshrrev_b32_e32 v2, 16, v2
	v_add3_u32 v5, v8, v5, s96
	v_and_or_b32 v7, v5, s97, v2
	v_bfe_u32 v2, v9, 16, 1
	v_add3_u32 v2, v9, v2, s96
	v_bfe_u32 v5, v12, 16, 1
	v_lshrrev_b32_e32 v2, 16, v2
	v_add3_u32 v5, v12, v5, s96
	v_and_or_b32 v8, v5, s97, v2
	v_bfe_u32 v2, v13, 16, 1
	v_add3_u32 v2, v13, v2, s96
	v_bfe_u32 v5, v14, 16, 1
	v_lshrrev_b32_e32 v2, 16, v2
	v_add3_u32 v5, v14, v5, s96
	v_and_or_b32 v9, v5, s97, v2
	v_or_b32_e32 v2, s0, v33
	v_lshlrev_b32_e32 v2, 12, v2
	v_lshl_add_u64 v[12:13], v[10:11], 0, v[2:3]
	global_store_dwordx4 v[12:13], v[6:9], off
	ds_read_b32 v2, v31 offset:96
	ds_read_b32 v5, v31 offset:228
	ds_read_b32 v7, v31 offset:360
	ds_read_b32 v8, v31 offset:492
	ds_read_b32 v9, v31 offset:624
	ds_read_b32 v12, v31 offset:756
	ds_read_b32 v13, v31 offset:888
	ds_read_b32 v14, v31 offset:1020
	s_waitcnt lgkmcnt(0)
	v_bfe_u32 v6, v2, 16, 1
	v_add3_u32 v2, v2, v6, s96
	v_bfe_u32 v6, v5, 16, 1
	v_lshrrev_b32_e32 v2, 16, v2
	v_add3_u32 v5, v5, v6, s96
	v_and_or_b32 v6, v5, s97, v2
	v_bfe_u32 v2, v7, 16, 1
	v_add3_u32 v2, v7, v2, s96
	v_bfe_u32 v5, v8, 16, 1
	v_lshrrev_b32_e32 v2, 16, v2
	v_add3_u32 v5, v8, v5, s96
	v_and_or_b32 v7, v5, s97, v2
	v_bfe_u32 v2, v9, 16, 1
	v_add3_u32 v2, v9, v2, s96
	v_bfe_u32 v5, v12, 16, 1
	v_lshrrev_b32_e32 v2, 16, v2
	v_add3_u32 v5, v12, v5, s96
	v_and_or_b32 v8, v5, s97, v2
	v_bfe_u32 v2, v13, 16, 1
	v_add3_u32 v2, v13, v2, s96
	v_bfe_u32 v5, v14, 16, 1
	v_lshrrev_b32_e32 v2, 16, v2
	v_add3_u32 v5, v14, v5, s96
	v_and_or_b32 v9, v5, s97, v2
	v_or_b32_e32 v2, s0, v34
	v_lshlrev_b32_e32 v2, 12, v2
	v_lshl_add_u64 v[10:11], v[10:11], 0, v[2:3]
	global_store_dwordx4 v[10:11], v[6:9], off
	s_waitcnt lgkmcnt(0)
	v_readlane_b32 s76, v254, 4
	v_readlane_b32 s77, v254, 5
	v_readlane_b32 s78, v254, 6
	v_readlane_b32 s79, v254, 7

; #define LAS __attribute__((address_space(3)))
; template <int MAP>
; __device__ __forceinline__ void transpose_item(const float* W, int K, int N, int Npad, bf16_t* WT, const float* gk, LAS float* scr, int item, int lane) {
;     const int nblk = Npad / 32, kb = item / nblk, nb = item % nblk, k0 = 64 * kb, n0 = 32 * nb;
;     float sc; const int ns = srcmap<MAP>(n0 + (lane & 31), sc);
;     float wv[32];
;     const float* Wp = W + (size_t)(k0 + (lane >> 5)) * N + (ns >= 0 ? ns : 0);
; #pragma unroll
;     for (int i = 0; i < 32; ++i) wv[i] = Wp[(size_t)(2 * i) * N];
.LBB0_17:
	s_andn2_b64 vcc, exec, s[0:1]
	s_cbranch_vccnz .LBB0_19
	s_ashr_i32 s37, s36, 31
	s_lshl_b64 s[0:1], s[36:37], 24
	s_add_u32 s66, s18, s0
	s_addc_u32 s67, s19, s1
	s_lshl_b64 s[40:41], s[36:37], 23
	v_readlane_b32 s0, v254, 32
	s_add_u32 s1, s0, s40
	v_readlane_b32 s0, v254, 33
	s_addc_u32 s37, s0, s41
	s_add_i32 s0, s64, 0xedf0
	s_and_b32 s40, s0, 0xffc0
	s_lshl_b32 s0, s0, 5
	s_and_b32 s0, s0, 0x7e0
	v_or_b32_e32 v2, s40, v27
	v_or_b32_e32 v5, s0, v26
	v_lshlrev_b32_e32 v2, 13, v2
	v_lshl_add_u64 v[6:7], s[66:67], 0, v[2:3]
	v_lshlrev_b32_e32 v2, 2, v5
	v_lshl_add_u64 v[6:7], v[6:7], 0, v[2:3]
	v_add_co_u32_e32 v8, vcc, s53, v6
	s_mov_b32 s41, 0x14000
	s_nop 0
	v_addc_co_u32_e32 v9, vcc, 0, v7, vcc
	v_add_co_u32_e32 v10, vcc, s54, v6
	s_lshl_b32 s40, s40, 1
	s_nop 0
	v_addc_co_u32_e32 v11, vcc, 0, v7, vcc
	v_add_co_u32_e32 v12, vcc, s55, v6
	s_add_u32 s40, s1, s40
	s_nop 0
	v_addc_co_u32_e32 v13, vcc, 0, v7, vcc
	v_add_co_u32_e32 v14, vcc, s68, v6
	s_nop 1
	v_addc_co_u32_e32 v15, vcc, 0, v7, vcc
	v_add_co_u32_e32 v16, vcc, s41, v6
	s_mov_b32 s41, 0x3c000
	s_nop 0
	v_addc_co_u32_e32 v17, vcc, 0, v7, vcc
	v_add_co_u32_e32 v18, vcc, s70, v6
	s_nop 1
	v_addc_co_u32_e32 v19, vcc, 0, v7, vcc
	v_add_co_u32_e32 v20, vcc, s71, v6
	s_nop 1
	v_addc_co_u32_e32 v21, vcc, 0, v7, vcc
	global_load_dword v2, v[6:7], off
	global_load_dword v5, v[8:9], off
	global_load_dword v55, v[10:11], off
	global_load_dword v56, v[12:13], off
	global_load_dword v57, v[14:15], off
	global_load_dword v58, v[16:17], off
	global_load_dword v59, v[18:19], off
	global_load_dword v60, v[20:21], off
	v_add_co_u32_e32 v8, vcc, s95, v6
	s_nop 1
	v_addc_co_u32_e32 v9, vcc, 0, v7, vcc
	v_add_co_u32_e32 v10, vcc, s3, v6
	s_nop 1
	v_addc_co_u32_e32 v11, vcc, 0, v7, vcc
	v_add_co_u32_e32 v12, vcc, s88, v6
	s_nop 1
	v_addc_co_u32_e32 v13, vcc, 0, v7, vcc
	v_add_co_u32_e32 v14, vcc, s92, v6
	s_nop 1
	v_addc_co_u32_e32 v15, vcc, 0, v7, vcc
	v_add_co_u32_e32 v16, vcc, s45, v6
	s_nop 1
	v_addc_co_u32_e32 v17, vcc, 0, v7, vcc
	v_add_co_u32_e32 v18, vcc, s46, v6
	s_nop 1
	v_addc_co_u32_e32 v19, vcc, 0, v7, vcc
	v_add_co_u32_e32 v20, vcc, s69, v6
	s_nop 1
	v_addc_co_u32_e32 v21, vcc, 0, v7, vcc
	v_add_co_u32_e32 v22, vcc, s41, v6
	s_mov_b32 s41, 0x40000
	s_nop 0
	v_addc_co_u32_e32 v23, vcc, 0, v7, vcc
	global_load_dword v61, v[8:9], off
	global_load_dword v62, v[10:11], off
	global_load_dword v63, v[12:13], off
	global_load_dword v64, v[14:15], off
	global_load_dword v65, v[16:17], off
	global_load_dword v66, v[18:19], off
	global_load_dword v67, v[20:21], off
	global_load_dword v68, v[22:23], off
	v_add_co_u32_e32 v8, vcc, s41, v6
	s_mov_b32 s41, 0x44000
	s_nop 0
	v_addc_co_u32_e32 v9, vcc, 0, v7, vcc
	v_add_co_u32_e32 v10, vcc, s41, v6
	s_mov_b32 s41, 0x48000
	s_nop 0
	v_addc_co_u32_e32 v11, vcc, 0, v7, vcc
	v_add_co_u32_e32 v12, vcc, s41, v6
	s_mov_b32 s41, 0x4c000
	s_nop 0
	v_addc_co_u32_e32 v13, vcc, 0, v7, vcc
	v_add_co_u32_e32 v14, vcc, s41, v6
	s_mov_b32 s41, 0x50000
	s_nop 0
	v_addc_co_u32_e32 v15, vcc, 0, v7, vcc
	v_add_co_u32_e32 v16, vcc, s41, v6
	s_mov_b32 s41, 0x54000
	s_nop 0
	v_addc_co_u32_e32 v17, vcc, 0, v7, vcc
	v_add_co_u32_e32 v18, vcc, s41, v6
	s_mov_b32 s41, 0x58000
	s_nop 0
	v_addc_co_u32_e32 v19, vcc, 0, v7, vcc
	v_add_co_u32_e32 v20, vcc, s41, v6
	s_mov_b32 s41, 0x60000
	s_nop 0
	v_addc_co_u32_e32 v21, vcc, 0, v7, vcc
	v_add_co_u32_e32 v22, vcc, s47, v6
	s_nop 1
	v_addc_co_u32_e32 v23, vcc, 0, v7, vcc
	global_load_dword v69, v[8:9], off
	global_load_dword v70, v[10:11], off
	global_load_dword v71, v[12:13], off
	global_load_dword v72, v[14:15], off
	global_load_dword v73, v[16:17], off
	global_load_dword v74, v[18:19], off
	global_load_dword v75, v[20:21], off
	s_nop 0
	global_load_dword v22, v[22:23], off
	v_add_co_u32_e32 v8, vcc, s41, v6
	s_mov_b32 s41, 0x68000
	s_nop 0
	v_addc_co_u32_e32 v9, vcc, 0, v7, vcc
	v_add_co_u32_e32 v10, vcc, s89, v6
	s_nop 1
	v_addc_co_u32_e32 v11, vcc, 0, v7, vcc
	v_add_co_u32_e32 v12, vcc, s41, v6
	s_mov_b32 s41, 0x70000
	s_nop 0
	v_addc_co_u32_e32 v13, vcc, 0, v7, vcc
	v_add_co_u32_e32 v14, vcc, s91, v6
	s_nop 1
	v_addc_co_u32_e32 v15, vcc, 0, v7, vcc
	v_add_co_u32_e32 v16, vcc, s41, v6
	s_mov_b32 s41, 0x74000
	s_nop 0
	v_addc_co_u32_e32 v17, vcc, 0, v7, vcc
	v_add_co_u32_e32 v18, vcc, s41, v6
	s_mov_b32 s41, 0x78000
	s_nop 0
	v_addc_co_u32_e32 v19, vcc, 0, v7, vcc
	v_add_co_u32_e32 v20, vcc, s41, v6
	s_mov_b32 s41, 0x7c000
	s_nop 0
	v_addc_co_u32_e32 v21, vcc, 0, v7, vcc
	v_add_co_u32_e32 v6, vcc, s41, v6
	s_addc_u32 s41, s37, 0
	s_nop 0
	v_addc_co_u32_e32 v7, vcc, 0, v7, vcc
	global_load_dword v8, v[8:9], off
	s_nop 0
	global_load_dword v9, v[10:11], off
	s_nop 0
	global_load_dword v10, v[12:13], off
	global_load_dword v11, v[14:15], off
	s_nop 0
	global_load_dword v12, v[16:17], off
	global_load_dword v13, v[18:19], off
	global_load_dword v14, v[20:21], off
	s_nop 0
	global_load_dword v6, v[6:7], off
	s_waitcnt vmcnt(0)
; #define LAS __attribute__((address_space(3)))
; __device__ __forceinline__ unsigned pk2(float lo, float hi) { return f2bf(lo) | (f2bf(hi) << 16); }
; template <int MAP>
; __device__ __forceinline__ void transpose_item(const float* W, int K, int N, int Npad, bf16_t* WT, const float* gk, LAS float* scr, int item, int lane) {
;     ...
; #pragma unroll
;     for (int i = 0; i < 32; ++i) { const int kk = 2 * i + (lane >> 5); float v = ns >= 0 ? wv[i] : 0.f; if (gk) v *= gk[k0 + kk]; scr[kk * 33 + (lane & 31)] = v * sc; }
;     asm volatile("s_waitcnt lgkmcnt(0)" ::: "memory");
;     const int c = lane & 7;
; #pragma unroll
;     for (int j = 0; j < 4; ++j) { const int n = (lane >> 3) + 8 * j; const LAS float* s = scr + (8 * c) * 33 + n;
;         u32x4 o; o.x = pk2(s[0 * 33], s[1 * 33]); o.y = pk2(s[2 * 33], s[3 * 33]); o.z = pk2(s[4 * 33], s[5 * 33]); o.w = pk2(s[6 * 33], s[7 * 33]);
;         *(u32x4*)(WT + (size_t)(n0 + n) * K + k0 + 8 * c) = o; }
;     asm volatile("s_waitcnt lgkmcnt(0)" ::: "memory");
	ds_write2_b32 v29, v2, v5 offset1:66
	ds_write2_b32 v29, v55, v56 offset0:132 offset1:198
	ds_write2_b32 v46, v57, v58 offset0:8 offset1:74
	ds_write2_b32 v46, v59, v60 offset0:140 offset1:206
	ds_write2_b32 v47, v61, v62 offset0:16 offset1:82
	ds_write2_b32 v47, v63, v64 offset0:148 offset1:214
	ds_write2_b32 v48, v65, v66 offset0:24 offset1:90
	ds_write2_b32 v48, v67, v68 offset0:156 offset1:222
	ds_write2_b32 v49, v69, v70 offset0:32 offset1:98
	ds_write2_b32 v49, v71, v72 offset0:164 offset1:230
	ds_write2_b32 v50, v73, v74 offset0:40 offset1:106
	ds_write2_b32 v50, v75, v22 offset0:172 offset1:238
	ds_write2_b32 v51, v8, v9 offset0:48 offset1:114
	ds_write2_b32 v51, v10, v11 offset0:180 offset1:246
	ds_write2_b32 v52, v12, v13 offset0:56 offset1:122
	ds_write2_b32 v52, v14, v6 offset0:188 offset1:254
	s_waitcnt lgkmcnt(0)
	v_mov_b32_e32 v5, v3
	v_lshl_add_u64 v[10:11], s[40:41], 0, v[4:5]
	ds_read_b32 v2, v31
	ds_read_b32 v5, v31 offset:132
	ds_read_b32 v7, v31 offset:264
	ds_read_b32 v8, v31 offset:396
	ds_read_b32 v9, v31 offset:528
	ds_read_b32 v12, v31 offset:660
	ds_read_b32 v13, v31 offset:792
	ds_read_b32 v14, v31 offset:924
	s_waitcnt lgkmcnt(0)
	v_bfe_u32 v6, v2, 16, 1
	v_add3_u32 v2, v2, v6, s96
	v_bfe_u32 v6, v5, 16, 1
	v_lshrrev_b32_e32 v2, 16, v2
	v_add3_u32 v5, v5, v6, s96
	v_and_or_b32 v6, v5, s97, v2
	v_bfe_u32 v2, v7, 16, 1
	v_add3_u32 v2, v7, v2, s96
	v_bfe_u32 v5, v8, 16, 1
	v_lshrrev_b32_e32 v2, 16, v2
	v_add3_u32 v5, v8, v5, s96
	v_and_or_b32 v7, v5, s97, v2
	v_bfe_u32 v2, v9, 16, 1
	v_add3_u32 v2, v9, v2, s96
	v_bfe_u32 v5, v12, 16, 1
	v_lshrrev_b32_e32 v2, 16, v2
	v_add3_u32 v5, v12, v5, s96
	v_and_or_b32 v8, v5, s97, v2
	v_bfe_u32 v2, v13, 16, 1
	v_add3_u32 v2, v13, v2, s96
	v_bfe_u32 v5, v14, 16, 1
	v_lshrrev_b32_e32 v2, 16, v2
	v_add3_u32 v5, v14, v5, s96
	v_and_or_b32 v9, v5, s97, v2
	v_or_b32_e32 v2, s0, v30
	v_lshlrev_b32_e32 v2, 12, v2
	v_lshl_add_u64 v[12:13], v[10:11], 0, v[2:3]
	global_store_dwordx4 v[12:13], v[6:9], off
	ds_read_b32 v2, v31 offset:32
	ds_read_b32 v5, v31 offset:164
	ds_read_b32 v7, v31 offset:296
	ds_read_b32 v8, v31 offset:428
	ds_read_b32 v9, v31 offset:560
	ds_read_b32 v12, v31 offset:692
	ds_read_b32 v13, v31 offset:824
	ds_read_b32 v14, v31 offset:956
	s_waitcnt lgkmcnt(0)
	v_bfe_u32 v6, v2, 16, 1
	v_add3_u32 v2, v2, v6, s96
	v_bfe_u32 v6, v5, 16, 1
	v_lshrrev_b32_e32 v2, 16, v2
	v_add3_u32 v5, v5, v6, s96
	v_and_or_b32 v6, v5, s97, v2
	v_bfe_u32 v2, v7, 16, 1
	v_add3_u32 v2, v7, v2, s96
	v_bfe_u32 v5, v8, 16, 1
	v_lshrrev_b32_e32 v2, 16, v2
	v_add3_u32 v5, v8, v5, s96
	v_and_or_b32 v7, v5, s97, v2
	v_bfe_u32 v2, v9, 16, 1
	v_add3_u32 v2, v9, v2, s96
	v_bfe_u32 v5, v12, 16, 1
	v_lshrrev_b32_e32 v2, 16, v2
	v_add3_u32 v5, v12, v5, s96
	v_and_or_b32 v8, v5, s97, v2
	v_bfe_u32 v2, v13, 16, 1
	v_add3_u32 v2, v13, v2, s96
	v_bfe_u32 v5, v14, 16, 1
	v_lshrrev_b32_e32 v2, 16, v2
	v_add3_u32 v5, v14, v5, s96
	v_and_or_b32 v9, v5, s97, v2
	v_or_b32_e32 v2, s0, v32
	v_lshlrev_b32_e32 v2, 12, v2
	v_lshl_add_u64 v[12:13], v[10:11], 0, v[2:3]
	global_store_dwordx4 v[12:13], v[6:9], off
	ds_read_b32 v2, v31 offset:64
	ds_read_b32 v5, v31 offset:196
	ds_read_b32 v7, v31 offset:328
	ds_read_b32 v8, v31 offset:460
	ds_read_b32 v9, v31 offset:592
	ds_read_b32 v12, v31 offset:724
	ds_read_b32 v13, v31 offset:856
	ds_read_b32 v14, v31 offset:988
	s_waitcnt lgkmcnt(0)
	v_bfe_u32 v6, v2, 16, 1
	v_add3_u32 v2, v2, v6, s96
	v_bfe_u32 v6, v5, 16, 1
	v_lshrrev_b32_e32 v2, 16, v2
	v_add3_u32 v5, v5, v6, s96
	v_and_or_b32 v6, v5, s97, v2
	v_bfe_u32 v2, v7, 16, 1
	v_add3_u32 v2, v7, v2, s96
	v_bfe_u32 v5, v8, 16, 1
	v_lshrrev_b32_e32 v2, 16, v2
	v_add3_u32 v5, v8, v5, s96
	v_and_or_b32 v7, v5, s97, v2
	v_bfe_u32 v2, v9, 16, 1
	v_add3_u32 v2, v9, v2, s96
	v_bfe_u32 v5, v12, 16, 1
	v_lshrrev_b32_e32 v2, 16, v2
	v_add3_u32 v5, v12, v5, s96
	v_and_or_b32 v8, v5, s97, v2
	v_bfe_u32 v2, v13, 16, 1
	v_add3_u32 v2, v13, v2, s96
	v_bfe_u32 v5, v14, 16, 1
	v_lshrrev_b32_e32 v2, 16, v2
	v_add3_u32 v5, v14, v5, s96
	v_and_or_b32 v9, v5, s97, v2
	v_or_b32_e32 v2, s0, v33
	v_lshlrev_b32_e32 v2, 12, v2
	v_lshl_add_u64 v[12:13], v[10:11], 0, v[2:3]
	global_store_dwordx4 v[12:13], v[6:9], off
	ds_read_b32 v2, v31 offset:96
	ds_read_b32 v5, v31 offset:228
	ds_read_b32 v7, v31 offset:360
	ds_read_b32 v8, v31 offset:492
	ds_read_b32 v9, v31 offset:624
	ds_read_b32 v12, v31 offset:756
	ds_read_b32 v13, v31 offset:888
	ds_read_b32 v14, v31 offset:1020
	s_waitcnt lgkmcnt(0)
	v_bfe_u32 v6, v2, 16, 1
	v_add3_u32 v2, v2, v6, s96
	v_bfe_u32 v6, v5, 16, 1
	v_lshrrev_b32_e32 v2, 16, v2
	v_add3_u32 v5, v5, v6, s96
	v_and_or_b32 v6, v5, s97, v2
	v_bfe_u32 v2, v7, 16, 1
	v_add3_u32 v2, v7, v2, s96
	v_bfe_u32 v5, v8, 16, 1
	v_lshrrev_b32_e32 v2, 16, v2
	v_add3_u32 v5, v8, v5, s96
	v_and_or_b32 v7, v5, s97, v2
	v_bfe_u32 v2, v9, 16, 1
	v_add3_u32 v2, v9, v2, s96
	v_bfe_u32 v5, v12, 16, 1
	v_lshrrev_b32_e32 v2, 16, v2
	v_add3_u32 v5, v12, v5, s96
	v_and_or_b32 v8, v5, s97, v2
	v_bfe_u32 v2, v13, 16, 1
	v_add3_u32 v2, v13, v2, s96
	v_bfe_u32 v5, v14, 16, 1
	v_lshrrev_b32_e32 v2, 16, v2
	v_add3_u32 v5, v14, v5, s96
	v_and_or_b32 v9, v5, s97, v2
	v_or_b32_e32 v2, s0, v34
	v_lshlrev_b32_e32 v2, 12, v2
	v_lshl_add_u64 v[10:11], v[10:11], 0, v[2:3]
	global_store_dwordx4 v[10:11], v[6:9], off
	s_waitcnt lgkmcnt(0)

; #define LAS __attribute__((address_space(3)))
; __device__ __forceinline__ unsigned pk2(float lo, float hi) { return f2bf(lo) | (f2bf(hi) << 16); }
; template <int MAP>
; __device__ __forceinline__ void transpose_item(const float* W, int K, int N, int Npad, bf16_t* WT, const float* gk, LAS float* scr, int item, int lane) {
;     ...
; #pragma unroll
;     for (int i = 0; i < 32; ++i) { const int kk = 2 * i + (lane >> 5); float v = ns >= 0 ? wv[i] : 0.f; if (gk) v *= gk[k0 + kk]; scr[kk * 33 + (lane & 31)] = v * sc; }
;     asm volatile("s_waitcnt lgkmcnt(0)" ::: "memory");
;     const int c = lane & 7;
; #pragma unroll
;     for (int j = 0; j < 4; ++j) { const int n = (lane >> 3) + 8 * j; const LAS float* s = scr + (8 * c) * 33 + n;
;         u32x4 o; o.x = pk2(s[0 * 33], s[1 * 33]); o.y = pk2(s[2 * 33], s[3 * 33]); o.z = pk2(s[4 * 33], s[5 * 33]); o.w = pk2(s[6 * 33], s[7 * 33]);
;         *(u32x4*)(WT + (size_t)(n0 + n) * K + k0 + 8 * c) = o; }
;     asm volatile("s_waitcnt lgkmcnt(0)" ::: "memory");
.LBB0_45:
	s_lshl_b64 s[0:1], s[36:37], 19
	v_readlane_b32 s37, v254, 34
	s_add_u32 s0, s37, s0
	v_readlane_b32 s37, v254, 35
	s_addc_u32 s1, s37, s1
	s_lshl_b32 s37, s94, 1
	ds_write2_b32 v10, v8, v9 offset0:148 offset1:214
	s_add_u32 s0, s0, s37
	s_waitcnt lgkmcnt(0)
	s_addc_u32 s1, s1, 0
	v_mov_b32_e32 v5, v3
	v_lshl_add_u64 v[10:11], s[0:1], 0, v[4:5]
	ds_read_b32 v2, v31
	ds_read_b32 v5, v31 offset:132
	ds_read_b32 v7, v31 offset:264
	ds_read_b32 v8, v31 offset:396
	ds_read_b32 v9, v31 offset:528
	ds_read_b32 v12, v31 offset:660
	ds_read_b32 v13, v31 offset:792
	ds_read_b32 v14, v31 offset:924
	s_waitcnt lgkmcnt(0)
	v_bfe_u32 v6, v2, 16, 1
	v_add3_u32 v2, v2, v6, s96
	v_bfe_u32 v6, v5, 16, 1
	v_lshrrev_b32_e32 v2, 16, v2
	v_add3_u32 v5, v5, v6, s96
	v_and_or_b32 v6, v5, s97, v2
	v_bfe_u32 v2, v7, 16, 1
	v_add3_u32 v2, v7, v2, s96
	v_bfe_u32 v5, v8, 16, 1
	v_lshrrev_b32_e32 v2, 16, v2
	v_add3_u32 v5, v8, v5, s96
	v_and_or_b32 v7, v5, s97, v2
	v_bfe_u32 v2, v9, 16, 1
	v_add3_u32 v2, v9, v2, s96
	v_bfe_u32 v5, v12, 16, 1
	v_lshrrev_b32_e32 v2, 16, v2
	v_add3_u32 v5, v12, v5, s96
	v_and_or_b32 v8, v5, s97, v2
	v_bfe_u32 v2, v13, 16, 1
	v_add3_u32 v2, v13, v2, s96
	v_bfe_u32 v5, v14, 16, 1
	v_lshrrev_b32_e32 v2, 16, v2
	v_add3_u32 v5, v14, v5, s96
	v_and_or_b32 v9, v5, s97, v2
	v_or_b32_e32 v2, s65, v30
	v_lshlrev_b32_e32 v2, 9, v2
	v_lshl_add_u64 v[12:13], v[10:11], 0, v[2:3]
	global_store_dwordx4 v[12:13], v[6:9], off
	ds_read_b32 v2, v31 offset:32
	ds_read_b32 v5, v31 offset:164
	ds_read_b32 v7, v31 offset:296
	ds_read_b32 v8, v31 offset:428
	ds_read_b32 v9, v31 offset:560
	ds_read_b32 v12, v31 offset:692
	ds_read_b32 v13, v31 offset:824
	ds_read_b32 v14, v31 offset:956
	s_waitcnt lgkmcnt(0)
	v_bfe_u32 v6, v2, 16, 1
	v_add3_u32 v2, v2, v6, s96
	v_bfe_u32 v6, v5, 16, 1
	v_lshrrev_b32_e32 v2, 16, v2
	v_add3_u32 v5, v5, v6, s96
	v_and_or_b32 v6, v5, s97, v2
	v_bfe_u32 v2, v7, 16, 1
	v_add3_u32 v2, v7, v2, s96
	v_bfe_u32 v5, v8, 16, 1
	v_lshrrev_b32_e32 v2, 16, v2
	v_add3_u32 v5, v8, v5, s96
	v_and_or_b32 v7, v5, s97, v2
	v_bfe_u32 v2, v9, 16, 1
	v_add3_u32 v2, v9, v2, s96
	v_bfe_u32 v5, v12, 16, 1
	v_lshrrev_b32_e32 v2, 16, v2
	v_add3_u32 v5, v12, v5, s96
	v_and_or_b32 v8, v5, s97, v2
	v_bfe_u32 v2, v13, 16, 1
	v_add3_u32 v2, v13, v2, s96
	v_bfe_u32 v5, v14, 16, 1
	v_lshrrev_b32_e32 v2, 16, v2
	v_add3_u32 v5, v14, v5, s96
	v_and_or_b32 v9, v5, s97, v2
	v_or_b32_e32 v2, s65, v32
	v_lshlrev_b32_e32 v2, 9, v2
	v_lshl_add_u64 v[12:13], v[10:11], 0, v[2:3]
	global_store_dwordx4 v[12:13], v[6:9], off
	ds_read_b32 v2, v31 offset:64
	ds_read_b32 v5, v31 offset:196
	ds_read_b32 v7, v31 offset:328
	ds_read_b32 v8, v31 offset:460
	ds_read_b32 v9, v31 offset:592
	ds_read_b32 v12, v31 offset:724
	ds_read_b32 v13, v31 offset:856
	ds_read_b32 v14, v31 offset:988
	s_waitcnt lgkmcnt(0)
	v_bfe_u32 v6, v2, 16, 1
	v_add3_u32 v2, v2, v6, s96
	v_bfe_u32 v6, v5, 16, 1
	v_lshrrev_b32_e32 v2, 16, v2
	v_add3_u32 v5, v5, v6, s96
	v_and_or_b32 v6, v5, s97, v2
	v_bfe_u32 v2, v7, 16, 1
	v_add3_u32 v2, v7, v2, s96
	v_bfe_u32 v5, v8, 16, 1
	v_lshrrev_b32_e32 v2, 16, v2
	v_add3_u32 v5, v8, v5, s96
	v_and_or_b32 v7, v5, s97, v2
	v_bfe_u32 v2, v9, 16, 1
	v_add3_u32 v2, v9, v2, s96
	v_bfe_u32 v5, v12, 16, 1
	v_lshrrev_b32_e32 v2, 16, v2
	v_add3_u32 v5, v12, v5, s96
	v_and_or_b32 v8, v5, s97, v2
	v_bfe_u32 v2, v13, 16, 1
	v_add3_u32 v2, v13, v2, s96
	v_bfe_u32 v5, v14, 16, 1
	v_lshrrev_b32_e32 v2, 16, v2
	v_add3_u32 v5, v14, v5, s96
	v_and_or_b32 v9, v5, s97, v2
	v_or_b32_e32 v2, s65, v33
	v_lshlrev_b32_e32 v2, 9, v2
	v_lshl_add_u64 v[12:13], v[10:11], 0, v[2:3]
	global_store_dwordx4 v[12:13], v[6:9], off
	ds_read_b32 v2, v31 offset:96
	ds_read_b32 v5, v31 offset:228
	ds_read_b32 v7, v31 offset:360
	ds_read_b32 v8, v31 offset:492
	ds_read_b32 v9, v31 offset:624
	ds_read_b32 v12, v31 offset:756
	ds_read_b32 v13, v31 offset:888
	ds_read_b32 v14, v31 offset:1020
	s_waitcnt lgkmcnt(0)
	v_bfe_u32 v6, v2, 16, 1
	v_add3_u32 v2, v2, v6, s96
	v_bfe_u32 v6, v5, 16, 1
	v_lshrrev_b32_e32 v2, 16, v2
	v_add3_u32 v5, v5, v6, s96
	v_and_or_b32 v6, v5, s97, v2
	v_bfe_u32 v2, v7, 16, 1
	v_add3_u32 v2, v7, v2, s96
	v_bfe_u32 v5, v8, 16, 1
	v_lshrrev_b32_e32 v2, 16, v2
	v_add3_u32 v5, v8, v5, s96
	v_and_or_b32 v7, v5, s97, v2
	v_bfe_u32 v2, v9, 16, 1
	v_add3_u32 v2, v9, v2, s96
	v_bfe_u32 v5, v12, 16, 1
	v_lshrrev_b32_e32 v2, 16, v2
	v_add3_u32 v5, v12, v5, s96
	v_and_or_b32 v8, v5, s97, v2
	v_bfe_u32 v2, v13, 16, 1
	v_add3_u32 v2, v13, v2, s96
	v_bfe_u32 v5, v14, 16, 1
	v_lshrrev_b32_e32 v2, 16, v2
	v_add3_u32 v5, v14, v5, s96
	v_and_or_b32 v9, v5, s97, v2
	v_or_b32_e32 v2, s65, v34
	v_lshlrev_b32_e32 v2, 9, v2
	v_lshl_add_u64 v[10:11], v[10:11], 0, v[2:3]
	global_store_dwordx4 v[10:11], v[6:9], off
	s_waitcnt lgkmcnt(0)

; #define LAS __attribute__((address_space(3)))
; __device__ __forceinline__ unsigned pk2(float lo, float hi) { return f2bf(lo) | (f2bf(hi) << 16); }
; template <int MAP>
; __device__ __forceinline__ void transpose_item(const float* W, int K, int N, int Npad, bf16_t* WT, const float* gk, LAS float* scr, int item, int lane) {
;     ...
; #pragma unroll
;     for (int i = 0; i < 32; ++i) { const int kk = 2 * i + (lane >> 5); float v = ns >= 0 ? wv[i] : 0.f; if (gk) v *= gk[k0 + kk]; scr[kk * 33 + (lane & 31)] = v * sc; }
;     asm volatile("s_waitcnt lgkmcnt(0)" ::: "memory");
;     const int c = lane & 7;
; #pragma unroll
;     for (int j = 0; j < 4; ++j) { const int n = (lane >> 3) + 8 * j; const LAS float* s = scr + (8 * c) * 33 + n;
;         u32x4 o; o.x = pk2(s[0 * 33], s[1 * 33]); o.y = pk2(s[2 * 33], s[3 * 33]); o.z = pk2(s[4 * 33], s[5 * 33]); o.w = pk2(s[6 * 33], s[7 * 33]);
;         *(u32x4*)(WT + (size_t)(n0 + n) * K + k0 + 8 * c) = o; }
;     asm volatile("s_waitcnt lgkmcnt(0)" ::: "memory");
.LBB0_74:
	s_mul_i32 s1, s36, 0x90000
	s_mul_hi_i32 s0, s36, 0x90000
	s_add_u32 s1, s49, s1
	s_addc_u32 s40, s50, s0
	v_mul_f32_e32 v2, 0x3dd53b94, v8
	v_mul_f32_e32 v5, 0x3dd53b94, v9
	s_lshl_b32 s0, s65, 1
	ds_write2_b32 v10, v2, v5 offset0:148 offset1:214
	s_add_u32 s0, s1, s0
	s_waitcnt lgkmcnt(0)
	s_addc_u32 s1, s40, 0
	v_mov_b32_e32 v5, v3
	v_lshl_add_u64 v[10:11], s[0:1], 0, v[4:5]
	ds_read_b32 v2, v31
	ds_read_b32 v5, v31 offset:132
	ds_read_b32 v7, v31 offset:264
	ds_read_b32 v8, v31 offset:396
	ds_read_b32 v9, v31 offset:528
	ds_read_b32 v12, v31 offset:660
	ds_read_b32 v13, v31 offset:792
	ds_read_b32 v14, v31 offset:924
	s_waitcnt lgkmcnt(0)
	v_bfe_u32 v6, v2, 16, 1
	v_add3_u32 v2, v2, v6, s96
	v_bfe_u32 v6, v5, 16, 1
	v_lshrrev_b32_e32 v2, 16, v2
	v_add3_u32 v5, v5, v6, s96
	v_and_or_b32 v6, v5, s97, v2
	v_bfe_u32 v2, v7, 16, 1
	v_add3_u32 v2, v7, v2, s96
	v_bfe_u32 v5, v8, 16, 1
	v_lshrrev_b32_e32 v2, 16, v2
	v_add3_u32 v5, v8, v5, s96
	v_and_or_b32 v7, v5, s97, v2
	v_bfe_u32 v2, v9, 16, 1
	v_add3_u32 v2, v9, v2, s96
	v_bfe_u32 v5, v12, 16, 1
	v_lshrrev_b32_e32 v2, 16, v2
	v_add3_u32 v5, v12, v5, s96
	v_and_or_b32 v8, v5, s97, v2
	v_bfe_u32 v2, v13, 16, 1
	v_add3_u32 v2, v13, v2, s96
	v_bfe_u32 v5, v14, 16, 1
	v_lshrrev_b32_e32 v2, 16, v2
	v_add3_u32 v5, v14, v5, s96
	v_and_or_b32 v9, v5, s97, v2
	v_or_b32_e32 v2, s37, v30
	v_mul_u32_u24_e32 v2, 0x180, v2
	v_lshlrev_b32_e32 v2, 1, v2
	v_lshl_add_u64 v[12:13], v[10:11], 0, v[2:3]
	global_store_dwordx4 v[12:13], v[6:9], off
	ds_read_b32 v2, v31 offset:32
	ds_read_b32 v5, v31 offset:164
	ds_read_b32 v7, v31 offset:296
	ds_read_b32 v8, v31 offset:428
	ds_read_b32 v9, v31 offset:560
	ds_read_b32 v12, v31 offset:692
	ds_read_b32 v13, v31 offset:824
	ds_read_b32 v14, v31 offset:956
	s_waitcnt lgkmcnt(0)
	v_bfe_u32 v6, v2, 16, 1
	v_add3_u32 v2, v2, v6, s96
	v_bfe_u32 v6, v5, 16, 1
	v_lshrrev_b32_e32 v2, 16, v2
	v_add3_u32 v5, v5, v6, s96
	v_and_or_b32 v6, v5, s97, v2
	v_bfe_u32 v2, v7, 16, 1
	v_add3_u32 v2, v7, v2, s96
	v_bfe_u32 v5, v8, 16, 1
	v_lshrrev_b32_e32 v2, 16, v2
	v_add3_u32 v5, v8, v5, s96
	v_and_or_b32 v7, v5, s97, v2
	v_bfe_u32 v2, v9, 16, 1
	v_add3_u32 v2, v9, v2, s96
	v_bfe_u32 v5, v12, 16, 1
	v_lshrrev_b32_e32 v2, 16, v2
	v_add3_u32 v5, v12, v5, s96
	v_and_or_b32 v8, v5, s97, v2
	v_bfe_u32 v2, v13, 16, 1
	v_add3_u32 v2, v13, v2, s96
	v_bfe_u32 v5, v14, 16, 1
	v_lshrrev_b32_e32 v2, 16, v2
	v_add3_u32 v5, v14, v5, s96
	v_and_or_b32 v9, v5, s97, v2
	v_or_b32_e32 v2, s37, v32
	v_mul_u32_u24_e32 v2, 0x180, v2
	v_lshlrev_b32_e32 v2, 1, v2
	v_lshl_add_u64 v[12:13], v[10:11], 0, v[2:3]
	global_store_dwordx4 v[12:13], v[6:9], off
	ds_read_b32 v2, v31 offset:64
	ds_read_b32 v5, v31 offset:196
	ds_read_b32 v7, v31 offset:328
	ds_read_b32 v8, v31 offset:460
	ds_read_b32 v9, v31 offset:592
	ds_read_b32 v12, v31 offset:724
	ds_read_b32 v13, v31 offset:856
	ds_read_b32 v14, v31 offset:988
	s_waitcnt lgkmcnt(0)
	v_bfe_u32 v6, v2, 16, 1
	v_add3_u32 v2, v2, v6, s96
	v_bfe_u32 v6, v5, 16, 1
	v_lshrrev_b32_e32 v2, 16, v2
	v_add3_u32 v5, v5, v6, s96
	v_and_or_b32 v6, v5, s97, v2
	v_bfe_u32 v2, v7, 16, 1
	v_add3_u32 v2, v7, v2, s96
	v_bfe_u32 v5, v8, 16, 1
	v_lshrrev_b32_e32 v2, 16, v2
	v_add3_u32 v5, v8, v5, s96
	v_and_or_b32 v7, v5, s97, v2
	v_bfe_u32 v2, v9, 16, 1
	v_add3_u32 v2, v9, v2, s96
	v_bfe_u32 v5, v12, 16, 1
	v_lshrrev_b32_e32 v2, 16, v2
	v_add3_u32 v5, v12, v5, s96
	v_and_or_b32 v8, v5, s97, v2
	v_bfe_u32 v2, v13, 16, 1
	v_add3_u32 v2, v13, v2, s96
	v_bfe_u32 v5, v14, 16, 1
	v_lshrrev_b32_e32 v2, 16, v2
	v_add3_u32 v5, v14, v5, s96
	v_and_or_b32 v9, v5, s97, v2
	v_or_b32_e32 v2, s37, v33
	v_mul_u32_u24_e32 v2, 0x180, v2
	v_lshlrev_b32_e32 v2, 1, v2
	v_lshl_add_u64 v[12:13], v[10:11], 0, v[2:3]
	global_store_dwordx4 v[12:13], v[6:9], off
	ds_read_b32 v2, v31 offset:96
	ds_read_b32 v5, v31 offset:228
	ds_read_b32 v7, v31 offset:360
	ds_read_b32 v8, v31 offset:492
	ds_read_b32 v9, v31 offset:624
	ds_read_b32 v12, v31 offset:756
	ds_read_b32 v13, v31 offset:888
	ds_read_b32 v14, v31 offset:1020
	s_waitcnt lgkmcnt(0)
	v_bfe_u32 v6, v2, 16, 1
	v_add3_u32 v2, v2, v6, s96
	v_bfe_u32 v6, v5, 16, 1
	v_lshrrev_b32_e32 v2, 16, v2
	v_add3_u32 v5, v5, v6, s96
	v_and_or_b32 v6, v5, s97, v2
	v_bfe_u32 v2, v7, 16, 1
	v_add3_u32 v2, v7, v2, s96
	v_bfe_u32 v5, v8, 16, 1
	v_lshrrev_b32_e32 v2, 16, v2
	v_add3_u32 v5, v8, v5, s96
	v_and_or_b32 v7, v5, s97, v2
	v_bfe_u32 v2, v9, 16, 1
	v_add3_u32 v2, v9, v2, s96
	v_bfe_u32 v5, v12, 16, 1
	v_lshrrev_b32_e32 v2, 16, v2
	v_add3_u32 v5, v12, v5, s96
	v_and_or_b32 v8, v5, s97, v2
	v_bfe_u32 v2, v13, 16, 1
	v_add3_u32 v2, v13, v2, s96
	v_bfe_u32 v5, v14, 16, 1
	v_lshrrev_b32_e32 v2, 16, v2
	v_add3_u32 v5, v14, v5, s96
	v_and_or_b32 v9, v5, s97, v2
	v_or_b32_e32 v2, s37, v34
	v_mul_u32_u24_e32 v2, 0x180, v2
	v_lshlrev_b32_e32 v2, 1, v2
	v_lshl_add_u64 v[10:11], v[10:11], 0, v[2:3]
	global_store_dwordx4 v[10:11], v[6:9], off
	s_waitcnt lgkmcnt(0)

; __global__ void __launch_bounds__(NTHR, 2) mega_fwd(Args a) {
;     ...
;         for (int e = bx * NTHR + tid; e < SEQ * 32; e += G * NTHR) {
;             const int pos = e >> 5, i = e & 31;
;             const float inv = (float)exp2(-(double)i * (13.287712379549449 / 32.0));
;             const float ang = (float)pos * inv;
;             const double rev = (double)ang * 0.15915494309189535; const float fr = (float)(rev - rint(rev));
;             TAB[e] = (f32x2){__builtin_amdgcn_cosf(fr), __builtin_amdgcn_sinf(fr)};
;         }
.LBB0_102:
	v_ashrrev_i32_e32 v3, 5, v2
	v_cvt_f32_i32_e32 v3, v3
	v_add_u32_e32 v2, s6, v2
	v_cmp_lt_i32_e32 vcc, s7, v2
	s_or_b64 s[8:9], vcc, s[8:9]
	v_mul_f32_e32 v3, v3, v6
	v_cvt_f64_f32_e32 v[8:9], v3
	v_mul_f64 v[10:11], v[8:9], s[10:11]
	v_rndne_f64_e32 v[10:11], v[10:11]
	v_fma_f64 v[8:9], v[8:9], s[10:11], -v[10:11]
	v_cvt_f32_f64_e32 v3, v[8:9]
	v_cos_f32_e32 v8, v3
	v_sin_f32_e32 v9, v3
	global_store_dwordx2 v[4:5], v[8:9], off
	v_lshl_add_u64 v[4:5], v[4:5], 0, s[0:1]
	s_andn2_b64 exec, exec, s[8:9]
	s_cbranch_execnz .LBB0_102

; __global__ void __launch_bounds__(NTHR, 2) mega_fwd(Args a) {
;     ...
;         if (bx == 0 && wave == 0) {
;             for (int l = 0; l < NLAYER; ++l) { const float* lf = a.d_lambda + l * 256;
;                 const float sa = wave_sum(lf[lane] * lf[64 + lane]), sb = wave_sum(lf[128 + lane] * lf[192 + lane]);
;                 const float lam_init = 0.8f - 0.6f * expf(-0.3f * (float)l);
;                 if (lane == 0) LAM[l] = expf(sa) - expf(sb) + lam_init; }
;         }
.LBB0_106:
	s_or_b64 exec, exec, s[4:5]
	s_cmp_gt_u32 s39, 63
	s_cselect_b64 s[4:5], -1, 0
	s_xor_b64 s[0:1], s[0:1], -1
	s_or_b64 s[0:1], s[0:1], s[4:5]
	s_and_b64 vcc, exec, s[0:1]
	s_cbranch_vccnz .LBB0_112
	v_lshlrev_b32_e32 v2, 2, v25
	global_load_dword v3, v2, s[14:15]
	global_load_dword v4, v2, s[14:15] offset:256
	global_load_dword v5, v2, s[14:15] offset:512
	global_load_dword v6, v2, s[14:15] offset:768
	v_cmp_eq_u32_e32 vcc, 0, v25
	s_waitcnt vmcnt(0)
	v_mul_f32_e32 v7, v3, v4
	ds_swizzle_b32 v7, v7 offset:swizzle(SWAP,1)
	v_mul_f32_e32 v8, v5, v6
	ds_swizzle_b32 v8, v8 offset:swizzle(SWAP,1)
	s_waitcnt lgkmcnt(0)
	v_fmac_f32_e32 v7, v3, v4
	ds_swizzle_b32 v3, v7 offset:swizzle(SWAP,2)
	v_fmac_f32_e32 v8, v5, v6
	ds_swizzle_b32 v4, v8 offset:swizzle(SWAP,2)
	s_waitcnt lgkmcnt(1)
	v_add_f32_e32 v3, v7, v3
	ds_swizzle_b32 v5, v3 offset:swizzle(SWAP,4)
	s_waitcnt lgkmcnt(1)
	v_add_f32_e32 v4, v8, v4
	ds_swizzle_b32 v6, v4 offset:swizzle(SWAP,4)
	s_waitcnt lgkmcnt(1)
	v_add_f32_e32 v3, v3, v5
	ds_swizzle_b32 v5, v3 offset:swizzle(SWAP,8)
	s_waitcnt lgkmcnt(1)
	v_add_f32_e32 v4, v4, v6
	ds_swizzle_b32 v6, v4 offset:swizzle(SWAP,8)
	s_waitcnt lgkmcnt(1)
	v_add_f32_e32 v5, v3, v5
	v_mov_b32_e32 v3, 0
	s_waitcnt lgkmcnt(0)
	v_add_f32_e32 v4, v4, v6
	ds_swizzle_b32 v6, v5 offset:swizzle(SWAP,16)
	ds_swizzle_b32 v7, v4 offset:swizzle(SWAP,16)
	v_lshl_add_u64 v[2:3], s[14:15], 0, v[2:3]
	s_waitcnt lgkmcnt(1)
	v_add_f32_e32 v6, v5, v6
	s_waitcnt lgkmcnt(0)
	v_add_f32_e32 v4, v4, v7
	v_mov_b32_e32 v7, v6
	v_mov_b32_e32 v5, v4
	s_nop 0
	v_permlane32_swap_b32_e32 v6, v7
	v_permlane32_swap_b32_e32 v4, v5
	s_and_saveexec_b64 s[4:5], vcc
	s_cbranch_execz .LBB0_109
	v_add_f32_e32 v6, v6, v7
	s_mov_b32 s6, 0x3fb8aa3b
	v_mul_f32_e32 v7, 0x3fb8aa3b, v6
	v_fma_f32 v8, v6, s6, -v7
	v_rndne_f32_e32 v9, v7
	v_fmac_f32_e32 v8, 0x32a5705f, v6
	v_sub_f32_e32 v7, v7, v9
	v_add_f32_e32 v7, v7, v8
	v_exp_f32_e32 v7, v7
	v_cvt_i32_f32_e32 v8, v9
	v_add_f32_e32 v4, v4, v5
	s_mov_b32 s7, 0xc2ce8ed0
	v_cmp_ngt_f32_e64 s[0:1], s7, v6
	v_ldexp_f32 v5, v7, v8
	v_mul_f32_e32 v7, 0x3fb8aa3b, v4
	v_fma_f32 v8, v4, s6, -v7
	v_rndne_f32_e32 v9, v7
	v_fmac_f32_e32 v8, 0x32a5705f, v4
	v_sub_f32_e32 v7, v7, v9
	v_add_f32_e32 v7, v7, v8
	v_exp_f32_e32 v7, v7
	v_cvt_i32_f32_e32 v8, v9
	s_mov_b32 s8, 0x42b17218
	v_cndmask_b32_e64 v5, 0, v5, s[0:1]
	v_mov_b32_e32 v9, 0x7f800000
	v_cmp_nlt_f32_e64 s[0:1], s8, v6
	v_ldexp_f32 v6, v7, v8
	s_nop 0
	v_cndmask_b32_e64 v5, v9, v5, s[0:1]
	v_cmp_ngt_f32_e64 s[0:1], s7, v4
	s_nop 1
	v_cndmask_b32_e64 v6, 0, v6, s[0:1]
	v_cmp_nlt_f32_e64 s[0:1], s8, v4
	s_nop 1
	v_cndmask_b32_e64 v4, v9, v6, s[0:1]
	v_sub_f32_e32 v4, v5, v4
	v_add_f32_e32 v6, 0x3e4ccccc, v4
	v_mov_b64_e32 v[4:5], s[28:29]
	global_store_dword v[4:5], v6, off
.LBB0_109:
	s_or_b64 exec, exec, s[4:5]
	global_load_dword v4, v[2:3], off offset:1024
	global_load_dword v5, v[2:3], off offset:1280
	global_load_dword v6, v[2:3], off offset:1536
	global_load_dword v7, v[2:3], off offset:1792
	s_waitcnt vmcnt(0)
	v_mul_f32_e32 v2, v4, v5
	ds_swizzle_b32 v2, v2 offset:swizzle(SWAP,1)
	v_mul_f32_e32 v3, v6, v7
	ds_swizzle_b32 v3, v3 offset:swizzle(SWAP,1)
	s_waitcnt lgkmcnt(0)
	v_fmac_f32_e32 v2, v4, v5
	ds_swizzle_b32 v4, v2 offset:swizzle(SWAP,2)
	v_fmac_f32_e32 v3, v6, v7
	ds_swizzle_b32 v5, v3 offset:swizzle(SWAP,2)
	s_waitcnt lgkmcnt(1)
	v_add_f32_e32 v2, v2, v4
	ds_swizzle_b32 v4, v2 offset:swizzle(SWAP,4)
	s_waitcnt lgkmcnt(1)
	v_add_f32_e32 v3, v3, v5
	ds_swizzle_b32 v5, v3 offset:swizzle(SWAP,4)
	s_waitcnt lgkmcnt(1)
	v_add_f32_e32 v2, v2, v4
	ds_swizzle_b32 v4, v2 offset:swizzle(SWAP,8)
	s_waitcnt lgkmcnt(1)
	v_add_f32_e32 v3, v3, v5
	ds_swizzle_b32 v5, v3 offset:swizzle(SWAP,8)
	s_waitcnt lgkmcnt(1)
	v_add_f32_e32 v2, v2, v4
	ds_swizzle_b32 v4, v2 offset:swizzle(SWAP,16)
	s_waitcnt lgkmcnt(1)
	v_add_f32_e32 v3, v3, v5
	ds_swizzle_b32 v5, v3 offset:swizzle(SWAP,16)
	s_waitcnt lgkmcnt(1)
	v_add_f32_e32 v4, v2, v4
	s_waitcnt lgkmcnt(0)
	v_add_f32_e32 v2, v3, v5
	v_mov_b32_e32 v5, v4
	v_mov_b32_e32 v3, v2
	s_nop 0
	v_permlane32_swap_b32_e32 v4, v5
	v_permlane32_swap_b32_e32 v2, v3
	s_and_saveexec_b64 s[0:1], vcc
	s_cbranch_execz .LBB0_111
	v_add_f32_e32 v4, v4, v5
	s_mov_b32 s4, 0x3fb8aa3b
	v_mul_f32_e32 v5, 0x3fb8aa3b, v4
	v_fma_f32 v6, v4, s4, -v5
	v_rndne_f32_e32 v7, v5
	v_fmac_f32_e32 v6, 0x32a5705f, v4
	v_sub_f32_e32 v5, v5, v7
	v_add_f32_e32 v5, v5, v6
	v_exp_f32_e32 v5, v5
	v_cvt_i32_f32_e32 v6, v7
	v_add_f32_e32 v2, v2, v3
	s_mov_b32 s5, 0xc2ce8ed0
	v_cmp_ngt_f32_e32 vcc, s5, v4
	v_ldexp_f32 v3, v5, v6
	v_mul_f32_e32 v5, 0x3fb8aa3b, v2
	v_fma_f32 v6, v2, s4, -v5
	v_rndne_f32_e32 v7, v5
	v_fmac_f32_e32 v6, 0x32a5705f, v2
	v_sub_f32_e32 v5, v5, v7
	v_add_f32_e32 v5, v5, v6
	v_exp_f32_e32 v5, v5
	v_cvt_i32_f32_e32 v6, v7
	s_mov_b32 s6, 0x42b17218
	v_cndmask_b32_e32 v3, 0, v3, vcc
	v_mov_b32_e32 v7, 0x7f800000
	v_cmp_nlt_f32_e32 vcc, s6, v4
	v_ldexp_f32 v4, v5, v6
	s_nop 0
	v_cndmask_b32_e32 v3, v7, v3, vcc
	v_cmp_ngt_f32_e32 vcc, s5, v2
	s_nop 1
	v_cndmask_b32_e32 v4, 0, v4, vcc
	v_cmp_nlt_f32_e32 vcc, s6, v2
	s_nop 1
	v_cndmask_b32_e32 v2, v7, v4, vcc
	v_sub_f32_e32 v2, v3, v2
	v_add_f32_e32 v4, 0x3eb60549, v2
	v_mov_b64_e32 v[2:3], s[28:29]
	global_store_dword v[2:3], v4, off offset:4

; __global__ void __launch_bounds__(NTHR, 2) mega_fwd(Args a) {
;     ...
;         for (int ch = bx; ch < NLAYER * 192; ch += G) {
;             const int l = ch / 192, n0 = (ch % 192) * 64; const float* W = a.w_ada + (size_t)l * DM * 12288;
;             const int cg4 = lane & 15, ksub = lane >> 4; f32x4 acc = {0.f, 0.f, 0.f, 0.f};
; #pragma unroll 16
;             for (int kk = 0; kk < 64; ++kk) { const int k = wave * 256 + kk * 4 + ksub; const float cv = a.c[k]; const float sv = cv / (1.f + expf(-cv));
;                 const f32x4 w = *(const f32x4*)(W + (size_t)k * 12288 + n0 + cg4 * 4); acc += w * sv; }
.LBB0_116:
	v_add_u32_e32 v68, s45, v78
	v_lshl_add_u64 v[2:3], v[68:69], 2, s[18:19]
	v_mad_u64_u32 v[18:19], s[4:5], v68, s42, v[72:73]
	v_add_u32_e32 v4, 4, v68
	v_add_u32_e32 v5, 8, v68
	v_add_u32_e32 v6, 12, v68
	v_add_u32_e32 v7, 16, v68
	v_add_u32_e32 v8, 20, v68
	v_add_u32_e32 v9, 24, v68
	v_add_u32_e32 v10, 28, v68
	v_add_u32_e32 v11, 32, v68
	v_add_u32_e32 v12, 36, v68
	v_add_u32_e32 v13, 40, v68
	v_add_u32_e32 v14, 44, v68
	v_add_u32_e32 v15, 48, v68
	v_add_u32_e32 v16, 52, v68
	v_add_u32_e32 v17, 56, v68
	v_add_u32_e32 v22, 60, v68
	global_load_dword v81, v[2:3], off
	global_load_dword v110, v[2:3], off offset:16
	global_load_dword v111, v[2:3], off offset:32
	global_load_dword v112, v[2:3], off offset:48
	global_load_dword v113, v[2:3], off offset:64
	global_load_dword v114, v[2:3], off offset:80
	global_load_dword v115, v[2:3], off offset:96
	global_load_dword v116, v[2:3], off offset:112
	global_load_dword v117, v[2:3], off offset:128
	global_load_dword v118, v[2:3], off offset:144
	global_load_dword v119, v[2:3], off offset:160
	global_load_dword v120, v[2:3], off offset:176
	global_load_dword v121, v[2:3], off offset:192
	global_load_dword v122, v[2:3], off offset:208
	global_load_dword v123, v[2:3], off offset:224
	global_load_dword v68, v[2:3], off offset:240
	v_mad_u64_u32 v[20:21], s[4:5], v4, s42, v[72:73]
	v_mad_u64_u32 v[82:83], s[4:5], v5, s42, v[72:73]
	v_mad_u64_u32 v[84:85], s[4:5], v6, s42, v[72:73]
	v_mad_u64_u32 v[86:87], s[4:5], v7, s42, v[72:73]
	v_mad_u64_u32 v[88:89], s[4:5], v8, s42, v[72:73]
	v_mad_u64_u32 v[90:91], s[4:5], v9, s42, v[72:73]
	v_mad_u64_u32 v[92:93], s[4:5], v10, s42, v[72:73]
	v_mad_u64_u32 v[94:95], s[4:5], v11, s42, v[72:73]
	v_mad_u64_u32 v[96:97], s[4:5], v12, s42, v[72:73]
	v_mad_u64_u32 v[98:99], s[4:5], v13, s42, v[72:73]
	v_mad_u64_u32 v[100:101], s[4:5], v14, s42, v[72:73]
	v_mad_u64_u32 v[102:103], s[4:5], v15, s42, v[72:73]
	v_mad_u64_u32 v[104:105], s[4:5], v16, s42, v[72:73]
	v_mad_u64_u32 v[106:107], s[4:5], v17, s42, v[72:73]
	v_mad_u64_u32 v[108:109], s[4:5], v22, s42, v[72:73]
	global_load_dwordx4 v[62:65], v[18:19], off
	global_load_dwordx4 v[58:61], v[20:21], off
	global_load_dwordx4 v[54:57], v[82:83], off
	global_load_dwordx4 v[50:53], v[84:85], off
	global_load_dwordx4 v[46:49], v[86:87], off
	global_load_dwordx4 v[42:45], v[88:89], off
	global_load_dwordx4 v[38:41], v[90:91], off
	global_load_dwordx4 v[34:37], v[92:93], off
	global_load_dwordx4 v[30:33], v[94:95], off
	global_load_dwordx4 v[26:29], v[96:97], off
	global_load_dwordx4 v[22:25], v[98:99], off
	global_load_dwordx4 v[14:17], v[100:101], off
	global_load_dwordx4 v[10:13], v[102:103], off
	global_load_dwordx4 v[6:9], v[104:105], off
	global_load_dwordx4 v[2:5], v[106:107], off
	global_load_dwordx4 v[18:21], v[108:109], off
	s_add_i32 s45, s45, 64
	s_cmpk_lg_i32 s45, 0x100
	s_waitcnt vmcnt(0)
	v_mul_f32_e32 v82, 0xbfb8aa3b, v81
	v_mul_f32_e32 v83, 0xbfb8aa3b, v110
	v_fma_f32 v98, v81, s33, -v82
	v_rndne_f32_e32 v99, v82
	v_mul_f32_e32 v84, 0xbfb8aa3b, v111
	v_fma_f32 v100, v110, s33, -v83
	v_rndne_f32_e32 v101, v83
	v_fmac_f32_e32 v98, 0xb2a5705f, v81
	v_sub_f32_e32 v82, v82, v99
	v_mul_f32_e32 v85, 0xbfb8aa3b, v112
	v_fma_f32 v102, v111, s33, -v84
	v_rndne_f32_e32 v103, v84
	v_fmac_f32_e32 v100, 0xb2a5705f, v110
	v_sub_f32_e32 v83, v83, v101
	v_add_f32_e32 v82, v82, v98
	v_mul_f32_e32 v86, 0xbfb8aa3b, v113
	v_fma_f32 v104, v112, s33, -v85
	v_rndne_f32_e32 v105, v85
	v_cvt_i32_f32_e32 v99, v99
	v_fmac_f32_e32 v102, 0xb2a5705f, v111
	v_sub_f32_e32 v84, v84, v103
	v_add_f32_e32 v83, v83, v100
	v_exp_f32_e32 v82, v82
	v_mul_f32_e32 v87, 0xbfb8aa3b, v114
	v_fma_f32 v106, v113, s33, -v86
	v_rndne_f32_e32 v107, v86
	v_cvt_i32_f32_e32 v101, v101
	v_fmac_f32_e32 v104, 0xb2a5705f, v112
	v_sub_f32_e32 v85, v85, v105
	v_add_f32_e32 v84, v84, v102
	v_exp_f32_e32 v83, v83
	v_mul_f32_e32 v88, 0xbfb8aa3b, v115
	v_fma_f32 v108, v114, s33, -v87
	v_rndne_f32_e32 v109, v87
	v_cvt_i32_f32_e32 v103, v103
	v_fmac_f32_e32 v106, 0xb2a5705f, v113
	v_sub_f32_e32 v86, v86, v107
	v_add_f32_e32 v85, v85, v104
	v_exp_f32_e32 v84, v84
	v_mul_f32_e32 v89, 0xbfb8aa3b, v116
	v_fma_f32 v124, v115, s33, -v88
	v_rndne_f32_e32 v125, v88
	v_cvt_i32_f32_e32 v105, v105
	v_fmac_f32_e32 v108, 0xb2a5705f, v114
	v_sub_f32_e32 v87, v87, v109
	v_add_f32_e32 v86, v86, v106
	v_exp_f32_e32 v85, v85
	v_mul_f32_e32 v90, 0xbfb8aa3b, v117
	v_fma_f32 v126, v116, s33, -v89
	v_rndne_f32_e32 v127, v89
	v_fmac_f32_e32 v124, 0xb2a5705f, v115
	v_sub_f32_e32 v88, v88, v125
	v_cvt_i32_f32_e32 v107, v107
	v_add_f32_e32 v87, v87, v108
	v_exp_f32_e32 v86, v86
	v_ldexp_f32 v82, v82, v99
	v_cmp_nlt_f32_e64 s[34:35], s40, v81
	v_mul_f32_e32 v91, 0xbfb8aa3b, v118
	v_fma_f32 v128, v117, s33, -v90
	v_rndne_f32_e32 v129, v90
	v_fmac_f32_e32 v126, 0xb2a5705f, v116
	v_sub_f32_e32 v89, v89, v127
	v_cvt_i32_f32_e32 v109, v109
	v_add_f32_e32 v88, v88, v124
	v_exp_f32_e32 v87, v87
	v_ldexp_f32 v83, v83, v101
	v_cmp_nlt_f32_e32 vcc, s40, v110
	v_cndmask_b32_e64 v82, 0, v82, s[34:35]
	v_cmp_ngt_f32_e64 s[34:35], s41, v81
	v_mul_f32_e32 v92, 0xbfb8aa3b, v119
	v_fma_f32 v130, v118, s33, -v91
	v_rndne_f32_e32 v131, v91
	v_fmac_f32_e32 v128, 0xb2a5705f, v117
	v_sub_f32_e32 v90, v90, v129
	v_cvt_i32_f32_e32 v125, v125
	v_add_f32_e32 v89, v89, v126
	v_exp_f32_e32 v88, v88
	v_ldexp_f32 v84, v84, v103
	v_cmp_nlt_f32_e64 s[4:5], s40, v111
	v_cndmask_b32_e32 v83, 0, v83, vcc
	v_cmp_ngt_f32_e32 vcc, s41, v110
	v_cndmask_b32_e64 v82, v79, v82, s[34:35]
	v_mul_f32_e32 v93, 0xbfb8aa3b, v120
	v_mul_f32_e32 v97, 0xbfb8aa3b, v68
	v_fma_f32 v132, v119, s33, -v92
	v_rndne_f32_e32 v133, v92
; __global__ void __launch_bounds__(NTHR, 2) mega_fwd(Args a) {
;     ...
;             for (int kk = 0; kk < 64; ++kk) { const int k = wave * 256 + kk * 4 + ksub; const float cv = a.c[k]; const float sv = cv / (1.f + expf(-cv));
;                 const f32x4 w = *(const f32x4*)(W + (size_t)k * 12288 + n0 + cg4 * 4); acc += w * sv; }
	v_fmac_f32_e32 v130, 0xb2a5705f, v118
	v_sub_f32_e32 v91, v91, v131
	v_cvt_i32_f32_e32 v127, v127
	v_add_f32_e32 v90, v90, v128
	v_exp_f32_e32 v89, v89
	v_ldexp_f32 v85, v85, v105
	v_cmp_nlt_f32_e64 s[6:7], s40, v112
	v_cndmask_b32_e64 v84, 0, v84, s[4:5]
	v_cmp_ngt_f32_e64 s[4:5], s41, v111
	v_cndmask_b32_e32 v83, v79, v83, vcc
	v_add_f32_e32 v82, 1.0, v82
	v_mul_f32_e32 v94, 0xbfb8aa3b, v121
	v_mul_f32_e32 v96, 0xbfb8aa3b, v123
	v_fma_f32 v134, v120, s33, -v93
	v_rndne_f32_e32 v135, v93
	v_fma_f32 v142, v68, s33, -v97
	v_rndne_f32_e32 v143, v97
	v_fmac_f32_e32 v132, 0xb2a5705f, v119
	v_sub_f32_e32 v92, v92, v133
	v_cvt_i32_f32_e32 v129, v129
	v_add_f32_e32 v91, v91, v130
	v_exp_f32_e32 v90, v90
	v_ldexp_f32 v86, v86, v107
	v_cmp_nlt_f32_e64 s[8:9], s40, v113
	v_cndmask_b32_e64 v85, 0, v85, s[6:7]
	v_cmp_ngt_f32_e64 s[6:7], s41, v112
	v_cndmask_b32_e64 v84, v79, v84, s[4:5]
	v_add_f32_e32 v83, 1.0, v83
	v_div_scale_f32 v98, s[4:5], v82, v82, v81
	v_mul_f32_e32 v95, 0xbfb8aa3b, v122
	v_fma_f32 v136, v121, s33, -v94
	v_rndne_f32_e32 v137, v94
	v_fma_f32 v140, v123, s33, -v96
	v_rndne_f32_e32 v141, v96
	v_fmac_f32_e32 v134, 0xb2a5705f, v120
	v_sub_f32_e32 v93, v93, v135
	v_fmac_f32_e32 v142, 0xb2a5705f, v68
	v_sub_f32_e32 v97, v97, v143
	v_cvt_i32_f32_e32 v131, v131
	v_add_f32_e32 v92, v92, v132
	v_exp_f32_e32 v91, v91
	v_ldexp_f32 v87, v87, v109
	v_cmp_nlt_f32_e64 s[30:31], s40, v114
	v_cndmask_b32_e64 v86, 0, v86, s[8:9]
	v_cmp_ngt_f32_e64 s[8:9], s41, v113
	v_cndmask_b32_e64 v85, v79, v85, s[6:7]
	v_add_f32_e32 v84, 1.0, v84
	v_div_scale_f32 v100, s[4:5], v83, v83, v110
	v_rcp_f32_e32 v144, v98
	v_fma_f32 v138, v122, s33, -v95
	v_rndne_f32_e32 v139, v95
	v_fmac_f32_e32 v136, 0xb2a5705f, v121
	v_sub_f32_e32 v94, v94, v137
	v_fmac_f32_e32 v140, 0xb2a5705f, v123
	v_sub_f32_e32 v96, v96, v141
	v_cvt_i32_f32_e32 v133, v133
	v_add_f32_e32 v93, v93, v134
	v_add_f32_e32 v97, v97, v142
	v_exp_f32_e32 v92, v92
	v_ldexp_f32 v88, v88, v125
	v_cmp_nlt_f32_e64 s[10:11], s40, v115
	v_cndmask_b32_e64 v87, 0, v87, s[30:31]
	v_cmp_ngt_f32_e64 s[30:31], s41, v114
	v_cndmask_b32_e64 v86, v79, v86, s[8:9]
	v_add_f32_e32 v85, 1.0, v85
	v_div_scale_f32 v102, s[4:5], v84, v84, v111
	v_rcp_f32_e32 v145, v100
	v_fmac_f32_e32 v138, 0xb2a5705f, v122
	v_sub_f32_e32 v95, v95, v139
	v_cvt_i32_f32_e32 v135, v135
	v_cvt_i32_f32_e32 v143, v143
	v_add_f32_e32 v94, v94, v136
	v_add_f32_e32 v96, v96, v140
	v_exp_f32_e32 v93, v93
	v_exp_f32_e32 v97, v97
	v_ldexp_f32 v89, v89, v127
	v_cmp_nlt_f32_e64 s[12:13], s40, v116
	v_cndmask_b32_e64 v88, 0, v88, s[10:11]
	v_cmp_ngt_f32_e64 s[10:11], s41, v115
	v_cndmask_b32_e64 v87, v79, v87, s[30:31]
	v_add_f32_e32 v86, 1.0, v86
	v_div_scale_f32 v104, s[4:5], v85, v85, v112
	v_rcp_f32_e32 v146, v102
	v_cvt_i32_f32_e32 v137, v137
	v_cvt_i32_f32_e32 v141, v141
	v_add_f32_e32 v95, v95, v138
	v_exp_f32_e32 v94, v94
	v_exp_f32_e32 v96, v96
	v_ldexp_f32 v90, v90, v129
	v_cmp_nlt_f32_e64 s[14:15], s40, v117
	v_cndmask_b32_e64 v89, 0, v89, s[12:13]
	v_cmp_ngt_f32_e64 s[12:13], s41, v116
	v_cndmask_b32_e64 v88, v79, v88, s[10:11]
	v_add_f32_e32 v87, 1.0, v87
	v_div_scale_f32 v106, s[4:5], v86, v86, v113
	v_rcp_f32_e32 v147, v104
	v_cvt_i32_f32_e32 v139, v139
	v_exp_f32_e32 v95, v95
	v_ldexp_f32 v91, v91, v131
	v_cmp_nlt_f32_e64 s[16:17], s40, v118
	v_cndmask_b32_e64 v90, 0, v90, s[14:15]
	v_cmp_ngt_f32_e64 s[14:15], s41, v117
	v_cndmask_b32_e64 v89, v79, v89, s[12:13]
	v_add_f32_e32 v88, 1.0, v88
	v_div_scale_f32 v108, s[4:5], v87, v87, v114
	v_rcp_f32_e32 v148, v106
	v_fma_f32 v160, -v98, v144, 1.0
	v_ldexp_f32 v92, v92, v133
	v_cmp_nlt_f32_e64 s[18:19], s40, v119
	v_cndmask_b32_e64 v91, 0, v91, s[16:17]
	v_cmp_ngt_f32_e64 s[16:17], s41, v118
	v_cndmask_b32_e64 v90, v79, v90, s[14:15]
	v_add_f32_e32 v89, 1.0, v89
	v_div_scale_f32 v99, vcc, v81, v82, v81
	v_div_scale_f32 v124, s[4:5], v88, v88, v115
	v_rcp_f32_e32 v149, v108
	v_fma_f32 v161, -v100, v145, 1.0
	v_fmac_f32_e32 v144, v160, v144
	v_ldexp_f32 v93, v93, v135
	v_ldexp_f32 v97, v97, v143
	v_cmp_nlt_f32_e64 s[20:21], s40, v120
	v_cmp_nlt_f32_e64 s[28:29], s40, v68
	v_cndmask_b32_e64 v92, 0, v92, s[18:19]
	v_cmp_ngt_f32_e64 s[18:19], s41, v119
	v_cndmask_b32_e64 v91, v79, v91, s[16:17]
	v_add_f32_e32 v90, 1.0, v90
	v_div_scale_f32 v101, s[34:35], v110, v83, v110
	v_div_scale_f32 v126, s[4:5], v89, v89, v116
	v_rcp_f32_e32 v150, v124
	v_fma_f32 v162, -v102, v146, 1.0
	v_fmac_f32_e32 v145, v161, v145
	v_mul_f32_e32 v160, v99, v144
	v_ldexp_f32 v94, v94, v137
	v_ldexp_f32 v96, v96, v141
	v_cmp_nlt_f32_e64 s[22:23], s40, v121
	v_cmp_nlt_f32_e64 s[26:27], s40, v123
	v_cndmask_b32_e64 v93, 0, v93, s[20:21]
	v_cmp_ngt_f32_e64 s[20:21], s41, v120
	v_cndmask_b32_e64 v97, 0, v97, s[28:29]
	v_cmp_ngt_f32_e64 s[28:29], s41, v68
	v_cndmask_b32_e64 v92, v79, v92, s[18:19]
	v_add_f32_e32 v91, 1.0, v91
	v_div_scale_f32 v103, s[30:31], v111, v84, v111
	v_div_scale_f32 v128, s[4:5], v90, v90, v117
	v_rcp_f32_e32 v151, v126
	v_fma_f32 v163, -v104, v147, 1.0
	v_fmac_f32_e32 v146, v162, v146
	v_mul_f32_e32 v161, v101, v145
	v_fma_f32 v176, -v98, v160, v99
	v_ldexp_f32 v95, v95, v139
	v_cmp_nlt_f32_e64 s[24:25], s40, v122
	v_cndmask_b32_e64 v94, 0, v94, s[22:23]
	v_cmp_ngt_f32_e64 s[22:23], s41, v121
	v_cndmask_b32_e64 v96, 0, v96, s[26:27]
	v_cmp_ngt_f32_e64 s[26:27], s41, v123
	v_cndmask_b32_e64 v93, v79, v93, s[20:21]
	v_cndmask_b32_e64 v97, v79, v97, s[28:29]
	v_add_f32_e32 v92, 1.0, v92
	v_div_scale_f32 v105, s[28:29], v112, v85, v112
	v_div_scale_f32 v130, s[4:5], v91, v91, v118
	v_rcp_f32_e32 v152, v128
	v_fma_f32 v164, -v106, v148, 1.0
	v_fmac_f32_e32 v147, v163, v147
	v_mul_f32_e32 v162, v103, v146
; __global__ void __launch_bounds__(NTHR, 2) mega_fwd(Args a) {
;     ...
;             for (int kk = 0; kk < 64; ++kk) { const int k = wave * 256 + kk * 4 + ksub; const float cv = a.c[k]; const float sv = cv / (1.f + expf(-cv));
;                 const f32x4 w = *(const f32x4*)(W + (size_t)k * 12288 + n0 + cg4 * 4); acc += w * sv; }
	v_fma_f32 v177, -v100, v161, v101
	v_fmac_f32_e32 v160, v176, v144
	v_cndmask_b32_e64 v95, 0, v95, s[24:25]
	v_cmp_ngt_f32_e64 s[24:25], s41, v122
	v_cndmask_b32_e64 v94, v79, v94, s[22:23]
	v_cndmask_b32_e64 v96, v79, v96, s[26:27]
	v_add_f32_e32 v93, 1.0, v93
	v_div_scale_f32 v107, s[26:27], v113, v86, v113
	v_div_scale_f32 v132, s[4:5], v92, v92, v119
	v_rcp_f32_e32 v153, v130
	v_fma_f32 v165, -v108, v149, 1.0
	v_fmac_f32_e32 v148, v164, v148
	v_mul_f32_e32 v163, v105, v147
	v_fma_f32 v178, -v102, v162, v103
	v_fmac_f32_e32 v161, v177, v145
	v_fma_f32 v98, -v98, v160, v99
	v_cndmask_b32_e64 v95, v79, v95, s[24:25]
	v_add_f32_e32 v94, 1.0, v94
	v_div_scale_f32 v109, s[24:25], v114, v87, v114
	v_div_scale_f32 v134, s[4:5], v93, v93, v120
	v_rcp_f32_e32 v154, v132
	v_fma_f32 v166, -v124, v150, 1.0
	v_fmac_f32_e32 v149, v165, v149
	v_mul_f32_e32 v164, v107, v148
	v_fma_f32 v179, -v104, v163, v105
	v_fmac_f32_e32 v162, v178, v146
	v_fma_f32 v99, -v100, v161, v101
	v_div_fmas_f32 v98, v98, v144, v160
	s_mov_b64 vcc, s[34:35]
	v_add_f32_e32 v95, 1.0, v95
	v_div_scale_f32 v125, s[22:23], v115, v88, v115
	v_div_scale_f32 v136, s[4:5], v94, v94, v121
	v_rcp_f32_e32 v155, v134
	v_fma_f32 v167, -v126, v151, 1.0
	v_fmac_f32_e32 v150, v166, v150
	v_mul_f32_e32 v165, v109, v149
	v_fma_f32 v180, -v106, v164, v107
	v_fmac_f32_e32 v163, v179, v147
	v_fma_f32 v100, -v102, v162, v103
	v_div_fixup_f32 v82, v98, v82, v81
	v_div_fmas_f32 v81, v99, v145, v161
	s_mov_b64 vcc, s[30:31]
	v_add_f32_e32 v96, 1.0, v96
	v_div_scale_f32 v127, s[20:21], v116, v89, v116
	v_div_scale_f32 v138, s[4:5], v95, v95, v122
	v_rcp_f32_e32 v156, v136
	v_fma_f32 v168, -v128, v152, 1.0
	v_fmac_f32_e32 v151, v167, v151
	v_mul_f32_e32 v166, v125, v150
	v_fma_f32 v181, -v108, v165, v109
	v_fmac_f32_e32 v164, v180, v148
	v_fma_f32 v101, -v104, v163, v105
	v_pk_fma_f32 v[62:63], v[62:63], v[82:83], v[76:77] op_sel_hi:[1,0,1]
	v_pk_fma_f32 v[64:65], v[64:65], v[82:83], v[74:75] op_sel_hi:[1,0,1]
	v_div_fixup_f32 v74, v81, v83, v110
	v_div_fmas_f32 v75, v100, v146, v162
	s_mov_b64 vcc, s[28:29]
	v_add_f32_e32 v97, 1.0, v97
	v_div_scale_f32 v129, s[18:19], v117, v90, v117
	v_div_scale_f32 v140, s[4:5], v96, v96, v123
	v_rcp_f32_e32 v157, v138
	v_fma_f32 v169, -v130, v153, 1.0
	v_fmac_f32_e32 v152, v168, v152
	v_mul_f32_e32 v167, v127, v151
	v_fma_f32 v182, -v124, v166, v125
	v_fmac_f32_e32 v165, v181, v149
	v_fma_f32 v102, -v106, v164, v107
	v_pk_fma_f32 v[60:61], v[60:61], v[74:75], v[64:65] op_sel_hi:[1,0,1]
	v_pk_fma_f32 v[58:59], v[58:59], v[74:75], v[62:63] op_sel_hi:[1,0,1]
	v_div_fixup_f32 v62, v75, v84, v111
	v_div_fmas_f32 v63, v101, v147, v163
	s_mov_b64 vcc, s[26:27]
	v_div_scale_f32 v131, s[16:17], v118, v91, v118
	v_div_scale_f32 v141, s[4:5], v97, v97, v68
	v_rcp_f32_e32 v158, v140
	v_fma_f32 v170, -v132, v154, 1.0
	v_fmac_f32_e32 v153, v169, v153
	v_mul_f32_e32 v168, v129, v152
	v_fma_f32 v183, -v126, v167, v127
	v_fmac_f32_e32 v166, v182, v150
	v_fma_f32 v103, -v108, v165, v109
	v_pk_fma_f32 v[54:55], v[54:55], v[62:63], v[58:59] op_sel_hi:[1,0,1]
	v_pk_fma_f32 v[56:57], v[56:57], v[62:63], v[60:61] op_sel_hi:[1,0,1]
	v_div_fixup_f32 v58, v63, v85, v112
	v_div_fmas_f32 v59, v102, v148, v164
	s_mov_b64 vcc, s[24:25]
	v_div_scale_f32 v133, s[14:15], v119, v92, v119
	v_rcp_f32_e32 v159, v141
	v_fma_f32 v171, -v134, v155, 1.0
	v_fmac_f32_e32 v154, v170, v154
	v_mul_f32_e32 v169, v131, v153
	v_fma_f32 v184, -v128, v168, v129
	v_fmac_f32_e32 v167, v183, v151
	v_fma_f32 v104, -v124, v166, v125
	v_pk_fma_f32 v[52:53], v[52:53], v[58:59], v[56:57] op_sel_hi:[1,0,1]
	v_pk_fma_f32 v[50:51], v[50:51], v[58:59], v[54:55] op_sel_hi:[1,0,1]
	v_div_fixup_f32 v54, v59, v86, v113
	v_div_fmas_f32 v55, v103, v149, v165
	s_mov_b64 vcc, s[22:23]
	v_div_scale_f32 v135, s[12:13], v120, v93, v120
	v_fma_f32 v172, -v136, v156, 1.0
	v_fmac_f32_e32 v155, v171, v155
	v_mul_f32_e32 v170, v133, v154
	v_fma_f32 v185, -v130, v169, v131
	v_fmac_f32_e32 v168, v184, v152
	v_fma_f32 v105, -v126, v167, v127
	v_pk_fma_f32 v[46:47], v[46:47], v[54:55], v[50:51] op_sel_hi:[1,0,1]
	v_pk_fma_f32 v[48:49], v[48:49], v[54:55], v[52:53] op_sel_hi:[1,0,1]
	v_div_fixup_f32 v50, v55, v87, v114
	v_div_fmas_f32 v51, v104, v150, v166
	s_mov_b64 vcc, s[20:21]
	v_div_scale_f32 v137, s[10:11], v121, v94, v121
	v_fma_f32 v173, -v138, v157, 1.0
	v_fmac_f32_e32 v156, v172, v156
	v_mul_f32_e32 v171, v135, v155
	v_fma_f32 v186, -v132, v170, v133
	v_fmac_f32_e32 v169, v185, v153
	v_fma_f32 v106, -v128, v168, v129
	v_pk_fma_f32 v[44:45], v[44:45], v[50:51], v[48:49] op_sel_hi:[1,0,1]
	v_pk_fma_f32 v[42:43], v[42:43], v[50:51], v[46:47] op_sel_hi:[1,0,1]
	v_div_fixup_f32 v46, v51, v88, v115
	v_div_fmas_f32 v47, v105, v151, v167
	s_mov_b64 vcc, s[18:19]
	v_div_scale_f32 v139, s[8:9], v122, v95, v122
	v_fma_f32 v174, -v140, v158, 1.0
	v_fmac_f32_e32 v157, v173, v157
	v_mul_f32_e32 v172, v137, v156
	v_fma_f32 v187, -v134, v171, v135
	v_fmac_f32_e32 v170, v186, v154
	v_fma_f32 v107, -v130, v169, v131
	v_pk_fma_f32 v[38:39], v[38:39], v[46:47], v[42:43] op_sel_hi:[1,0,1]
	v_pk_fma_f32 v[40:41], v[40:41], v[46:47], v[44:45] op_sel_hi:[1,0,1]
; template <int X> __device__ __forceinline__ float swz_xor(float v) { return __builtin_bit_cast(float, __builtin_amdgcn_ds_swizzle(__builtin_bit_cast(int, v), 0x1f | (X << 10))); }
; __global__ void __launch_bounds__(NTHR, 2) mega_fwd(Args a) {
;     ...
; #pragma unroll 16
;             for (int kk = 0; kk < 64; ++kk) { const int k = wave * 256 + kk * 4 + ksub; const float cv = a.c[k]; const float sv = cv / (1.f + expf(-cv));
;                 const f32x4 w = *(const f32x4*)(W + (size_t)k * 12288 + n0 + cg4 * 4); acc += w * sv; }
; #pragma unroll
;             for (int e = 0; e < 4; ++e) { acc[e] += swz_xor<16>(acc[e]); auto rr = __builtin_amdgcn_permlane32_swap(__float_as_uint(acc[e]), __float_as_uint(acc[e]), false, false); acc[e] = __uint_as_float(rr[0]) + __uint_as_float(rr[1]); }
;             if (ksub == 0) { red[wave * 64 + cg4 * 4 + 0] = acc[0]; red[wave * 64 + cg4 * 4 + 1] = acc[1]; red[wave * 64 + cg4 * 4 + 2] = acc[2]; red[wave * 64 + cg4 * 4 + 3] = acc[3]; }
;             __syncthreads();
;             if (tid < 64) { float s = 0.f;
; #pragma unroll
;                 for (int w = 0; w < 8; ++w) s += red[w * 64 + tid];
;                 MOD[l * 12288 + n0 + tid] = s + a.b_ada[l * 12288 + n0 + tid]; }
;             __syncthreads();
	v_div_fixup_f32 v42, v47, v89, v116
	v_div_fmas_f32 v43, v106, v152, v168
	s_mov_b64 vcc, s[16:17]
	v_div_scale_f32 v142, s[6:7], v123, v96, v123
	v_fma_f32 v175, -v141, v159, 1.0
	v_fmac_f32_e32 v158, v174, v158
	v_mul_f32_e32 v173, v139, v157
	v_fma_f32 v188, -v136, v172, v137
	v_fmac_f32_e32 v171, v187, v155
	v_fma_f32 v108, -v132, v170, v133
	v_pk_fma_f32 v[36:37], v[36:37], v[42:43], v[40:41] op_sel_hi:[1,0,1]
	v_pk_fma_f32 v[34:35], v[34:35], v[42:43], v[38:39] op_sel_hi:[1,0,1]
	v_div_fixup_f32 v38, v43, v90, v117
	v_div_fmas_f32 v39, v107, v153, v169
	s_mov_b64 vcc, s[14:15]
	v_div_scale_f32 v143, s[4:5], v68, v97, v68
	v_fmac_f32_e32 v159, v175, v159
	v_mul_f32_e32 v174, v142, v158
	v_fma_f32 v189, -v138, v173, v139
	v_fmac_f32_e32 v172, v188, v156
	v_fma_f32 v109, -v134, v171, v135
	v_pk_fma_f32 v[30:31], v[30:31], v[38:39], v[34:35] op_sel_hi:[1,0,1]
	v_pk_fma_f32 v[32:33], v[32:33], v[38:39], v[36:37] op_sel_hi:[1,0,1]
	v_div_fixup_f32 v34, v39, v91, v118
	v_div_fmas_f32 v35, v108, v154, v170
	s_mov_b64 vcc, s[12:13]
	v_mul_f32_e32 v175, v143, v159
	v_fma_f32 v190, -v140, v174, v142
	v_fmac_f32_e32 v173, v189, v157
	v_fma_f32 v124, -v136, v172, v137
	v_pk_fma_f32 v[28:29], v[28:29], v[34:35], v[32:33] op_sel_hi:[1,0,1]
	v_pk_fma_f32 v[26:27], v[26:27], v[34:35], v[30:31] op_sel_hi:[1,0,1]
	v_div_fixup_f32 v30, v35, v92, v119
	v_div_fmas_f32 v31, v109, v155, v171
	s_mov_b64 vcc, s[10:11]
	v_fma_f32 v191, -v141, v175, v143
	v_fmac_f32_e32 v174, v190, v158
	v_fma_f32 v125, -v138, v173, v139
	v_pk_fma_f32 v[22:23], v[22:23], v[30:31], v[26:27] op_sel_hi:[1,0,1]
	v_pk_fma_f32 v[24:25], v[24:25], v[30:31], v[28:29] op_sel_hi:[1,0,1]
	v_div_fixup_f32 v26, v31, v93, v120
	v_div_fmas_f32 v27, v124, v156, v172
	s_mov_b64 vcc, s[8:9]
	v_fmac_f32_e32 v175, v191, v159
	v_fma_f32 v126, -v140, v174, v142
	v_pk_fma_f32 v[16:17], v[16:17], v[26:27], v[24:25] op_sel_hi:[1,0,1]
	v_pk_fma_f32 v[14:15], v[14:15], v[26:27], v[22:23] op_sel_hi:[1,0,1]
	v_div_fixup_f32 v22, v27, v94, v121
	v_div_fmas_f32 v23, v125, v157, v173
	s_mov_b64 vcc, s[6:7]
	v_fma_f32 v127, -v141, v175, v143
	v_pk_fma_f32 v[10:11], v[10:11], v[22:23], v[14:15] op_sel_hi:[1,0,1]
	v_pk_fma_f32 v[12:13], v[12:13], v[22:23], v[16:17] op_sel_hi:[1,0,1]
	v_div_fixup_f32 v14, v23, v95, v122
	v_div_fmas_f32 v15, v126, v158, v174
	s_mov_b64 vcc, s[4:5]
	v_pk_fma_f32 v[8:9], v[8:9], v[14:15], v[12:13] op_sel_hi:[1,0,1]
	v_pk_fma_f32 v[6:7], v[6:7], v[14:15], v[10:11] op_sel_hi:[1,0,1]
	v_div_fixup_f32 v10, v15, v96, v123
	v_div_fmas_f32 v11, v127, v159, v175
	v_readlane_b32 s16, v254, 12
	v_pk_fma_f32 v[2:3], v[2:3], v[10:11], v[6:7] op_sel_hi:[1,0,1]
	v_pk_fma_f32 v[4:5], v[4:5], v[10:11], v[8:9] op_sel_hi:[1,0,1]
	v_div_fixup_f32 v6, v11, v97, v68
	v_readlane_b32 s18, v254, 14
	v_readlane_b32 s19, v254, 15
	v_readlane_b32 s22, v254, 18
	v_readlane_b32 s23, v254, 19
	v_pk_fma_f32 v[74:75], v[20:21], v[6:7], v[4:5] op_sel_hi:[1,0,1]
	v_pk_fma_f32 v[76:77], v[18:19], v[6:7], v[2:3] op_sel_hi:[1,0,1]
	v_readlane_b32 s17, v254, 13
	v_readlane_b32 s20, v254, 16
	v_readlane_b32 s21, v254, 17
	v_readlane_b32 s24, v254, 20
	v_readlane_b32 s25, v254, 21
	v_readlane_b32 s26, v254, 22
	v_readlane_b32 s27, v254, 23
	v_readlane_b32 s28, v254, 24
	v_readlane_b32 s29, v254, 25
	v_readlane_b32 s30, v254, 26
	v_readlane_b32 s31, v254, 27
	s_cbranch_scc1 .LBB0_116
	ds_swizzle_b32 v2, v76 offset:swizzle(SWAP,16)
	ds_swizzle_b32 v3, v77 offset:swizzle(SWAP,16)
	ds_swizzle_b32 v6, v74 offset:swizzle(SWAP,16)
	ds_swizzle_b32 v7, v75 offset:swizzle(SWAP,16)
	s_waitcnt lgkmcnt(3)
	v_add_f32_e32 v2, v76, v2
	s_waitcnt lgkmcnt(2)
	v_add_f32_e32 v3, v77, v3
	s_waitcnt lgkmcnt(1)
	v_add_f32_e32 v6, v74, v6
	s_waitcnt lgkmcnt(0)
	v_add_f32_e32 v7, v75, v7
	v_mov_b32_e32 v4, v2
	v_mov_b32_e32 v5, v3
	v_mov_b32_e32 v8, v6
	v_mov_b32_e32 v9, v7
	v_permlane32_swap_b32_e32 v2, v4
	v_permlane32_swap_b32_e32 v3, v5
	v_permlane32_swap_b32_e32 v6, v8
	v_permlane32_swap_b32_e32 v7, v9
	s_and_saveexec_b64 s[4:5], s[0:1]
	v_pk_add_f32 v[2:3], v[2:3], v[4:5]
	v_pk_add_f32 v[4:5], v[6:7], v[8:9]
	ds_write_b128 v80, v[2:5]
	s_or_b64 exec, exec, s[4:5]
	s_waitcnt lgkmcnt(0)
	s_barrier
	s_and_saveexec_b64 s[4:5], s[36:37]
	s_cbranch_execz .LBB0_114
	s_mul_i32 s6, s44, 0x3000
	s_add_i32 s6, s6, s50
	v_add_u32_e32 v2, s6, v66
	v_ashrrev_i32_e32 v3, 31, v2
	v_lshlrev_b64 v[2:3], 2, v[2:3]
	v_lshl_add_u64 v[4:5], s[22:23], 0, v[2:3]
	global_load_dword v12, v[4:5], off
	ds_read2st64_b32 v[4:5], v67 offset1:1
	ds_read2st64_b32 v[6:7], v67 offset0:2 offset1:3
	ds_read2st64_b32 v[8:9], v67 offset0:4 offset1:5
	ds_read2st64_b32 v[10:11], v67 offset0:6 offset1:7
	v_lshl_add_u64 v[2:3], s[48:49], 0, v[2:3]
	s_waitcnt lgkmcnt(3)
	v_add_f32_e32 v4, 0, v4
	v_add_f32_e32 v4, v4, v5
	s_waitcnt lgkmcnt(2)
	v_add_f32_e32 v4, v4, v6
	v_add_f32_e32 v4, v4, v7
	s_waitcnt lgkmcnt(1)
	v_add_f32_e32 v4, v4, v8
	v_add_f32_e32 v4, v4, v9
	s_waitcnt lgkmcnt(0)
	v_add_f32_e32 v4, v4, v10
	v_add_f32_e32 v4, v4, v11
	s_waitcnt vmcnt(0)
	v_add_f32_e32 v4, v4, v12
	global_store_dword v[2:3], v4, off
	s_branch .LBB0_114

; __device__ __forceinline__ int tid_of(int wave_s) { int l; asm volatile("v_mbcnt_lo_u32_b32 %0, -1, 0\n\tv_mbcnt_hi_u32_b32 %0, -1, %0" : "=v"(l)); return wave_s * 64 + l; }
; template <bool FINAL>
; __device__ __forceinline__ void norm_pass(const float* X, const float* g, const float* scale, const float* shift, bf16_t* H, float* OUTF, int vcu_, int NGW_, int wave_s) {
;     int vcu = vcu_, NGW = NGW_; asm volatile("" : "+s"(vcu), "+s"(NGW));
;     int tid_ = tid_of(wave_s);
;     const int lane = tid_ & 63, gw = vcu * NWAVES + wave_s;
;     f32x4 gm[8], sh[8];
.LBB0_137:
	s_mov_b64 s[0:1], s[60:61]
	s_mov_b32 s5, s84
	v_readlane_b32 s6, v255, 31
	s_mov_b32 s4, s92
	v_mbcnt_lo_u32_b32 v144, -1, 0
	v_mbcnt_hi_u32_b32 v144, -1, v144
	s_lshl_b32 s28, s6, 3
	s_add_i32 s6, s28, s86
	s_cmpk_gt_i32 s6, 0x3fff
	v_mbcnt_lo_u32_b32 v0, -1, 0
	v_mbcnt_hi_u32_b32 v0, -1, v0
	s_cbranch_scc1 .LBB0_142
; template <bool FINAL>
; __device__ __forceinline__ void norm_pass(const float* X, const float* g, const float* scale, const float* shift, bf16_t* H, float* OUTF, int vcu_, int NGW_, int wave_s) {
;     ...
;     f32x4 gm[8], sh[8];
; #pragma unroll
;     for (int j = 0; j < 8; ++j) { const f32x4 gv = ((const f32x4*)g)[64 * j + lane];
;         if (!FINAL) { const f32x4 s = ((const f32x4*)scale)[64 * j + lane]; gm[j] = gv * (1.f + s); sh[j] = ((const f32x4*)shift)[64 * j + lane]; } else { gm[j] = gv; sh[j] = (f32x4){0.f, 0.f, 0.f, 0.f}; } }
;     f32x4 nv[8];
;     { const f32x4* xr = (const f32x4*)(X + (size_t)gw * DM) + lane;
; #pragma unroll
;         for (int j = 0; j < 8; ++j) nv[j] = xr[64 * j]; }
	s_mul_i32 s8, s5, 0x3000
	s_ashr_i32 s9, s8, 31
	s_lshl_b64 s[8:9], s[8:9], 2
	s_add_u32 s7, s0, s8
	s_addc_u32 s29, s1, s9
	s_add_u32 s8, s7, 0x100000
	s_addc_u32 s9, s29, 0
	v_readlane_b32 s12, v254, 12
	s_cmp_eq_u32 s5, 0
	v_readlane_b32 s13, v254, 13
	v_readlane_b32 s15, v254, 15
	v_readlane_b32 s16, v254, 16
	s_cselect_b32 s15, s13, s59
	s_cselect_b32 s16, s12, s58
	s_lshl_b32 s10, s5, 11
	s_ashr_i32 s11, s10, 31
	s_lshl_b64 s[10:11], s[10:11], 2
	s_add_u32 s5, s0, s10
	s_addc_u32 s10, s1, s11
	s_add_u32 s12, s5, 0x20000
	s_addc_u32 s13, s10, 0
	s_add_u32 s10, s7, 0x102000
	v_and_b32_e32 v140, 63, v0
	s_addc_u32 s11, s29, 0
	v_lshlrev_b32_e32 v0, 4, v140
	v_lshl_add_u64 v[2:3], s[10:11], 0, v[0:1]
	global_load_dwordx4 v[46:49], v[2:3], off
	v_or_b32_e32 v2, 0x400, v0
	v_mov_b32_e32 v3, v1
	v_lshl_add_u64 v[2:3], s[10:11], 0, v[2:3]
	global_load_dwordx4 v[50:53], v[2:3], off
	v_or_b32_e32 v2, 0x800, v0
	v_mov_b32_e32 v3, v1
	v_lshl_add_u64 v[2:3], s[10:11], 0, v[2:3]
	v_or_b32_e32 v4, 0xc00, v0
	v_mov_b32_e32 v5, v1
	v_or_b32_e32 v6, 0x1000, v0
	v_mov_b32_e32 v7, v1
	v_lshl_add_u64 v[4:5], s[10:11], 0, v[4:5]
	global_load_dwordx4 v[58:61], v[2:3], off
	global_load_dwordx4 v[54:57], v[4:5], off
	v_lshl_add_u64 v[2:3], s[10:11], 0, v[6:7]
	v_or_b32_e32 v10, 0x1400, v0
	v_mov_b32_e32 v11, v1
	global_load_dwordx4 v[62:65], v[2:3], off
	v_lshl_add_u64 v[2:3], s[10:11], 0, v[10:11]
	global_load_dwordx4 v[66:69], v[2:3], off
	v_lshl_add_u64 v[2:3], s[12:13], 0, v[0:1]
	global_load_dwordx4 v[70:73], v[2:3], off
	global_load_dwordx4 v[74:77], v[2:3], off offset:1024
	global_load_dwordx4 v[108:111], v[2:3], off offset:2048
	global_load_dwordx4 v[112:115], v[2:3], off offset:3072
	v_lshl_add_u64 v[2:3], s[12:13], 0, v[6:7]
	global_load_dwordx4 v[116:119], v[2:3], off
	v_lshl_add_u64 v[2:3], s[12:13], 0, v[10:11]
	global_load_dwordx4 v[120:123], v[2:3], off
	v_mov_b32_e32 v3, v1
	v_or_b32_e32 v2, 0x1800, v0
	v_lshl_add_u64 v[4:5], s[12:13], 0, v[2:3]
	v_mov_b32_e32 v13, v1
	v_or_b32_e32 v12, 0x1c00, v0
	v_lshl_add_u64 v[8:9], s[10:11], 0, v[2:3]
	global_load_dwordx4 v[124:127], v[4:5], off
	global_load_dwordx4 v[128:131], v[8:9], off
	v_lshl_add_u64 v[2:3], s[8:9], 0, v[2:3]
	v_lshl_add_u64 v[4:5], s[10:11], 0, v[12:13]
	v_lshl_add_u64 v[8:9], s[12:13], 0, v[12:13]
	global_load_dwordx4 v[132:135], v[4:5], off
	s_nop 0
	global_load_dwordx4 v[2:5], v[2:3], off
	s_nop 0
	global_load_dwordx4 v[136:139], v[8:9], off
	s_ashr_i32 s7, s6, 31
	v_lshl_add_u64 v[6:7], s[8:9], 0, v[6:7]
	v_lshl_add_u64 v[22:23], s[8:9], 0, v[0:1]
	v_lshl_add_u64 v[26:27], s[8:9], 0, v[10:11]
	v_lshl_add_u64 v[30:31], s[8:9], 0, v[12:13]
	s_lshl_b64 s[8:9], s[6:7], 13
	s_add_u32 s8, s16, s8
	s_addc_u32 s9, s15, s9
	v_lshl_add_u64 v[32:33], s[8:9], 0, v[0:1]
	s_movk_i32 s5, 0x1000
	global_load_dwordx4 v[6:9], v[6:7], off
	s_nop 0
	global_load_dwordx4 v[10:13], v[22:23], off offset:1024
	global_load_dwordx4 v[14:17], v[22:23], off offset:2048
	global_load_dwordx4 v[18:21], v[22:23], off
	s_nop 0
	global_load_dwordx4 v[22:25], v[22:23], off offset:3072
	s_nop 0
	global_load_dwordx4 v[26:29], v[26:27], off
	v_add_co_u32_e32 v32, vcc, s5, v32
	v_readlane_b32 s14, v254, 14
	s_nop 0
	v_addc_co_u32_e32 v33, vcc, 0, v33, vcc
	global_load_dwordx4 v[34:37], v[32:33], off offset:3072
	global_load_dwordx4 v[38:41], v[32:33], off offset:2048
	global_load_dwordx4 v[42:45], v[32:33], off offset:1024
	global_load_dwordx4 v[78:81], v[32:33], off
	global_load_dwordx4 v[82:85], v0, s[8:9] offset:3072
	global_load_dwordx4 v[86:89], v0, s[8:9] offset:2048
	global_load_dwordx4 v[90:93], v0, s[8:9] offset:1024
	global_load_dwordx4 v[94:97], v0, s[8:9]
	s_nop 0
	global_load_dwordx4 v[30:33], v[30:31], off
	s_lshl_b64 s[8:9], s[6:7], 12
	s_add_u32 s0, s0, s8
	s_addc_u32 s1, s1, s9
	s_ashr_i32 s5, s4, 31
	s_lshl_b64 s[8:9], s[4:5], 12
	v_readlane_b32 s17, v254, 17
	v_readlane_b32 s18, v254, 18
	v_readlane_b32 s19, v254, 19
	v_readlane_b32 s20, v254, 20
	v_readlane_b32 s21, v254, 21
	v_readlane_b32 s22, v254, 22
	v_readlane_b32 s23, v254, 23
	v_readlane_b32 s24, v254, 24
	v_readlane_b32 s25, v254, 25
	v_readlane_b32 s26, v254, 26
	v_readlane_b32 s27, v254, 27
	s_waitcnt vmcnt(0) lgkmcnt(0)
	v_pk_add_f32 v[46:47], v[46:47], 1.0 op_sel_hi:[1,0]
	v_pk_add_f32 v[48:49], v[48:49], 1.0 op_sel_hi:[1,0]
	v_pk_add_f32 v[52:53], v[52:53], 1.0 op_sel_hi:[1,0]
	v_pk_add_f32 v[50:51], v[50:51], 1.0 op_sel_hi:[1,0]
	v_pk_add_f32 v[60:61], v[60:61], 1.0 op_sel_hi:[1,0]
	v_pk_add_f32 v[56:57], v[56:57], 1.0 op_sel_hi:[1,0]
	v_pk_add_f32 v[58:59], v[58:59], 1.0 op_sel_hi:[1,0]
	v_pk_add_f32 v[54:55], v[54:55], 1.0 op_sel_hi:[1,0]
	v_pk_add_f32 v[64:65], v[64:65], 1.0 op_sel_hi:[1,0]
	v_pk_mul_f32 v[100:101], v[70:71], v[46:47]
	v_pk_add_f32 v[68:69], v[68:69], 1.0 op_sel_hi:[1,0]
	v_pk_mul_f32 v[106:107], v[110:111], v[60:61]
	v_pk_mul_f32 v[110:111], v[114:115], v[56:57]
	v_pk_mul_f32 v[98:99], v[72:73], v[48:49]
	v_pk_mul_f32 v[114:115], v[118:119], v[64:65]
	v_pk_add_f32 v[62:63], v[62:63], 1.0 op_sel_hi:[1,0]
	v_pk_mul_f32 v[118:119], v[122:123], v[68:69]
	v_pk_add_f32 v[66:67], v[66:67], 1.0 op_sel_hi:[1,0]
	v_pk_mul_f32 v[102:103], v[76:77], v[52:53]
	v_pk_mul_f32 v[104:105], v[74:75], v[50:51]
	v_pk_mul_f32 v[108:109], v[108:109], v[58:59]
	v_pk_mul_f32 v[112:113], v[112:113], v[54:55]
	v_pk_mul_f32 v[116:117], v[116:117], v[62:63]
	v_pk_add_f32 v[46:47], v[130:131], 1.0 op_sel_hi:[1,0]
	v_pk_add_f32 v[48:49], v[128:129], 1.0 op_sel_hi:[1,0]
	v_pk_mul_f32 v[122:123], v[126:127], v[46:47]
	v_pk_add_f32 v[46:47], v[134:135], 1.0 op_sel_hi:[1,0]
	v_pk_mul_f32 v[124:125], v[124:125], v[48:49]
	v_pk_mul_f32 v[126:127], v[138:139], v[46:47]
	v_lshlrev_b32_e32 v46, 3, v140
	v_mov_b32_e32 v47, v1
	v_lshl_add_u64 v[46:47], s[0:1], 0, v[46:47]
	s_mov_b64 s[0:1], 0xbe00000
	v_lshl_add_u64 v[130:131], v[46:47], 0, s[0:1]
	s_add_i32 s0, s86, s4
	s_add_i32 s0, s0, s28
	s_ashr_i32 s1, s0, 31
	s_lshl_b64 s[0:1], s[0:1], 13
	s_add_u32 s0, s16, s0
	s_addc_u32 s1, s15, s1
	v_pk_add_f32 v[48:49], v[132:133], 1.0 op_sel_hi:[1,0]
	v_lshl_add_u64 v[46:47], s[0:1], 0, v[0:1]
	s_mov_b64 s[0:1], 0x1000
	v_pk_mul_f32 v[120:121], v[120:121], v[66:67]
	v_pk_mul_f32 v[128:129], v[136:137], v[48:49]
	v_lshl_add_u64 v[132:133], v[46:47], 0, s[0:1]
	v_mov_b64_e32 v[48:49], v[36:37]
	v_mov_b64_e32 v[52:53], v[40:41]
	v_mov_b64_e32 v[56:57], v[44:45]
	v_mov_b64_e32 v[58:59], v[78:79]
	v_mov_b64_e32 v[62:63], v[82:83]
	v_mov_b64_e32 v[66:67], v[86:87]
	v_mov_b64_e32 v[70:71], v[90:91]
	v_mov_b64_e32 v[74:75], v[94:95]
	s_lshl_b64 s[10:11], s[4:5], 13
	v_mov_b64_e32 v[46:47], v[34:35]
	v_mov_b64_e32 v[50:51], v[38:39]
	v_mov_b64_e32 v[54:55], v[42:43]
	v_mov_b64_e32 v[60:61], v[80:81]
	v_mov_b64_e32 v[64:65], v[84:85]
	v_mov_b64_e32 v[68:69], v[88:89]
	v_mov_b64_e32 v[72:73], v[92:93]
	v_mov_b64_e32 v[76:77], v[96:97]
	s_branch .LBB0_140

; __device__ __forceinline__ unsigned xb_ld(unsigned* p)              { return __hip_atomic_load(p, __ATOMIC_RELAXED, __HIP_MEMORY_SCOPE_AGENT); }
; __device__ __forceinline__ void xcd_barrier_complete(unsigned* bar, unsigned x, unsigned& nloc, unsigned& nx) {
;     const unsigned G = gridDim.x * gridDim.y * gridDim.z;
;     unsigned sum, cnt, mine, sp = 0u;
;     for (;;) {
;         sum = 0u; cnt = 0u; mine = 0u;
; #pragma unroll
;         for (unsigned j = 0; j < 16; ++j) { const unsigned c = xb_ld(&bar[XB_XCNT(j)]); sum += c; cnt += (c > 0u) ? 1u : 0u; mine = (j == x) ? c : mine; }
;         if (sum == G) break;
;         __builtin_amdgcn_s_sleep(1);
;         if ((++sp & 255u) == 0u) { if (xb_ld(&bar[XB_TMO])) break; if (sp > XB_SPIN_CAP) { atomicAdd(&bar[XB_TMO], 1u); break; } }
;     }
.LBB0_147:
	v_mov_b64_e32 v[2:3], s[4:5]
	s_waitcnt lgkmcnt(0)
	global_load_dword v0, v[2:3], off sc1
	v_mov_b64_e32 v[2:3], s[6:7]
	global_load_dword v2, v[2:3], off sc1
	v_mov_b64_e32 v[4:5], s[8:9]
	global_load_dword v3, v[4:5], off sc1
	v_mov_b64_e32 v[4:5], s[10:11]
	global_load_dword v4, v[4:5], off sc1
	v_readlane_b32 s40, v254, 8
	s_or_b64 s[88:89], s[88:89], exec
	s_or_b64 s[86:87], s[86:87], exec
	s_waitcnt vmcnt(0) lgkmcnt(0)
	v_add_u32_e32 v6, v2, v0
	v_add_u32_e32 v6, v6, v3
	v_add_u32_e32 v8, v6, v4
	v_mov_b64_e32 v[6:7], s[12:13]
	global_load_dword v5, v[6:7], off sc1
	v_mov_b64_e32 v[6:7], s[14:15]
	global_load_dword v6, v[6:7], off sc1
	s_waitcnt vmcnt(0) lgkmcnt(0)
	v_add_u32_e32 v8, v8, v5
	v_add_u32_e32 v10, v8, v6
	v_mov_b64_e32 v[8:9], s[16:17]
	global_load_dword v7, v[8:9], off sc1
	v_mov_b64_e32 v[8:9], s[18:19]
	global_load_dword v8, v[8:9], off sc1
	s_waitcnt vmcnt(0) lgkmcnt(0)
	v_add_u32_e32 v10, v10, v7
	v_add_u32_e32 v12, v10, v8
	v_mov_b64_e32 v[10:11], s[20:21]
	global_load_dword v9, v[10:11], off sc1
	v_mov_b64_e32 v[10:11], s[22:23]
	global_load_dword v10, v[10:11], off sc1
	s_waitcnt vmcnt(0) lgkmcnt(0)
	v_add_u32_e32 v12, v12, v9
	v_add_u32_e32 v14, v12, v10
	v_mov_b64_e32 v[12:13], s[24:25]
	global_load_dword v11, v[12:13], off sc1
	v_mov_b64_e32 v[12:13], s[26:27]
	global_load_dword v12, v[12:13], off sc1
	s_waitcnt vmcnt(0) lgkmcnt(0)
	v_add_u32_e32 v14, v14, v11
	v_add_u32_e32 v16, v14, v12
	v_mov_b64_e32 v[14:15], s[28:29]
	global_load_dword v13, v[14:15], off sc1
	v_mov_b64_e32 v[14:15], s[30:31]
	global_load_dword v14, v[14:15], off sc1
	s_waitcnt vmcnt(0) lgkmcnt(0)
	v_add_u32_e32 v16, v16, v13
	v_add_u32_e32 v18, v16, v14
	v_mov_b64_e32 v[16:17], s[78:79]
	global_load_dword v15, v[16:17], off sc1
	v_mov_b64_e32 v[16:17], s[92:93]
	global_load_dword v16, v[16:17], off sc1
	s_waitcnt vmcnt(0) lgkmcnt(0)
	v_add_u32_e32 v18, v18, v15
	v_add_u32_e32 v17, v18, v16
	v_cmp_ne_u32_e32 vcc, s40, v17
	s_and_saveexec_b64 s[90:91], vcc
	s_cbranch_execz .LBB0_146
	s_and_b32 s40, s85, 0xff
	s_mov_b64 s[64:65], -1
	s_cmp_eq_u32 s40, 0
	s_mov_b64 s[72:73], -1
	s_mov_b64 s[40:41], -1
	s_sleep 1
	s_cbranch_scc1 .LBB0_150
	s_and_saveexec_b64 s[70:71], s[72:73]
	s_cbranch_execz .LBB0_145
	s_branch .LBB0_153
.LBB0_150:
	v_mov_b64_e32 v[18:19], s[0:1]
	global_load_dword v17, v[18:19], off sc1
	s_mov_b64 s[72:73], 0
	s_waitcnt vmcnt(0) lgkmcnt(0)
	v_cmp_eq_u32_e32 vcc, 0, v17
	s_and_saveexec_b64 s[70:71], vcc
	s_cmp_lt_u32 s85, 0x400001
	s_cselect_b64 s[72:73], -1, 0
	s_xor_b64 s[40:41], exec, -1
	s_and_b64 s[72:73], s[72:73], exec
	s_or_b64 exec, exec, s[70:71]
	s_and_saveexec_b64 s[70:71], s[72:73]
	s_cbranch_execz .LBB0_145

; __device__ __forceinline__ unsigned xb_ld(unsigned* p)              { return __hip_atomic_load(p, __ATOMIC_RELAXED, __HIP_MEMORY_SCOPE_AGENT); }
; __device__ __forceinline__ unsigned xb_add(unsigned* p, unsigned v) { return __hip_atomic_fetch_add(p, v, __ATOMIC_RELAXED, __HIP_MEMORY_SCOPE_AGENT); }
; #define XB_SPIN(cond, bar) do { unsigned _sp = 0; while (cond) {     \
;     if ((++_sp & 255u) == 0u) { if (xb_ld(&(bar)[XB_TMO])) break; if (_sp > XB_SPIN_CAP) { atomicAdd(&(bar)[XB_TMO], 1u); break; } } } } while (0)
; __device__ __forceinline__ void xcd_barrier(const XcdBarrier& b, int wave_s) {
;     ...
;         const unsigned old = xb_add(&bar[XB_XSUB(b.x)], 1u);
;         const unsigned gen = old / nloc;
;         if (old + 1u == (gen + 1u) * nloc) {
;             __builtin_amdgcn_fence(__ATOMIC_RELEASE, "agent");
;             asm volatile("s_waitcnt vmcnt(0)" ::: "memory");
;             const unsigned og = xb_add(&bar[XB_TOP], 1u);
;             const unsigned tg = og / nx;
;             if (og + 1u == (tg + 1u) * nx) xb_add(&bar[XB_TOPGEN], 1u);
;             else XB_SPIN(xb_ld(&bar[XB_TOPGEN]) == tg, bar);
;             __builtin_amdgcn_fence(__ATOMIC_ACQUIRE, "agent");
;             xb_add(&bar[XB_XGEN(b.x)], 1u);
;             asm volatile("s_waitcnt vmcnt(0)" ::: "memory");
;         } else {
;             XB_SPIN(xb_ld(&bar[XB_XGEN(b.x)]) == gen, bar);
.LBB0_157:
	s_lshl_b32 s0, s37, 8
	s_add_u32 s0, s56, s0
	s_addc_u32 s1, s57, 0
	v_mov_b32_e32 v3, s0
	v_add_co_u32_e32 v4, vcc, 0x11000, v3
	v_mov_b32_e32 v3, s1
	s_nop 0
	v_addc_co_u32_e32 v5, vcc, 0, v3, vcc
	flat_atomic_add v4, v[4:5], v220 offset:1024 sc0
	v_cvt_f32_u32_e32 v3, v2
	v_sub_u32_e32 v5, 0, v2
	s_add_u32 s25, s0, 0x10000
	s_addc_u32 s24, s1, 0
	v_rcp_iflag_f32_e32 v3, v3
	s_nop 0
	v_mul_f32_e32 v3, 0x4f7ffffe, v3
	v_cvt_u32_f32_e32 v3, v3
	v_mul_lo_u32 v5, v5, v3
	v_mul_hi_u32 v5, v3, v5
	v_add_u32_e32 v3, v3, v5
	s_waitcnt vmcnt(0) lgkmcnt(0)
	v_mul_hi_u32 v3, v4, v3
	v_mul_lo_u32 v5, v3, v2
	v_sub_u32_e32 v5, v4, v5
	v_cmp_ge_u32_e32 vcc, v5, v2
	v_add_u32_e32 v6, 1, v3
	s_nop 0
	v_cndmask_b32_e32 v3, v3, v6, vcc
	v_sub_u32_e32 v6, v5, v2
	v_cndmask_b32_e32 v5, v5, v6, vcc
	v_cmp_ge_u32_e32 vcc, v5, v2
	v_add_u32_e32 v5, 1, v3
	v_add_u32_e32 v6, 1, v4
	v_cndmask_b32_e32 v3, v3, v5, vcc
	v_mad_u64_u32 v[4:5], s[0:1], v2, v3, v[2:3]
	v_cmp_ne_u32_e32 vcc, v6, v4
	s_and_saveexec_b64 s[0:1], vcc
	s_xor_b64 s[0:1], exec, s[0:1]
	s_cbranch_execz .LBB0_170
	v_mov_b32_e32 v0, s25
	v_add_co_u32_e32 v4, vcc, 0x2000, v0
	v_mov_b32_e32 v0, s24
	s_nop 0
	v_addc_co_u32_e32 v5, vcc, 0, v0, vcc
	global_load_dword v0, v[4:5], off offset:1024 sc1
	s_add_u32 s6, s25, 0x2400
	s_addc_u32 s7, s24, 0
	s_waitcnt vmcnt(0) lgkmcnt(0)
	v_cmp_eq_u32_e32 vcc, v0, v3
	s_and_saveexec_b64 s[4:5], vcc
	s_cbranch_execz .LBB0_169
	s_add_u32 s8, s56, 0x10200
	s_addc_u32 s9, s57, 0
	s_mov_b32 s26, 1
	s_mov_b64 s[10:11], 0
	s_branch .LBB0_161

; __device__ __forceinline__ unsigned xb_ld(unsigned* p)              { return __hip_atomic_load(p, __ATOMIC_RELAXED, __HIP_MEMORY_SCOPE_AGENT); }
; #define XB_SPIN(cond, bar) do { unsigned _sp = 0; while (cond) {     \
;     if ((++_sp & 255u) == 0u) { if (xb_ld(&(bar)[XB_TMO])) break; if (_sp > XB_SPIN_CAP) { atomicAdd(&(bar)[XB_TMO], 1u); break; } } } } while (0)
; __device__ __forceinline__ void xcd_barrier(const XcdBarrier& b, int wave_s) {
;     ...
;             XB_SPIN(xb_ld(&bar[XB_XGEN(b.x)]) == gen, bar);
.LBB0_161:
	s_and_b32 s18, s26, 0xff
	s_mov_b64 s[16:17], -1
	s_cmp_lg_u32 s18, 0
	s_mov_b64 s[18:19], -1
	s_cbranch_scc1 .LBB0_165
	v_mov_b64_e32 v[4:5], s[8:9]
	global_load_dword v0, v[4:5], off sc1
	s_mov_b64 s[18:19], 0
	s_mov_b64 s[20:21], -1
	s_waitcnt vmcnt(0) lgkmcnt(0)
	v_cmp_eq_u32_e32 vcc, 0, v0
	s_and_saveexec_b64 s[22:23], vcc
	s_cmp_lt_u32 s26, 0x400001
	s_cselect_b64 s[18:19], -1, 0
	s_xor_b64 s[20:21], exec, -1
	s_and_b64 s[18:19], s[18:19], exec
	s_or_b64 exec, exec, s[22:23]
.LBB0_165:
	s_andn2_b64 s[14:15], s[14:15], exec
	s_and_b64 s[20:21], s[20:21], exec
	s_or_b64 s[14:15], s[14:15], s[20:21]
	s_and_saveexec_b64 s[20:21], s[18:19]
	s_cbranch_execz .LBB0_160
	v_mov_b64_e32 v[4:5], s[6:7]
	global_load_dword v0, v[4:5], off sc1
	s_add_i32 s26, s26, 1
	s_or_b64 s[14:15], s[14:15], exec
	s_waitcnt vmcnt(0) lgkmcnt(0)
	v_cmp_ne_u32_e32 vcc, v0, v3
	s_orn2_b64 s[16:17], vcc, exec
	s_branch .LBB0_160

; __device__ __forceinline__ unsigned xb_ld(unsigned* p)              { return __hip_atomic_load(p, __ATOMIC_RELAXED, __HIP_MEMORY_SCOPE_AGENT); }
; __device__ __forceinline__ unsigned xb_add(unsigned* p, unsigned v) { return __hip_atomic_fetch_add(p, v, __ATOMIC_RELAXED, __HIP_MEMORY_SCOPE_AGENT); }
; #define XB_SPIN(cond, bar) do { unsigned _sp = 0; while (cond) {     \
;     if ((++_sp & 255u) == 0u) { if (xb_ld(&(bar)[XB_TMO])) break; if (_sp > XB_SPIN_CAP) { atomicAdd(&(bar)[XB_TMO], 1u); break; } } } } while (0)
; __device__ __forceinline__ void xcd_barrier(const XcdBarrier& b, int wave_s) {
;     ...
;         if (old + 1u == (gen + 1u) * nloc) {
;             __builtin_amdgcn_fence(__ATOMIC_RELEASE, "agent");
;             asm volatile("s_waitcnt vmcnt(0)" ::: "memory");
;             const unsigned og = xb_add(&bar[XB_TOP], 1u);
;             const unsigned tg = og / nx;
;             if (og + 1u == (tg + 1u) * nx) xb_add(&bar[XB_TOPGEN], 1u);
;             else XB_SPIN(xb_ld(&bar[XB_TOPGEN]) == tg, bar);
.LBB0_170:
	s_andn2_saveexec_b64 s[0:1], s[0:1]
	s_cbranch_execz .LBB0_186
	v_mov_b32_e32 v2, s56
	v_add_co_u32_e32 v2, vcc, 0x13000, v2
	v_mov_b32_e32 v3, s57
	buffer_wbl2 sc1
	s_waitcnt vmcnt(0)
	v_addc_co_u32_e32 v3, vcc, 0, v3, vcc
	flat_atomic_add v2, v[2:3], v220 offset:1024 sc0
	v_cvt_f32_u32_e32 v3, v0
	v_sub_u32_e32 v4, 0, v0
	s_mov_b64 s[6:7], -1
	v_rcp_iflag_f32_e32 v3, v3
	s_nop 0
	v_mul_f32_e32 v3, 0x4f7ffffe, v3
	v_cvt_u32_f32_e32 v3, v3
	v_mul_lo_u32 v4, v4, v3
	v_mul_hi_u32 v4, v3, v4
	v_add_u32_e32 v3, v3, v4
	s_waitcnt vmcnt(0) lgkmcnt(0)
	v_mul_hi_u32 v3, v2, v3
	v_mul_lo_u32 v4, v3, v0
	v_sub_u32_e32 v4, v2, v4
	v_cmp_ge_u32_e32 vcc, v4, v0
	v_add_u32_e32 v5, 1, v3
	s_nop 0
	v_cndmask_b32_e32 v3, v3, v5, vcc
	v_sub_u32_e32 v5, v4, v0
	v_cndmask_b32_e32 v4, v4, v5, vcc
	v_cmp_ge_u32_e32 vcc, v4, v0
	v_add_u32_e32 v4, 1, v3
	v_add_u32_e32 v5, 1, v2
	v_cndmask_b32_e32 v4, v3, v4, vcc
	v_mad_u64_u32 v[2:3], s[0:1], v0, v4, v[0:1]
	s_add_u32 s0, s56, 0x13500
	s_addc_u32 s1, s57, 0
	v_cmp_ne_u32_e32 vcc, v5, v2
	v_mov_b64_e32 v[2:3], s[0:1]
	s_and_saveexec_b64 s[4:5], vcc
	s_cbranch_execz .LBB0_183
	v_mov_b64_e32 v[2:3], s[0:1]
	global_load_dword v0, v[2:3], off sc1
	s_mov_b64 s[10:11], 0
	s_waitcnt vmcnt(0) lgkmcnt(0)
	v_cmp_eq_u32_e32 vcc, v0, v4
	s_and_saveexec_b64 s[8:9], vcc
	s_cbranch_execz .LBB0_182
	s_add_u32 s6, s56, 0x10200
	s_addc_u32 s7, s57, 0
	s_mov_b32 s22, 1
	s_branch .LBB0_175

; __device__ __forceinline__ unsigned xb_ld(unsigned* p)              { return __hip_atomic_load(p, __ATOMIC_RELAXED, __HIP_MEMORY_SCOPE_AGENT); }
; #define XB_SPIN(cond, bar) do { unsigned _sp = 0; while (cond) {     \
;     if ((++_sp & 255u) == 0u) { if (xb_ld(&(bar)[XB_TMO])) break; if (_sp > XB_SPIN_CAP) { atomicAdd(&(bar)[XB_TMO], 1u); break; } } } } while (0)
; __device__ __forceinline__ void xcd_barrier(const XcdBarrier& b, int wave_s) {
;     ...
;             else XB_SPIN(xb_ld(&bar[XB_TOPGEN]) == tg, bar);
.LBB0_177:
	v_mov_b64_e32 v[2:3], s[6:7]
	global_load_dword v0, v[2:3], off sc1
	s_mov_b64 s[18:19], 0
	s_mov_b64 s[16:17], -1
	s_waitcnt vmcnt(0) lgkmcnt(0)
	v_cmp_eq_u32_e32 vcc, 0, v0
	s_and_saveexec_b64 s[20:21], vcc
	s_cmp_lt_u32 s22, 0x400001
	s_cselect_b64 s[18:19], -1, 0
	s_xor_b64 s[16:17], exec, -1
	s_and_b64 s[18:19], s[18:19], exec
	s_or_b64 exec, exec, s[20:21]
	s_and_saveexec_b64 s[20:21], s[18:19]
	s_cbranch_execz .LBB0_174
.LBB0_180:
	v_mov_b64_e32 v[2:3], s[0:1]
	global_load_dword v0, v[2:3], off sc1
	s_add_i32 s22, s22, 1
	s_or_b64 s[16:17], s[16:17], exec
	s_waitcnt vmcnt(0) lgkmcnt(0)
	v_cmp_ne_u32_e32 vcc, v0, v4
	s_orn2_b64 s[14:15], vcc, exec
	s_branch .LBB0_174

; __device__ __forceinline__ unsigned cvtpk(float lo, float hi) { unsigned r; asm volatile("v_cvt_pk_bf16_f32 %0, %1, %2" : "=v"(r) : "v"(lo), "v"(hi)); return r; }
; #define PG8_BAR __builtin_amdgcn_s_barrier()
;     __device__ __forceinline__ void operator()(const f32x4 (&acc)[2][2][4][2], const Unit& u, int wr, int wc, int fr, int fq) const {
;     ...
;             for (int m = 2 * (am & 1); m < 2 * (am & 1) + 2; ++m) { const int row = row0 + ai * HALF + m * 16; bf16_t* rowp = O + (size_t)row * ldc + col0;
;                 const float rsvv = rsv[ai][m];
; #pragma unroll
;                 for (int bj = 0; bj < 2; ++bj) { f32x4 v0 = acc[ai][bj][m][0], v1 = acc[ai][bj][m][1];
;                     if (MODE == 1) {
; #pragma unroll
;                         for (int e = 0; e < 4; ++e) { float a = fmaxf(v0[e], 0.f), b = fmaxf(v1[e], 0.f); v0[e] = a * a; v1[e] = b * b; } }
;                     if (MODE >= 2) { v0 = v0 * rsvv; v1 = v1 * rsvv; }
;                     if (MODE == 3) { const f32x4 a0 = t0[m][bj], a1 = t1[m][bj]; f32x4 w0, w1;
;                         w0[0] = v0[0] * a0[0] - v0[1] * a0[1]; w0[1] = v0[1] * a0[0] + v0[0] * a0[1]; w0[2] = v0[2] * a0[2] - v0[3] * a0[3]; w0[3] = v0[3] * a0[2] + v0[2] * a0[3];
;                         w1[0] = v1[0] * a1[0] - v1[1] * a1[1]; w1[1] = v1[1] * a1[0] + v1[0] * a1[1]; w1[2] = v1[2] * a1[2] - v1[3] * a1[3]; w1[3] = v1[3] * a1[2] + v1[2] * a1[3];
;                         v0 = w0; v1 = w1; }
;                     u32x4 w; w.x = cvtpk(v0[0], v0[1]); w.y = cvtpk(v0[2], v0[3]); w.z = cvtpk(v1[0], v1[1]); w.w = cvtpk(v1[2], v1[3]);
;                     *(u32x4*)(rowp + bj * HALF) = w; } }
; template <class Epi>
; __device__ __forceinline__ void gemm_phase(LAS unsigned char* lds, const Gemm g, const StaticOrder& S, const Epi& E, int wave_s) {
;     ...
;         if (wr == 1) PG8_BAR;
.LBB0_198:
	s_lshl_b32 s11, s56, 8
	v_mbcnt_lo_u32_b32 v140, -1, 0
	v_mbcnt_hi_u32_b32 v140, -1, v140
	s_add_i32 s11, s11, s35
	v_and_or_b32 v147, v140, 15, s11
	v_lshrrev_b32_e32 v140, 1, v140
	s_lshl_b32 s11, s41, 8
	v_and_or_b32 v140, v140, 24, s11
	v_or_b32_e32 v142, s37, v140
	v_ashrrev_i32_e32 v143, 31, v142
	v_mov_b64_e32 v[140:141], s[6:7]
	v_mad_i64_i32 v[148:149], s[18:19], v147, s69, v[140:141]
	v_lshlrev_b64 v[142:143], 1, v[142:143]
	v_lshl_add_u64 v[148:149], v[148:149], 0, v[142:143]
	v_cvt_pk_bf16_f32 v126, v126, v127
	v_cvt_pk_bf16_f32 v127, v128, v129
	v_cvt_pk_bf16_f32 v128, v122, v123
	v_cvt_pk_bf16_f32 v129, v124, v125
	global_store_dwordx4 v[148:149], v[126:129], off
	v_cvt_pk_bf16_f32 v114, v114, v115
	v_cvt_pk_bf16_f32 v115, v116, v117
	v_cvt_pk_bf16_f32 v116, v106, v107
	v_or_b32_e32 v106, 16, v147
	v_mad_i64_i32 v[106:107], s[18:19], v106, s69, v[140:141]
	v_cvt_pk_bf16_f32 v117, v108, v109
	global_store_dwordx4 v[148:149], v[114:117], off offset:256
	s_andn2_b64 vcc, exec, s[0:1]
	s_mov_b64 s[0:1], -1
	v_lshl_add_u64 v[114:115], v[106:107], 0, v[142:143]
	v_cvt_pk_bf16_f32 v106, v118, v119
	v_cvt_pk_bf16_f32 v107, v120, v121
	v_cvt_pk_bf16_f32 v108, v110, v111
	v_cvt_pk_bf16_f32 v109, v112, v113
	global_store_dwordx4 v[114:115], v[106:109], off
	v_cvt_pk_bf16_f32 v98, v98, v99
	v_cvt_pk_bf16_f32 v99, v100, v101
	v_cvt_pk_bf16_f32 v100, v90, v91
	v_or_b32_e32 v90, 32, v147
	v_mad_i64_i32 v[90:91], s[18:19], v90, s69, v[140:141]
	v_cvt_pk_bf16_f32 v101, v92, v93
	global_store_dwordx4 v[114:115], v[98:101], off offset:256
	s_nop 1
	v_lshl_add_u64 v[98:99], v[90:91], 0, v[142:143]
	v_cvt_pk_bf16_f32 v90, v102, v103
	v_cvt_pk_bf16_f32 v91, v104, v105
	v_cvt_pk_bf16_f32 v92, v94, v95
	v_cvt_pk_bf16_f32 v93, v96, v97
	global_store_dwordx4 v[98:99], v[90:93], off
	v_cvt_pk_bf16_f32 v82, v82, v83
	v_cvt_pk_bf16_f32 v83, v84, v85
	v_cvt_pk_bf16_f32 v84, v74, v75
	v_or_b32_e32 v74, 48, v147
	v_mad_i64_i32 v[74:75], s[18:19], v74, s69, v[140:141]
	v_cvt_pk_bf16_f32 v85, v76, v77
	global_store_dwordx4 v[98:99], v[82:85], off offset:256
	s_nop 1
	v_lshl_add_u64 v[82:83], v[74:75], 0, v[142:143]
	v_cvt_pk_bf16_f32 v74, v86, v87
	v_cvt_pk_bf16_f32 v75, v88, v89
	v_cvt_pk_bf16_f32 v76, v78, v79
	v_cvt_pk_bf16_f32 v77, v80, v81
	global_store_dwordx4 v[82:83], v[74:77], off
	v_cvt_pk_bf16_f32 v70, v70, v71
	v_cvt_pk_bf16_f32 v71, v72, v73
	v_cvt_pk_bf16_f32 v72, v66, v67
	v_add_u32_e32 v66, 0x80, v147
	v_mad_i64_i32 v[66:67], s[18:19], v66, s69, v[140:141]
	v_lshl_add_u64 v[66:67], v[66:67], 0, v[142:143]
	v_cvt_pk_bf16_f32 v73, v68, v69
	global_store_dwordx4 v[82:83], v[70:73], off offset:256
	v_cvt_pk_bf16_f32 v62, v62, v63
	v_cvt_pk_bf16_f32 v63, v64, v65
	v_cvt_pk_bf16_f32 v64, v58, v59
	v_cvt_pk_bf16_f32 v65, v60, v61
	global_store_dwordx4 v[66:67], v[62:65], off
	v_cvt_pk_bf16_f32 v50, v50, v51
	v_cvt_pk_bf16_f32 v51, v52, v53
	v_cvt_pk_bf16_f32 v52, v42, v43
	v_add_u32_e32 v42, 0x90, v147
	v_mad_i64_i32 v[42:43], s[18:19], v42, s69, v[140:141]
	v_cvt_pk_bf16_f32 v53, v44, v45
	global_store_dwordx4 v[66:67], v[50:53], off offset:256
	s_nop 1
	v_lshl_add_u64 v[50:51], v[42:43], 0, v[142:143]
	v_cvt_pk_bf16_f32 v42, v54, v55
	v_cvt_pk_bf16_f32 v43, v56, v57
	v_cvt_pk_bf16_f32 v44, v46, v47
	v_cvt_pk_bf16_f32 v45, v48, v49
	global_store_dwordx4 v[50:51], v[42:45], off
	v_cvt_pk_bf16_f32 v34, v34, v35
	v_cvt_pk_bf16_f32 v35, v36, v37
	v_cvt_pk_bf16_f32 v36, v26, v27
	v_add_u32_e32 v26, 0xa0, v147
	v_mad_i64_i32 v[26:27], s[18:19], v26, s69, v[140:141]
	v_cvt_pk_bf16_f32 v37, v28, v29
	global_store_dwordx4 v[50:51], v[34:37], off offset:256
	s_nop 1
	v_lshl_add_u64 v[34:35], v[26:27], 0, v[142:143]
	v_cvt_pk_bf16_f32 v26, v38, v39
	v_cvt_pk_bf16_f32 v27, v40, v41
	v_cvt_pk_bf16_f32 v28, v30, v31
	v_cvt_pk_bf16_f32 v29, v32, v33
	global_store_dwordx4 v[34:35], v[26:29], off
	v_cvt_pk_bf16_f32 v18, v18, v19
	v_cvt_pk_bf16_f32 v19, v20, v21
	v_cvt_pk_bf16_f32 v20, v10, v11
	v_add_u32_e32 v10, 0xb0, v147
	v_mad_i64_i32 v[10:11], s[18:19], v10, s69, v[140:141]
	v_cvt_pk_bf16_f32 v21, v12, v13
	global_store_dwordx4 v[34:35], v[18:21], off offset:256
	s_nop 1
	v_lshl_add_u64 v[18:19], v[10:11], 0, v[142:143]
	v_cvt_pk_bf16_f32 v10, v22, v23
	v_cvt_pk_bf16_f32 v11, v24, v25
	v_cvt_pk_bf16_f32 v12, v14, v15
	v_cvt_pk_bf16_f32 v13, v16, v17
	global_store_dwordx4 v[18:19], v[10:13], off
	v_cvt_pk_bf16_f32 v6, v6, v7
	v_cvt_pk_bf16_f32 v7, v8, v9
	v_cvt_pk_bf16_f32 v8, v2, v3
	v_cvt_pk_bf16_f32 v9, v4, v5
	global_store_dwordx4 v[18:19], v[6:9], off offset:256
	s_cbranch_vccnz .LBB0_191
	s_andn2_b64 vcc, exec, s[4:5]
	s_cbranch_vccnz .LBB0_190
	s_barrier
	s_branch .LBB0_190

; __device__ __forceinline__ unsigned xb_ld(unsigned* p)              { return __hip_atomic_load(p, __ATOMIC_RELAXED, __HIP_MEMORY_SCOPE_AGENT); }
; __device__ __forceinline__ void xcd_barrier_complete(unsigned* bar, unsigned x, unsigned& nloc, unsigned& nx) {
;     ...
;     for (;;) {
;         sum = 0u; cnt = 0u; mine = 0u;
; #pragma unroll
;         for (unsigned j = 0; j < 16; ++j) { const unsigned c = xb_ld(&bar[XB_XCNT(j)]); sum += c; cnt += (c > 0u) ? 1u : 0u; mine = (j == x) ? c : mine; }
;         if (sum == G) break;
;         __builtin_amdgcn_s_sleep(1);
;         if ((++sp & 255u) == 0u) { if (xb_ld(&bar[XB_TMO])) break; if (sp > XB_SPIN_CAP) { atomicAdd(&bar[XB_TMO], 1u); break; } }
;     }
;     nloc = mine > 0u ? mine : 1u; nx = cnt > 0u ? cnt : 1u;
.LBB0_207:
	v_mov_b64_e32 v[2:3], s[4:5]
	s_waitcnt lgkmcnt(0)
	global_load_dword v0, v[2:3], off sc1
	v_mov_b64_e32 v[2:3], s[6:7]
	global_load_dword v2, v[2:3], off sc1
	v_mov_b64_e32 v[4:5], s[8:9]
	global_load_dword v3, v[4:5], off sc1
	v_mov_b64_e32 v[4:5], s[10:11]
	global_load_dword v4, v[4:5], off sc1
	v_readlane_b32 s40, v254, 8
	s_or_b64 s[88:89], s[88:89], exec
	s_or_b64 s[86:87], s[86:87], exec
	s_waitcnt vmcnt(0) lgkmcnt(0)
	v_add_u32_e32 v6, v2, v0
	v_add_u32_e32 v6, v6, v3
	v_add_u32_e32 v8, v6, v4
	v_mov_b64_e32 v[6:7], s[12:13]
	global_load_dword v5, v[6:7], off sc1
	v_mov_b64_e32 v[6:7], s[14:15]
	global_load_dword v6, v[6:7], off sc1
	s_waitcnt vmcnt(0) lgkmcnt(0)
	v_add_u32_e32 v8, v8, v5
	v_add_u32_e32 v10, v8, v6
	v_mov_b64_e32 v[8:9], s[16:17]
	global_load_dword v7, v[8:9], off sc1
	v_mov_b64_e32 v[8:9], s[18:19]
	global_load_dword v8, v[8:9], off sc1
	s_waitcnt vmcnt(0) lgkmcnt(0)
	v_add_u32_e32 v10, v10, v7
	v_add_u32_e32 v12, v10, v8
	v_mov_b64_e32 v[10:11], s[20:21]
	global_load_dword v9, v[10:11], off sc1
	v_mov_b64_e32 v[10:11], s[22:23]
	global_load_dword v10, v[10:11], off sc1
	s_waitcnt vmcnt(0) lgkmcnt(0)
	v_add_u32_e32 v12, v12, v9
	v_add_u32_e32 v14, v12, v10
	v_mov_b64_e32 v[12:13], s[24:25]
	global_load_dword v11, v[12:13], off sc1
	v_mov_b64_e32 v[12:13], s[26:27]
	global_load_dword v12, v[12:13], off sc1
	s_waitcnt vmcnt(0) lgkmcnt(0)
	v_add_u32_e32 v14, v14, v11
	v_add_u32_e32 v16, v14, v12
	v_mov_b64_e32 v[14:15], s[28:29]
	global_load_dword v13, v[14:15], off sc1
	v_mov_b64_e32 v[14:15], s[30:31]
	global_load_dword v14, v[14:15], off sc1
	s_waitcnt vmcnt(0) lgkmcnt(0)
	v_add_u32_e32 v16, v16, v13
	v_add_u32_e32 v18, v16, v14
	v_mov_b64_e32 v[16:17], s[56:57]
	global_load_dword v15, v[16:17], off sc1
	v_mov_b64_e32 v[16:17], s[78:79]
	global_load_dword v16, v[16:17], off sc1
	s_waitcnt vmcnt(0) lgkmcnt(0)
	v_add_u32_e32 v18, v18, v15
	v_add_u32_e32 v17, v18, v16
	v_cmp_ne_u32_e32 vcc, s40, v17
	s_and_saveexec_b64 s[90:91], vcc
	s_cbranch_execz .LBB0_206
	s_and_b32 s40, s85, 0xff
	s_mov_b64 s[64:65], -1
	s_cmp_eq_u32 s40, 0
	s_mov_b64 s[72:73], -1
	s_mov_b64 s[40:41], -1
	s_sleep 1
	s_cbranch_scc1 .LBB0_210
	s_and_saveexec_b64 s[70:71], s[72:73]
	s_cbranch_execz .LBB0_205
	s_branch .LBB0_213
.LBB0_210:
	v_mov_b64_e32 v[18:19], s[0:1]
	global_load_dword v17, v[18:19], off sc1
	s_mov_b64 s[72:73], 0
	s_waitcnt vmcnt(0) lgkmcnt(0)
	v_cmp_eq_u32_e32 vcc, 0, v17
	s_and_saveexec_b64 s[70:71], vcc
	s_cmp_lt_u32 s85, 0x400001
	s_cselect_b64 s[72:73], -1, 0
	s_xor_b64 s[40:41], exec, -1
	s_and_b64 s[72:73], s[72:73], exec
	s_or_b64 exec, exec, s[70:71]
	v_readlane_b32 s92, v255, 41
	v_readlane_b32 s93, v255, 42
	s_and_saveexec_b64 s[70:71], s[72:73]
	s_cbranch_execz .LBB0_205

; __device__ __forceinline__ unsigned xb_ld(unsigned* p)              { return __hip_atomic_load(p, __ATOMIC_RELAXED, __HIP_MEMORY_SCOPE_AGENT); }
; __device__ __forceinline__ unsigned xb_add(unsigned* p, unsigned v) { return __hip_atomic_fetch_add(p, v, __ATOMIC_RELAXED, __HIP_MEMORY_SCOPE_AGENT); }
; #define XB_SPIN(cond, bar) do { unsigned _sp = 0; while (cond) {     \
;     if ((++_sp & 255u) == 0u) { if (xb_ld(&(bar)[XB_TMO])) break; if (_sp > XB_SPIN_CAP) { atomicAdd(&(bar)[XB_TMO], 1u); break; } } } } while (0)
; __device__ __forceinline__ void xcd_barrier(const XcdBarrier& b, int wave_s) {
;     ...
;         const unsigned old = xb_add(&bar[XB_XSUB(b.x)], 1u);
;         const unsigned gen = old / nloc;
;         if (old + 1u == (gen + 1u) * nloc) {
;             __builtin_amdgcn_fence(__ATOMIC_RELEASE, "agent");
;             asm volatile("s_waitcnt vmcnt(0)" ::: "memory");
;             const unsigned og = xb_add(&bar[XB_TOP], 1u);
;             const unsigned tg = og / nx;
;             if (og + 1u == (tg + 1u) * nx) xb_add(&bar[XB_TOPGEN], 1u);
;             else XB_SPIN(xb_ld(&bar[XB_TOPGEN]) == tg, bar);
;             __builtin_amdgcn_fence(__ATOMIC_ACQUIRE, "agent");
;             xb_add(&bar[XB_XGEN(b.x)], 1u);
;             asm volatile("s_waitcnt vmcnt(0)" ::: "memory");
;         } else {
;             XB_SPIN(xb_ld(&bar[XB_XGEN(b.x)]) == gen, bar);
.LBB0_217:
	s_lshl_b32 s0, s37, 8
	s_add_u32 s0, s38, s0
	s_addc_u32 s1, s39, 0
	v_mov_b32_e32 v3, s0
	v_add_co_u32_e32 v4, vcc, 0x11000, v3
	v_mov_b32_e32 v3, s1
	s_nop 0
	v_addc_co_u32_e32 v5, vcc, 0, v3, vcc
	flat_atomic_add v4, v[4:5], v220 offset:1024 sc0
	v_cvt_f32_u32_e32 v3, v2
	v_sub_u32_e32 v5, 0, v2
	s_add_u32 s25, s0, 0x10000
	s_addc_u32 s24, s1, 0
	v_rcp_iflag_f32_e32 v3, v3
	s_nop 0
	v_mul_f32_e32 v3, 0x4f7ffffe, v3
	v_cvt_u32_f32_e32 v3, v3
	v_mul_lo_u32 v5, v5, v3
	v_mul_hi_u32 v5, v3, v5
	v_add_u32_e32 v3, v3, v5
	s_waitcnt vmcnt(0) lgkmcnt(0)
	v_mul_hi_u32 v3, v4, v3
	v_mul_lo_u32 v5, v3, v2
	v_sub_u32_e32 v5, v4, v5
	v_cmp_ge_u32_e32 vcc, v5, v2
	v_add_u32_e32 v6, 1, v3
	s_nop 0
	v_cndmask_b32_e32 v3, v3, v6, vcc
	v_sub_u32_e32 v6, v5, v2
	v_cndmask_b32_e32 v5, v5, v6, vcc
	v_cmp_ge_u32_e32 vcc, v5, v2
	v_add_u32_e32 v5, 1, v3
	v_add_u32_e32 v6, 1, v4
	v_cndmask_b32_e32 v3, v3, v5, vcc
	v_mad_u64_u32 v[4:5], s[0:1], v2, v3, v[2:3]
	v_cmp_ne_u32_e32 vcc, v6, v4
	s_and_saveexec_b64 s[0:1], vcc
	s_xor_b64 s[0:1], exec, s[0:1]
	s_cbranch_execz .LBB0_230
	v_mov_b32_e32 v0, s25
	v_add_co_u32_e32 v4, vcc, 0x2000, v0
	v_mov_b32_e32 v0, s24
	s_nop 0
	v_addc_co_u32_e32 v5, vcc, 0, v0, vcc
	global_load_dword v0, v[4:5], off offset:1024 sc1
	s_add_u32 s6, s25, 0x2400
	s_addc_u32 s7, s24, 0
	s_waitcnt vmcnt(0) lgkmcnt(0)
	v_cmp_eq_u32_e32 vcc, v0, v3
	s_and_saveexec_b64 s[4:5], vcc
	s_cbranch_execz .LBB0_229
	s_add_u32 s8, s38, 0x10200
	s_addc_u32 s9, s39, 0
	s_mov_b32 s26, 1
	s_mov_b64 s[10:11], 0
	s_branch .LBB0_221

; __device__ __forceinline__ unsigned xb_ld(unsigned* p)              { return __hip_atomic_load(p, __ATOMIC_RELAXED, __HIP_MEMORY_SCOPE_AGENT); }
; __device__ __forceinline__ unsigned xb_add(unsigned* p, unsigned v) { return __hip_atomic_fetch_add(p, v, __ATOMIC_RELAXED, __HIP_MEMORY_SCOPE_AGENT); }
; #define XB_SPIN(cond, bar) do { unsigned _sp = 0; while (cond) {     \
;     if ((++_sp & 255u) == 0u) { if (xb_ld(&(bar)[XB_TMO])) break; if (_sp > XB_SPIN_CAP) { atomicAdd(&(bar)[XB_TMO], 1u); break; } } } } while (0)
; __device__ __forceinline__ void xcd_barrier(const XcdBarrier& b, int wave_s) {
;     ...
;         if (old + 1u == (gen + 1u) * nloc) {
;             __builtin_amdgcn_fence(__ATOMIC_RELEASE, "agent");
;             asm volatile("s_waitcnt vmcnt(0)" ::: "memory");
;             const unsigned og = xb_add(&bar[XB_TOP], 1u);
;             const unsigned tg = og / nx;
;             if (og + 1u == (tg + 1u) * nx) xb_add(&bar[XB_TOPGEN], 1u);
;             else XB_SPIN(xb_ld(&bar[XB_TOPGEN]) == tg, bar);
.LBB0_230:
	s_andn2_saveexec_b64 s[0:1], s[0:1]
	s_cbranch_execz .LBB0_246
	v_mov_b32_e32 v2, s38
	v_add_co_u32_e32 v2, vcc, 0x13000, v2
	v_mov_b32_e32 v3, s39
	buffer_wbl2 sc1
	s_waitcnt vmcnt(0)
	v_addc_co_u32_e32 v3, vcc, 0, v3, vcc
	flat_atomic_add v2, v[2:3], v220 offset:1024 sc0
	v_cvt_f32_u32_e32 v3, v0
	v_sub_u32_e32 v4, 0, v0
	s_mov_b64 s[6:7], -1
	v_rcp_iflag_f32_e32 v3, v3
	s_nop 0
	v_mul_f32_e32 v3, 0x4f7ffffe, v3
	v_cvt_u32_f32_e32 v3, v3
	v_mul_lo_u32 v4, v4, v3
	v_mul_hi_u32 v4, v3, v4
	v_add_u32_e32 v3, v3, v4
	s_waitcnt vmcnt(0) lgkmcnt(0)
	v_mul_hi_u32 v3, v2, v3
	v_mul_lo_u32 v4, v3, v0
	v_sub_u32_e32 v4, v2, v4
	v_cmp_ge_u32_e32 vcc, v4, v0
	v_add_u32_e32 v5, 1, v3
	s_nop 0
	v_cndmask_b32_e32 v3, v3, v5, vcc
	v_sub_u32_e32 v5, v4, v0
	v_cndmask_b32_e32 v4, v4, v5, vcc
	v_cmp_ge_u32_e32 vcc, v4, v0
	v_add_u32_e32 v4, 1, v3
	v_add_u32_e32 v5, 1, v2
	v_cndmask_b32_e32 v4, v3, v4, vcc
	v_mad_u64_u32 v[2:3], s[0:1], v0, v4, v[0:1]
	s_add_u32 s0, s38, 0x13500
	s_addc_u32 s1, s39, 0
	v_cmp_ne_u32_e32 vcc, v5, v2
	v_mov_b64_e32 v[2:3], s[0:1]
	s_and_saveexec_b64 s[4:5], vcc
	s_cbranch_execz .LBB0_243
	v_mov_b64_e32 v[2:3], s[0:1]
	global_load_dword v0, v[2:3], off sc1
	s_mov_b64 s[10:11], 0
	s_waitcnt vmcnt(0) lgkmcnt(0)
	v_cmp_eq_u32_e32 vcc, v0, v4
	s_and_saveexec_b64 s[8:9], vcc
	s_cbranch_execz .LBB0_242
	s_add_u32 s6, s38, 0x10200
	s_addc_u32 s7, s39, 0
	s_mov_b32 s22, 1
	s_branch .LBB0_235

; __global__ void __launch_bounds__(NTHR, 2) mega_fwd(Args a) {
;     ...
;             const float* gq = SMV + SM_AQ + lq * 128; const float* gk = SMV + SM_AK + lq * 128;
;             const int p0i = perm128(2 * lane), p1i = perm128(2 * lane + 1);
;             const float gq0 = gq[p0i], gq1 = gq[p1i], gk0 = gk[p0i], gk1 = gk[p1i];
;             for (int t = gw; t < SEQ; t += NGW) {
.LBB0_246:
	s_or_b64 exec, exec, s[34:35]
	v_readlane_b32 s4, v254, 39
	v_readlane_b32 s5, v254, 40
	s_mov_b64 s[8:9], s[60:61]
	s_mov_b32 s0, s84
	s_andn2_b64 vcc, exec, s[4:5]
	s_waitcnt lgkmcnt(0)
	s_barrier
	s_cbranch_vccnz .LBB0_253
	s_lshl_b32 s0, s0, 7
	s_ashr_i32 s1, s0, 31
	s_lshl_b64 s[0:1], s[0:1], 2
	v_lshlrev_b32_e32 v0, 1, v144
	v_and_b32_e32 v16, 31, v144
	s_add_u32 s0, s8, s0
	v_and_or_b32 v0, v0, 64, v16
	s_addc_u32 s1, s9, s1
	v_lshlrev_b32_e32 v0, 2, v0
	v_lshl_add_u64 v[2:3], s[0:1], 0, v[0:1]
	s_mov_b64 s[0:1], 0x2a000
	v_lshl_add_u64 v[4:5], v[2:3], 0, s[0:1]
	s_mov_b32 s0, 0x2a000
	v_add_co_u32_e32 v6, vcc, s0, v2
	s_mov_b64 s[0:1], 0x2a400
	s_nop 0
	v_addc_co_u32_e32 v7, vcc, 0, v3, vcc
	global_load_dword v17, v[6:7], off
	global_load_dword v18, v[4:5], off offset:128
	v_lshl_add_u64 v[2:3], v[2:3], 0, s[0:1]
	global_load_dword v19, v[6:7], off offset:1024
	global_load_dword v20, v[2:3], off offset:128
	v_readlane_b32 s6, v255, 23
	v_lshlrev_b32_e32 v0, 2, v16
	v_readlane_b32 s7, v255, 24
	v_and_b32_e32 v8, 63, v144
	s_add_u32 s10, s8, 0x200000
	v_lshl_add_u64 v[2:3], s[6:7], 0, v[0:1]
	v_readlane_b32 s6, v255, 21
	v_lshlrev_b32_e32 v0, 2, v8
	v_readlane_b32 s7, v255, 22
	v_readlane_b32 s12, v255, 27
	v_cmp_gt_u32_e64 s[0:1], 32, v8
	v_lshl_add_u64 v[4:5], s[6:7], 0, v[0:1]
	v_readlane_b32 s6, v255, 33
	s_addc_u32 s11, s9, 0
	v_cmp_eq_u32_e64 s[4:5], 0, v8
	v_add_u32_e32 v6, s6, v16
	v_readlane_b32 s6, v254, 29
	v_readlane_b32 s13, v255, 28
	s_mov_b32 s16, s6
	v_readlane_b32 s7, v254, 30
	s_branch .LBB0_249

; __device__ __forceinline__ unsigned pk2(float lo, float hi) { return f2bf(lo) | (f2bf(hi) << 16); }
; __global__ void __launch_bounds__(NTHR, 2) mega_fwd(Args a) {
;     ...
;             for (int t = gw; t < SEQ; t += NGW) {
;                 bf16_t* row = P + (size_t)t * INP;
;                 unsigned w[12];
; #pragma unroll
;                 for (int hd = 0; hd < 6; ++hd) w[hd] = ((const unsigned*)(row + hd * 128))[lane];
;                 w[6] = ((const unsigned*)(row + C_BKR))[lane & 31];
; #pragma unroll
;                 for (int j = 0; j < 3; ++j) w[7 + j] = ((const unsigned*)(row + C_BCQ))[lane + 64 * j];
; #pragma unroll
;                 for (int j = 0; j < 2; ++j) w[10 + j] = ((const unsigned*)(row + C_BCKV))[lane + 64 * j];
;                 const int pos = lane < 32 ? (t >> 6) : (t & 63); const f32x2 cs = TAB[pos * 32 + (lane & 31)], c2 = TAB[t * 32 + (lane & 31)];
; #pragma unroll
;                 for (int hd = 0; hd < 6; ++hd) {
;                     float x0 = bf2f((unsigned short)(w[hd] & 0xffff)), x1 = bf2f((unsigned short)(w[hd] >> 16));
;                     const float rstd = 1.0f / sqrtf(wave_sum(x0 * x0 + x1 * x1) * (1.f / 128.f) + EPS);
;                     const float qs = hd < 4 ? SC_A : 1.f;
;                     x0 *= rstd * (hd < 4 ? gq0 : gk0) * qs; x1 *= rstd * (hd < 4 ? gq1 : gk1) * qs;
;                     ((unsigned*)(row + hd * 128))[lane] = pk2(x0 * cs.x - x1 * cs.y, x1 * cs.x + x0 * cs.y); }
.LBB0_249:
	v_lshl_add_u64 v[8:9], s[8:9], 0, v[4:5]
	v_add_co_u32_e32 v10, vcc, 0x12000000, v8
	v_lshl_add_u64 v[12:13], s[8:9], 0, v[2:3]
	s_nop 0
	v_addc_co_u32_e32 v11, vcc, 0, v9, vcc
	global_load_dword v30, v[10:11], off
	global_load_dword v31, v[10:11], off offset:256
	global_load_dword v29, v[10:11], off offset:512
	global_load_dword v28, v[10:11], off offset:768
	global_load_dword v27, v[10:11], off offset:1024
	global_load_dword v26, v[10:11], off offset:1280
	s_ashr_i32 s6, s16, 6
	s_and_b32 s7, s16, 63
	global_load_dword v25, v[12:13], off
	global_load_dword v24, v[10:11], off offset:2048
	global_load_dword v23, v[10:11], off offset:2304
	global_load_dword v22, v[10:11], off offset:2560
	global_load_dword v21, v[10:11], off offset:2816
	global_load_dword v0, v[10:11], off offset:3072
	v_mov_b32_e32 v7, s7
	v_mov_b32_e32 v12, s6
	v_cndmask_b32_e64 v7, v7, v12, s[0:1]
	v_lshl_or_b32 v12, v7, 5, v16
	v_ashrrev_i32_e32 v13, 31, v12
	v_lshl_add_u64 v[12:13], v[12:13], 3, s[10:11]
	global_load_dwordx2 v[12:13], v[12:13], off
	v_ashrrev_i32_e32 v7, 31, v6
	v_lshl_add_u64 v[14:15], v[6:7], 3, s[10:11]
	global_load_dwordx2 v[14:15], v[14:15], off
	s_waitcnt vmcnt(0) lgkmcnt(0)
	v_lshlrev_b32_e32 v7, 16, v30
	v_and_b32_e32 v30, 0xffff0000, v30
	v_mul_f32_e32 v32, v30, v30
	v_fmac_f32_e32 v32, v7, v7
	ds_swizzle_b32 v33, v32 offset:swizzle(SWAP,1)
	s_waitcnt lgkmcnt(0)
	v_add_f32_e32 v32, v32, v33
	ds_swizzle_b32 v33, v32 offset:swizzle(SWAP,2)
	s_waitcnt lgkmcnt(0)
	v_add_f32_e32 v32, v32, v33
	ds_swizzle_b32 v33, v32 offset:swizzle(SWAP,4)
	s_waitcnt lgkmcnt(0)
	v_add_f32_e32 v32, v32, v33
	ds_swizzle_b32 v33, v32 offset:swizzle(SWAP,8)
	s_waitcnt lgkmcnt(0)
	v_add_f32_e32 v32, v32, v33
	ds_swizzle_b32 v33, v32 offset:swizzle(SWAP,16)
	s_waitcnt lgkmcnt(0)
	v_add_f32_e32 v32, v32, v33
	v_mov_b32_e32 v33, v32
	s_nop 1
	v_permlane32_swap_b32_e32 v32, v33
	v_add_f32_e32 v32, v32, v33
	v_fmamk_f32 v32, v32, 0x3c000000, v218
	v_cmp_gt_f32_e32 vcc, s68, v32
	v_mul_f32_e32 v33, 0x4f800000, v32
	s_nop 0
	v_cndmask_b32_e32 v32, v32, v33, vcc
	v_sqrt_f32_e32 v33, v32
	s_nop 0
	v_add_u32_e32 v34, -1, v33
	v_fma_f32 v35, -v34, v33, v32
	v_cmp_ge_f32_e64 s[6:7], 0, v35
	v_add_u32_e32 v35, 1, v33
	s_nop 0
	v_cndmask_b32_e64 v34, v33, v34, s[6:7]
	v_fma_f32 v33, -v35, v33, v32
	v_cmp_lt_f32_e64 s[6:7], 0, v33
	s_nop 1
	v_cndmask_b32_e64 v33, v34, v35, s[6:7]
	v_mul_f32_e32 v34, 0x37800000, v33
	v_cndmask_b32_e32 v33, v33, v34, vcc
	v_cmp_class_f32_e32 vcc, v32, v219
	s_nop 1
	v_cndmask_b32_e32 v32, v33, v32, vcc
	v_div_scale_f32 v33, s[6:7], v32, v32, 1.0
	v_rcp_f32_e32 v34, v33
	s_nop 0
	v_fma_f32 v35, -v33, v34, 1.0
	v_fmac_f32_e32 v34, v35, v34
	v_div_scale_f32 v35, vcc, 1.0, v32, 1.0
	v_mul_f32_e32 v36, v35, v34
	v_fma_f32 v37, -v33, v36, v35
	v_fmac_f32_e32 v36, v37, v34
	v_fma_f32 v33, -v33, v36, v35
	v_div_fmas_f32 v33, v33, v34, v36
	v_div_fixup_f32 v32, v33, v32, 1.0
	v_mul_f32_e32 v33, v17, v32
	v_mul_f32_e32 v32, v18, v32
	v_mul_f32_e32 v32, 0x3e0293ee, v32
	v_mul_f32_e32 v33, 0x3e0293ee, v33
	v_mul_f32_e32 v30, v32, v30
	v_mul_f32_e32 v7, v33, v7
	v_mul_f32_e32 v32, v13, v30
	v_fma_f32 v32, v12, v7, -v32
	v_mul_f32_e32 v7, v13, v7
	v_fmac_f32_e32 v7, v12, v30
	v_bfe_u32 v30, v32, 16, 1
	v_add3_u32 v30, v32, v30, s33
	v_bfe_u32 v32, v7, 16, 1
	v_lshrrev_b32_e32 v30, 16, v30
	v_add3_u32 v7, v7, v32, s33
	v_and_or_b32 v7, v7, s48, v30
	v_and_b32_e32 v30, 0xffff0000, v31
	global_store_dword v[10:11], v7, off
	v_lshlrev_b32_e32 v7, 16, v31
	v_mul_f32_e32 v31, v30, v30
	v_fmac_f32_e32 v31, v7, v7
	ds_swizzle_b32 v32, v31 offset:swizzle(SWAP,1)
	s_waitcnt lgkmcnt(0)
	v_add_f32_e32 v31, v31, v32
	ds_swizzle_b32 v32, v31 offset:swizzle(SWAP,2)
	s_waitcnt lgkmcnt(0)
	v_add_f32_e32 v31, v31, v32
	ds_swizzle_b32 v32, v31 offset:swizzle(SWAP,4)
	s_waitcnt lgkmcnt(0)
	v_add_f32_e32 v31, v31, v32
	ds_swizzle_b32 v32, v31 offset:swizzle(SWAP,8)
	s_waitcnt lgkmcnt(0)
	v_add_f32_e32 v31, v31, v32
	ds_swizzle_b32 v32, v31 offset:swizzle(SWAP,16)
	s_waitcnt lgkmcnt(0)
	v_add_f32_e32 v31, v31, v32
	v_mov_b32_e32 v32, v31
	s_nop 1
	v_permlane32_swap_b32_e32 v31, v32
	v_add_f32_e32 v31, v31, v32
	v_fmamk_f32 v31, v31, 0x3c000000, v218
	v_cmp_gt_f32_e32 vcc, s68, v31
	v_mul_f32_e32 v32, 0x4f800000, v31
	s_nop 0
	v_cndmask_b32_e32 v31, v31, v32, vcc
	v_sqrt_f32_e32 v32, v31
	s_nop 0
	v_add_u32_e32 v33, -1, v32
	v_fma_f32 v34, -v33, v32, v31
	v_cmp_ge_f32_e64 s[6:7], 0, v34
	v_add_u32_e32 v34, 1, v32
	s_nop 0
	v_cndmask_b32_e64 v33, v32, v33, s[6:7]
	v_fma_f32 v32, -v34, v32, v31
	v_cmp_lt_f32_e64 s[6:7], 0, v32
	s_nop 1
	v_cndmask_b32_e64 v32, v33, v34, s[6:7]
	v_mul_f32_e32 v33, 0x37800000, v32
	v_cndmask_b32_e32 v32, v32, v33, vcc
	v_cmp_class_f32_e32 vcc, v31, v219
	s_nop 1
	v_cndmask_b32_e32 v31, v32, v31, vcc
	v_div_scale_f32 v32, s[6:7], v31, v31, 1.0
	v_rcp_f32_e32 v33, v32
	s_nop 0
	v_fma_f32 v34, -v32, v33, 1.0
	v_fmac_f32_e32 v33, v34, v33
	v_div_scale_f32 v34, vcc, 1.0, v31, 1.0
	v_mul_f32_e32 v35, v34, v33
	v_fma_f32 v36, -v32, v35, v34
	v_fmac_f32_e32 v35, v36, v33
	v_fma_f32 v32, -v32, v35, v34
	v_div_fmas_f32 v32, v32, v33, v35
	v_div_fixup_f32 v31, v32, v31, 1.0
	v_mul_f32_e32 v32, v17, v31
	v_mul_f32_e32 v31, v18, v31
	v_mul_f32_e32 v31, 0x3e0293ee, v31
	v_mul_f32_e32 v32, 0x3e0293ee, v32
	v_mul_f32_e32 v30, v31, v30
	v_mul_f32_e32 v7, v32, v7
	v_mul_f32_e32 v31, v13, v30
	v_fma_f32 v31, v12, v7, -v31
	v_mul_f32_e32 v7, v13, v7
	v_fmac_f32_e32 v7, v12, v30
	v_bfe_u32 v30, v31, 16, 1
	v_add3_u32 v30, v31, v30, s33
	v_bfe_u32 v31, v7, 16, 1
	v_lshrrev_b32_e32 v30, 16, v30
	v_add3_u32 v7, v7, v31, s33
	v_and_or_b32 v7, v7, s48, v30
	global_store_dword v[10:11], v7, off offset:256
	v_and_b32_e32 v7, 0xffff0000, v29
	v_lshlrev_b32_e32 v30, 16, v29
	v_mul_f32_e32 v29, v7, v7
	v_fmac_f32_e32 v29, v30, v30
	ds_swizzle_b32 v31, v29 offset:swizzle(SWAP,1)
	s_waitcnt lgkmcnt(0)
; __device__ __forceinline__ unsigned pk2(float lo, float hi) { return f2bf(lo) | (f2bf(hi) << 16); }
; __global__ void __launch_bounds__(NTHR, 2) mega_fwd(Args a) {
;     ...
;                 for (int hd = 0; hd < 6; ++hd) {
;                     float x0 = bf2f((unsigned short)(w[hd] & 0xffff)), x1 = bf2f((unsigned short)(w[hd] >> 16));
;                     const float rstd = 1.0f / sqrtf(wave_sum(x0 * x0 + x1 * x1) * (1.f / 128.f) + EPS);
;                     const float qs = hd < 4 ? SC_A : 1.f;
;                     x0 *= rstd * (hd < 4 ? gq0 : gk0) * qs; x1 *= rstd * (hd < 4 ? gq1 : gk1) * qs;
;                     ((unsigned*)(row + hd * 128))[lane] = pk2(x0 * cs.x - x1 * cs.y, x1 * cs.x + x0 * cs.y); }
	v_add_f32_e32 v29, v29, v31
	ds_swizzle_b32 v31, v29 offset:swizzle(SWAP,2)
	s_waitcnt lgkmcnt(0)
	v_add_f32_e32 v29, v29, v31
	ds_swizzle_b32 v31, v29 offset:swizzle(SWAP,4)
	s_waitcnt lgkmcnt(0)
	v_add_f32_e32 v29, v29, v31
	ds_swizzle_b32 v31, v29 offset:swizzle(SWAP,8)
	s_waitcnt lgkmcnt(0)
	v_add_f32_e32 v29, v29, v31
	ds_swizzle_b32 v31, v29 offset:swizzle(SWAP,16)
	s_waitcnt lgkmcnt(0)
	v_add_f32_e32 v29, v29, v31
	v_mov_b32_e32 v31, v29
	s_nop 1
	v_permlane32_swap_b32_e32 v29, v31
	v_add_f32_e32 v29, v29, v31
	v_fmamk_f32 v29, v29, 0x3c000000, v218
	v_cmp_gt_f32_e32 vcc, s68, v29
	v_mul_f32_e32 v31, 0x4f800000, v29
	s_nop 0
	v_cndmask_b32_e32 v29, v29, v31, vcc
	v_sqrt_f32_e32 v31, v29
	s_nop 0
	v_add_u32_e32 v32, -1, v31
	v_fma_f32 v33, -v32, v31, v29
	v_cmp_ge_f32_e64 s[6:7], 0, v33
	v_add_u32_e32 v33, 1, v31
	s_nop 0
	v_cndmask_b32_e64 v32, v31, v32, s[6:7]
	v_fma_f32 v31, -v33, v31, v29
	v_cmp_lt_f32_e64 s[6:7], 0, v31
	s_nop 1
	v_cndmask_b32_e64 v31, v32, v33, s[6:7]
	v_mul_f32_e32 v32, 0x37800000, v31
	v_cndmask_b32_e32 v31, v31, v32, vcc
	v_cmp_class_f32_e32 vcc, v29, v219
	s_nop 1
	v_cndmask_b32_e32 v29, v31, v29, vcc
	v_div_scale_f32 v31, s[6:7], v29, v29, 1.0
	v_rcp_f32_e32 v32, v31
	s_nop 0
	v_fma_f32 v33, -v31, v32, 1.0
	v_fmac_f32_e32 v32, v33, v32
	v_div_scale_f32 v33, vcc, 1.0, v29, 1.0
	v_mul_f32_e32 v34, v33, v32
	v_fma_f32 v35, -v31, v34, v33
	v_fmac_f32_e32 v34, v35, v32
	v_fma_f32 v31, -v31, v34, v33
	v_div_fmas_f32 v31, v31, v32, v34
	v_div_fixup_f32 v29, v31, v29, 1.0
	v_mul_f32_e32 v31, v17, v29
	v_mul_f32_e32 v29, v18, v29
	v_mul_f32_e32 v29, 0x3e0293ee, v29
	v_mul_f32_e32 v31, 0x3e0293ee, v31
	v_mul_f32_e32 v7, v29, v7
	v_mul_f32_e32 v30, v31, v30
	v_mul_f32_e32 v29, v13, v7
	v_fma_f32 v29, v12, v30, -v29
	v_mul_f32_e32 v30, v13, v30
	v_fmac_f32_e32 v30, v12, v7
	v_bfe_u32 v7, v29, 16, 1
	v_add3_u32 v7, v29, v7, s33
	v_bfe_u32 v29, v30, 16, 1
	v_lshrrev_b32_e32 v7, 16, v7
	v_add3_u32 v29, v30, v29, s33
	v_and_or_b32 v7, v29, s48, v7
	global_store_dword v[10:11], v7, off offset:512
	v_lshlrev_b32_e32 v7, 16, v28
	v_and_b32_e32 v28, 0xffff0000, v28
	v_mul_f32_e32 v29, v28, v28
	v_fmac_f32_e32 v29, v7, v7
	ds_swizzle_b32 v30, v29 offset:swizzle(SWAP,1)
	s_waitcnt lgkmcnt(0)
	v_add_f32_e32 v29, v29, v30
	ds_swizzle_b32 v30, v29 offset:swizzle(SWAP,2)
	s_waitcnt lgkmcnt(0)
	v_add_f32_e32 v29, v29, v30
	ds_swizzle_b32 v30, v29 offset:swizzle(SWAP,4)
	s_waitcnt lgkmcnt(0)
	v_add_f32_e32 v29, v29, v30
	ds_swizzle_b32 v30, v29 offset:swizzle(SWAP,8)
	s_waitcnt lgkmcnt(0)
	v_add_f32_e32 v29, v29, v30
	ds_swizzle_b32 v30, v29 offset:swizzle(SWAP,16)
	s_waitcnt lgkmcnt(0)
	v_add_f32_e32 v29, v29, v30
	v_mov_b32_e32 v30, v29
	s_nop 1
	v_permlane32_swap_b32_e32 v29, v30
	v_add_f32_e32 v29, v29, v30
	v_fmamk_f32 v29, v29, 0x3c000000, v218
	v_cmp_gt_f32_e32 vcc, s68, v29
	v_mul_f32_e32 v30, 0x4f800000, v29
	s_nop 0
	v_cndmask_b32_e32 v29, v29, v30, vcc
	v_sqrt_f32_e32 v30, v29
	s_nop 0
	v_add_u32_e32 v31, -1, v30
	v_fma_f32 v32, -v31, v30, v29
	v_cmp_ge_f32_e64 s[6:7], 0, v32
	v_add_u32_e32 v32, 1, v30
	s_nop 0
	v_cndmask_b32_e64 v31, v30, v31, s[6:7]
	v_fma_f32 v30, -v32, v30, v29
	v_cmp_lt_f32_e64 s[6:7], 0, v30
	s_nop 1
	v_cndmask_b32_e64 v30, v31, v32, s[6:7]
	v_mul_f32_e32 v31, 0x37800000, v30
	v_cndmask_b32_e32 v30, v30, v31, vcc
	v_cmp_class_f32_e32 vcc, v29, v219
	s_nop 1
	v_cndmask_b32_e32 v29, v30, v29, vcc
	v_div_scale_f32 v30, s[6:7], v29, v29, 1.0
	v_rcp_f32_e32 v31, v30
	s_nop 0
	v_fma_f32 v32, -v30, v31, 1.0
	v_fmac_f32_e32 v31, v32, v31
	v_div_scale_f32 v32, vcc, 1.0, v29, 1.0
	v_mul_f32_e32 v33, v32, v31
	v_fma_f32 v34, -v30, v33, v32
	v_fmac_f32_e32 v33, v34, v31
	v_fma_f32 v30, -v30, v33, v32
	v_div_fmas_f32 v30, v30, v31, v33
	v_div_fixup_f32 v29, v30, v29, 1.0
	v_mul_f32_e32 v30, v17, v29
	v_mul_f32_e32 v29, v18, v29
	v_mul_f32_e32 v29, 0x3e0293ee, v29
	v_mul_f32_e32 v30, 0x3e0293ee, v30
	v_mul_f32_e32 v28, v29, v28
	v_mul_f32_e32 v7, v30, v7
	v_mul_f32_e32 v29, v13, v28
	v_fma_f32 v29, v12, v7, -v29
	v_mul_f32_e32 v7, v13, v7
	v_fmac_f32_e32 v7, v12, v28
	v_bfe_u32 v28, v29, 16, 1
	v_add3_u32 v28, v29, v28, s33
	v_bfe_u32 v29, v7, 16, 1
	v_lshrrev_b32_e32 v28, 16, v28
	v_add3_u32 v7, v7, v29, s33
	v_and_or_b32 v7, v7, s48, v28
	global_store_dword v[10:11], v7, off offset:768
	v_lshlrev_b32_e32 v7, 16, v27
	v_and_b32_e32 v27, 0xffff0000, v27
	v_mul_f32_e32 v28, v27, v27
	v_fmac_f32_e32 v28, v7, v7
	ds_swizzle_b32 v29, v28 offset:swizzle(SWAP,1)
	s_waitcnt lgkmcnt(0)
	v_add_f32_e32 v28, v28, v29
	ds_swizzle_b32 v29, v28 offset:swizzle(SWAP,2)
	s_waitcnt lgkmcnt(0)
	v_add_f32_e32 v28, v28, v29
	ds_swizzle_b32 v29, v28 offset:swizzle(SWAP,4)
	s_waitcnt lgkmcnt(0)
	v_add_f32_e32 v28, v28, v29
	ds_swizzle_b32 v29, v28 offset:swizzle(SWAP,8)
	s_waitcnt lgkmcnt(0)
	v_add_f32_e32 v28, v28, v29
	ds_swizzle_b32 v29, v28 offset:swizzle(SWAP,16)
	s_waitcnt lgkmcnt(0)
; __device__ __forceinline__ unsigned pk2(float lo, float hi) { return f2bf(lo) | (f2bf(hi) << 16); }
; __global__ void __launch_bounds__(NTHR, 2) mega_fwd(Args a) {
;     ...
;                 for (int hd = 0; hd < 6; ++hd) {
;                     float x0 = bf2f((unsigned short)(w[hd] & 0xffff)), x1 = bf2f((unsigned short)(w[hd] >> 16));
;                     const float rstd = 1.0f / sqrtf(wave_sum(x0 * x0 + x1 * x1) * (1.f / 128.f) + EPS);
;                     const float qs = hd < 4 ? SC_A : 1.f;
;                     x0 *= rstd * (hd < 4 ? gq0 : gk0) * qs; x1 *= rstd * (hd < 4 ? gq1 : gk1) * qs;
;                     ((unsigned*)(row + hd * 128))[lane] = pk2(x0 * cs.x - x1 * cs.y, x1 * cs.x + x0 * cs.y); }
;                 if (lane < 32) { const float x0 = bf2f((unsigned short)(w[6] & 0xffff)), x1 = bf2f((unsigned short)(w[6] >> 16));
;                     ((unsigned*)(row + C_BKR))[lane] = pk2(x0 * c2.x - x1 * c2.y, x1 * c2.x + x0 * c2.y); }
	v_add_f32_e32 v28, v28, v29
	v_mov_b32_e32 v29, v28
	s_nop 1
	v_permlane32_swap_b32_e32 v28, v29
	v_add_f32_e32 v28, v28, v29
	v_fmamk_f32 v28, v28, 0x3c000000, v218
	v_cmp_gt_f32_e32 vcc, s68, v28
	v_mul_f32_e32 v29, 0x4f800000, v28
	s_nop 0
	v_cndmask_b32_e32 v28, v28, v29, vcc
	v_sqrt_f32_e32 v29, v28
	s_nop 0
	v_add_u32_e32 v30, -1, v29
	v_fma_f32 v31, -v30, v29, v28
	v_cmp_ge_f32_e64 s[6:7], 0, v31
	v_add_u32_e32 v31, 1, v29
	s_nop 0
	v_cndmask_b32_e64 v30, v29, v30, s[6:7]
	v_fma_f32 v29, -v31, v29, v28
	v_cmp_lt_f32_e64 s[6:7], 0, v29
	s_nop 1
	v_cndmask_b32_e64 v29, v30, v31, s[6:7]
	v_mul_f32_e32 v30, 0x37800000, v29
	v_cndmask_b32_e32 v29, v29, v30, vcc
	v_cmp_class_f32_e32 vcc, v28, v219
	s_nop 1
	v_cndmask_b32_e32 v28, v29, v28, vcc
	v_div_scale_f32 v29, s[6:7], v28, v28, 1.0
	v_rcp_f32_e32 v30, v29
	s_nop 0
	v_fma_f32 v31, -v29, v30, 1.0
	v_fmac_f32_e32 v30, v31, v30
	v_div_scale_f32 v31, vcc, 1.0, v28, 1.0
	v_mul_f32_e32 v32, v31, v30
	v_fma_f32 v33, -v29, v32, v31
	v_fmac_f32_e32 v32, v33, v30
	v_fma_f32 v29, -v29, v32, v31
	v_div_fmas_f32 v29, v29, v30, v32
	v_div_fixup_f32 v28, v29, v28, 1.0
	v_mul_f32_e32 v29, v19, v28
	v_mul_f32_e32 v28, v20, v28
	v_mul_f32_e32 v27, v28, v27
	v_mul_f32_e32 v7, v29, v7
	v_mul_f32_e32 v28, v13, v27
	v_fma_f32 v28, v12, v7, -v28
	v_mul_f32_e32 v7, v13, v7
	v_fmac_f32_e32 v7, v12, v27
	v_bfe_u32 v27, v28, 16, 1
	v_add3_u32 v27, v28, v27, s33
	v_bfe_u32 v28, v7, 16, 1
	v_lshrrev_b32_e32 v27, 16, v27
	v_add3_u32 v7, v7, v28, s33
	v_and_or_b32 v7, v7, s48, v27
	global_store_dword v[10:11], v7, off offset:1024
	v_lshlrev_b32_e32 v7, 16, v26
	v_and_b32_e32 v26, 0xffff0000, v26
	v_mul_f32_e32 v27, v26, v26
	v_fmac_f32_e32 v27, v7, v7
	ds_swizzle_b32 v28, v27 offset:swizzle(SWAP,1)
	s_waitcnt lgkmcnt(0)
	v_add_f32_e32 v27, v27, v28
	ds_swizzle_b32 v28, v27 offset:swizzle(SWAP,2)
	s_waitcnt lgkmcnt(0)
	v_add_f32_e32 v27, v27, v28
	ds_swizzle_b32 v28, v27 offset:swizzle(SWAP,4)
	s_waitcnt lgkmcnt(0)
	v_add_f32_e32 v27, v27, v28
	ds_swizzle_b32 v28, v27 offset:swizzle(SWAP,8)
	s_waitcnt lgkmcnt(0)
	v_add_f32_e32 v27, v27, v28
	ds_swizzle_b32 v28, v27 offset:swizzle(SWAP,16)
	s_waitcnt lgkmcnt(0)
	v_add_f32_e32 v27, v27, v28
	v_mov_b32_e32 v28, v27
	s_nop 1
	v_permlane32_swap_b32_e32 v27, v28
	v_add_f32_e32 v27, v27, v28
	v_fmamk_f32 v27, v27, 0x3c000000, v218
	v_cmp_gt_f32_e32 vcc, s68, v27
	v_mul_f32_e32 v28, 0x4f800000, v27
	s_nop 0
	v_cndmask_b32_e32 v27, v27, v28, vcc
	v_sqrt_f32_e32 v28, v27
	s_nop 0
	v_add_u32_e32 v29, -1, v28
	v_fma_f32 v30, -v29, v28, v27
	v_cmp_ge_f32_e64 s[6:7], 0, v30
	v_add_u32_e32 v30, 1, v28
	s_nop 0
	v_cndmask_b32_e64 v29, v28, v29, s[6:7]
	v_fma_f32 v28, -v30, v28, v27
	v_cmp_lt_f32_e64 s[6:7], 0, v28
	s_nop 1
	v_cndmask_b32_e64 v28, v29, v30, s[6:7]
	v_mul_f32_e32 v29, 0x37800000, v28
	v_cndmask_b32_e32 v28, v28, v29, vcc
	v_cmp_class_f32_e32 vcc, v27, v219
	s_nop 1
	v_cndmask_b32_e32 v27, v28, v27, vcc
	v_div_scale_f32 v28, s[6:7], v27, v27, 1.0
	v_rcp_f32_e32 v29, v28
	s_nop 0
	v_fma_f32 v30, -v28, v29, 1.0
	v_fmac_f32_e32 v29, v30, v29
	v_div_scale_f32 v30, vcc, 1.0, v27, 1.0
	v_mul_f32_e32 v31, v30, v29
	v_fma_f32 v32, -v28, v31, v30
	v_fmac_f32_e32 v31, v32, v29
	v_fma_f32 v28, -v28, v31, v30
	v_div_fmas_f32 v28, v28, v29, v31
	v_div_fixup_f32 v27, v28, v27, 1.0
	v_mul_f32_e32 v28, v19, v27
	v_mul_f32_e32 v27, v20, v27
	v_mul_f32_e32 v26, v27, v26
	v_mul_f32_e32 v7, v28, v7
	v_mul_f32_e32 v27, v13, v26
	v_fma_f32 v27, v12, v7, -v27
	v_mul_f32_e32 v7, v13, v7
	v_fmac_f32_e32 v7, v12, v26
	v_bfe_u32 v12, v27, 16, 1
	v_add3_u32 v12, v27, v12, s33
	v_bfe_u32 v13, v7, 16, 1
	v_lshrrev_b32_e32 v12, 16, v12
	v_add3_u32 v7, v7, v13, s33
	v_and_or_b32 v7, v7, s48, v12
	global_store_dword v[10:11], v7, off offset:1280
	s_and_saveexec_b64 s[6:7], s[0:1]
	s_cbranch_execz .LBB0_251
	v_and_b32_e32 v12, 0xffff0000, v25
	v_lshlrev_b32_e32 v10, 16, v25
	v_pk_mul_f32 v[12:13], v[14:15], v[12:13] op_sel_hi:[1,0]
	v_add_co_u32_e32 v8, vcc, 0x12000000, v8
	v_pk_fma_f32 v[26:27], v[14:15], v[10:11], v[12:13] op_sel:[1,0,0] op_sel_hi:[0,1,1]
	v_pk_fma_f32 v[10:11], v[14:15], v[10:11], v[12:13] op_sel:[1,0,0] op_sel_hi:[0,0,1] neg_lo:[0,0,1] neg_hi:[0,0,1]
	v_and_b32_sdwa v7, v11, v220 dst_sel:DWORD dst_unused:UNUSED_PAD src0_sel:WORD_1 src1_sel:DWORD
	v_and_b32_sdwa v10, v26, v220 dst_sel:DWORD dst_unused:UNUSED_PAD src0_sel:WORD_1 src1_sel:DWORD
	v_add3_u32 v7, v11, v7, s33
	v_add3_u32 v10, v26, v10, s33
	v_lshrrev_b32_e32 v7, 16, v7
	v_and_or_b32 v7, v10, s48, v7
	v_addc_co_u32_e32 v9, vcc, 0, v9, vcc
	global_store_dword v[8:9], v7, off offset:3328
; __global__ void __launch_bounds__(NTHR, 2) mega_fwd(Args a) {
;     ...
;                 float sq = 0.f, skv = 0.f;
; #pragma unroll
;                 for (int j = 0; j < 3; ++j) { const float x0 = bf2f((unsigned short)(w[7 + j] & 0xffff)), x1 = bf2f((unsigned short)(w[7 + j] >> 16)); sq += x0 * x0 + x1 * x1; }
; #pragma unroll
;                 for (int j = 0; j < 2; ++j) { const float x0 = bf2f((unsigned short)(w[10 + j] & 0xffff)), x1 = bf2f((unsigned short)(w[10 + j] >> 16)); skv += x0 * x0 + x1 * x1; }
;                 sq = wave_sum(sq); skv = wave_sum(skv);
;                 if (lane == 0) { RS[t] = 1.0f / sqrtf(sq * (1.f / 384.f) + EPS); RS[SEQ + t] = 1.0f / sqrtf(skv * (1.f / 256.f) + EPS); }
.LBB0_251:
	s_or_b64 exec, exec, s[6:7]
	v_and_b32_e32 v10, 0xffff0000, v23
	v_lshlrev_b32_e32 v9, 16, v23
	v_mul_f32_e32 v10, v10, v10
	v_and_b32_e32 v11, 0xffff0000, v22
	v_fmac_f32_e32 v10, v9, v9
	v_lshlrev_b32_e32 v9, 16, v22
	v_mul_f32_e32 v11, v11, v11
	v_and_b32_e32 v12, 0xffff0000, v21
	v_and_b32_e32 v8, 0xffff0000, v24
	v_fmac_f32_e32 v11, v9, v9
	v_lshlrev_b32_e32 v9, 16, v21
	v_mul_f32_e32 v12, v12, v12
	v_lshlrev_b32_e32 v7, 16, v24
	v_mul_f32_e32 v8, v8, v8
	v_fmac_f32_e32 v12, v9, v9
	v_lshlrev_b32_e32 v9, 16, v0
	v_and_b32_e32 v0, 0xffff0000, v0
	v_fmac_f32_e32 v8, v7, v7
	v_mul_f32_e32 v0, v0, v0
	v_add_f32_e32 v7, v8, v10
	v_fmac_f32_e32 v0, v9, v9
	v_add_f32_e32 v7, v7, v11
	v_add_f32_e32 v0, v12, v0
	ds_swizzle_b32 v8, v7 offset:swizzle(SWAP,1)
	ds_swizzle_b32 v9, v0 offset:swizzle(SWAP,1)
	s_waitcnt lgkmcnt(0)
	v_add_f32_e32 v7, v7, v8
	v_add_f32_e32 v0, v0, v9
	ds_swizzle_b32 v8, v7 offset:swizzle(SWAP,2)
	ds_swizzle_b32 v9, v0 offset:swizzle(SWAP,2)
	s_waitcnt lgkmcnt(0)
	v_add_f32_e32 v7, v7, v8
	v_add_f32_e32 v0, v0, v9
	ds_swizzle_b32 v8, v7 offset:swizzle(SWAP,4)
	ds_swizzle_b32 v9, v0 offset:swizzle(SWAP,4)
	s_waitcnt lgkmcnt(0)
	v_add_f32_e32 v7, v7, v8
	v_add_f32_e32 v0, v0, v9
	ds_swizzle_b32 v8, v7 offset:swizzle(SWAP,8)
	ds_swizzle_b32 v9, v0 offset:swizzle(SWAP,8)
	s_waitcnt lgkmcnt(0)
	v_add_f32_e32 v7, v7, v8
	v_add_f32_e32 v0, v0, v9
	ds_swizzle_b32 v8, v7 offset:swizzle(SWAP,16)
	ds_swizzle_b32 v10, v0 offset:swizzle(SWAP,16)
	s_waitcnt lgkmcnt(0)
	v_add_f32_e32 v8, v7, v8
	v_add_f32_e32 v0, v0, v10
	v_mov_b32_e32 v9, v8
	v_mov_b32_e32 v7, v0
	s_nop 0
	v_permlane32_swap_b32_e32 v8, v9
	v_permlane32_swap_b32_e32 v0, v7
	s_and_saveexec_b64 s[14:15], s[4:5]
	s_cbranch_execz .LBB0_248
	v_add_f32_e32 v8, v8, v9
	v_fmamk_f32 v8, v8, 0x3b2aaaab, v218
	v_mul_f32_e32 v9, 0x4f800000, v8
	v_cmp_gt_f32_e32 vcc, s68, v8
	v_add_f32_e32 v0, v0, v7
	v_fmamk_f32 v0, v0, 0x3b800000, v218
	v_cndmask_b32_e32 v8, v8, v9, vcc
	v_sqrt_f32_e32 v9, v8
	s_nop 0
	v_add_u32_e32 v10, -1, v9
	v_fma_f32 v12, -v10, v9, v8
	v_add_u32_e32 v11, 1, v9
	v_cmp_ge_f32_e64 s[6:7], 0, v12
	s_nop 1
	v_cndmask_b32_e64 v10, v9, v10, s[6:7]
	v_fma_f32 v9, -v11, v9, v8
	v_cmp_lt_f32_e64 s[6:7], 0, v9
	s_nop 1
	v_cndmask_b32_e64 v9, v10, v11, s[6:7]
	v_mul_f32_e32 v10, 0x37800000, v9
	v_cndmask_b32_e32 v9, v9, v10, vcc
	v_cmp_class_f32_e32 vcc, v8, v219
	s_nop 1
	v_cndmask_b32_e32 v8, v9, v8, vcc
	v_div_scale_f32 v9, s[6:7], v8, v8, 1.0
	v_rcp_f32_e32 v10, v9
	s_add_u32 s6, s8, s12
	s_addc_u32 s7, s9, s13
	v_fma_f32 v7, -v9, v10, 1.0
	v_fmac_f32_e32 v10, v7, v10
	v_div_scale_f32 v7, vcc, 1.0, v8, 1.0
	v_mul_f32_e32 v11, v7, v10
	v_fma_f32 v12, -v9, v11, v7
	v_fmac_f32_e32 v11, v12, v10
	v_fma_f32 v7, -v9, v11, v7
	v_div_fmas_f32 v7, v7, v10, v11
	v_div_fixup_f32 v7, v7, v8, 1.0
	v_mul_f32_e32 v8, 0x4f800000, v0
	v_cmp_gt_f32_e32 vcc, s68, v0
	v_mov_b32_e32 v10, s6
	v_mov_b32_e32 v11, s7
	v_cndmask_b32_e32 v0, v0, v8, vcc
	v_sqrt_f32_e32 v8, v0
	s_nop 0
	v_add_u32_e32 v9, -1, v8
	v_fma_f32 v12, -v9, v8, v0
	v_cmp_ge_f32_e64 s[6:7], 0, v12
	v_add_u32_e32 v12, 1, v8
	s_nop 0
	v_cndmask_b32_e64 v9, v8, v9, s[6:7]
	v_fma_f32 v8, -v12, v8, v0
	v_cmp_lt_f32_e64 s[6:7], 0, v8
	s_nop 1
	v_cndmask_b32_e64 v8, v9, v12, s[6:7]
	v_mul_f32_e32 v9, 0x37800000, v8
	v_cndmask_b32_e32 v8, v8, v9, vcc
	v_cmp_class_f32_e32 vcc, v0, v219
	s_nop 1
	v_cndmask_b32_e32 v0, v8, v0, vcc
	v_div_scale_f32 v12, s[6:7], v0, v0, 1.0
	v_rcp_f32_e32 v13, v12
	s_mov_b32 s6, 0x600000
	v_add_co_u32_e32 v8, vcc, s6, v10
	s_nop 1
	v_addc_co_u32_e32 v9, vcc, 0, v11, vcc
	global_store_dword v[8:9], v7, off
	v_fma_f32 v7, -v12, v13, 1.0
	v_fmac_f32_e32 v13, v7, v13
	v_div_scale_f32 v7, vcc, 1.0, v0, 1.0
	v_mul_f32_e32 v8, v7, v13
	v_fma_f32 v9, -v12, v8, v7
	v_fmac_f32_e32 v8, v9, v13
	v_fma_f32 v7, -v12, v8, v7
	v_div_fmas_f32 v7, v7, v13, v8
	v_add_co_u32_e32 v8, vcc, 0x610000, v10
	v_div_fixup_f32 v0, v7, v0, 1.0
	s_nop 0
	v_addc_co_u32_e32 v9, vcc, 0, v11, vcc
	global_store_dword v[8:9], v0, off
	s_branch .LBB0_248

;     __device__ __forceinline__ void operator()(const f32x4 (&acc)[2][2][4][2], const Unit& u, int wr, int wc, int fr, int fq) const {
;         const int row0 = u.pm * BM + wr * 64 + fr; const int col0 = u.pn * BM + wc * 32 + 8 * fq;
;         bool rot[2]; int i0[2];
; #pragma unroll
;         for (int bj = 0; bj < 2; ++bj) { const int cm = (col0 + bj * HALF) % 192; rot[bj] = (MODE == 3) && cm >= 128; i0[bj] = rot[bj] ? (cm - 128) >> 1 : 0; }
; #pragma unroll
;         for (int am = 0; am < 4; ++am) { const int ai = am >> 1;
;             f32x4 t0[4][2], t1[4][2]; float rsv[2][4];
; #pragma unroll
;             for (int m = 2 * (am & 1); m < 2 * (am & 1) + 2; ++m) rsv[ai][m] = (MODE >= 2) ? rs[row0 + ai * HALF + m * 16] : 1.f;
;             if (MODE == 3) {
; #pragma unroll
;                 for (int m = 2 * (am & 1); m < 2 * (am & 1) + 2; ++m)
; #pragma unroll
;                     for (int bj = 0; bj < 2; ++bj) { const f32x4* tp = (const f32x4*)(tab + (size_t)(row0 + ai * HALF + m * 16) * 32 + i0[bj]); t0[m][bj] = tp[0]; t1[m][bj] = tp[1];
;                         if (!rot[bj]) { t0[m][bj] = (f32x4){1.f, 0.f, 1.f, 0.f}; t1[m][bj] = t0[m][bj]; } }
;                 asm volatile("" ::: "memory");
;             }
; #pragma unroll
;             for (int m = 2 * (am & 1); m < 2 * (am & 1) + 2; ++m) { const int row = row0 + ai * HALF + m * 16; bf16_t* rowp = O + (size_t)row * ldc + col0;
;                 const float rsvv = rsv[ai][m];
; #pragma unroll
;                 for (int bj = 0; bj < 2; ++bj) { f32x4 v0 = acc[ai][bj][m][0], v1 = acc[ai][bj][m][1];
;                     if (MODE == 1) {
; #pragma unroll
;                         for (int e = 0; e < 4; ++e) { float a = fmaxf(v0[e], 0.f), b = fmaxf(v1[e], 0.f); v0[e] = a * a; v1[e] = b * b; } }
;                     if (MODE >= 2) { v0 = v0 * rsvv; v1 = v1 * rsvv; }
;                     if (MODE == 3) { const f32x4 a0 = t0[m][bj], a1 = t1[m][bj]; f32x4 w0, w1;
;                         w0[0] = v0[0] * a0[0] - v0[1] * a0[1]; w0[1] = v0[1] * a0[0] + v0[0] * a0[1]; w0[2] = v0[2] * a0[2] - v0[3] * a0[3]; w0[3] = v0[3] * a0[2] + v0[2] * a0[3];
;                         w1[0] = v1[0] * a1[0] - v1[1] * a1[1]; w1[1] = v1[1] * a1[0] + v1[0] * a1[1]; w1[2] = v1[2] * a1[2] - v1[3] * a1[3]; w1[3] = v1[3] * a1[2] + v1[2] * a1[3];
;                         v0 = w0; v1 = w1; }
.LBB0_311:
	s_lshl_b32 s4, s65, 8
	v_mbcnt_lo_u32_b32 v139, -1, 0
	v_mbcnt_hi_u32_b32 v139, -1, v139
	s_add_i32 s22, s4, s38
	s_lshl_b32 s4, s64, 8
	v_lshrrev_b32_e32 v0, 1, v139
	v_and_or_b32 v0, v0, 24, s4
	v_or_b32_e32 v144, s39, v0
	s_mov_b32 s24, 0x2aaaaaab
	v_mul_hi_i32 v0, v144, s24
	v_lshrrev_b32_e32 v138, 31, v0
	v_lshrrev_b32_e32 v0, 5, v0
	v_add_u32_e32 v0, v0, v138
	v_or_b32_e32 v138, 0x80, v144
	s_movk_i32 s23, 0xc0
	v_mul_hi_i32 v140, v138, s24
	v_mul_lo_u32 v0, v0, s23
	v_lshrrev_b32_e32 v141, 31, v140
	v_lshrrev_b32_e32 v140, 5, v140
	v_and_or_b32 v146, v139, 15, s22
	v_sub_u32_e32 v0, v144, v0
	s_movk_i32 s25, 0x7f
	v_add_u32_e32 v140, v140, v141
	v_or_b32_e32 v152, 16, v146
	v_cmp_lt_i32_e64 s[4:5], s25, v0
	v_add_u32_e32 v0, 0xffffff80, v0
	v_mul_lo_u32 v140, v140, s23
	v_ashrrev_i32_e32 v147, 31, v146
	v_ashrrev_i32_e32 v153, 31, v152
	v_lshrrev_b32_e32 v0, 1, v0
	v_sub_u32_e32 v138, v138, v140
	v_lshl_add_u64 v[148:149], v[146:147], 2, s[10:11]
	v_lshl_add_u64 v[140:141], v[152:153], 2, s[10:11]
	v_cndmask_b32_e64 v0, 0, v0, s[4:5]
	global_load_dword v154, v[148:149], off
	global_load_dword v150, v[140:141], off
	v_lshlrev_b64 v[140:141], 8, v[146:147]
	v_lshl_add_u64 v[142:143], s[12:13], 0, v[140:141]
	v_lshlrev_b64 v[140:141], 3, v[0:1]
	v_lshl_add_u64 v[160:161], v[142:143], 0, v[140:141]
	global_load_dwordx4 v[156:159], v[160:161], off
	s_nop 0
	global_load_dwordx4 v[160:163], v[160:161], off offset:16
	v_cmp_lt_i32_e32 vcc, s25, v138
	v_add_u32_e32 v138, 0xffffff80, v138
	v_ashrrev_i32_e32 v138, 1, v138
	v_cndmask_b32_e32 v138, 0, v138, vcc
	v_ashrrev_i32_e32 v139, 31, v138
	v_lshlrev_b64 v[138:139], 3, v[138:139]
	v_lshl_add_u64 v[142:143], v[142:143], 0, v[138:139]
	v_ashrrev_i32_e32 v145, 31, v144
	s_movk_i32 s24, 0x600
	v_lshlrev_b64 v[144:145], 1, v[144:145]
	s_waitcnt vmcnt(0) lgkmcnt(0)
	v_pk_mul_f32 v[126:127], v[126:127], v[154:155] op_sel_hi:[1,0]
	v_pk_mul_f32 v[128:129], v[128:129], v[154:155] op_sel_hi:[1,0]
	v_pk_mul_f32 v[122:123], v[122:123], v[154:155] op_sel_hi:[1,0]
	v_pk_mul_f32 v[124:125], v[124:125], v[154:155] op_sel_hi:[1,0]
	v_pk_mul_f32 v[118:119], v[118:119], v[154:155] op_sel_hi:[1,0]
	v_cndmask_b32_e64 v169, 0, v159, s[4:5]
	v_cndmask_b32_e64 v167, 0, v161, s[4:5]
	v_cndmask_b32_e64 v166, 1.0, v160, s[4:5]
	v_cndmask_b32_e64 v168, 1.0, v158, s[4:5]
	global_load_dwordx4 v[172:175], v[142:143], off
	global_load_dwordx4 v[158:161], v[142:143], off offset:16
	v_lshlrev_b64 v[142:143], 8, v[152:153]
	v_lshl_add_u64 v[142:143], s[12:13], 0, v[142:143]
	v_cndmask_b32_e64 v165, 0, v163, s[4:5]
	v_cndmask_b32_e64 v164, 1.0, v162, s[4:5]
	v_cndmask_b32_e64 v171, 0, v157, s[4:5]
	v_cndmask_b32_e64 v170, 1.0, v156, s[4:5]
	v_pk_mul_f32 v[192:193], v[126:127], v[170:171]
	v_pk_mul_f32 v[126:127], v[126:127], v[170:171] op_sel:[1,0] op_sel_hi:[0,1]
	v_pk_mul_f32 v[190:191], v[128:129], v[168:169]
	v_add_f32_e32 v147, v126, v127
	v_pk_mul_f32 v[126:127], v[128:129], v[168:169] op_sel:[1,0] op_sel_hi:[0,1]
	v_pk_mul_f32 v[128:129], v[122:123], v[166:167]
	v_pk_mul_f32 v[122:123], v[122:123], v[166:167] op_sel:[1,0] op_sel_hi:[0,1]
	v_sub_f32_e32 v128, v128, v129
	v_add_f32_e32 v129, v122, v123
	v_pk_mul_f32 v[122:123], v[124:125], v[164:165] op_sel:[1,0] op_sel_hi:[0,1]
	v_add_f32_e32 v168, v126, v127
	v_pk_mul_f32 v[126:127], v[124:125], v[164:165]
	v_add_f32_e32 v125, v122, v123
	v_sub_f32_e32 v0, v192, v193
	v_sub_f32_e32 v153, v190, v191
	v_sub_f32_e32 v126, v126, v127
	v_pk_mul_f32 v[120:121], v[120:121], v[154:155] op_sel_hi:[1,0]
	v_pk_mul_f32 v[114:115], v[114:115], v[154:155] op_sel_hi:[1,0]
	v_pk_mul_f32 v[116:117], v[116:117], v[154:155] op_sel_hi:[1,0]
	v_pk_mul_f32 v[110:111], v[110:111], v[150:151] op_sel_hi:[1,0]
	v_pk_mul_f32 v[112:113], v[112:113], v[150:151] op_sel_hi:[1,0]
	v_pk_mul_f32 v[106:107], v[106:107], v[150:151] op_sel_hi:[1,0]
	v_pk_mul_f32 v[108:109], v[108:109], v[150:151] op_sel_hi:[1,0]
	v_pk_mul_f32 v[102:103], v[102:103], v[150:151] op_sel_hi:[1,0]
	v_pk_mul_f32 v[104:105], v[104:105], v[150:151] op_sel_hi:[1,0]
	v_pk_mul_f32 v[98:99], v[98:99], v[150:151] op_sel_hi:[1,0]
	v_pk_mul_f32 v[100:101], v[100:101], v[150:151] op_sel_hi:[1,0]
	s_waitcnt vmcnt(0) lgkmcnt(0)
	v_cndmask_b32_e32 v163, 0, v173, vcc
	v_cndmask_b32_e32 v162, 1.0, v172, vcc
	v_lshl_add_u64 v[172:173], v[142:143], 0, v[140:141]
	v_lshl_add_u64 v[142:143], v[142:143], 0, v[138:139]
	v_cndmask_b32_e32 v157, 0, v161, vcc
	v_cndmask_b32_e32 v156, 1.0, v160, vcc
	v_cndmask_b32_e32 v161, 0, v175, vcc
	v_cndmask_b32_e32 v160, 1.0, v174, vcc
	global_load_dwordx4 v[178:181], v[172:173], off
	global_load_dwordx4 v[174:177], v[172:173], off offset:16
	global_load_dwordx4 v[186:189], v[142:143], off
	global_load_dwordx4 v[182:185], v[142:143], off offset:16
	v_mov_b64_e32 v[142:143], s[8:9]
	v_cvt_pk_bf16_f32 v122, v0, v147
	v_cvt_pk_bf16_f32 v123, v153, v168
	v_cvt_pk_bf16_f32 v124, v128, v129
	v_cvt_pk_bf16_f32 v125, v126, v125
	v_cndmask_b32_e32 v159, 0, v159, vcc
	v_cndmask_b32_e32 v158, 1.0, v158, vcc
	s_waitcnt vmcnt(0) lgkmcnt(0)
; __device__ __forceinline__ unsigned cvtpk(float lo, float hi) { unsigned r; asm volatile("v_cvt_pk_bf16_f32 %0, %1, %2" : "=v"(r) : "v"(lo), "v"(hi)); return r; }
;     __device__ __forceinline__ void operator()(const f32x4 (&acc)[2][2][4][2], const Unit& u, int wr, int wc, int fr, int fq) const {
;     ...
;             for (int m = 2 * (am & 1); m < 2 * (am & 1) + 2; ++m) rsv[ai][m] = (MODE >= 2) ? rs[row0 + ai * HALF + m * 16] : 1.f;
;             if (MODE == 3) {
; #pragma unroll
;                 for (int m = 2 * (am & 1); m < 2 * (am & 1) + 2; ++m)
; #pragma unroll
;                     for (int bj = 0; bj < 2; ++bj) { const f32x4* tp = (const f32x4*)(tab + (size_t)(row0 + ai * HALF + m * 16) * 32 + i0[bj]); t0[m][bj] = tp[0]; t1[m][bj] = tp[1];
;                         if (!rot[bj]) { t0[m][bj] = (f32x4){1.f, 0.f, 1.f, 0.f}; t1[m][bj] = t0[m][bj]; } }
;                 asm volatile("" ::: "memory");
;             }
; #pragma unroll
;             for (int m = 2 * (am & 1); m < 2 * (am & 1) + 2; ++m) { const int row = row0 + ai * HALF + m * 16; bf16_t* rowp = O + (size_t)row * ldc + col0;
;                 const float rsvv = rsv[ai][m];
; #pragma unroll
;                 for (int bj = 0; bj < 2; ++bj) { f32x4 v0 = acc[ai][bj][m][0], v1 = acc[ai][bj][m][1];
;                     if (MODE == 1) {
; #pragma unroll
;                         for (int e = 0; e < 4; ++e) { float a = fmaxf(v0[e], 0.f), b = fmaxf(v1[e], 0.f); v0[e] = a * a; v1[e] = b * b; } }
;                     if (MODE >= 2) { v0 = v0 * rsvv; v1 = v1 * rsvv; }
;                     if (MODE == 3) { const f32x4 a0 = t0[m][bj], a1 = t1[m][bj]; f32x4 w0, w1;
;                         w0[0] = v0[0] * a0[0] - v0[1] * a0[1]; w0[1] = v0[1] * a0[0] + v0[0] * a0[1]; w0[2] = v0[2] * a0[2] - v0[3] * a0[3]; w0[3] = v0[3] * a0[2] + v0[2] * a0[3];
;                         w1[0] = v1[0] * a1[0] - v1[1] * a1[1]; w1[1] = v1[1] * a1[0] + v1[0] * a1[1]; w1[2] = v1[2] * a1[2] - v1[3] * a1[3]; w1[3] = v1[3] * a1[2] + v1[2] * a1[3];
;                         v0 = w0; v1 = w1; }
;                     u32x4 w; w.x = cvtpk(v0[0], v0[1]); w.y = cvtpk(v0[2], v0[3]); w.z = cvtpk(v1[0], v1[1]); w.w = cvtpk(v1[2], v1[3]);
;                     *(u32x4*)(rowp + bj * HALF) = w; } }
	v_cndmask_b32_e64 v179, 0, v179, s[4:5]
	v_cndmask_b32_e64 v173, 0, v177, s[4:5]
	v_cndmask_b32_e64 v172, 1.0, v176, s[4:5]
	v_cndmask_b32_e64 v177, 0, v181, s[4:5]
	v_cndmask_b32_e64 v176, 1.0, v180, s[4:5]
	v_cndmask_b32_e32 v181, 0, v185, vcc
	v_cndmask_b32_e32 v180, 1.0, v184, vcc
	v_cndmask_b32_e32 v185, 0, v189, vcc
	v_cndmask_b32_e32 v184, 1.0, v188, vcc
	v_mad_i64_i32 v[188:189], s[22:23], v146, s24, v[142:143]
	v_lshl_add_u64 v[188:189], v[188:189], 0, v[144:145]
	global_store_dwordx4 v[188:189], v[122:125], off
	v_cndmask_b32_e64 v178, 1.0, v178, s[4:5]
	v_cndmask_b32_e64 v175, 0, v175, s[4:5]
	v_pk_mul_f32 v[124:125], v[118:119], v[162:163]
	v_pk_mul_f32 v[118:119], v[118:119], v[162:163] op_sel:[1,0] op_sel_hi:[0,1]
	v_pk_mul_f32 v[122:123], v[120:121], v[160:161]
	v_sub_f32_e32 v0, v124, v125
	v_add_f32_e32 v124, v118, v119
	v_pk_mul_f32 v[118:119], v[120:121], v[160:161] op_sel:[1,0] op_sel_hi:[0,1]
	v_pk_mul_f32 v[120:121], v[114:115], v[158:159]
	v_pk_mul_f32 v[114:115], v[114:115], v[158:159] op_sel:[1,0] op_sel_hi:[0,1]
	v_sub_f32_e32 v122, v122, v123
	v_add_f32_e32 v123, v118, v119
	v_pk_mul_f32 v[118:119], v[116:117], v[156:157]
	v_sub_f32_e32 v120, v120, v121
	v_add_f32_e32 v121, v114, v115
	v_pk_mul_f32 v[114:115], v[116:117], v[156:157] op_sel:[1,0] op_sel_hi:[0,1]
	v_sub_f32_e32 v118, v118, v119
	v_add_f32_e32 v117, v114, v115
	v_cndmask_b32_e64 v174, 1.0, v174, s[4:5]
	v_cvt_pk_bf16_f32 v114, v0, v124
	v_cvt_pk_bf16_f32 v115, v122, v123
	v_cvt_pk_bf16_f32 v116, v120, v121
	v_cvt_pk_bf16_f32 v117, v118, v117
	v_pk_mul_f32 v[118:119], v[110:111], v[178:179]
	v_pk_mul_f32 v[110:111], v[110:111], v[178:179] op_sel:[1,0] op_sel_hi:[0,1]
	global_store_dwordx4 v[188:189], v[114:117], off offset:256
	v_sub_f32_e32 v0, v118, v119
	v_add_f32_e32 v118, v110, v111
	v_pk_mul_f32 v[116:117], v[112:113], v[176:177]
	v_pk_mul_f32 v[110:111], v[112:113], v[176:177] op_sel:[1,0] op_sel_hi:[0,1]
	v_pk_mul_f32 v[112:113], v[106:107], v[174:175]
	v_pk_mul_f32 v[106:107], v[106:107], v[174:175] op_sel:[1,0] op_sel_hi:[0,1]
	v_sub_f32_e32 v112, v112, v113
	v_add_f32_e32 v113, v106, v107
	v_pk_mul_f32 v[106:107], v[108:109], v[172:173] op_sel:[1,0] op_sel_hi:[0,1]
	v_mad_i64_i32 v[114:115], s[22:23], v152, s24, v[142:143]
	v_sub_f32_e32 v116, v116, v117
	v_add_f32_e32 v117, v110, v111
	v_pk_mul_f32 v[110:111], v[108:109], v[172:173]
	v_add_f32_e32 v109, v106, v107
	v_cndmask_b32_e32 v187, 0, v187, vcc
	v_cndmask_b32_e32 v186, 1.0, v186, vcc
	v_lshl_add_u64 v[114:115], v[114:115], 0, v[144:145]
	v_sub_f32_e32 v110, v110, v111
	v_cvt_pk_bf16_f32 v106, v0, v118
	v_cvt_pk_bf16_f32 v107, v116, v117
	v_cvt_pk_bf16_f32 v108, v112, v113
	v_cvt_pk_bf16_f32 v109, v110, v109
	v_cndmask_b32_e32 v183, 0, v183, vcc
	v_cndmask_b32_e32 v182, 1.0, v182, vcc
	global_store_dwordx4 v[114:115], v[106:109], off
	s_nop 1
	v_pk_mul_f32 v[108:109], v[102:103], v[186:187]
	v_pk_mul_f32 v[102:103], v[102:103], v[186:187] op_sel:[1,0] op_sel_hi:[0,1]
	v_pk_mul_f32 v[106:107], v[104:105], v[184:185]
	v_sub_f32_e32 v0, v108, v109
	v_add_f32_e32 v108, v102, v103
	v_pk_mul_f32 v[102:103], v[104:105], v[184:185] op_sel:[1,0] op_sel_hi:[0,1]
	v_pk_mul_f32 v[104:105], v[98:99], v[182:183]
	v_pk_mul_f32 v[98:99], v[98:99], v[182:183] op_sel:[1,0] op_sel_hi:[0,1]
	v_sub_f32_e32 v106, v106, v107
	v_add_f32_e32 v107, v102, v103
	v_pk_mul_f32 v[102:103], v[100:101], v[180:181]
	v_sub_f32_e32 v104, v104, v105
	v_add_f32_e32 v105, v98, v99
	v_pk_mul_f32 v[98:99], v[100:101], v[180:181] op_sel:[1,0] op_sel_hi:[0,1]
	v_sub_f32_e32 v102, v102, v103
	v_add_f32_e32 v101, v98, v99
	v_cvt_pk_bf16_f32 v98, v0, v108
	v_cvt_pk_bf16_f32 v99, v106, v107
	v_cvt_pk_bf16_f32 v100, v104, v105
	v_cvt_pk_bf16_f32 v101, v102, v101
	v_or_b32_e32 v102, 32, v146
	global_store_dwordx4 v[114:115], v[98:101], off offset:256
	v_ashrrev_i32_e32 v103, 31, v102
	s_nop 0
	v_lshl_add_u64 v[98:99], v[102:103], 2, s[10:11]
	global_load_dword v100, v[98:99], off
	v_or_b32_e32 v98, 48, v146
	v_ashrrev_i32_e32 v99, 31, v98
	v_lshl_add_u64 v[104:105], v[98:99], 2, s[10:11]
	global_load_dword v0, v[104:105], off
	v_lshlrev_b64 v[104:105], 8, v[102:103]
	v_lshl_add_u64 v[116:117], s[12:13], 0, v[104:105]
	v_lshl_add_u64 v[104:105], v[116:117], 0, v[140:141]
	global_load_dwordx4 v[108:111], v[104:105], off
	global_load_dwordx4 v[112:115], v[104:105], off offset:16
	v_mad_i64_i32 v[102:103], s[22:23], v102, s24, v[142:143]
	v_lshl_add_u64 v[102:103], v[102:103], 0, v[144:145]
	s_waitcnt vmcnt(0) lgkmcnt(0)
	v_pk_mul_f32 v[94:95], v[94:95], v[100:101] op_sel_hi:[1,0]
	v_pk_mul_f32 v[96:97], v[96:97], v[100:101] op_sel_hi:[1,0]
	v_pk_mul_f32 v[90:91], v[90:91], v[100:101] op_sel_hi:[1,0]
	v_pk_mul_f32 v[92:93], v[92:93], v[100:101] op_sel_hi:[1,0]
	v_pk_mul_f32 v[78:79], v[78:79], v[0:1] op_sel_hi:[1,0]
	v_pk_mul_f32 v[80:81], v[80:81], v[0:1] op_sel_hi:[1,0]
	v_pk_mul_f32 v[74:75], v[74:75], v[0:1] op_sel_hi:[1,0]
	v_pk_mul_f32 v[76:77], v[76:77], v[0:1] op_sel_hi:[1,0]
	v_cndmask_b32_e64 v105, 0, v115, s[4:5]
	v_cndmask_b32_e64 v104, 1.0, v114, s[4:5]
	v_cndmask_b32_e64 v115, 0, v109, s[4:5]
	v_cndmask_b32_e64 v114, 1.0, v108, s[4:5]
	v_lshl_add_u64 v[108:109], v[116:117], 0, v[138:139]
	global_load_dwordx4 v[118:121], v[108:109], off
	global_load_dwordx4 v[122:125], v[108:109], off offset:16
	v_cndmask_b32_e64 v107, 0, v113, s[4:5]
	v_cndmask_b32_e64 v106, 1.0, v112, s[4:5]
	v_cndmask_b32_e64 v113, 0, v111, s[4:5]
	v_cndmask_b32_e64 v112, 1.0, v110, s[4:5]
	v_pk_mul_f32 v[70:71], v[70:71], v[0:1] op_sel_hi:[1,0]
	v_pk_mul_f32 v[72:73], v[72:73], v[0:1] op_sel_hi:[1,0]
	v_pk_mul_f32 v[66:67], v[66:67], v[0:1] op_sel_hi:[1,0]
	v_pk_mul_f32 v[68:69], v[68:69], v[0:1] op_sel_hi:[1,0]
	s_waitcnt vmcnt(0) lgkmcnt(0)
; __device__ __forceinline__ unsigned cvtpk(float lo, float hi) { unsigned r; asm volatile("v_cvt_pk_bf16_f32 %0, %1, %2" : "=v"(r) : "v"(lo), "v"(hi)); return r; }
;     __device__ __forceinline__ void operator()(const f32x4 (&acc)[2][2][4][2], const Unit& u, int wr, int wc, int fr, int fq) const {
;     ...
;             for (int m = 2 * (am & 1); m < 2 * (am & 1) + 2; ++m) rsv[ai][m] = (MODE >= 2) ? rs[row0 + ai * HALF + m * 16] : 1.f;
;             if (MODE == 3) {
; #pragma unroll
;                 for (int m = 2 * (am & 1); m < 2 * (am & 1) + 2; ++m)
; #pragma unroll
;                     for (int bj = 0; bj < 2; ++bj) { const f32x4* tp = (const f32x4*)(tab + (size_t)(row0 + ai * HALF + m * 16) * 32 + i0[bj]); t0[m][bj] = tp[0]; t1[m][bj] = tp[1];
;                         if (!rot[bj]) { t0[m][bj] = (f32x4){1.f, 0.f, 1.f, 0.f}; t1[m][bj] = t0[m][bj]; } }
;                 asm volatile("" ::: "memory");
;             }
; #pragma unroll
;             for (int m = 2 * (am & 1); m < 2 * (am & 1) + 2; ++m) { const int row = row0 + ai * HALF + m * 16; bf16_t* rowp = O + (size_t)row * ldc + col0;
;                 const float rsvv = rsv[ai][m];
; #pragma unroll
;                 for (int bj = 0; bj < 2; ++bj) { f32x4 v0 = acc[ai][bj][m][0], v1 = acc[ai][bj][m][1];
;                     if (MODE == 1) {
; #pragma unroll
;                         for (int e = 0; e < 4; ++e) { float a = fmaxf(v0[e], 0.f), b = fmaxf(v1[e], 0.f); v0[e] = a * a; v1[e] = b * b; } }
;                     if (MODE >= 2) { v0 = v0 * rsvv; v1 = v1 * rsvv; }
;                     if (MODE == 3) { const f32x4 a0 = t0[m][bj], a1 = t1[m][bj]; f32x4 w0, w1;
;                         w0[0] = v0[0] * a0[0] - v0[1] * a0[1]; w0[1] = v0[1] * a0[0] + v0[0] * a0[1]; w0[2] = v0[2] * a0[2] - v0[3] * a0[3]; w0[3] = v0[3] * a0[2] + v0[2] * a0[3];
;                         w1[0] = v1[0] * a1[0] - v1[1] * a1[1]; w1[1] = v1[1] * a1[0] + v1[0] * a1[1]; w1[2] = v1[2] * a1[2] - v1[3] * a1[3]; w1[3] = v1[3] * a1[2] + v1[2] * a1[3];
;                         v0 = w0; v1 = w1; }
;                     u32x4 w; w.x = cvtpk(v0[0], v0[1]); w.y = cvtpk(v0[2], v0[3]); w.z = cvtpk(v1[0], v1[1]); w.w = cvtpk(v1[2], v1[3]);
;                     *(u32x4*)(rowp + bj * HALF) = w; } }
	v_cndmask_b32_e32 v117, 0, v121, vcc
	v_cndmask_b32_e32 v116, 1.0, v120, vcc
	v_cndmask_b32_e32 v121, 0, v119, vcc
	v_cndmask_b32_e32 v120, 1.0, v118, vcc
	v_lshlrev_b64 v[118:119], 8, v[98:99]
	v_lshl_add_u64 v[152:153], s[12:13], 0, v[118:119]
	v_lshl_add_u64 v[118:119], v[152:153], 0, v[140:141]
	v_cndmask_b32_e32 v109, 0, v125, vcc
	v_cndmask_b32_e32 v108, 1.0, v124, vcc
	v_cndmask_b32_e32 v111, 0, v123, vcc
	v_cndmask_b32_e32 v110, 1.0, v122, vcc
	global_load_dwordx4 v[126:129], v[118:119], off
	global_load_dwordx4 v[122:125], v[118:119], off offset:16
	s_waitcnt vmcnt(0) lgkmcnt(0)
	v_cndmask_b32_e64 v127, 0, v127, s[4:5]
	v_cndmask_b32_e64 v119, 0, v125, s[4:5]
	v_cndmask_b32_e64 v118, 1.0, v124, s[4:5]
	v_cndmask_b32_e64 v125, 0, v129, s[4:5]
	v_cndmask_b32_e64 v124, 1.0, v128, s[4:5]
	v_lshl_add_u64 v[128:129], v[152:153], 0, v[138:139]
	global_load_dwordx4 v[156:159], v[128:129], off
	global_load_dwordx4 v[160:163], v[128:129], off offset:16
	v_cndmask_b32_e64 v126, 1.0, v126, s[4:5]
	v_cndmask_b32_e64 v123, 0, v123, s[4:5]
	v_cndmask_b32_e64 v122, 1.0, v122, s[4:5]
	s_waitcnt vmcnt(0) lgkmcnt(0)
	v_cndmask_b32_e32 v157, 0, v157, vcc
	v_cndmask_b32_e32 v129, 0, v163, vcc
	v_cndmask_b32_e32 v128, 1.0, v162, vcc
	v_pk_mul_f32 v[162:163], v[114:115], v[94:95]
	v_pk_mul_f32 v[94:95], v[114:115], v[94:95] op_sel:[0,1] op_sel_hi:[1,0]
	v_cndmask_b32_e32 v153, 0, v161, vcc
	v_cndmask_b32_e32 v152, 1.0, v160, vcc
	v_pk_mul_f32 v[160:161], v[112:113], v[96:97]
	v_add_f32_e32 v101, v94, v95
	v_pk_mul_f32 v[94:95], v[112:113], v[96:97] op_sel:[0,1] op_sel_hi:[1,0]
	v_pk_mul_f32 v[96:97], v[90:91], v[106:107]
	v_pk_mul_f32 v[90:91], v[90:91], v[106:107] op_sel:[1,0] op_sel_hi:[0,1]
	v_sub_f32_e32 v96, v96, v97
	v_add_f32_e32 v97, v90, v91
	v_pk_mul_f32 v[90:91], v[92:93], v[104:105] op_sel:[1,0] op_sel_hi:[0,1]
	v_add_f32_e32 v112, v94, v95
	v_pk_mul_f32 v[94:95], v[92:93], v[104:105]
	v_add_f32_e32 v93, v90, v91
	v_sub_f32_e32 v99, v162, v163
	v_sub_f32_e32 v114, v160, v161
	v_sub_f32_e32 v94, v94, v95
	v_cvt_pk_bf16_f32 v90, v99, v101
	v_cvt_pk_bf16_f32 v91, v114, v112
	v_cvt_pk_bf16_f32 v92, v96, v97
	v_cvt_pk_bf16_f32 v93, v94, v93
	v_pk_mul_f32 v[86:87], v[86:87], v[100:101] op_sel_hi:[1,0]
	global_store_dwordx4 v[102:103], v[90:93], off
	v_pk_mul_f32 v[88:89], v[88:89], v[100:101] op_sel_hi:[1,0]
	v_pk_mul_f32 v[82:83], v[82:83], v[100:101] op_sel_hi:[1,0]
	v_pk_mul_f32 v[92:93], v[86:87], v[120:121]
	v_pk_mul_f32 v[86:87], v[86:87], v[120:121] op_sel:[1,0] op_sel_hi:[0,1]
	v_pk_mul_f32 v[84:85], v[84:85], v[100:101] op_sel_hi:[1,0]
	v_pk_mul_f32 v[90:91], v[88:89], v[116:117]
	v_sub_f32_e32 v92, v92, v93
	v_add_f32_e32 v93, v86, v87
	v_pk_mul_f32 v[86:87], v[88:89], v[116:117] op_sel:[1,0] op_sel_hi:[0,1]
	v_pk_mul_f32 v[88:89], v[82:83], v[110:111]
	v_pk_mul_f32 v[82:83], v[82:83], v[110:111] op_sel:[1,0] op_sel_hi:[0,1]
	v_sub_f32_e32 v90, v90, v91
	v_add_f32_e32 v91, v86, v87
	v_pk_mul_f32 v[86:87], v[84:85], v[108:109]
	v_sub_f32_e32 v88, v88, v89
	v_add_f32_e32 v89, v82, v83
	v_pk_mul_f32 v[82:83], v[84:85], v[108:109] op_sel:[1,0] op_sel_hi:[0,1]
	v_sub_f32_e32 v86, v86, v87
	v_add_f32_e32 v85, v82, v83
	v_cvt_pk_bf16_f32 v82, v92, v93
	v_cvt_pk_bf16_f32 v83, v90, v91
	v_cvt_pk_bf16_f32 v84, v88, v89
	v_cvt_pk_bf16_f32 v85, v86, v85
	v_pk_mul_f32 v[86:87], v[78:79], v[126:127]
	v_pk_mul_f32 v[78:79], v[78:79], v[126:127] op_sel:[1,0] op_sel_hi:[0,1]
	global_store_dwordx4 v[102:103], v[82:85], off offset:256
	v_sub_f32_e32 v86, v86, v87
	v_add_f32_e32 v87, v78, v79
	v_pk_mul_f32 v[84:85], v[80:81], v[124:125]
	v_pk_mul_f32 v[78:79], v[80:81], v[124:125] op_sel:[1,0] op_sel_hi:[0,1]
	v_pk_mul_f32 v[80:81], v[74:75], v[122:123]
	v_pk_mul_f32 v[74:75], v[74:75], v[122:123] op_sel:[1,0] op_sel_hi:[0,1]
	v_sub_f32_e32 v80, v80, v81
	v_add_f32_e32 v81, v74, v75
	v_pk_mul_f32 v[74:75], v[76:77], v[118:119] op_sel:[1,0] op_sel_hi:[0,1]
	v_mad_i64_i32 v[82:83], s[22:23], v98, s24, v[142:143]
	v_sub_f32_e32 v84, v84, v85
	v_add_f32_e32 v85, v78, v79
	v_pk_mul_f32 v[78:79], v[76:77], v[118:119]
	v_add_f32_e32 v77, v74, v75
	v_cndmask_b32_e32 v156, 1.0, v156, vcc
	v_lshl_add_u64 v[82:83], v[82:83], 0, v[144:145]
	v_sub_f32_e32 v78, v78, v79
	v_cvt_pk_bf16_f32 v74, v86, v87
	v_cvt_pk_bf16_f32 v75, v84, v85
	v_cvt_pk_bf16_f32 v76, v80, v81
	v_cvt_pk_bf16_f32 v77, v78, v77
	v_cndmask_b32_e32 v159, 0, v159, vcc
	v_cndmask_b32_e32 v158, 1.0, v158, vcc
	global_store_dwordx4 v[82:83], v[74:77], off
	s_nop 1
	v_pk_mul_f32 v[76:77], v[70:71], v[156:157]
	v_pk_mul_f32 v[70:71], v[70:71], v[156:157] op_sel:[1,0] op_sel_hi:[0,1]
	v_pk_mul_f32 v[74:75], v[72:73], v[158:159]
	v_sub_f32_e32 v0, v76, v77
	v_add_f32_e32 v76, v70, v71
	v_pk_mul_f32 v[70:71], v[72:73], v[158:159] op_sel:[1,0] op_sel_hi:[0,1]
	v_pk_mul_f32 v[72:73], v[66:67], v[152:153]
	v_pk_mul_f32 v[66:67], v[66:67], v[152:153] op_sel:[1,0] op_sel_hi:[0,1]
	v_sub_f32_e32 v74, v74, v75
	v_add_f32_e32 v75, v70, v71
	v_pk_mul_f32 v[70:71], v[68:69], v[128:129]
	v_sub_f32_e32 v72, v72, v73
	v_add_f32_e32 v73, v66, v67
	v_pk_mul_f32 v[66:67], v[68:69], v[128:129] op_sel:[1,0] op_sel_hi:[0,1]
	v_sub_f32_e32 v70, v70, v71
	v_add_f32_e32 v69, v66, v67
	v_cvt_pk_bf16_f32 v66, v0, v76
	v_cvt_pk_bf16_f32 v67, v74, v75
	v_cvt_pk_bf16_f32 v68, v72, v73
	v_cvt_pk_bf16_f32 v69, v70, v69
	v_add_u32_e32 v70, 0x80, v146
	v_ashrrev_i32_e32 v71, 31, v70
	v_lshlrev_b64 v[72:73], 8, v[70:71]
	global_store_dwordx4 v[82:83], v[66:69], off offset:256
	v_lshl_add_u64 v[84:85], s[12:13], 0, v[72:73]
	v_lshl_add_u64 v[72:73], v[84:85], 0, v[140:141]
	global_load_dword v68, v[148:149], off offset:512
	global_load_dword v0, v[148:149], off offset:576
	global_load_dwordx4 v[76:79], v[72:73], off
	global_load_dwordx4 v[80:83], v[72:73], off offset:16
	v_add_u32_e32 v66, 0x90, v146
	v_ashrrev_i32_e32 v67, 31, v66
	v_mad_i64_i32 v[70:71], s[22:23], v70, s24, v[142:143]
	v_lshl_add_u64 v[70:71], v[70:71], 0, v[144:145]
	s_waitcnt vmcnt(0) lgkmcnt(0)
; __device__ __forceinline__ unsigned cvtpk(float lo, float hi) { unsigned r; asm volatile("v_cvt_pk_bf16_f32 %0, %1, %2" : "=v"(r) : "v"(lo), "v"(hi)); return r; }
;     __device__ __forceinline__ void operator()(const f32x4 (&acc)[2][2][4][2], const Unit& u, int wr, int wc, int fr, int fq) const {
;     ...
;             for (int m = 2 * (am & 1); m < 2 * (am & 1) + 2; ++m) rsv[ai][m] = (MODE >= 2) ? rs[row0 + ai * HALF + m * 16] : 1.f;
;             if (MODE == 3) {
; #pragma unroll
;                 for (int m = 2 * (am & 1); m < 2 * (am & 1) + 2; ++m)
; #pragma unroll
;                     for (int bj = 0; bj < 2; ++bj) { const f32x4* tp = (const f32x4*)(tab + (size_t)(row0 + ai * HALF + m * 16) * 32 + i0[bj]); t0[m][bj] = tp[0]; t1[m][bj] = tp[1];
;                         if (!rot[bj]) { t0[m][bj] = (f32x4){1.f, 0.f, 1.f, 0.f}; t1[m][bj] = t0[m][bj]; } }
;                 asm volatile("" ::: "memory");
;             }
; #pragma unroll
;             for (int m = 2 * (am & 1); m < 2 * (am & 1) + 2; ++m) { const int row = row0 + ai * HALF + m * 16; bf16_t* rowp = O + (size_t)row * ldc + col0;
;                 const float rsvv = rsv[ai][m];
; #pragma unroll
;                 for (int bj = 0; bj < 2; ++bj) { f32x4 v0 = acc[ai][bj][m][0], v1 = acc[ai][bj][m][1];
;                     if (MODE == 1) {
; #pragma unroll
;                         for (int e = 0; e < 4; ++e) { float a = fmaxf(v0[e], 0.f), b = fmaxf(v1[e], 0.f); v0[e] = a * a; v1[e] = b * b; } }
;                     if (MODE >= 2) { v0 = v0 * rsvv; v1 = v1 * rsvv; }
;                     if (MODE == 3) { const f32x4 a0 = t0[m][bj], a1 = t1[m][bj]; f32x4 w0, w1;
;                         w0[0] = v0[0] * a0[0] - v0[1] * a0[1]; w0[1] = v0[1] * a0[0] + v0[0] * a0[1]; w0[2] = v0[2] * a0[2] - v0[3] * a0[3]; w0[3] = v0[3] * a0[2] + v0[2] * a0[3];
;                         w1[0] = v1[0] * a1[0] - v1[1] * a1[1]; w1[1] = v1[1] * a1[0] + v1[0] * a1[1]; w1[2] = v1[2] * a1[2] - v1[3] * a1[3]; w1[3] = v1[3] * a1[2] + v1[2] * a1[3];
;                         v0 = w0; v1 = w1; }
;                     u32x4 w; w.x = cvtpk(v0[0], v0[1]); w.y = cvtpk(v0[2], v0[3]); w.z = cvtpk(v1[0], v1[1]); w.w = cvtpk(v1[2], v1[3]);
;                     *(u32x4*)(rowp + bj * HALF) = w; } }
	v_pk_mul_f32 v[62:63], v[62:63], v[68:69] op_sel_hi:[1,0]
	v_pk_mul_f32 v[64:65], v[64:65], v[68:69] op_sel_hi:[1,0]
	v_cndmask_b32_e64 v73, 0, v83, s[4:5]
	v_cndmask_b32_e64 v72, 1.0, v82, s[4:5]
	v_cndmask_b32_e64 v83, 0, v77, s[4:5]
	v_cndmask_b32_e64 v82, 1.0, v76, s[4:5]
	v_lshl_add_u64 v[76:77], v[84:85], 0, v[138:139]
	global_load_dwordx4 v[86:89], v[76:77], off
	global_load_dwordx4 v[90:93], v[76:77], off offset:16
	v_cndmask_b32_e64 v75, 0, v81, s[4:5]
	v_cndmask_b32_e64 v74, 1.0, v80, s[4:5]
	v_cndmask_b32_e64 v81, 0, v79, s[4:5]
	v_cndmask_b32_e64 v80, 1.0, v78, s[4:5]
	v_pk_mul_f32 v[58:59], v[58:59], v[68:69] op_sel_hi:[1,0]
	v_pk_mul_f32 v[106:107], v[82:83], v[62:63]
	v_pk_mul_f32 v[62:63], v[82:83], v[62:63] op_sel:[0,1] op_sel_hi:[1,0]
	v_pk_mul_f32 v[60:61], v[60:61], v[68:69] op_sel_hi:[1,0]
	v_pk_mul_f32 v[104:105], v[80:81], v[64:65]
	v_add_f32_e32 v69, v62, v63
	v_pk_mul_f32 v[62:63], v[80:81], v[64:65] op_sel:[0,1] op_sel_hi:[1,0]
	v_pk_mul_f32 v[64:65], v[58:59], v[74:75]
	v_pk_mul_f32 v[58:59], v[58:59], v[74:75] op_sel:[1,0] op_sel_hi:[0,1]
	v_sub_f32_e32 v64, v64, v65
	v_add_f32_e32 v65, v58, v59
	v_pk_mul_f32 v[58:59], v[60:61], v[72:73] op_sel:[1,0] op_sel_hi:[0,1]
	v_add_f32_e32 v80, v62, v63
	v_pk_mul_f32 v[62:63], v[60:61], v[72:73]
	v_add_f32_e32 v61, v58, v59
	v_sub_f32_e32 v82, v104, v105
	v_sub_f32_e32 v62, v62, v63
	v_pk_mul_f32 v[54:55], v[54:55], v[68:69] op_sel_hi:[1,0]
	v_pk_mul_f32 v[56:57], v[56:57], v[68:69] op_sel_hi:[1,0]
	v_pk_mul_f32 v[50:51], v[50:51], v[68:69] op_sel_hi:[1,0]
	v_pk_mul_f32 v[52:53], v[52:53], v[68:69] op_sel_hi:[1,0]
	v_pk_mul_f32 v[46:47], v[46:47], v[0:1] op_sel_hi:[1,0]
	v_pk_mul_f32 v[48:49], v[48:49], v[0:1] op_sel_hi:[1,0]
	v_pk_mul_f32 v[42:43], v[42:43], v[0:1] op_sel_hi:[1,0]
	v_pk_mul_f32 v[44:45], v[44:45], v[0:1] op_sel_hi:[1,0]
	v_pk_mul_f32 v[38:39], v[38:39], v[0:1] op_sel_hi:[1,0]
	v_pk_mul_f32 v[40:41], v[40:41], v[0:1] op_sel_hi:[1,0]
	v_pk_mul_f32 v[34:35], v[34:35], v[0:1] op_sel_hi:[1,0]
	v_pk_mul_f32 v[36:37], v[36:37], v[0:1] op_sel_hi:[1,0]
	s_waitcnt vmcnt(0) lgkmcnt(0)
	v_cndmask_b32_e32 v85, 0, v89, vcc
	v_cndmask_b32_e32 v84, 1.0, v88, vcc
	v_cndmask_b32_e32 v89, 0, v87, vcc
	v_cndmask_b32_e32 v88, 1.0, v86, vcc
	v_lshlrev_b64 v[86:87], 8, v[66:67]
	v_lshl_add_u64 v[98:99], s[12:13], 0, v[86:87]
	v_lshl_add_u64 v[86:87], v[98:99], 0, v[140:141]
	v_cndmask_b32_e32 v77, 0, v93, vcc
	v_cndmask_b32_e32 v76, 1.0, v92, vcc
	v_cndmask_b32_e32 v79, 0, v91, vcc
	v_cndmask_b32_e32 v78, 1.0, v90, vcc
	global_load_dwordx4 v[94:97], v[86:87], off
	global_load_dwordx4 v[90:93], v[86:87], off offset:16
	v_lshl_add_u64 v[100:101], v[98:99], 0, v[138:139]
	v_sub_f32_e32 v67, v106, v107
	s_waitcnt vmcnt(0) lgkmcnt(0)
	v_cndmask_b32_e64 v95, 0, v95, s[4:5]
	v_cndmask_b32_e64 v87, 0, v93, s[4:5]
	v_cndmask_b32_e64 v86, 1.0, v92, s[4:5]
	v_cndmask_b32_e64 v93, 0, v97, s[4:5]
	v_cndmask_b32_e64 v92, 1.0, v96, s[4:5]
	global_load_dwordx4 v[96:99], v[100:101], off
	s_nop 0
	global_load_dwordx4 v[100:103], v[100:101], off offset:16
	v_cvt_pk_bf16_f32 v58, v67, v69
	v_cvt_pk_bf16_f32 v59, v82, v80
	v_cvt_pk_bf16_f32 v60, v64, v65
	v_cvt_pk_bf16_f32 v61, v62, v61
	global_store_dwordx4 v[70:71], v[58:61], off
	v_cndmask_b32_e64 v94, 1.0, v94, s[4:5]
	v_cndmask_b32_e64 v91, 0, v91, s[4:5]
	v_pk_mul_f32 v[60:61], v[54:55], v[88:89]
	v_pk_mul_f32 v[54:55], v[54:55], v[88:89] op_sel:[1,0] op_sel_hi:[0,1]
	v_pk_mul_f32 v[58:59], v[56:57], v[84:85]
	v_sub_f32_e32 v60, v60, v61
	v_add_f32_e32 v61, v54, v55
	v_pk_mul_f32 v[54:55], v[56:57], v[84:85] op_sel:[1,0] op_sel_hi:[0,1]
	v_pk_mul_f32 v[56:57], v[50:51], v[78:79]
	v_pk_mul_f32 v[50:51], v[50:51], v[78:79] op_sel:[1,0] op_sel_hi:[0,1]
	v_sub_f32_e32 v58, v58, v59
	v_add_f32_e32 v59, v54, v55
	v_pk_mul_f32 v[54:55], v[52:53], v[76:77]
	v_sub_f32_e32 v56, v56, v57
	v_add_f32_e32 v57, v50, v51
	v_pk_mul_f32 v[50:51], v[52:53], v[76:77] op_sel:[1,0] op_sel_hi:[0,1]
	v_sub_f32_e32 v54, v54, v55
	v_add_f32_e32 v53, v50, v51
	v_cndmask_b32_e64 v90, 1.0, v90, s[4:5]
	v_cvt_pk_bf16_f32 v50, v60, v61
	v_cvt_pk_bf16_f32 v51, v58, v59
	v_cvt_pk_bf16_f32 v52, v56, v57
	v_cvt_pk_bf16_f32 v53, v54, v53
	v_pk_mul_f32 v[54:55], v[46:47], v[94:95]
	v_pk_mul_f32 v[46:47], v[46:47], v[94:95] op_sel:[1,0] op_sel_hi:[0,1]
	global_store_dwordx4 v[70:71], v[50:53], off offset:256
	v_sub_f32_e32 v54, v54, v55
	v_add_f32_e32 v55, v46, v47
	v_pk_mul_f32 v[52:53], v[48:49], v[92:93]
	v_pk_mul_f32 v[46:47], v[48:49], v[92:93] op_sel:[1,0] op_sel_hi:[0,1]
	v_pk_mul_f32 v[48:49], v[42:43], v[90:91]
	v_pk_mul_f32 v[42:43], v[42:43], v[90:91] op_sel:[1,0] op_sel_hi:[0,1]
	v_sub_f32_e32 v48, v48, v49
	v_add_f32_e32 v49, v42, v43
	v_pk_mul_f32 v[42:43], v[44:45], v[86:87] op_sel:[1,0] op_sel_hi:[0,1]
	v_mad_i64_i32 v[50:51], s[22:23], v66, s24, v[142:143]
	v_sub_f32_e32 v52, v52, v53
	v_add_f32_e32 v53, v46, v47
	v_pk_mul_f32 v[46:47], v[44:45], v[86:87]
	v_add_f32_e32 v45, v42, v43
	v_lshl_add_u64 v[50:51], v[50:51], 0, v[144:145]
	v_sub_f32_e32 v46, v46, v47
	v_cvt_pk_bf16_f32 v42, v54, v55
	v_cvt_pk_bf16_f32 v43, v52, v53
	v_cvt_pk_bf16_f32 v44, v48, v49
	v_cvt_pk_bf16_f32 v45, v46, v45
	global_store_dwordx4 v[50:51], v[42:45], off
	s_waitcnt vmcnt(0) lgkmcnt(0)
; __device__ __forceinline__ unsigned cvtpk(float lo, float hi) { unsigned r; asm volatile("v_cvt_pk_bf16_f32 %0, %1, %2" : "=v"(r) : "v"(lo), "v"(hi)); return r; }
;     __device__ __forceinline__ void operator()(const f32x4 (&acc)[2][2][4][2], const Unit& u, int wr, int wc, int fr, int fq) const {
;     ...
;             for (int m = 2 * (am & 1); m < 2 * (am & 1) + 2; ++m) rsv[ai][m] = (MODE >= 2) ? rs[row0 + ai * HALF + m * 16] : 1.f;
;             if (MODE == 3) {
; #pragma unroll
;                 for (int m = 2 * (am & 1); m < 2 * (am & 1) + 2; ++m)
; #pragma unroll
;                     for (int bj = 0; bj < 2; ++bj) { const f32x4* tp = (const f32x4*)(tab + (size_t)(row0 + ai * HALF + m * 16) * 32 + i0[bj]); t0[m][bj] = tp[0]; t1[m][bj] = tp[1];
;                         if (!rot[bj]) { t0[m][bj] = (f32x4){1.f, 0.f, 1.f, 0.f}; t1[m][bj] = t0[m][bj]; } }
;                 asm volatile("" ::: "memory");
;             }
; #pragma unroll
;             for (int m = 2 * (am & 1); m < 2 * (am & 1) + 2; ++m) { const int row = row0 + ai * HALF + m * 16; bf16_t* rowp = O + (size_t)row * ldc + col0;
;                 const float rsvv = rsv[ai][m];
; #pragma unroll
;                 for (int bj = 0; bj < 2; ++bj) { f32x4 v0 = acc[ai][bj][m][0], v1 = acc[ai][bj][m][1];
;                     if (MODE == 1) {
; #pragma unroll
;                         for (int e = 0; e < 4; ++e) { float a = fmaxf(v0[e], 0.f), b = fmaxf(v1[e], 0.f); v0[e] = a * a; v1[e] = b * b; } }
;                     if (MODE >= 2) { v0 = v0 * rsvv; v1 = v1 * rsvv; }
;                     if (MODE == 3) { const f32x4 a0 = t0[m][bj], a1 = t1[m][bj]; f32x4 w0, w1;
;                         w0[0] = v0[0] * a0[0] - v0[1] * a0[1]; w0[1] = v0[1] * a0[0] + v0[0] * a0[1]; w0[2] = v0[2] * a0[2] - v0[3] * a0[3]; w0[3] = v0[3] * a0[2] + v0[2] * a0[3];
;                         w1[0] = v1[0] * a1[0] - v1[1] * a1[1]; w1[1] = v1[1] * a1[0] + v1[0] * a1[1]; w1[2] = v1[2] * a1[2] - v1[3] * a1[3]; w1[3] = v1[3] * a1[2] + v1[2] * a1[3];
;                         v0 = w0; v1 = w1; }
;                     u32x4 w; w.x = cvtpk(v0[0], v0[1]); w.y = cvtpk(v0[2], v0[3]); w.z = cvtpk(v1[0], v1[1]); w.w = cvtpk(v1[2], v1[3]);
;                     *(u32x4*)(rowp + bj * HALF) = w; } }
	v_cndmask_b32_e32 v97, 0, v97, vcc
	v_cndmask_b32_e32 v96, 1.0, v96, vcc
	v_cndmask_b32_e32 v101, 0, v101, vcc
	v_cndmask_b32_e32 v100, 1.0, v100, vcc
	v_cndmask_b32_e32 v99, 0, v99, vcc
	v_cndmask_b32_e32 v98, 1.0, v98, vcc
	v_pk_mul_f32 v[44:45], v[38:39], v[96:97]
	v_pk_mul_f32 v[38:39], v[38:39], v[96:97] op_sel:[1,0] op_sel_hi:[0,1]
	v_cndmask_b32_e32 v103, 0, v103, vcc
	v_cndmask_b32_e32 v102, 1.0, v102, vcc
	v_pk_mul_f32 v[42:43], v[40:41], v[98:99]
	v_sub_f32_e32 v0, v44, v45
	v_add_f32_e32 v44, v38, v39
	v_pk_mul_f32 v[38:39], v[40:41], v[98:99] op_sel:[1,0] op_sel_hi:[0,1]
	v_pk_mul_f32 v[40:41], v[34:35], v[100:101]
	v_pk_mul_f32 v[34:35], v[34:35], v[100:101] op_sel:[1,0] op_sel_hi:[0,1]
	v_sub_f32_e32 v42, v42, v43
	v_add_f32_e32 v43, v38, v39
	v_pk_mul_f32 v[38:39], v[36:37], v[102:103]
	v_sub_f32_e32 v40, v40, v41
	v_add_f32_e32 v41, v34, v35
	v_pk_mul_f32 v[34:35], v[36:37], v[102:103] op_sel:[1,0] op_sel_hi:[0,1]
	v_sub_f32_e32 v38, v38, v39
	v_add_f32_e32 v37, v34, v35
	v_cvt_pk_bf16_f32 v34, v0, v44
	v_cvt_pk_bf16_f32 v35, v42, v43
	v_cvt_pk_bf16_f32 v36, v40, v41
	v_cvt_pk_bf16_f32 v37, v38, v37
	v_add_u32_e32 v38, 0xa0, v146
	v_ashrrev_i32_e32 v39, 31, v38
	v_lshlrev_b64 v[40:41], 8, v[38:39]
	global_store_dwordx4 v[50:51], v[34:37], off offset:256
	v_lshl_add_u64 v[52:53], s[12:13], 0, v[40:41]
	v_lshl_add_u64 v[40:41], v[52:53], 0, v[140:141]
	global_load_dword v36, v[148:149], off offset:640
	global_load_dword v0, v[148:149], off offset:704
	global_load_dwordx4 v[44:47], v[40:41], off
	global_load_dwordx4 v[48:51], v[40:41], off offset:16
	v_add_u32_e32 v34, 0xb0, v146
	v_ashrrev_i32_e32 v35, 31, v34
	s_waitcnt vmcnt(0) lgkmcnt(0)
	v_pk_mul_f32 v[30:31], v[30:31], v[36:37] op_sel_hi:[1,0]
	v_pk_mul_f32 v[32:33], v[32:33], v[36:37] op_sel_hi:[1,0]
	v_cndmask_b32_e64 v41, 0, v51, s[4:5]
	v_cndmask_b32_e64 v40, 1.0, v50, s[4:5]
	v_cndmask_b32_e64 v51, 0, v45, s[4:5]
	v_cndmask_b32_e64 v50, 1.0, v44, s[4:5]
	v_lshl_add_u64 v[44:45], v[52:53], 0, v[138:139]
	global_load_dwordx4 v[52:55], v[44:45], off
	global_load_dwordx4 v[56:59], v[44:45], off offset:16
	v_cndmask_b32_e64 v43, 0, v49, s[4:5]
	v_cndmask_b32_e64 v42, 1.0, v48, s[4:5]
	v_cndmask_b32_e64 v49, 0, v47, s[4:5]
	v_cndmask_b32_e64 v48, 1.0, v46, s[4:5]
	v_pk_mul_f32 v[26:27], v[26:27], v[36:37] op_sel_hi:[1,0]
	v_pk_mul_f32 v[74:75], v[50:51], v[30:31]
	v_pk_mul_f32 v[30:31], v[50:51], v[30:31] op_sel:[0,1] op_sel_hi:[1,0]
	v_pk_mul_f32 v[28:29], v[28:29], v[36:37] op_sel_hi:[1,0]
	v_pk_mul_f32 v[72:73], v[48:49], v[32:33]
	v_add_f32_e32 v37, v30, v31
	v_pk_mul_f32 v[30:31], v[48:49], v[32:33] op_sel:[0,1] op_sel_hi:[1,0]
	v_pk_mul_f32 v[32:33], v[26:27], v[42:43]
	v_pk_mul_f32 v[26:27], v[26:27], v[42:43] op_sel:[1,0] op_sel_hi:[0,1]
	v_sub_f32_e32 v32, v32, v33
	v_add_f32_e32 v33, v26, v27
	v_pk_mul_f32 v[26:27], v[28:29], v[40:41] op_sel:[1,0] op_sel_hi:[0,1]
	v_add_f32_e32 v48, v30, v31
	v_pk_mul_f32 v[30:31], v[28:29], v[40:41]
	v_add_f32_e32 v29, v26, v27
	v_sub_f32_e32 v50, v72, v73
	v_sub_f32_e32 v30, v30, v31
	v_pk_mul_f32 v[22:23], v[22:23], v[36:37] op_sel_hi:[1,0]
	v_pk_mul_f32 v[24:25], v[24:25], v[36:37] op_sel_hi:[1,0]
	v_pk_mul_f32 v[18:19], v[18:19], v[36:37] op_sel_hi:[1,0]
	v_pk_mul_f32 v[20:21], v[20:21], v[36:37] op_sel_hi:[1,0]
	v_pk_mul_f32 v[14:15], v[14:15], v[0:1] op_sel_hi:[1,0]
	v_pk_mul_f32 v[16:17], v[16:17], v[0:1] op_sel_hi:[1,0]
	v_pk_mul_f32 v[10:11], v[10:11], v[0:1] op_sel_hi:[1,0]
	v_pk_mul_f32 v[12:13], v[12:13], v[0:1] op_sel_hi:[1,0]
	v_pk_mul_f32 v[6:7], v[6:7], v[0:1] op_sel_hi:[1,0]
	v_pk_mul_f32 v[8:9], v[8:9], v[0:1] op_sel_hi:[1,0]
	v_pk_mul_f32 v[2:3], v[2:3], v[0:1] op_sel_hi:[1,0]
	v_pk_mul_f32 v[4:5], v[4:5], v[0:1] op_sel_hi:[1,0]
	s_waitcnt vmcnt(0) lgkmcnt(0)
	v_cndmask_b32_e32 v55, 0, v55, vcc
	v_cndmask_b32_e32 v45, 0, v59, vcc
	v_cndmask_b32_e32 v44, 1.0, v58, vcc
	v_cndmask_b32_e32 v59, 0, v53, vcc
	v_cndmask_b32_e32 v58, 1.0, v52, vcc
	v_lshlrev_b64 v[52:53], 8, v[34:35]
	v_lshl_add_u64 v[70:71], s[12:13], 0, v[52:53]
	v_lshl_add_u64 v[52:53], v[70:71], 0, v[140:141]
	global_load_dwordx4 v[62:65], v[52:53], off
	global_load_dwordx4 v[66:69], v[52:53], off offset:16
	v_cndmask_b32_e32 v47, 0, v57, vcc
	v_cndmask_b32_e32 v46, 1.0, v56, vcc
	v_sub_f32_e32 v35, v74, v75
	v_cndmask_b32_e32 v54, 1.0, v54, vcc
	s_waitcnt vmcnt(0) lgkmcnt(0)
; #define PG8_BAR __builtin_amdgcn_s_barrier()
;     __device__ __forceinline__ void operator()(const f32x4 (&acc)[2][2][4][2], const Unit& u, int wr, int wc, int fr, int fq) const {
;     ...
;             for (int m = 2 * (am & 1); m < 2 * (am & 1) + 2; ++m) rsv[ai][m] = (MODE >= 2) ? rs[row0 + ai * HALF + m * 16] : 1.f;
;             if (MODE == 3) {
; #pragma unroll
;                 for (int m = 2 * (am & 1); m < 2 * (am & 1) + 2; ++m)
; #pragma unroll
;                     for (int bj = 0; bj < 2; ++bj) { const f32x4* tp = (const f32x4*)(tab + (size_t)(row0 + ai * HALF + m * 16) * 32 + i0[bj]); t0[m][bj] = tp[0]; t1[m][bj] = tp[1];
;                         if (!rot[bj]) { t0[m][bj] = (f32x4){1.f, 0.f, 1.f, 0.f}; t1[m][bj] = t0[m][bj]; } }
;                 asm volatile("" ::: "memory");
;             }
; #pragma unroll
;             for (int m = 2 * (am & 1); m < 2 * (am & 1) + 2; ++m) { const int row = row0 + ai * HALF + m * 16; bf16_t* rowp = O + (size_t)row * ldc + col0;
;                 const float rsvv = rsv[ai][m];
; #pragma unroll
;                 for (int bj = 0; bj < 2; ++bj) { f32x4 v0 = acc[ai][bj][m][0], v1 = acc[ai][bj][m][1];
;                     if (MODE == 1) {
; #pragma unroll
;                         for (int e = 0; e < 4; ++e) { float a = fmaxf(v0[e], 0.f), b = fmaxf(v1[e], 0.f); v0[e] = a * a; v1[e] = b * b; } }
;                     if (MODE >= 2) { v0 = v0 * rsvv; v1 = v1 * rsvv; }
;                     if (MODE == 3) { const f32x4 a0 = t0[m][bj], a1 = t1[m][bj]; f32x4 w0, w1;
;                         w0[0] = v0[0] * a0[0] - v0[1] * a0[1]; w0[1] = v0[1] * a0[0] + v0[0] * a0[1]; w0[2] = v0[2] * a0[2] - v0[3] * a0[3]; w0[3] = v0[3] * a0[2] + v0[2] * a0[3];
;                         w1[0] = v1[0] * a1[0] - v1[1] * a1[1]; w1[1] = v1[1] * a1[0] + v1[0] * a1[1]; w1[2] = v1[2] * a1[2] - v1[3] * a1[3]; w1[3] = v1[3] * a1[2] + v1[2] * a1[3];
;                         v0 = w0; v1 = w1; }
;                     u32x4 w; w.x = cvtpk(v0[0], v0[1]); w.y = cvtpk(v0[2], v0[3]); w.z = cvtpk(v1[0], v1[1]); w.w = cvtpk(v1[2], v1[3]);
;                     *(u32x4*)(rowp + bj * HALF) = w; } }
; template <class Epi>
; __device__ __forceinline__ void gemm_phase(LAS unsigned char* lds, const Gemm g, const StaticOrder& S, const Epi& E, int wave_s) {
;     ...
;         if (wr == 1) PG8_BAR;
	v_cndmask_b32_e64 v61, 0, v65, s[4:5]
	v_cndmask_b32_e64 v53, 0, v69, s[4:5]
	v_cndmask_b32_e64 v52, 1.0, v68, s[4:5]
	v_lshl_add_u64 v[68:69], v[70:71], 0, v[138:139]
	v_cndmask_b32_e64 v57, 0, v67, s[4:5]
	v_cndmask_b32_e64 v56, 1.0, v66, s[4:5]
	v_cndmask_b32_e64 v60, 1.0, v64, s[4:5]
	global_load_dwordx4 v[64:67], v[68:69], off
	s_nop 0
	global_load_dwordx4 v[68:71], v[68:69], off offset:16
	v_cndmask_b32_e64 v63, 0, v63, s[4:5]
	v_cndmask_b32_e64 v62, 1.0, v62, s[4:5]
	v_mad_i64_i32 v[38:39], s[4:5], v38, s24, v[142:143]
	v_lshl_add_u64 v[38:39], v[38:39], 0, v[144:145]
	v_cvt_pk_bf16_f32 v26, v35, v37
	v_cvt_pk_bf16_f32 v27, v50, v48
	v_cvt_pk_bf16_f32 v28, v32, v33
	v_cvt_pk_bf16_f32 v29, v30, v29
	global_store_dwordx4 v[38:39], v[26:29], off
	s_waitcnt vmcnt(0) lgkmcnt(0)
	v_cndmask_b32_e32 v65, 0, v65, vcc
	v_pk_mul_f32 v[28:29], v[22:23], v[58:59]
	v_pk_mul_f32 v[22:23], v[22:23], v[58:59] op_sel:[1,0] op_sel_hi:[0,1]
	v_pk_mul_f32 v[26:27], v[24:25], v[54:55]
	v_sub_f32_e32 v28, v28, v29
	v_add_f32_e32 v29, v22, v23
	v_pk_mul_f32 v[22:23], v[24:25], v[54:55] op_sel:[1,0] op_sel_hi:[0,1]
	v_pk_mul_f32 v[24:25], v[18:19], v[46:47]
	v_pk_mul_f32 v[18:19], v[18:19], v[46:47] op_sel:[1,0] op_sel_hi:[0,1]
	v_sub_f32_e32 v26, v26, v27
	v_add_f32_e32 v27, v22, v23
	v_pk_mul_f32 v[22:23], v[20:21], v[44:45]
	v_sub_f32_e32 v24, v24, v25
	v_add_f32_e32 v25, v18, v19
	v_pk_mul_f32 v[18:19], v[20:21], v[44:45] op_sel:[1,0] op_sel_hi:[0,1]
	v_sub_f32_e32 v22, v22, v23
	v_add_f32_e32 v21, v18, v19
	v_cvt_pk_bf16_f32 v18, v28, v29
	v_cvt_pk_bf16_f32 v19, v26, v27
	v_cvt_pk_bf16_f32 v20, v24, v25
	v_cvt_pk_bf16_f32 v21, v22, v21
	v_pk_mul_f32 v[22:23], v[14:15], v[62:63]
	v_pk_mul_f32 v[14:15], v[14:15], v[62:63] op_sel:[1,0] op_sel_hi:[0,1]
	global_store_dwordx4 v[38:39], v[18:21], off offset:256
	v_sub_f32_e32 v22, v22, v23
	v_add_f32_e32 v23, v14, v15
	v_pk_mul_f32 v[20:21], v[16:17], v[60:61]
	v_pk_mul_f32 v[14:15], v[16:17], v[60:61] op_sel:[1,0] op_sel_hi:[0,1]
	v_pk_mul_f32 v[16:17], v[10:11], v[56:57]
	v_pk_mul_f32 v[10:11], v[10:11], v[56:57] op_sel:[1,0] op_sel_hi:[0,1]
	v_sub_f32_e32 v16, v16, v17
	v_add_f32_e32 v17, v10, v11
	v_pk_mul_f32 v[10:11], v[12:13], v[52:53] op_sel:[1,0] op_sel_hi:[0,1]
	v_mad_i64_i32 v[18:19], s[4:5], v34, s24, v[142:143]
	v_sub_f32_e32 v20, v20, v21
	v_add_f32_e32 v21, v14, v15
	v_pk_mul_f32 v[14:15], v[12:13], v[52:53]
	v_add_f32_e32 v13, v10, v11
	v_cndmask_b32_e32 v64, 1.0, v64, vcc
	v_lshl_add_u64 v[18:19], v[18:19], 0, v[144:145]
	v_sub_f32_e32 v14, v14, v15
	v_cvt_pk_bf16_f32 v10, v22, v23
	v_cvt_pk_bf16_f32 v11, v20, v21
	v_cvt_pk_bf16_f32 v12, v16, v17
	v_cvt_pk_bf16_f32 v13, v14, v13
	v_cndmask_b32_e32 v69, 0, v69, vcc
	v_cndmask_b32_e32 v68, 1.0, v68, vcc
	v_cndmask_b32_e32 v67, 0, v67, vcc
	v_cndmask_b32_e32 v66, 1.0, v66, vcc
	global_store_dwordx4 v[18:19], v[10:13], off
	v_cndmask_b32_e32 v71, 0, v71, vcc
	v_cndmask_b32_e32 v70, 1.0, v70, vcc
	v_pk_mul_f32 v[12:13], v[6:7], v[64:65]
	v_pk_mul_f32 v[6:7], v[6:7], v[64:65] op_sel:[1,0] op_sel_hi:[0,1]
	v_pk_mul_f32 v[10:11], v[8:9], v[66:67]
	v_sub_f32_e32 v0, v12, v13
	v_add_f32_e32 v12, v6, v7
	v_pk_mul_f32 v[6:7], v[8:9], v[66:67] op_sel:[1,0] op_sel_hi:[0,1]
	v_pk_mul_f32 v[8:9], v[2:3], v[68:69]
	v_pk_mul_f32 v[2:3], v[2:3], v[68:69] op_sel:[1,0] op_sel_hi:[0,1]
	v_sub_f32_e32 v8, v8, v9
	v_add_f32_e32 v9, v2, v3
	v_pk_mul_f32 v[2:3], v[4:5], v[70:71] op_sel:[1,0] op_sel_hi:[0,1]
	v_sub_f32_e32 v10, v10, v11
	v_add_f32_e32 v11, v6, v7
	v_pk_mul_f32 v[6:7], v[4:5], v[70:71]
	v_add_f32_e32 v5, v2, v3
	v_sub_f32_e32 v6, v6, v7
	v_cvt_pk_bf16_f32 v2, v0, v12
	v_cvt_pk_bf16_f32 v3, v10, v11
	v_cvt_pk_bf16_f32 v4, v8, v9
	v_cvt_pk_bf16_f32 v5, v6, v5
	global_store_dwordx4 v[18:19], v[2:5], off offset:256
	s_mov_b64 s[4:5], -1
	s_and_b64 vcc, exec, s[0:1]
	s_cbranch_vccnz .LBB0_302
	s_andn2_b64 vcc, exec, s[6:7]
	s_cbranch_vccnz .LBB0_301
	s_barrier
	s_branch .LBB0_301

; __device__ __forceinline__ unsigned cvtpk(float lo, float hi) { unsigned r; asm volatile("v_cvt_pk_bf16_f32 %0, %1, %2" : "=v"(r) : "v"(lo), "v"(hi)); return r; }
;     __device__ __forceinline__ void operator()(const f32x4 (&acc)[2][2][4][2], const Unit& u, int wr, int wc, int fr, int fq) const {
;     ...
;             for (int m = 2 * (am & 1); m < 2 * (am & 1) + 2; ++m) rsv[ai][m] = (MODE >= 2) ? rs[row0 + ai * HALF + m * 16] : 1.f;
;             if (MODE == 3) {
; #pragma unroll
;                 for (int m = 2 * (am & 1); m < 2 * (am & 1) + 2; ++m)
; #pragma unroll
;                     for (int bj = 0; bj < 2; ++bj) { const f32x4* tp = (const f32x4*)(tab + (size_t)(row0 + ai * HALF + m * 16) * 32 + i0[bj]); t0[m][bj] = tp[0]; t1[m][bj] = tp[1];
;                         if (!rot[bj]) { t0[m][bj] = (f32x4){1.f, 0.f, 1.f, 0.f}; t1[m][bj] = t0[m][bj]; } }
;                 asm volatile("" ::: "memory");
;             }
; #pragma unroll
;             for (int m = 2 * (am & 1); m < 2 * (am & 1) + 2; ++m) { const int row = row0 + ai * HALF + m * 16; bf16_t* rowp = O + (size_t)row * ldc + col0;
;                 const float rsvv = rsv[ai][m];
; #pragma unroll
;                 for (int bj = 0; bj < 2; ++bj) { f32x4 v0 = acc[ai][bj][m][0], v1 = acc[ai][bj][m][1];
;                     if (MODE == 1) {
; #pragma unroll
;                         for (int e = 0; e < 4; ++e) { float a = fmaxf(v0[e], 0.f), b = fmaxf(v1[e], 0.f); v0[e] = a * a; v1[e] = b * b; } }
;                     if (MODE >= 2) { v0 = v0 * rsvv; v1 = v1 * rsvv; }
;                     if (MODE == 3) { const f32x4 a0 = t0[m][bj], a1 = t1[m][bj]; f32x4 w0, w1;
;                         w0[0] = v0[0] * a0[0] - v0[1] * a0[1]; w0[1] = v0[1] * a0[0] + v0[0] * a0[1]; w0[2] = v0[2] * a0[2] - v0[3] * a0[3]; w0[3] = v0[3] * a0[2] + v0[2] * a0[3];
;                         w1[0] = v1[0] * a1[0] - v1[1] * a1[1]; w1[1] = v1[1] * a1[0] + v1[0] * a1[1]; w1[2] = v1[2] * a1[2] - v1[3] * a1[3]; w1[3] = v1[3] * a1[2] + v1[2] * a1[3];
;                         v0 = w0; v1 = w1; }
;                     u32x4 w; w.x = cvtpk(v0[0], v0[1]); w.y = cvtpk(v0[2], v0[3]); w.z = cvtpk(v1[0], v1[1]); w.w = cvtpk(v1[2], v1[3]);
;                     *(u32x4*)(rowp + bj * HALF) = w; } }
.LBB0_331:
	s_lshl_b32 s4, s64, 8
	s_add_i32 s4, s4, s38
	v_mbcnt_lo_u32_b32 v136, -1, 0
	v_mbcnt_hi_u32_b32 v136, -1, v136
	s_nop 0
	v_and_or_b32 v142, v136, 15, s4
	v_ashrrev_i32_e32 v143, 31, v142
	v_lshl_add_u64 v[138:139], v[142:143], 2, s[10:11]
	global_load_dword v146, v[138:139], off
	v_or_b32_e32 v148, 16, v142
	v_ashrrev_i32_e32 v149, 31, v148
	v_lshl_add_u64 v[140:141], v[148:149], 2, s[10:11]
	global_load_dword v150, v[140:141], off
	v_lshrrev_b32_e32 v136, 1, v136
	s_lshl_b32 s4, s57, 8
	v_and_or_b32 v136, v136, 24, s4
	v_or_b32_e32 v136, s39, v136
	v_ashrrev_i32_e32 v137, 31, v136
	v_lshlrev_b64 v[140:141], 11, v[142:143]
	v_lshl_add_u64 v[152:153], s[8:9], 0, v[140:141]
	v_lshlrev_b64 v[140:141], 1, v[136:137]
	v_lshl_add_u64 v[136:137], v[152:153], 0, v[140:141]
	s_mov_b64 s[4:5], 0x40000
	s_waitcnt vmcnt(0) lgkmcnt(0)
	v_pk_mul_f32 v[114:115], v[114:115], v[146:147] op_sel_hi:[1,0]
	v_pk_mul_f32 v[116:117], v[116:117], v[146:147] op_sel_hi:[1,0]
	v_cvt_pk_bf16_f32 v114, v114, v115
	v_pk_mul_f32 v[120:121], v[120:121], v[146:147] op_sel_hi:[1,0]
	v_cvt_pk_bf16_f32 v115, v116, v117
	v_pk_mul_f32 v[118:119], v[118:119], v[146:147] op_sel_hi:[1,0]
	v_pk_mul_f32 v[98:99], v[98:99], v[150:151] op_sel_hi:[1,0]
	v_cvt_pk_bf16_f32 v116, v118, v119
	v_cvt_pk_bf16_f32 v117, v120, v121
	global_store_dwordx4 v[136:137], v[114:117], off
	v_pk_mul_f32 v[118:119], v[128:129], v[146:147] op_sel_hi:[1,0]
	v_pk_mul_f32 v[120:121], v[126:127], v[146:147] op_sel_hi:[1,0]
	v_pk_mul_f32 v[114:115], v[122:123], v[146:147] op_sel_hi:[1,0]
	v_pk_mul_f32 v[116:117], v[124:125], v[146:147] op_sel_hi:[1,0]
	v_cvt_pk_bf16_f32 v114, v114, v115
	v_pk_mul_f32 v[100:101], v[100:101], v[150:151] op_sel_hi:[1,0]
	v_cvt_pk_bf16_f32 v115, v116, v117
	v_cvt_pk_bf16_f32 v116, v120, v121
	v_cvt_pk_bf16_f32 v117, v118, v119
	global_store_dwordx4 v[136:137], v[114:117], off offset:256
	v_cvt_pk_bf16_f32 v98, v98, v99
	v_cvt_pk_bf16_f32 v99, v100, v101
	v_pk_mul_f32 v[104:105], v[104:105], v[150:151] op_sel_hi:[1,0]
	v_pk_mul_f32 v[102:103], v[102:103], v[150:151] op_sel_hi:[1,0]
	v_lshlrev_b64 v[114:115], 11, v[148:149]
	v_lshl_add_u64 v[114:115], s[8:9], 0, v[114:115]
	v_lshl_add_u64 v[114:115], v[114:115], 0, v[140:141]
	v_cvt_pk_bf16_f32 v100, v102, v103
	v_cvt_pk_bf16_f32 v101, v104, v105
	global_store_dwordx4 v[114:115], v[98:101], off
	v_pk_mul_f32 v[102:103], v[112:113], v[150:151] op_sel_hi:[1,0]
	v_pk_mul_f32 v[104:105], v[110:111], v[150:151] op_sel_hi:[1,0]
	v_pk_mul_f32 v[98:99], v[106:107], v[150:151] op_sel_hi:[1,0]
	v_pk_mul_f32 v[100:101], v[108:109], v[150:151] op_sel_hi:[1,0]
	v_cvt_pk_bf16_f32 v98, v98, v99
	s_nop 0
	v_cvt_pk_bf16_f32 v99, v100, v101
	v_cvt_pk_bf16_f32 v100, v104, v105
	v_cvt_pk_bf16_f32 v101, v102, v103
	global_store_dwordx4 v[114:115], v[98:101], off offset:256
	v_or_b32_e32 v102, 48, v142
	v_ashrrev_i32_e32 v103, 31, v102
	v_or_b32_e32 v98, 32, v142
	v_ashrrev_i32_e32 v99, 31, v98
	v_lshl_add_u64 v[100:101], v[98:99], 2, s[10:11]
	global_load_dword v100, v[100:101], off
	v_lshl_add_u64 v[104:105], v[102:103], 2, s[10:11]
	global_load_dword v104, v[104:105], off
	v_lshlrev_b64 v[98:99], 11, v[98:99]
	v_lshl_add_u64 v[98:99], s[8:9], 0, v[98:99]
	v_lshl_add_u64 v[98:99], v[98:99], 0, v[140:141]
	s_waitcnt vmcnt(0) lgkmcnt(0)
	v_pk_mul_f32 v[82:83], v[82:83], v[100:101] op_sel_hi:[1,0]
	v_pk_mul_f32 v[84:85], v[84:85], v[100:101] op_sel_hi:[1,0]
	v_cvt_pk_bf16_f32 v82, v82, v83
	v_pk_mul_f32 v[88:89], v[88:89], v[100:101] op_sel_hi:[1,0]
	v_cvt_pk_bf16_f32 v83, v84, v85
	v_pk_mul_f32 v[86:87], v[86:87], v[100:101] op_sel_hi:[1,0]
	v_pk_mul_f32 v[80:81], v[80:81], v[104:105] op_sel_hi:[1,0]
	v_cvt_pk_bf16_f32 v84, v86, v87
	v_cvt_pk_bf16_f32 v85, v88, v89
	global_store_dwordx4 v[98:99], v[82:85], off
	v_pk_mul_f32 v[86:87], v[96:97], v[100:101] op_sel_hi:[1,0]
	v_pk_mul_f32 v[88:89], v[94:95], v[100:101] op_sel_hi:[1,0]
	v_pk_mul_f32 v[82:83], v[90:91], v[100:101] op_sel_hi:[1,0]
	v_pk_mul_f32 v[84:85], v[92:93], v[100:101] op_sel_hi:[1,0]
	v_cvt_pk_bf16_f32 v82, v82, v83
	v_pk_mul_f32 v[78:79], v[78:79], v[104:105] op_sel_hi:[1,0]
	v_cvt_pk_bf16_f32 v83, v84, v85
	v_cvt_pk_bf16_f32 v84, v88, v89
	v_cvt_pk_bf16_f32 v85, v86, v87
	global_store_dwordx4 v[98:99], v[82:85], off offset:256
	v_pk_mul_f32 v[72:73], v[72:73], v[104:105] op_sel_hi:[1,0]
	v_pk_mul_f32 v[70:71], v[70:71], v[104:105] op_sel_hi:[1,0]
	v_lshlrev_b64 v[82:83], 11, v[102:103]
	v_lshl_add_u64 v[82:83], s[8:9], 0, v[82:83]
	v_lshl_add_u64 v[82:83], v[82:83], 0, v[140:141]
	v_pk_mul_f32 v[84:85], v[76:77], v[104:105] op_sel_hi:[1,0]
	v_pk_mul_f32 v[76:77], v[74:75], v[104:105] op_sel_hi:[1,0]
	v_cvt_pk_bf16_f32 v74, v78, v79
	v_cvt_pk_bf16_f32 v75, v80, v81
	s_nop 0
	v_cvt_pk_bf16_f32 v76, v76, v77
	v_cvt_pk_bf16_f32 v77, v84, v85
	global_store_dwordx4 v[82:83], v[74:77], off
	s_nop 1
	v_pk_mul_f32 v[74:75], v[68:69], v[104:105] op_sel_hi:[1,0]
	v_pk_mul_f32 v[68:69], v[66:67], v[104:105] op_sel_hi:[1,0]
	v_cvt_pk_bf16_f32 v66, v70, v71
	v_cvt_pk_bf16_f32 v67, v72, v73
	v_lshl_add_u64 v[70:71], v[136:137], 0, s[4:5]
	v_cvt_pk_bf16_f32 v68, v68, v69
	v_cvt_pk_bf16_f32 v69, v74, v75
	global_store_dwordx4 v[82:83], v[66:69], off offset:256
	global_load_dword v68, v[138:139], off offset:512
	global_load_dword v66, v[138:139], off offset:576
	s_mov_b32 s4, 0x40000
	s_waitcnt vmcnt(0) lgkmcnt(0)
; #define PG8_BAR __builtin_amdgcn_s_barrier()
;     __device__ __forceinline__ void operator()(const f32x4 (&acc)[2][2][4][2], const Unit& u, int wr, int wc, int fr, int fq) const {
;     ...
;             for (int m = 2 * (am & 1); m < 2 * (am & 1) + 2; ++m) rsv[ai][m] = (MODE >= 2) ? rs[row0 + ai * HALF + m * 16] : 1.f;
;             if (MODE == 3) {
; #pragma unroll
;                 for (int m = 2 * (am & 1); m < 2 * (am & 1) + 2; ++m)
; #pragma unroll
;                     for (int bj = 0; bj < 2; ++bj) { const f32x4* tp = (const f32x4*)(tab + (size_t)(row0 + ai * HALF + m * 16) * 32 + i0[bj]); t0[m][bj] = tp[0]; t1[m][bj] = tp[1];
;                         if (!rot[bj]) { t0[m][bj] = (f32x4){1.f, 0.f, 1.f, 0.f}; t1[m][bj] = t0[m][bj]; } }
;                 asm volatile("" ::: "memory");
;             }
; #pragma unroll
;             for (int m = 2 * (am & 1); m < 2 * (am & 1) + 2; ++m) { const int row = row0 + ai * HALF + m * 16; bf16_t* rowp = O + (size_t)row * ldc + col0;
;                 const float rsvv = rsv[ai][m];
; #pragma unroll
;                 for (int bj = 0; bj < 2; ++bj) { f32x4 v0 = acc[ai][bj][m][0], v1 = acc[ai][bj][m][1];
;                     if (MODE == 1) {
; #pragma unroll
;                         for (int e = 0; e < 4; ++e) { float a = fmaxf(v0[e], 0.f), b = fmaxf(v1[e], 0.f); v0[e] = a * a; v1[e] = b * b; } }
;                     if (MODE >= 2) { v0 = v0 * rsvv; v1 = v1 * rsvv; }
;                     if (MODE == 3) { const f32x4 a0 = t0[m][bj], a1 = t1[m][bj]; f32x4 w0, w1;
;                         w0[0] = v0[0] * a0[0] - v0[1] * a0[1]; w0[1] = v0[1] * a0[0] + v0[0] * a0[1]; w0[2] = v0[2] * a0[2] - v0[3] * a0[3]; w0[3] = v0[3] * a0[2] + v0[2] * a0[3];
;                         w1[0] = v1[0] * a1[0] - v1[1] * a1[1]; w1[1] = v1[1] * a1[0] + v1[0] * a1[1]; w1[2] = v1[2] * a1[2] - v1[3] * a1[3]; w1[3] = v1[3] * a1[2] + v1[2] * a1[3];
;                         v0 = w0; v1 = w1; }
;                     u32x4 w; w.x = cvtpk(v0[0], v0[1]); w.y = cvtpk(v0[2], v0[3]); w.z = cvtpk(v1[0], v1[1]); w.w = cvtpk(v1[2], v1[3]);
;                     *(u32x4*)(rowp + bj * HALF) = w; } }
; template <class Epi>
; __device__ __forceinline__ void gemm_phase(LAS unsigned char* lds, const Gemm g, const StaticOrder& S, const Epi& E, int wave_s) {
;     ...
;         if (wr == 1) PG8_BAR;
	v_pk_mul_f32 v[60:61], v[60:61], v[68:69] op_sel_hi:[1,0]
	v_pk_mul_f32 v[58:59], v[58:59], v[68:69] op_sel_hi:[1,0]
	v_pk_mul_f32 v[62:63], v[62:63], v[68:69] op_sel_hi:[1,0]
	v_cvt_pk_bf16_f32 v58, v58, v59
	v_cvt_pk_bf16_f32 v59, v60, v61
	v_pk_mul_f32 v[50:51], v[50:51], v[68:69] op_sel_hi:[1,0]
	v_cvt_pk_bf16_f32 v60, v62, v63
	v_add_co_u32_e32 v62, vcc, s4, v136
	v_pk_mul_f32 v[64:65], v[64:65], v[68:69] op_sel_hi:[1,0]
	s_nop 0
	v_addc_co_u32_e32 v63, vcc, 0, v137, vcc
	v_cvt_pk_bf16_f32 v61, v64, v65
	global_store_dwordx4 v[62:63], v[58:61], off
	v_pk_mul_f32 v[52:53], v[52:53], v[68:69] op_sel_hi:[1,0]
	v_cvt_pk_bf16_f32 v50, v50, v51
	s_mov_b64 s[4:5], 0x48000
	v_cvt_pk_bf16_f32 v51, v52, v53
	v_pk_mul_f32 v[56:57], v[56:57], v[68:69] op_sel_hi:[1,0]
	v_pk_mul_f32 v[54:55], v[54:55], v[68:69] op_sel_hi:[1,0]
	v_pk_mul_f32 v[44:45], v[44:45], v[66:67] op_sel_hi:[1,0]
	v_cvt_pk_bf16_f32 v52, v54, v55
	v_cvt_pk_bf16_f32 v53, v56, v57
	global_store_dwordx4 v[70:71], v[50:53], off offset:256
	v_pk_mul_f32 v[42:43], v[42:43], v[66:67] op_sel_hi:[1,0]
	v_pk_mul_f32 v[46:47], v[46:47], v[66:67] op_sel_hi:[1,0]
	v_lshl_add_u64 v[50:51], v[136:137], 0, s[4:5]
	s_mov_b32 s4, 0x48000
	v_cvt_pk_bf16_f32 v42, v42, v43
	v_cvt_pk_bf16_f32 v43, v44, v45
	v_cvt_pk_bf16_f32 v44, v46, v47
	v_add_co_u32_e32 v46, vcc, s4, v136
	v_pk_mul_f32 v[48:49], v[48:49], v[66:67] op_sel_hi:[1,0]
	s_nop 0
	v_addc_co_u32_e32 v47, vcc, 0, v137, vcc
	v_cvt_pk_bf16_f32 v45, v48, v49
	global_store_dwordx4 v[46:47], v[42:45], off
	v_pk_mul_f32 v[40:41], v[40:41], v[66:67] op_sel_hi:[1,0]
	v_pk_mul_f32 v[38:39], v[38:39], v[66:67] op_sel_hi:[1,0]
	v_pk_mul_f32 v[42:43], v[36:37], v[66:67] op_sel_hi:[1,0]
	v_pk_mul_f32 v[36:37], v[34:35], v[66:67] op_sel_hi:[1,0]
	v_cvt_pk_bf16_f32 v34, v38, v39
	v_cvt_pk_bf16_f32 v35, v40, v41
	s_mov_b64 s[4:5], 0x50000
	v_cvt_pk_bf16_f32 v36, v36, v37
	v_cvt_pk_bf16_f32 v37, v42, v43
	global_store_dwordx4 v[50:51], v[34:37], off offset:256
	global_load_dword v36, v[138:139], off offset:640
	global_load_dword v34, v[138:139], off offset:704
	v_lshl_add_u64 v[38:39], v[136:137], 0, s[4:5]
	s_mov_b32 s4, 0x50000
	s_waitcnt vmcnt(0) lgkmcnt(0)
	v_pk_mul_f32 v[28:29], v[28:29], v[36:37] op_sel_hi:[1,0]
	v_pk_mul_f32 v[26:27], v[26:27], v[36:37] op_sel_hi:[1,0]
	v_pk_mul_f32 v[30:31], v[30:31], v[36:37] op_sel_hi:[1,0]
	v_cvt_pk_bf16_f32 v26, v26, v27
	v_cvt_pk_bf16_f32 v27, v28, v29
	v_pk_mul_f32 v[18:19], v[18:19], v[36:37] op_sel_hi:[1,0]
	v_cvt_pk_bf16_f32 v28, v30, v31
	v_add_co_u32_e32 v30, vcc, s4, v136
	v_pk_mul_f32 v[32:33], v[32:33], v[36:37] op_sel_hi:[1,0]
	s_nop 0
	v_addc_co_u32_e32 v31, vcc, 0, v137, vcc
	v_cvt_pk_bf16_f32 v29, v32, v33
	global_store_dwordx4 v[30:31], v[26:29], off
	v_pk_mul_f32 v[20:21], v[20:21], v[36:37] op_sel_hi:[1,0]
	v_cvt_pk_bf16_f32 v18, v18, v19
	s_mov_b64 s[4:5], 0x58000
	v_cvt_pk_bf16_f32 v19, v20, v21
	v_pk_mul_f32 v[24:25], v[24:25], v[36:37] op_sel_hi:[1,0]
	v_pk_mul_f32 v[22:23], v[22:23], v[36:37] op_sel_hi:[1,0]
	v_pk_mul_f32 v[12:13], v[12:13], v[34:35] op_sel_hi:[1,0]
	v_cvt_pk_bf16_f32 v20, v22, v23
	v_cvt_pk_bf16_f32 v21, v24, v25
	global_store_dwordx4 v[38:39], v[18:21], off offset:256
	v_pk_mul_f32 v[10:11], v[10:11], v[34:35] op_sel_hi:[1,0]
	v_pk_mul_f32 v[14:15], v[14:15], v[34:35] op_sel_hi:[1,0]
	v_lshl_add_u64 v[18:19], v[136:137], 0, s[4:5]
	s_mov_b32 s4, 0x58000
	v_cvt_pk_bf16_f32 v10, v10, v11
	v_cvt_pk_bf16_f32 v11, v12, v13
	v_cvt_pk_bf16_f32 v12, v14, v15
	v_add_co_u32_e32 v14, vcc, s4, v136
	v_pk_mul_f32 v[16:17], v[16:17], v[34:35] op_sel_hi:[1,0]
	s_nop 0
	v_addc_co_u32_e32 v15, vcc, 0, v137, vcc
	v_cvt_pk_bf16_f32 v13, v16, v17
	global_store_dwordx4 v[14:15], v[10:13], off
	v_pk_mul_f32 v[8:9], v[8:9], v[34:35] op_sel_hi:[1,0]
	v_pk_mul_f32 v[6:7], v[6:7], v[34:35] op_sel_hi:[1,0]
	v_pk_mul_f32 v[10:11], v[4:5], v[34:35] op_sel_hi:[1,0]
	v_pk_mul_f32 v[4:5], v[2:3], v[34:35] op_sel_hi:[1,0]
	v_cvt_pk_bf16_f32 v2, v6, v7
	v_cvt_pk_bf16_f32 v3, v8, v9
	s_mov_b64 s[4:5], -1
	v_cvt_pk_bf16_f32 v4, v4, v5
	v_cvt_pk_bf16_f32 v5, v10, v11
	global_store_dwordx4 v[18:19], v[2:5], off offset:256
	s_and_b64 vcc, exec, s[0:1]
	s_cbranch_vccnz .LBB0_320
	s_andn2_b64 vcc, exec, s[6:7]
	s_cbranch_vccnz .LBB0_319
	s_barrier
	s_branch .LBB0_319

; __device__ __forceinline__ int tid_of(int wave_s) { int l; asm volatile("v_mbcnt_lo_u32_b32 %0, -1, 0\n\tv_mbcnt_hi_u32_b32 %0, -1, %0" : "=v"(l)); return wave_s * 64 + l; }
; __device__ __forceinline__ int crow(int r, int hi) { return (r & 3) + 8 * (r >> 2) + 4 * hi; }
; template <int NQ, int MODE> ...
;     ...
;     for (int r = 0; r < 16; ++r) { const float rl = __builtin_amdgcn_rcpf(RSM ? lacc[r] : li_l[crow(r, hi)]);
; #pragma unroll
;         for (int d = 0; d < 4; ++d) o[d][r] *= rl; }
; __global__ void __launch_bounds__(NTHR, 2) mega_fwd(Args a) {
;     ...
;               const int lane2 = tid_of(wave_s) & 63, r32b = lane2 & 31;
;               const float* scrq = DSCR + ((size_t)(u * 8 + wave_s) * 64) * 64 + lane2; asm volatile("" : "+v"(scrq) :: "memory");
;               const float lam = LAM[lq]; const float* gs = SMV + SM_DS + lq * 128; const float post = 1.f - (0.8f - 0.6f * expf(-0.3f * (float)lq));
;               float gv[4];
; #pragma unroll
;               for (int d0 = 0; d0 < 4; ++d0) gv[d0] = gs[d0 * 32 + r32b] * post;
; #pragma unroll
;               for (int r = 0; r < 16; ++r) { float ss = 0.f;
; #pragma unroll
;                   for (int d0 = 0; d0 < 4; ++d0) { const float dv = scrq[(d0 * 16 + r) * 64] - lam * o[d0][r]; o[d0][r] = dv; ss += dv * dv; }
;                   ss = half_sum(ss);
;                   const float rstd = 1.0f / sqrtf(ss * (1.f / 128.f) + EPS);
.LBB0_383:
	s_or_b64 exec, exec, s[0:1]
	v_rcp_f32_e32 v0, v80
	s_waitcnt lgkmcnt(0)
	s_ashr_i32 s31, s30, 31
	s_lshl_b64 s[0:1], s[30:31], 2
	v_mul_f32_e32 v4, v0, v64
	v_mul_f32_e32 v6, v0, v48
	v_mul_f32_e32 v8, v0, v32
	s_nop 2
	v_mul_f32_e32 v118, v0, v16
	v_rcp_f32_e32 v0, v81
	s_add_u32 s0, s28, s0
	s_addc_u32 s1, s29, s1
	v_mov_b64_e32 v[14:15], s[0:1]
	v_mul_f32_e32 v116, v0, v65
	v_mul_f32_e32 v117, v0, v49
	v_mul_f32_e32 v115, v0, v33
	v_mul_f32_e32 v114, v0, v17
	v_rcp_f32_e32 v0, v82
	s_mov_b32 s4, 0x3fb8aa3b
	s_lshl_b32 s0, s30, 7
	s_ashr_i32 s1, s0, 31
	v_mul_f32_e32 v112, v0, v66
	v_mul_f32_e32 v113, v0, v50
	v_mul_f32_e32 v33, v0, v34
	v_mul_f32_e32 v32, v0, v18
	v_rcp_f32_e32 v0, v83
	s_lshl_b64 s[0:1], s[0:1], 2
	s_add_u32 s0, s28, s0
	s_addc_u32 s1, s29, s1
	v_mul_f32_e32 v110, v0, v67
	v_mul_f32_e32 v111, v0, v51
	v_mul_f32_e32 v109, v0, v35
	v_mul_f32_e32 v108, v0, v19
	v_rcp_f32_e32 v0, v84
	s_add_i32 s41, s41, s62
	v_mul_f32_e32 v107, v0, v68
	v_mul_f32_e32 v106, v0, v52
	v_mul_f32_e32 v105, v0, v36
	v_mul_f32_e32 v104, v0, v20
	v_rcp_f32_e32 v0, v85
	s_nop 0
	v_mul_f32_e32 v102, v0, v69
	v_mul_f32_e32 v103, v0, v53
	v_mul_f32_e32 v101, v0, v37
	v_mul_f32_e32 v100, v0, v21
	v_rcp_f32_e32 v0, v86
	s_nop 0
	v_mul_f32_e32 v98, v0, v70
	v_mul_f32_e32 v99, v0, v54
	v_mul_f32_e32 v97, v0, v38
	v_mul_f32_e32 v96, v0, v22
	v_rcp_f32_e32 v0, v87
	s_nop 0
	v_mul_f32_e32 v85, v0, v71
	v_mul_f32_e32 v86, v0, v55
	v_mul_f32_e32 v84, v0, v39
	v_mul_f32_e32 v71, v0, v23
	v_rcp_f32_e32 v0, v88
	s_nop 0
	v_mul_f32_e32 v83, v0, v72
	v_mul_f32_e32 v82, v0, v56
	v_mul_f32_e32 v81, v0, v40
	v_mul_f32_e32 v80, v0, v24
	v_rcp_f32_e32 v0, v89
	s_nop 0
	v_mul_f32_e32 v69, v0, v73
	v_mul_f32_e32 v70, v0, v57
	v_mul_f32_e32 v68, v0, v41
	v_mul_f32_e32 v67, v0, v25
	v_rcp_f32_e32 v0, v90
	s_nop 0
	v_mul_f32_e32 v65, v0, v74
	v_mul_f32_e32 v66, v0, v58
	v_mul_f32_e32 v64, v0, v42
	v_mul_f32_e32 v58, v0, v26
	v_rcp_f32_e32 v0, v91
	s_nop 0
	v_mul_f32_e32 v52, v0, v75
	v_mul_f32_e32 v53, v0, v59
	v_mul_f32_e32 v51, v0, v43
	v_mul_f32_e32 v50, v0, v27
	v_rcp_f32_e32 v0, v92
	s_nop 0
	v_mul_f32_e32 v49, v0, v76
	v_mul_f32_e32 v48, v0, v60
	v_mul_f32_e32 v43, v0, v44
	v_mul_f32_e32 v42, v0, v28
	v_rcp_f32_e32 v0, v93
	s_nop 0
	v_mul_f32_e32 v36, v0, v77
	v_mul_f32_e32 v37, v0, v61
	v_mul_f32_e32 v35, v0, v45
	v_mul_f32_e32 v34, v0, v29
	v_rcp_f32_e32 v0, v94
	s_nop 0
	v_mul_f32_e32 v28, v0, v78
	v_mul_f32_e32 v29, v0, v62
	v_mul_f32_e32 v27, v0, v46
	v_mul_f32_e32 v26, v0, v30
	v_rcp_f32_e32 v0, v95
	s_nop 0
	v_mul_f32_e32 v12, v0, v79
	v_mul_f32_e32 v13, v0, v63
	v_mul_f32_e32 v11, v0, v47
	v_mul_f32_e32 v10, v0, v31
	v_mbcnt_lo_u32_b32 v0, -1, 0
	v_mbcnt_hi_u32_b32 v0, -1, v0
	s_nop 0
	v_and_b32_e32 v2, 63, v0
	v_and_b32_e32 v5, 31, v0
	v_lshlrev_b32_e32 v0, 2, v2
	v_lshl_add_u64 v[2:3], s[20:21], 0, v[0:1]
	v_cvt_f32_i32_e32 v0, s30
	global_load_dword v17, v[14:15], off
	v_mul_f32_e32 v0, 0xbe99999a, v0
	v_mul_f32_e32 v7, 0x3fb8aa3b, v0
	v_fma_f32 v9, v0, s4, -v7
	v_rndne_f32_e32 v14, v7
	v_fmac_f32_e32 v9, 0x32a5705f, v0
	v_sub_f32_e32 v7, v7, v14
	v_add_f32_e32 v7, v7, v9
	v_exp_f32_e32 v7, v7
	v_cvt_i32_f32_e32 v9, v14
	s_mov_b32 s4, 0xc2ce8ed0
	v_cmp_ngt_f32_e32 vcc, s4, v0
	s_mov_b32 s4, 0x42b17218
	v_ldexp_f32 v7, v7, v9
	v_cndmask_b32_e32 v7, 0, v7, vcc
	v_cmp_nlt_f32_e32 vcc, s4, v0
	v_mov_b32_e32 v0, 0x7f800000
	s_nop 0
	v_cndmask_b32_e32 v0, v0, v7, vcc
	v_mov_b32_e32 v7, 0xbf4ccccd
	v_fmamk_f32 v0, v0, 0x3f19999a, v7
	v_add_f32_e32 v7, 1.0, v0
	v_lshlrev_b32_e32 v0, 2, v5
	v_lshl_add_u64 v[14:15], s[0:1], 0, v[0:1]
	s_mov_b64 s[0:1], 0x2a800
	v_lshl_add_u64 v[18:19], v[14:15], 0, s[0:1]
	s_mov_b32 s0, 0x2a000
	v_add_co_u32_e32 v14, vcc, s0, v14
	global_load_dword v5, v[18:19], off offset:128
	s_nop 0
	v_addc_co_u32_e32 v15, vcc, 0, v15, vcc
	global_load_dword v0, v[14:15], off offset:2048
	s_movk_i32 s0, 0x1000
	s_waitcnt vmcnt(0) lgkmcnt(0)
	v_mul_f32_e32 v14, v7, v5
	global_load_dword v5, v[18:19], off offset:256
	v_mul_f32_e32 v0, v7, v0
	s_waitcnt vmcnt(0) lgkmcnt(0)
	v_mul_f32_e32 v15, v7, v5
	global_load_dword v5, v[18:19], off offset:384
	s_waitcnt vmcnt(0) lgkmcnt(0)
	v_mul_f32_e32 v16, v7, v5
	global_load_dword v5, v[2:3], off
	s_waitcnt vmcnt(0) lgkmcnt(0)
	v_fma_f32 v18, -v17, v4, v5
	v_add_co_u32_e32 v4, vcc, s0, v2
	s_movk_i32 s0, 0x2000
	s_nop 0
	v_addc_co_u32_e32 v5, vcc, 0, v3, vcc
	global_load_dword v7, v[4:5], off
	s_waitcnt vmcnt(0) lgkmcnt(0)
	v_fma_f32 v19, -v17, v6, v7
	v_add_co_u32_e32 v6, vcc, s0, v2
	s_movk_i32 s0, 0x3000
	s_nop 0
	v_addc_co_u32_e32 v7, vcc, 0, v3, vcc
	global_load_dword v9, v[6:7], off
	v_mul_f32_e32 v20, v19, v19
	v_fmac_f32_e32 v20, v18, v18
	s_waitcnt vmcnt(0) lgkmcnt(0)
	v_fma_f32 v22, -v17, v8, v9
	v_add_co_u32_e32 v8, vcc, s0, v2
	v_fmac_f32_e32 v20, v22, v22
	s_nop 0
	v_addc_co_u32_e32 v9, vcc, 0, v3, vcc
	global_load_dword v21, v[8:9], off
	s_waitcnt vmcnt(0) lgkmcnt(0)
	v_fma_f32 v23, -v17, v118, v21
	v_fmac_f32_e32 v20, v23, v23
	ds_swizzle_b32 v21, v20 offset:swizzle(SWAP,1)
	s_waitcnt lgkmcnt(0)
	v_add_f32_e32 v20, v20, v21
	ds_swizzle_b32 v21, v20 offset:swizzle(SWAP,2)
	s_waitcnt lgkmcnt(0)
	v_add_f32_e32 v20, v20, v21
	ds_swizzle_b32 v21, v20 offset:swizzle(SWAP,4)
	s_waitcnt lgkmcnt(0)
	v_add_f32_e32 v20, v20, v21
	ds_swizzle_b32 v21, v20 offset:swizzle(SWAP,8)
	s_waitcnt lgkmcnt(0)
	v_add_f32_e32 v20, v20, v21
	ds_swizzle_b32 v21, v20 offset:swizzle(SWAP,16)
	s_waitcnt lgkmcnt(0)
; __global__ void __launch_bounds__(NTHR, 2) mega_fwd(Args a) {
;     ...
;               for (int r = 0; r < 16; ++r) { float ss = 0.f;
; #pragma unroll
;                   for (int d0 = 0; d0 < 4; ++d0) { const float dv = scrq[(d0 * 16 + r) * 64] - lam * o[d0][r]; o[d0][r] = dv; ss += dv * dv; }
;                   ss = half_sum(ss);
;                   const float rstd = 1.0f / sqrtf(ss * (1.f / 128.f) + EPS);
; #pragma unroll
;                   for (int d0 = 0; d0 < 4; ++d0) o[d0][r] *= rstd * gv[d0];
;                   if ((r & 3) == 3) asm volatile("" ::: "memory"); }
	v_add_f32_e32 v20, v20, v21
	v_fmamk_f32 v20, v20, 0x3c000000, v218
	v_cmp_gt_f32_e32 vcc, s68, v20
	v_mul_f32_e32 v21, 0x4f800000, v20
	s_nop 0
	v_cndmask_b32_e32 v20, v20, v21, vcc
	v_sqrt_f32_e32 v21, v20
	s_nop 0
	v_add_u32_e32 v24, -1, v21
	v_fma_f32 v25, -v24, v21, v20
	v_cmp_ge_f32_e64 s[0:1], 0, v25
	v_add_u32_e32 v25, 1, v21
	s_nop 0
	v_cndmask_b32_e64 v24, v21, v24, s[0:1]
	v_fma_f32 v21, -v25, v21, v20
	v_cmp_lt_f32_e64 s[0:1], 0, v21
	s_nop 1
	v_cndmask_b32_e64 v21, v24, v25, s[0:1]
	v_mul_f32_e32 v24, 0x37800000, v21
	v_cndmask_b32_e32 v21, v21, v24, vcc
	v_cmp_class_f32_e32 vcc, v20, v219
	s_nop 1
	v_cndmask_b32_e32 v20, v21, v20, vcc
	v_div_scale_f32 v21, s[0:1], v20, v20, 1.0
	v_rcp_f32_e32 v24, v21
	s_nop 0
	v_fma_f32 v25, -v21, v24, 1.0
	v_fmac_f32_e32 v24, v25, v24
	v_div_scale_f32 v25, vcc, 1.0, v20, 1.0
	v_mul_f32_e32 v30, v25, v24
	v_fma_f32 v31, -v21, v30, v25
	v_fmac_f32_e32 v30, v31, v24
	v_fma_f32 v21, -v21, v30, v25
	v_div_fmas_f32 v21, v21, v24, v30
	v_div_fixup_f32 v24, v21, v20, 1.0
	v_mul_f32_e32 v20, v24, v0
	v_mul_f32_e32 v21, v20, v18
	v_mul_f32_e32 v18, v24, v14
	v_mul_f32_e32 v20, v18, v19
	v_mul_f32_e32 v18, v24, v15
	v_mul_f32_e32 v19, v18, v22
	v_mul_f32_e32 v18, v24, v16
	v_mul_f32_e32 v18, v18, v23
	global_load_dword v22, v[8:9], off offset:256
	global_load_dword v23, v[6:7], off offset:256
	global_load_dword v24, v[4:5], off offset:256
	global_load_dword v25, v[2:3], off offset:256
	s_waitcnt vmcnt(0) lgkmcnt(0)
	v_fma_f32 v22, -v17, v114, v22
	v_fma_f32 v23, -v17, v115, v23
	v_fma_f32 v24, -v17, v117, v24
	v_fma_f32 v25, -v17, v116, v25
	v_mul_f32_e32 v30, v24, v24
	v_fmac_f32_e32 v30, v25, v25
	v_fmac_f32_e32 v30, v23, v23
	v_fmac_f32_e32 v30, v22, v22
	ds_swizzle_b32 v31, v30 offset:swizzle(SWAP,1)
	s_waitcnt lgkmcnt(0)
	v_add_f32_e32 v30, v30, v31
	ds_swizzle_b32 v31, v30 offset:swizzle(SWAP,2)
	s_waitcnt lgkmcnt(0)
	v_add_f32_e32 v30, v30, v31
	ds_swizzle_b32 v31, v30 offset:swizzle(SWAP,4)
	s_waitcnt lgkmcnt(0)
	v_add_f32_e32 v30, v30, v31
	ds_swizzle_b32 v31, v30 offset:swizzle(SWAP,8)
	s_waitcnt lgkmcnt(0)
	v_add_f32_e32 v30, v30, v31
	ds_swizzle_b32 v31, v30 offset:swizzle(SWAP,16)
	s_waitcnt lgkmcnt(0)
	v_add_f32_e32 v30, v30, v31
	v_fmamk_f32 v30, v30, 0x3c000000, v218
	v_cmp_gt_f32_e32 vcc, s68, v30
	v_mul_f32_e32 v31, 0x4f800000, v30
	s_nop 0
	v_cndmask_b32_e32 v30, v30, v31, vcc
	v_sqrt_f32_e32 v31, v30
	s_nop 0
	v_add_u32_e32 v38, -1, v31
	v_fma_f32 v39, -v38, v31, v30
	v_cmp_ge_f32_e64 s[0:1], 0, v39
	v_add_u32_e32 v39, 1, v31
	s_nop 0
	v_cndmask_b32_e64 v38, v31, v38, s[0:1]
	v_fma_f32 v31, -v39, v31, v30
	v_cmp_lt_f32_e64 s[0:1], 0, v31
	s_nop 1
	v_cndmask_b32_e64 v31, v38, v39, s[0:1]
	v_mul_f32_e32 v38, 0x37800000, v31
	v_cndmask_b32_e32 v31, v31, v38, vcc
	v_cmp_class_f32_e32 vcc, v30, v219
	s_nop 1
	v_cndmask_b32_e32 v30, v31, v30, vcc
	v_div_scale_f32 v31, s[0:1], v30, v30, 1.0
	v_rcp_f32_e32 v38, v31
	s_nop 0
	v_fma_f32 v39, -v31, v38, 1.0
	v_fmac_f32_e32 v38, v39, v38
	v_div_scale_f32 v39, vcc, 1.0, v30, 1.0
	v_mul_f32_e32 v40, v39, v38
	v_fma_f32 v41, -v31, v40, v39
	v_fmac_f32_e32 v40, v41, v38
	v_fma_f32 v31, -v31, v40, v39
	v_div_fmas_f32 v31, v31, v38, v40
	v_div_fixup_f32 v30, v31, v30, 1.0
	v_mul_f32_e32 v31, v30, v0
	v_mul_f32_e32 v25, v31, v25
	v_mul_f32_e32 v31, v30, v14
	v_mul_f32_e32 v24, v31, v24
	v_mul_f32_e32 v31, v30, v15
	v_mul_f32_e32 v30, v30, v16
	v_mul_f32_e32 v23, v31, v23
	v_mul_f32_e32 v22, v30, v22
	global_load_dword v30, v[8:9], off offset:512
	global_load_dword v31, v[6:7], off offset:512
	global_load_dword v38, v[4:5], off offset:512
	global_load_dword v39, v[2:3], off offset:512
	s_waitcnt vmcnt(0) lgkmcnt(0)
	v_fma_f32 v30, -v17, v32, v30
	v_fma_f32 v31, -v17, v33, v31
	v_fma_f32 v38, -v17, v113, v38
	v_fma_f32 v39, -v17, v112, v39
	v_mul_f32_e32 v40, v38, v38
	v_fmac_f32_e32 v40, v39, v39
	v_fmac_f32_e32 v40, v31, v31
	v_fmac_f32_e32 v40, v30, v30
	ds_swizzle_b32 v32, v40 offset:swizzle(SWAP,1)
	s_waitcnt lgkmcnt(0)
	v_add_f32_e32 v32, v40, v32
	ds_swizzle_b32 v33, v32 offset:swizzle(SWAP,2)
	s_waitcnt lgkmcnt(0)
	v_add_f32_e32 v32, v32, v33
	ds_swizzle_b32 v33, v32 offset:swizzle(SWAP,4)
	s_waitcnt lgkmcnt(0)
	v_add_f32_e32 v32, v32, v33
	ds_swizzle_b32 v33, v32 offset:swizzle(SWAP,8)
	s_waitcnt lgkmcnt(0)
	v_add_f32_e32 v32, v32, v33
	ds_swizzle_b32 v33, v32 offset:swizzle(SWAP,16)
	s_waitcnt lgkmcnt(0)
	v_add_f32_e32 v32, v32, v33
	v_fmamk_f32 v32, v32, 0x3c000000, v218
	v_cmp_gt_f32_e32 vcc, s68, v32
	v_mul_f32_e32 v33, 0x4f800000, v32
	s_nop 0
	v_cndmask_b32_e32 v32, v32, v33, vcc
	v_sqrt_f32_e32 v33, v32
	s_nop 0
	v_add_u32_e32 v40, -1, v33
	v_fma_f32 v41, -v40, v33, v32
	v_cmp_ge_f32_e64 s[0:1], 0, v41
	v_add_u32_e32 v41, 1, v33
	s_nop 0
	v_cndmask_b32_e64 v40, v33, v40, s[0:1]
	v_fma_f32 v33, -v41, v33, v32
	v_cmp_lt_f32_e64 s[0:1], 0, v33
	s_nop 1
	v_cndmask_b32_e64 v33, v40, v41, s[0:1]
	v_mul_f32_e32 v40, 0x37800000, v33
	v_cndmask_b32_e32 v33, v33, v40, vcc
	v_cmp_class_f32_e32 vcc, v32, v219
	s_nop 1
	v_cndmask_b32_e32 v32, v33, v32, vcc
	v_div_scale_f32 v33, s[0:1], v32, v32, 1.0
	v_rcp_f32_e32 v40, v33
	s_nop 0
	v_fma_f32 v41, -v33, v40, 1.0
	v_fmac_f32_e32 v40, v41, v40
	v_div_scale_f32 v41, vcc, 1.0, v32, 1.0
	v_mul_f32_e32 v44, v41, v40
	v_fma_f32 v45, -v33, v44, v41
	v_fmac_f32_e32 v44, v45, v40
	v_fma_f32 v33, -v33, v44, v41
	v_div_fmas_f32 v33, v33, v40, v44
	v_div_fixup_f32 v40, v33, v32, 1.0
	v_mul_f32_e32 v32, v40, v0
	v_mul_f32_e32 v33, v32, v39
	v_mul_f32_e32 v32, v40, v14
	v_mul_f32_e32 v32, v32, v38
	v_mul_f32_e32 v38, v40, v15
	v_mul_f32_e32 v31, v38, v31
	v_mul_f32_e32 v38, v40, v16
	v_mul_f32_e32 v30, v38, v30
	global_load_dword v38, v[8:9], off offset:768
	global_load_dword v39, v[6:7], off offset:768
	global_load_dword v40, v[4:5], off offset:768
	global_load_dword v41, v[2:3], off offset:768
	s_waitcnt vmcnt(0) lgkmcnt(0)
; __global__ void __launch_bounds__(NTHR, 2) mega_fwd(Args a) {
;     ...
;               for (int r = 0; r < 16; ++r) { float ss = 0.f;
; #pragma unroll
;                   for (int d0 = 0; d0 < 4; ++d0) { const float dv = scrq[(d0 * 16 + r) * 64] - lam * o[d0][r]; o[d0][r] = dv; ss += dv * dv; }
;                   ss = half_sum(ss);
;                   const float rstd = 1.0f / sqrtf(ss * (1.f / 128.f) + EPS);
; #pragma unroll
;                   for (int d0 = 0; d0 < 4; ++d0) o[d0][r] *= rstd * gv[d0];
;                   if ((r & 3) == 3) asm volatile("" ::: "memory"); }
	v_fma_f32 v38, -v17, v108, v38
	v_fma_f32 v39, -v17, v109, v39
	v_fma_f32 v40, -v17, v111, v40
	v_fma_f32 v41, -v17, v110, v41
	v_mul_f32_e32 v44, v40, v40
	v_fmac_f32_e32 v44, v41, v41
	v_fmac_f32_e32 v44, v39, v39
	v_fmac_f32_e32 v44, v38, v38
	ds_swizzle_b32 v45, v44 offset:swizzle(SWAP,1)
	s_waitcnt lgkmcnt(0)
	v_add_f32_e32 v44, v44, v45
	ds_swizzle_b32 v45, v44 offset:swizzle(SWAP,2)
	s_waitcnt lgkmcnt(0)
	v_add_f32_e32 v44, v44, v45
	ds_swizzle_b32 v45, v44 offset:swizzle(SWAP,4)
	s_waitcnt lgkmcnt(0)
	v_add_f32_e32 v44, v44, v45
	ds_swizzle_b32 v45, v44 offset:swizzle(SWAP,8)
	s_waitcnt lgkmcnt(0)
	v_add_f32_e32 v44, v44, v45
	ds_swizzle_b32 v45, v44 offset:swizzle(SWAP,16)
	s_waitcnt lgkmcnt(0)
	v_add_f32_e32 v44, v44, v45
	v_fmamk_f32 v44, v44, 0x3c000000, v218
	v_cmp_gt_f32_e32 vcc, s68, v44
	v_mul_f32_e32 v45, 0x4f800000, v44
	s_nop 0
	v_cndmask_b32_e32 v44, v44, v45, vcc
	v_sqrt_f32_e32 v45, v44
	s_nop 0
	v_add_u32_e32 v46, -1, v45
	v_fma_f32 v47, -v46, v45, v44
	v_cmp_ge_f32_e64 s[0:1], 0, v47
	v_add_u32_e32 v47, 1, v45
	s_nop 0
	v_cndmask_b32_e64 v46, v45, v46, s[0:1]
	v_fma_f32 v45, -v47, v45, v44
	v_cmp_lt_f32_e64 s[0:1], 0, v45
	s_nop 1
	v_cndmask_b32_e64 v45, v46, v47, s[0:1]
	v_mul_f32_e32 v46, 0x37800000, v45
	v_cndmask_b32_e32 v45, v45, v46, vcc
	v_cmp_class_f32_e32 vcc, v44, v219
	s_nop 1
	v_cndmask_b32_e32 v44, v45, v44, vcc
	v_div_scale_f32 v45, s[0:1], v44, v44, 1.0
	v_rcp_f32_e32 v46, v45
	s_nop 0
	v_fma_f32 v47, -v45, v46, 1.0
	v_fmac_f32_e32 v46, v47, v46
	v_div_scale_f32 v47, vcc, 1.0, v44, 1.0
	v_mul_f32_e32 v54, v47, v46
	v_fma_f32 v55, -v45, v54, v47
	v_fmac_f32_e32 v54, v55, v46
	v_fma_f32 v45, -v45, v54, v47
	v_div_fmas_f32 v45, v45, v46, v54
	v_div_fixup_f32 v44, v45, v44, 1.0
	v_mul_f32_e32 v45, v44, v0
	v_mul_f32_e32 v41, v45, v41
	v_mul_f32_e32 v45, v44, v14
	v_mul_f32_e32 v40, v45, v40
	v_mul_f32_e32 v45, v44, v15
	v_mul_f32_e32 v44, v44, v16
	v_mul_f32_e32 v39, v45, v39
	v_mul_f32_e32 v38, v44, v38
	global_load_dword v44, v[2:3], off offset:1024
	global_load_dword v45, v[4:5], off offset:1024
	global_load_dword v47, v[6:7], off offset:1024
	s_waitcnt vmcnt(0) lgkmcnt(0)
	v_fma_f32 v44, -v17, v107, v44
	v_fma_f32 v45, -v17, v106, v45
	v_fma_f32 v54, -v17, v105, v47
	global_load_dword v47, v[8:9], off offset:1024
	v_mul_f32_e32 v46, v45, v45
	v_fmac_f32_e32 v46, v44, v44
	v_fmac_f32_e32 v46, v54, v54
	s_waitcnt vmcnt(0) lgkmcnt(0)
	v_fma_f32 v55, -v17, v104, v47
	v_fmac_f32_e32 v46, v55, v55
	ds_swizzle_b32 v47, v46 offset:swizzle(SWAP,1)
	s_waitcnt lgkmcnt(0)
	v_add_f32_e32 v46, v46, v47
	ds_swizzle_b32 v47, v46 offset:swizzle(SWAP,2)
	s_waitcnt lgkmcnt(0)
	v_add_f32_e32 v46, v46, v47
	ds_swizzle_b32 v47, v46 offset:swizzle(SWAP,4)
	s_waitcnt lgkmcnt(0)
	v_add_f32_e32 v46, v46, v47
	ds_swizzle_b32 v47, v46 offset:swizzle(SWAP,8)
	s_waitcnt lgkmcnt(0)
	v_add_f32_e32 v46, v46, v47
	ds_swizzle_b32 v47, v46 offset:swizzle(SWAP,16)
	s_waitcnt lgkmcnt(0)
	v_add_f32_e32 v46, v46, v47
	v_fmamk_f32 v46, v46, 0x3c000000, v218
	v_cmp_gt_f32_e32 vcc, s68, v46
	v_mul_f32_e32 v47, 0x4f800000, v46
	s_nop 0
	v_cndmask_b32_e32 v46, v46, v47, vcc
	v_sqrt_f32_e32 v47, v46
	s_nop 0
	v_add_u32_e32 v56, -1, v47
	v_fma_f32 v57, -v56, v47, v46
	v_cmp_ge_f32_e64 s[0:1], 0, v57
	v_add_u32_e32 v57, 1, v47
	s_nop 0
	v_cndmask_b32_e64 v56, v47, v56, s[0:1]
	v_fma_f32 v47, -v57, v47, v46
	v_cmp_lt_f32_e64 s[0:1], 0, v47
	s_nop 1
	v_cndmask_b32_e64 v47, v56, v57, s[0:1]
	v_mul_f32_e32 v56, 0x37800000, v47
	v_cndmask_b32_e32 v47, v47, v56, vcc
	v_cmp_class_f32_e32 vcc, v46, v219
	s_nop 1
	v_cndmask_b32_e32 v46, v47, v46, vcc
	v_div_scale_f32 v47, s[0:1], v46, v46, 1.0
	v_rcp_f32_e32 v56, v47
	s_nop 0
	v_fma_f32 v57, -v47, v56, 1.0
	v_fmac_f32_e32 v56, v57, v56
	v_div_scale_f32 v57, vcc, 1.0, v46, 1.0
	v_mul_f32_e32 v59, v57, v56
	v_fma_f32 v60, -v47, v59, v57
	v_fmac_f32_e32 v59, v60, v56
	v_fma_f32 v47, -v47, v59, v57
	v_div_fmas_f32 v47, v47, v56, v59
	v_div_fixup_f32 v56, v47, v46, 1.0
	v_mul_f32_e32 v46, v56, v0
	v_mul_f32_e32 v47, v46, v44
	v_mul_f32_e32 v44, v56, v14
	v_mul_f32_e32 v46, v44, v45
	v_mul_f32_e32 v44, v56, v15
	v_mul_f32_e32 v45, v44, v54
	v_mul_f32_e32 v44, v56, v16
	v_mul_f32_e32 v44, v44, v55
	global_load_dword v54, v[8:9], off offset:1280
	global_load_dword v55, v[6:7], off offset:1280
	global_load_dword v56, v[4:5], off offset:1280
	global_load_dword v57, v[2:3], off offset:1280
	s_waitcnt vmcnt(0) lgkmcnt(0)
	v_fma_f32 v54, -v17, v100, v54
	v_fma_f32 v55, -v17, v101, v55
	v_fma_f32 v56, -v17, v103, v56
	v_fma_f32 v57, -v17, v102, v57
	v_mul_f32_e32 v59, v56, v56
	v_fmac_f32_e32 v59, v57, v57
	v_fmac_f32_e32 v59, v55, v55
	v_fmac_f32_e32 v59, v54, v54
	ds_swizzle_b32 v60, v59 offset:swizzle(SWAP,1)
	s_waitcnt lgkmcnt(0)
	v_add_f32_e32 v59, v59, v60
	ds_swizzle_b32 v60, v59 offset:swizzle(SWAP,2)
	s_waitcnt lgkmcnt(0)
	v_add_f32_e32 v59, v59, v60
	ds_swizzle_b32 v60, v59 offset:swizzle(SWAP,4)
	s_waitcnt lgkmcnt(0)
	v_add_f32_e32 v59, v59, v60
	ds_swizzle_b32 v60, v59 offset:swizzle(SWAP,8)
	s_waitcnt lgkmcnt(0)
	v_add_f32_e32 v59, v59, v60
	ds_swizzle_b32 v60, v59 offset:swizzle(SWAP,16)
	s_waitcnt lgkmcnt(0)
; __global__ void __launch_bounds__(NTHR, 2) mega_fwd(Args a) {
;     ...
;               for (int r = 0; r < 16; ++r) { float ss = 0.f;
; #pragma unroll
;                   for (int d0 = 0; d0 < 4; ++d0) { const float dv = scrq[(d0 * 16 + r) * 64] - lam * o[d0][r]; o[d0][r] = dv; ss += dv * dv; }
;                   ss = half_sum(ss);
;                   const float rstd = 1.0f / sqrtf(ss * (1.f / 128.f) + EPS);
; #pragma unroll
;                   for (int d0 = 0; d0 < 4; ++d0) o[d0][r] *= rstd * gv[d0];
;                   if ((r & 3) == 3) asm volatile("" ::: "memory"); }
	v_add_f32_e32 v59, v59, v60
	v_fmamk_f32 v59, v59, 0x3c000000, v218
	v_cmp_gt_f32_e32 vcc, s68, v59
	v_mul_f32_e32 v60, 0x4f800000, v59
	s_nop 0
	v_cndmask_b32_e32 v59, v59, v60, vcc
	v_sqrt_f32_e32 v60, v59
	s_nop 0
	v_add_u32_e32 v61, -1, v60
	v_fma_f32 v62, -v61, v60, v59
	v_cmp_ge_f32_e64 s[0:1], 0, v62
	v_add_u32_e32 v62, 1, v60
	s_nop 0
	v_cndmask_b32_e64 v61, v60, v61, s[0:1]
	v_fma_f32 v60, -v62, v60, v59
	v_cmp_lt_f32_e64 s[0:1], 0, v60
	s_nop 1
	v_cndmask_b32_e64 v60, v61, v62, s[0:1]
	v_mul_f32_e32 v61, 0x37800000, v60
	v_cndmask_b32_e32 v60, v60, v61, vcc
	v_cmp_class_f32_e32 vcc, v59, v219
	s_nop 1
	v_cndmask_b32_e32 v59, v60, v59, vcc
	v_div_scale_f32 v60, s[0:1], v59, v59, 1.0
	v_rcp_f32_e32 v61, v60
	s_nop 0
	v_fma_f32 v62, -v60, v61, 1.0
	v_fmac_f32_e32 v61, v62, v61
	v_div_scale_f32 v62, vcc, 1.0, v59, 1.0
	v_mul_f32_e32 v63, v62, v61
	v_fma_f32 v72, -v60, v63, v62
	v_fmac_f32_e32 v63, v72, v61
	v_fma_f32 v60, -v60, v63, v62
	v_div_fmas_f32 v60, v60, v61, v63
	v_div_fixup_f32 v59, v60, v59, 1.0
	v_mul_f32_e32 v60, v59, v0
	v_mul_f32_e32 v57, v60, v57
	v_mul_f32_e32 v60, v59, v14
	v_mul_f32_e32 v56, v60, v56
	v_mul_f32_e32 v60, v59, v15
	v_mul_f32_e32 v59, v59, v16
	v_mul_f32_e32 v55, v60, v55
	v_mul_f32_e32 v54, v59, v54
	global_load_dword v59, v[8:9], off offset:1536
	global_load_dword v60, v[6:7], off offset:1536
	global_load_dword v61, v[4:5], off offset:1536
	global_load_dword v62, v[2:3], off offset:1536
	s_waitcnt vmcnt(0) lgkmcnt(0)
	v_fma_f32 v59, -v17, v96, v59
	v_fma_f32 v60, -v17, v97, v60
	v_fma_f32 v61, -v17, v99, v61
	v_fma_f32 v62, -v17, v98, v62
	v_mul_f32_e32 v63, v61, v61
	v_fmac_f32_e32 v63, v62, v62
	v_fmac_f32_e32 v63, v60, v60
	v_fmac_f32_e32 v63, v59, v59
	ds_swizzle_b32 v72, v63 offset:swizzle(SWAP,1)
	s_waitcnt lgkmcnt(0)
	v_add_f32_e32 v63, v63, v72
	ds_swizzle_b32 v72, v63 offset:swizzle(SWAP,2)
	s_waitcnt lgkmcnt(0)
	v_add_f32_e32 v63, v63, v72
	ds_swizzle_b32 v72, v63 offset:swizzle(SWAP,4)
	s_waitcnt lgkmcnt(0)
	v_add_f32_e32 v63, v63, v72
	ds_swizzle_b32 v72, v63 offset:swizzle(SWAP,8)
	s_waitcnt lgkmcnt(0)
	v_add_f32_e32 v63, v63, v72
	ds_swizzle_b32 v72, v63 offset:swizzle(SWAP,16)
	s_waitcnt lgkmcnt(0)
	v_add_f32_e32 v63, v63, v72
	v_fmamk_f32 v63, v63, 0x3c000000, v218
	v_cmp_gt_f32_e32 vcc, s68, v63
	v_mul_f32_e32 v72, 0x4f800000, v63
	s_nop 0
	v_cndmask_b32_e32 v63, v63, v72, vcc
	v_sqrt_f32_e32 v72, v63
	s_nop 0
	v_add_u32_e32 v73, -1, v72
	v_fma_f32 v74, -v73, v72, v63
	v_cmp_ge_f32_e64 s[0:1], 0, v74
	v_add_u32_e32 v74, 1, v72
	s_nop 0
	v_cndmask_b32_e64 v73, v72, v73, s[0:1]
	v_fma_f32 v72, -v74, v72, v63
	v_cmp_lt_f32_e64 s[0:1], 0, v72
	s_nop 1
	v_cndmask_b32_e64 v72, v73, v74, s[0:1]
	v_mul_f32_e32 v73, 0x37800000, v72
	v_cndmask_b32_e32 v72, v72, v73, vcc
	v_cmp_class_f32_e32 vcc, v63, v219
	s_nop 1
	v_cndmask_b32_e32 v63, v72, v63, vcc
	v_div_scale_f32 v72, s[0:1], v63, v63, 1.0
	v_rcp_f32_e32 v73, v72
	s_nop 0
	v_fma_f32 v74, -v72, v73, 1.0
	v_fmac_f32_e32 v73, v74, v73
	v_div_scale_f32 v74, vcc, 1.0, v63, 1.0
	v_mul_f32_e32 v75, v74, v73
	v_fma_f32 v76, -v72, v75, v74
	v_fmac_f32_e32 v75, v76, v73
	v_fma_f32 v72, -v72, v75, v74
	v_div_fmas_f32 v72, v72, v73, v75
	v_div_fixup_f32 v63, v72, v63, 1.0
	v_mul_f32_e32 v72, v63, v0
	v_mul_f32_e32 v62, v72, v62
	v_mul_f32_e32 v72, v63, v14
	v_mul_f32_e32 v61, v72, v61
	v_mul_f32_e32 v72, v63, v15
	v_mul_f32_e32 v63, v63, v16
	v_mul_f32_e32 v60, v72, v60
	v_mul_f32_e32 v59, v63, v59
	global_load_dword v63, v[8:9], off offset:1792
	global_load_dword v72, v[6:7], off offset:1792
	global_load_dword v73, v[4:5], off offset:1792
	global_load_dword v74, v[2:3], off offset:1792
	s_waitcnt vmcnt(0) lgkmcnt(0)
	v_fma_f32 v63, -v17, v71, v63
	v_fma_f32 v76, -v17, v84, v72
	v_fma_f32 v75, -v17, v86, v73
	v_fma_f32 v74, -v17, v85, v74
	v_mul_f32_e32 v73, v75, v75
	v_fmac_f32_e32 v73, v74, v74
	v_fmac_f32_e32 v73, v76, v76
	v_fmac_f32_e32 v73, v63, v63
	ds_swizzle_b32 v71, v73 offset:swizzle(SWAP,1)
	s_waitcnt lgkmcnt(0)
	v_add_f32_e32 v71, v73, v71
	ds_swizzle_b32 v72, v71 offset:swizzle(SWAP,2)
	s_waitcnt lgkmcnt(0)
	v_add_f32_e32 v71, v71, v72
	ds_swizzle_b32 v72, v71 offset:swizzle(SWAP,4)
	s_waitcnt lgkmcnt(0)
	v_add_f32_e32 v71, v71, v72
	ds_swizzle_b32 v72, v71 offset:swizzle(SWAP,8)
	s_waitcnt lgkmcnt(0)
	v_add_f32_e32 v71, v71, v72
	ds_swizzle_b32 v72, v71 offset:swizzle(SWAP,16)
	s_waitcnt lgkmcnt(0)
	v_add_f32_e32 v71, v71, v72
	v_fmamk_f32 v71, v71, 0x3c000000, v218
	v_cmp_gt_f32_e32 vcc, s68, v71
	v_mul_f32_e32 v72, 0x4f800000, v71
	s_nop 0
	v_cndmask_b32_e32 v71, v71, v72, vcc
	v_sqrt_f32_e32 v72, v71
	s_nop 0
	v_add_u32_e32 v73, -1, v72
	v_fma_f32 v77, -v73, v72, v71
	v_cmp_ge_f32_e64 s[0:1], 0, v77
	v_add_u32_e32 v77, 1, v72
	s_nop 0
	v_cndmask_b32_e64 v73, v72, v73, s[0:1]
	v_fma_f32 v72, -v77, v72, v71
	v_cmp_lt_f32_e64 s[0:1], 0, v72
	s_nop 1
	v_cndmask_b32_e64 v72, v73, v77, s[0:1]
	v_mul_f32_e32 v73, 0x37800000, v72
	v_cndmask_b32_e32 v72, v72, v73, vcc
	v_cmp_class_f32_e32 vcc, v71, v219
	s_nop 1
	v_cndmask_b32_e32 v71, v72, v71, vcc
	v_div_scale_f32 v72, s[0:1], v71, v71, 1.0
	v_rcp_f32_e32 v73, v72
	s_nop 0
	v_fma_f32 v77, -v72, v73, 1.0
	v_fmac_f32_e32 v73, v77, v73
	v_div_scale_f32 v77, vcc, 1.0, v71, 1.0
	v_mul_f32_e32 v78, v77, v73
	v_fma_f32 v79, -v72, v78, v77
	v_fmac_f32_e32 v78, v79, v73
	v_fma_f32 v72, -v72, v78, v77
	v_div_fmas_f32 v72, v72, v73, v78
	v_div_fixup_f32 v77, v72, v71, 1.0
	v_mul_f32_e32 v71, v77, v0
	v_mul_f32_e32 v73, v71, v74
	v_mul_f32_e32 v71, v77, v14
	v_mul_f32_e32 v74, v77, v16
	v_mul_f32_e32 v72, v71, v75
	v_mul_f32_e32 v71, v77, v15
	v_mul_f32_e32 v63, v74, v63
	global_load_dword v74, v[2:3], off offset:2048
	global_load_dword v75, v[4:5], off offset:2048
	global_load_dword v77, v[6:7], off offset:2048
	v_mul_f32_e32 v71, v71, v76
	s_waitcnt vmcnt(0) lgkmcnt(0)
; __global__ void __launch_bounds__(NTHR, 2) mega_fwd(Args a) {
;     ...
;               for (int r = 0; r < 16; ++r) { float ss = 0.f;
; #pragma unroll
;                   for (int d0 = 0; d0 < 4; ++d0) { const float dv = scrq[(d0 * 16 + r) * 64] - lam * o[d0][r]; o[d0][r] = dv; ss += dv * dv; }
;                   ss = half_sum(ss);
;                   const float rstd = 1.0f / sqrtf(ss * (1.f / 128.f) + EPS);
; #pragma unroll
;                   for (int d0 = 0; d0 < 4; ++d0) o[d0][r] *= rstd * gv[d0];
;                   if ((r & 3) == 3) asm volatile("" ::: "memory"); }
	v_fma_f32 v74, -v17, v83, v74
	v_fma_f32 v75, -v17, v82, v75
	v_fma_f32 v78, -v17, v81, v77
	global_load_dword v77, v[8:9], off offset:2048
	v_mul_f32_e32 v76, v75, v75
	v_fmac_f32_e32 v76, v74, v74
	v_fmac_f32_e32 v76, v78, v78
	s_waitcnt vmcnt(0) lgkmcnt(0)
	v_fma_f32 v79, -v17, v80, v77
	v_fmac_f32_e32 v76, v79, v79
	ds_swizzle_b32 v77, v76 offset:swizzle(SWAP,1)
	s_waitcnt lgkmcnt(0)
	v_add_f32_e32 v76, v76, v77
	ds_swizzle_b32 v77, v76 offset:swizzle(SWAP,2)
	s_waitcnt lgkmcnt(0)
	v_add_f32_e32 v76, v76, v77
	ds_swizzle_b32 v77, v76 offset:swizzle(SWAP,4)
	s_waitcnt lgkmcnt(0)
	v_add_f32_e32 v76, v76, v77
	ds_swizzle_b32 v77, v76 offset:swizzle(SWAP,8)
	s_waitcnt lgkmcnt(0)
	v_add_f32_e32 v76, v76, v77
	ds_swizzle_b32 v77, v76 offset:swizzle(SWAP,16)
	s_waitcnt lgkmcnt(0)
	v_add_f32_e32 v76, v76, v77
	v_fmamk_f32 v76, v76, 0x3c000000, v218
	v_cmp_gt_f32_e32 vcc, s68, v76
	v_mul_f32_e32 v77, 0x4f800000, v76
	s_nop 0
	v_cndmask_b32_e32 v76, v76, v77, vcc
	v_sqrt_f32_e32 v77, v76
	s_nop 0
	v_add_u32_e32 v80, -1, v77
	v_fma_f32 v81, -v80, v77, v76
	v_cmp_ge_f32_e64 s[0:1], 0, v81
	v_add_u32_e32 v81, 1, v77
	s_nop 0
	v_cndmask_b32_e64 v80, v77, v80, s[0:1]
	v_fma_f32 v77, -v81, v77, v76
	v_cmp_lt_f32_e64 s[0:1], 0, v77
	s_nop 1
	v_cndmask_b32_e64 v77, v80, v81, s[0:1]
	v_mul_f32_e32 v80, 0x37800000, v77
	v_cndmask_b32_e32 v77, v77, v80, vcc
	v_cmp_class_f32_e32 vcc, v76, v219
	s_nop 1
	v_cndmask_b32_e32 v76, v77, v76, vcc
	v_div_scale_f32 v77, s[0:1], v76, v76, 1.0
	v_rcp_f32_e32 v80, v77
	s_nop 0
	v_fma_f32 v81, -v77, v80, 1.0
	v_fmac_f32_e32 v80, v81, v80
	v_div_scale_f32 v81, vcc, 1.0, v76, 1.0
	v_mul_f32_e32 v82, v81, v80
	v_fma_f32 v83, -v77, v82, v81
	v_fmac_f32_e32 v82, v83, v80
	v_fma_f32 v77, -v77, v82, v81
	v_div_fmas_f32 v77, v77, v80, v82
	v_div_fixup_f32 v80, v77, v76, 1.0
	v_mul_f32_e32 v76, v80, v0
	v_mul_f32_e32 v77, v76, v74
	v_mul_f32_e32 v74, v80, v14
	v_mul_f32_e32 v76, v74, v75
	v_mul_f32_e32 v74, v80, v15
	v_mul_f32_e32 v75, v74, v78
	v_mul_f32_e32 v74, v80, v16
	v_mul_f32_e32 v74, v74, v79
	global_load_dword v78, v[8:9], off offset:2304
	global_load_dword v79, v[6:7], off offset:2304
	global_load_dword v80, v[4:5], off offset:2304
	global_load_dword v81, v[2:3], off offset:2304
	s_waitcnt vmcnt(0) lgkmcnt(0)
	v_fma_f32 v67, -v17, v67, v78
	v_fma_f32 v68, -v17, v68, v79
	v_fma_f32 v80, -v17, v70, v80
	v_fma_f32 v69, -v17, v69, v81
	v_mul_f32_e32 v70, v80, v80
	v_fmac_f32_e32 v70, v69, v69
	v_fmac_f32_e32 v70, v68, v68
	v_fmac_f32_e32 v70, v67, v67
	ds_swizzle_b32 v78, v70 offset:swizzle(SWAP,1)
	s_waitcnt lgkmcnt(0)
	v_add_f32_e32 v70, v70, v78
	ds_swizzle_b32 v78, v70 offset:swizzle(SWAP,2)
	s_waitcnt lgkmcnt(0)
	v_add_f32_e32 v70, v70, v78
	ds_swizzle_b32 v78, v70 offset:swizzle(SWAP,4)
	s_waitcnt lgkmcnt(0)
	v_add_f32_e32 v70, v70, v78
	ds_swizzle_b32 v78, v70 offset:swizzle(SWAP,8)
	s_waitcnt lgkmcnt(0)
	v_add_f32_e32 v70, v70, v78
	ds_swizzle_b32 v78, v70 offset:swizzle(SWAP,16)
	s_waitcnt lgkmcnt(0)
	v_add_f32_e32 v70, v70, v78
	v_fmamk_f32 v70, v70, 0x3c000000, v218
	v_cmp_gt_f32_e32 vcc, s68, v70
	v_mul_f32_e32 v78, 0x4f800000, v70
	s_nop 0
	v_cndmask_b32_e32 v70, v70, v78, vcc
	v_sqrt_f32_e32 v78, v70
	s_nop 0
	v_add_u32_e32 v79, -1, v78
	v_fma_f32 v81, -v79, v78, v70
	v_cmp_ge_f32_e64 s[0:1], 0, v81
	v_add_u32_e32 v81, 1, v78
	s_nop 0
	v_cndmask_b32_e64 v79, v78, v79, s[0:1]
	v_fma_f32 v78, -v81, v78, v70
	v_cmp_lt_f32_e64 s[0:1], 0, v78
	s_nop 1
	v_cndmask_b32_e64 v78, v79, v81, s[0:1]
	v_mul_f32_e32 v79, 0x37800000, v78
	v_cndmask_b32_e32 v78, v78, v79, vcc
	v_cmp_class_f32_e32 vcc, v70, v219
	s_nop 1
	v_cndmask_b32_e32 v70, v78, v70, vcc
	v_div_scale_f32 v78, s[0:1], v70, v70, 1.0
	v_rcp_f32_e32 v79, v78
	s_nop 0
	v_fma_f32 v81, -v78, v79, 1.0
	v_fmac_f32_e32 v79, v81, v79
	v_div_scale_f32 v81, vcc, 1.0, v70, 1.0
	v_mul_f32_e32 v82, v81, v79
	v_fma_f32 v83, -v78, v82, v81
	v_fmac_f32_e32 v82, v83, v79
	v_fma_f32 v78, -v78, v82, v81
	v_div_fmas_f32 v78, v78, v79, v82
	v_div_fixup_f32 v78, v78, v70, 1.0
	v_mul_f32_e32 v70, v78, v0
	v_mul_f32_e32 v70, v70, v69
	v_mul_f32_e32 v69, v78, v14
	v_mul_f32_e32 v79, v78, v15
	v_mul_f32_e32 v78, v78, v16
	v_mul_f32_e32 v69, v69, v80
	v_mul_f32_e32 v68, v79, v68
	v_mul_f32_e32 v67, v78, v67
	global_load_dword v78, v[8:9], off offset:2560
	global_load_dword v79, v[6:7], off offset:2560
	global_load_dword v80, v[4:5], off offset:2560
	global_load_dword v81, v[2:3], off offset:2560
	s_waitcnt vmcnt(0) lgkmcnt(0)
	v_fma_f32 v58, -v17, v58, v78
	v_fma_f32 v64, -v17, v64, v79
	v_fma_f32 v80, -v17, v66, v80
	v_fma_f32 v65, -v17, v65, v81
	v_mul_f32_e32 v66, v80, v80
	v_fmac_f32_e32 v66, v65, v65
	v_fmac_f32_e32 v66, v64, v64
	v_fmac_f32_e32 v66, v58, v58
	ds_swizzle_b32 v78, v66 offset:swizzle(SWAP,1)
	s_waitcnt lgkmcnt(0)
	v_add_f32_e32 v66, v66, v78
	ds_swizzle_b32 v78, v66 offset:swizzle(SWAP,2)
	s_waitcnt lgkmcnt(0)
	v_add_f32_e32 v66, v66, v78
	ds_swizzle_b32 v78, v66 offset:swizzle(SWAP,4)
	s_waitcnt lgkmcnt(0)
	v_add_f32_e32 v66, v66, v78
	ds_swizzle_b32 v78, v66 offset:swizzle(SWAP,8)
	s_waitcnt lgkmcnt(0)
	v_add_f32_e32 v66, v66, v78
	ds_swizzle_b32 v78, v66 offset:swizzle(SWAP,16)
	s_waitcnt lgkmcnt(0)
; __global__ void __launch_bounds__(NTHR, 2) mega_fwd(Args a) {
;     ...
;               for (int r = 0; r < 16; ++r) { float ss = 0.f;
; #pragma unroll
;                   for (int d0 = 0; d0 < 4; ++d0) { const float dv = scrq[(d0 * 16 + r) * 64] - lam * o[d0][r]; o[d0][r] = dv; ss += dv * dv; }
;                   ss = half_sum(ss);
;                   const float rstd = 1.0f / sqrtf(ss * (1.f / 128.f) + EPS);
; #pragma unroll
;                   for (int d0 = 0; d0 < 4; ++d0) o[d0][r] *= rstd * gv[d0];
;                   if ((r & 3) == 3) asm volatile("" ::: "memory"); }
	v_add_f32_e32 v66, v66, v78
	v_fmamk_f32 v66, v66, 0x3c000000, v218
	v_cmp_gt_f32_e32 vcc, s68, v66
	v_mul_f32_e32 v78, 0x4f800000, v66
	s_nop 0
	v_cndmask_b32_e32 v66, v66, v78, vcc
	v_sqrt_f32_e32 v78, v66
	s_nop 0
	v_add_u32_e32 v79, -1, v78
	v_fma_f32 v81, -v79, v78, v66
	v_cmp_ge_f32_e64 s[0:1], 0, v81
	v_add_u32_e32 v81, 1, v78
	s_nop 0
	v_cndmask_b32_e64 v79, v78, v79, s[0:1]
	v_fma_f32 v78, -v81, v78, v66
	v_cmp_lt_f32_e64 s[0:1], 0, v78
	s_nop 1
	v_cndmask_b32_e64 v78, v79, v81, s[0:1]
	v_mul_f32_e32 v79, 0x37800000, v78
	v_cndmask_b32_e32 v78, v78, v79, vcc
	v_cmp_class_f32_e32 vcc, v66, v219
	s_nop 1
	v_cndmask_b32_e32 v66, v78, v66, vcc
	v_div_scale_f32 v78, s[0:1], v66, v66, 1.0
	v_rcp_f32_e32 v79, v78
	s_nop 0
	v_fma_f32 v81, -v78, v79, 1.0
	v_fmac_f32_e32 v79, v81, v79
	v_div_scale_f32 v81, vcc, 1.0, v66, 1.0
	v_mul_f32_e32 v82, v81, v79
	v_fma_f32 v83, -v78, v82, v81
	v_fmac_f32_e32 v82, v83, v79
	v_fma_f32 v78, -v78, v82, v81
	v_div_fmas_f32 v78, v78, v79, v82
	v_div_fixup_f32 v78, v78, v66, 1.0
	v_mul_f32_e32 v66, v78, v0
	v_mul_f32_e32 v66, v66, v65
	v_mul_f32_e32 v65, v78, v14
	v_mul_f32_e32 v79, v78, v15
	v_mul_f32_e32 v78, v78, v16
	v_mul_f32_e32 v65, v65, v80
	v_mul_f32_e32 v64, v79, v64
	v_mul_f32_e32 v58, v78, v58
	global_load_dword v78, v[8:9], off offset:2816
	global_load_dword v79, v[6:7], off offset:2816
	global_load_dword v80, v[4:5], off offset:2816
	global_load_dword v81, v[2:3], off offset:2816
	s_waitcnt vmcnt(0) lgkmcnt(0)
	v_fma_f32 v50, -v17, v50, v78
	v_fma_f32 v51, -v17, v51, v79
	v_fma_f32 v80, -v17, v53, v80
	v_fma_f32 v52, -v17, v52, v81
	v_mul_f32_e32 v53, v80, v80
	v_fmac_f32_e32 v53, v52, v52
	v_fmac_f32_e32 v53, v51, v51
	v_fmac_f32_e32 v53, v50, v50
	ds_swizzle_b32 v78, v53 offset:swizzle(SWAP,1)
	s_waitcnt lgkmcnt(0)
	v_add_f32_e32 v53, v53, v78
	ds_swizzle_b32 v78, v53 offset:swizzle(SWAP,2)
	s_waitcnt lgkmcnt(0)
	v_add_f32_e32 v53, v53, v78
	ds_swizzle_b32 v78, v53 offset:swizzle(SWAP,4)
	s_waitcnt lgkmcnt(0)
	v_add_f32_e32 v53, v53, v78
	ds_swizzle_b32 v78, v53 offset:swizzle(SWAP,8)
	s_waitcnt lgkmcnt(0)
	v_add_f32_e32 v53, v53, v78
	ds_swizzle_b32 v78, v53 offset:swizzle(SWAP,16)
	s_waitcnt lgkmcnt(0)
	v_add_f32_e32 v53, v53, v78
	v_fmamk_f32 v53, v53, 0x3c000000, v218
	v_cmp_gt_f32_e32 vcc, s68, v53
	v_mul_f32_e32 v78, 0x4f800000, v53
	s_nop 0
	v_cndmask_b32_e32 v53, v53, v78, vcc
	v_sqrt_f32_e32 v78, v53
	s_nop 0
	v_add_u32_e32 v79, -1, v78
	v_fma_f32 v81, -v79, v78, v53
	v_cmp_ge_f32_e64 s[0:1], 0, v81
	v_add_u32_e32 v81, 1, v78
	s_nop 0
	v_cndmask_b32_e64 v79, v78, v79, s[0:1]
	v_fma_f32 v78, -v81, v78, v53
	v_cmp_lt_f32_e64 s[0:1], 0, v78
	s_nop 1
	v_cndmask_b32_e64 v78, v79, v81, s[0:1]
	v_mul_f32_e32 v79, 0x37800000, v78
	v_cndmask_b32_e32 v78, v78, v79, vcc
	v_cmp_class_f32_e32 vcc, v53, v219
	s_nop 1
	v_cndmask_b32_e32 v53, v78, v53, vcc
	v_div_scale_f32 v78, s[0:1], v53, v53, 1.0
	v_rcp_f32_e32 v79, v78
	s_nop 0
	v_fma_f32 v81, -v78, v79, 1.0
	v_fmac_f32_e32 v79, v81, v79
	v_div_scale_f32 v81, vcc, 1.0, v53, 1.0
	v_mul_f32_e32 v82, v81, v79
	v_fma_f32 v83, -v78, v82, v81
	v_fmac_f32_e32 v82, v83, v79
	v_fma_f32 v78, -v78, v82, v81
	v_div_fmas_f32 v78, v78, v79, v82
	v_div_fixup_f32 v78, v78, v53, 1.0
	v_mul_f32_e32 v53, v78, v0
	v_mul_f32_e32 v53, v53, v52
	v_mul_f32_e32 v52, v78, v14
	v_mul_f32_e32 v79, v78, v15
	v_mul_f32_e32 v78, v78, v16
	v_mul_f32_e32 v50, v78, v50
	global_load_dword v78, v[2:3], off offset:3072
	v_mul_f32_e32 v51, v79, v51
	global_load_dword v79, v[6:7], off offset:3072
	v_mul_f32_e32 v52, v52, v80
	s_waitcnt vmcnt(0) lgkmcnt(0)
	v_fma_f32 v49, -v17, v49, v78
	global_load_dword v78, v[4:5], off offset:3072
	v_fma_f32 v43, -v17, v43, v79
	global_load_dword v79, v[8:9], off offset:3072
	s_waitcnt vmcnt(0) lgkmcnt(0)
	v_fma_f32 v48, -v17, v48, v78
	v_mul_f32_e32 v78, v48, v48
	v_fmac_f32_e32 v78, v49, v49
	v_fmac_f32_e32 v78, v43, v43
	v_fma_f32 v42, -v17, v42, v79
	v_fmac_f32_e32 v78, v42, v42
	ds_swizzle_b32 v79, v78 offset:swizzle(SWAP,1)
	s_waitcnt lgkmcnt(0)
	v_add_f32_e32 v78, v78, v79
	ds_swizzle_b32 v79, v78 offset:swizzle(SWAP,2)
	s_waitcnt lgkmcnt(0)
	v_add_f32_e32 v78, v78, v79
	ds_swizzle_b32 v79, v78 offset:swizzle(SWAP,4)
	s_waitcnt lgkmcnt(0)
	v_add_f32_e32 v78, v78, v79
	ds_swizzle_b32 v79, v78 offset:swizzle(SWAP,8)
	s_waitcnt lgkmcnt(0)
	v_add_f32_e32 v78, v78, v79
	ds_swizzle_b32 v79, v78 offset:swizzle(SWAP,16)
	s_waitcnt lgkmcnt(0)
	v_add_f32_e32 v78, v78, v79
	v_fmamk_f32 v78, v78, 0x3c000000, v218
	v_cmp_gt_f32_e32 vcc, s68, v78
	v_mul_f32_e32 v79, 0x4f800000, v78
	s_nop 0
	v_cndmask_b32_e32 v78, v78, v79, vcc
	v_sqrt_f32_e32 v79, v78
	s_nop 0
	v_add_u32_e32 v80, -1, v79
	v_fma_f32 v81, -v80, v79, v78
	v_cmp_ge_f32_e64 s[0:1], 0, v81
	v_add_u32_e32 v81, 1, v79
	s_nop 0
	v_cndmask_b32_e64 v80, v79, v80, s[0:1]
	v_fma_f32 v79, -v81, v79, v78
	v_cmp_lt_f32_e64 s[0:1], 0, v79
	s_nop 1
	v_cndmask_b32_e64 v79, v80, v81, s[0:1]
	v_mul_f32_e32 v80, 0x37800000, v79
	v_cndmask_b32_e32 v79, v79, v80, vcc
	v_cmp_class_f32_e32 vcc, v78, v219
	s_nop 1
	v_cndmask_b32_e32 v78, v79, v78, vcc
	v_div_scale_f32 v79, s[0:1], v78, v78, 1.0
	v_rcp_f32_e32 v80, v79
	s_nop 0
	v_fma_f32 v81, -v79, v80, 1.0
	v_fmac_f32_e32 v80, v81, v80
	v_div_scale_f32 v81, vcc, 1.0, v78, 1.0
	v_mul_f32_e32 v82, v81, v80
	v_fma_f32 v83, -v79, v82, v81
	v_fmac_f32_e32 v82, v83, v80
	v_fma_f32 v79, -v79, v82, v81
	v_div_fmas_f32 v79, v79, v80, v82
	v_div_fixup_f32 v78, v79, v78, 1.0
	v_mul_f32_e32 v79, v78, v0
	v_mul_f32_e32 v49, v79, v49
	v_mul_f32_e32 v79, v78, v14
	v_mul_f32_e32 v48, v79, v48
	v_mul_f32_e32 v79, v78, v15
	v_mul_f32_e32 v78, v78, v16
	v_mul_f32_e32 v43, v79, v43
	v_mul_f32_e32 v42, v78, v42
	global_load_dword v78, v[8:9], off offset:3328
	global_load_dword v79, v[6:7], off offset:3328
	global_load_dword v80, v[4:5], off offset:3328
	global_load_dword v81, v[2:3], off offset:3328
	s_waitcnt vmcnt(0) lgkmcnt(0)
; __device__ __forceinline__ int tid_of(int wave_s) { int l; asm volatile("v_mbcnt_lo_u32_b32 %0, -1, 0\n\tv_mbcnt_hi_u32_b32 %0, -1, %0" : "=v"(l)); return wave_s * 64 + l; }
; __device__ __forceinline__ unsigned f2bf(float f) { unsigned u = __builtin_bit_cast(unsigned, f); return (u + 0x7fffu + ((u >> 16) & 1u)) >> 16; }
; __device__ __forceinline__ int crow(int r, int hi) { return (r & 3) + 8 * (r >> 2) + 4 * hi; }
; __device__ __forceinline__ void store_o_tile(const f32x16 (&o)[4], char* lds, bf16_t* Og, int wave_s) {
;     int tid_ = tid_of(wave_s);
;     const int wid = tid_ >> 6, lane = tid_ & 63, r32 = lane & 31, hi = lane >> 5;
;     __syncthreads();
;     bf16_t* stg = (bf16_t*)(lds + wid * 8192);
; #pragma unroll
;     for (int r = 0; r < 16; ++r) { const int orow = att::crow(r, hi);
; #pragma unroll
;         for (int d0 = 0; d0 < 4; ++d0) stg[orow * 128 + d0 * 32 + r32] = (bf16_t)f2bf(o[d0][r]); }
; __global__ void __launch_bounds__(NTHR, 2) mega_fwd(Args a) {
;     ...
;               for (int r = 0; r < 16; ++r) { float ss = 0.f;
; #pragma unroll
;                   for (int d0 = 0; d0 < 4; ++d0) { const float dv = scrq[(d0 * 16 + r) * 64] - lam * o[d0][r]; o[d0][r] = dv; ss += dv * dv; }
;                   ss = half_sum(ss);
;                   const float rstd = 1.0f / sqrtf(ss * (1.f / 128.f) + EPS);
; #pragma unroll
;                   for (int d0 = 0; d0 < 4; ++d0) o[d0][r] *= rstd * gv[d0];
;                   if ((r & 3) == 3) asm volatile("" ::: "memory"); }
	v_fma_f32 v34, -v17, v34, v78
	v_fma_f32 v35, -v17, v35, v79
	v_fma_f32 v80, -v17, v37, v80
	v_fma_f32 v36, -v17, v36, v81
	v_mul_f32_e32 v37, v80, v80
	v_fmac_f32_e32 v37, v36, v36
	v_fmac_f32_e32 v37, v35, v35
	v_fmac_f32_e32 v37, v34, v34
	ds_swizzle_b32 v78, v37 offset:swizzle(SWAP,1)
	s_waitcnt lgkmcnt(0)
	v_add_f32_e32 v37, v37, v78
	ds_swizzle_b32 v78, v37 offset:swizzle(SWAP,2)
	s_waitcnt lgkmcnt(0)
	v_add_f32_e32 v37, v37, v78
	ds_swizzle_b32 v78, v37 offset:swizzle(SWAP,4)
	s_waitcnt lgkmcnt(0)
	v_add_f32_e32 v37, v37, v78
	ds_swizzle_b32 v78, v37 offset:swizzle(SWAP,8)
	s_waitcnt lgkmcnt(0)
	v_add_f32_e32 v37, v37, v78
	ds_swizzle_b32 v78, v37 offset:swizzle(SWAP,16)
	s_waitcnt lgkmcnt(0)
	v_add_f32_e32 v37, v37, v78
	v_fmamk_f32 v37, v37, 0x3c000000, v218
	v_cmp_gt_f32_e32 vcc, s68, v37
	v_mul_f32_e32 v78, 0x4f800000, v37
	s_nop 0
	v_cndmask_b32_e32 v37, v37, v78, vcc
	v_sqrt_f32_e32 v78, v37
	s_nop 0
	v_add_u32_e32 v79, -1, v78
	v_fma_f32 v81, -v79, v78, v37
	v_cmp_ge_f32_e64 s[0:1], 0, v81
	v_add_u32_e32 v81, 1, v78
	s_nop 0
	v_cndmask_b32_e64 v79, v78, v79, s[0:1]
	v_fma_f32 v78, -v81, v78, v37
	v_cmp_lt_f32_e64 s[0:1], 0, v78
	s_nop 1
	v_cndmask_b32_e64 v78, v79, v81, s[0:1]
	v_mul_f32_e32 v79, 0x37800000, v78
	v_cndmask_b32_e32 v78, v78, v79, vcc
	v_cmp_class_f32_e32 vcc, v37, v219
	s_nop 1
	v_cndmask_b32_e32 v37, v78, v37, vcc
	v_div_scale_f32 v78, s[0:1], v37, v37, 1.0
	v_rcp_f32_e32 v79, v78
	s_nop 0
	v_fma_f32 v81, -v78, v79, 1.0
	v_fmac_f32_e32 v79, v81, v79
	v_div_scale_f32 v81, vcc, 1.0, v37, 1.0
	v_mul_f32_e32 v82, v81, v79
	v_fma_f32 v83, -v78, v82, v81
	v_fmac_f32_e32 v82, v83, v79
	v_fma_f32 v78, -v78, v82, v81
	v_div_fmas_f32 v78, v78, v79, v82
	v_div_fixup_f32 v78, v78, v37, 1.0
	v_mul_f32_e32 v37, v78, v0
	v_mul_f32_e32 v37, v37, v36
	v_mul_f32_e32 v36, v78, v14
	v_mul_f32_e32 v79, v78, v15
	v_mul_f32_e32 v78, v78, v16
	v_mul_f32_e32 v36, v36, v80
	v_mul_f32_e32 v35, v79, v35
	v_mul_f32_e32 v34, v78, v34
	global_load_dword v78, v[8:9], off offset:3584
	global_load_dword v79, v[6:7], off offset:3584
	global_load_dword v80, v[4:5], off offset:3584
	global_load_dword v81, v[2:3], off offset:3584
	s_nop 0
	global_load_dword v8, v[8:9], off offset:3840
	s_nop 0
	global_load_dword v6, v[6:7], off offset:3840
	s_nop 0
	global_load_dword v4, v[4:5], off offset:3840
	s_nop 0
	global_load_dword v2, v[2:3], off offset:3840
	s_waitcnt vmcnt(0) lgkmcnt(0)
	v_fma_f32 v26, -v17, v26, v78
	v_fma_f32 v27, -v17, v27, v79
	v_fma_f32 v80, -v17, v29, v80
	v_fma_f32 v28, -v17, v28, v81
	v_mul_f32_e32 v29, v80, v80
	v_fmac_f32_e32 v29, v28, v28
	v_fmac_f32_e32 v29, v27, v27
	v_fmac_f32_e32 v29, v26, v26
	ds_swizzle_b32 v78, v29 offset:swizzle(SWAP,1)
	v_fma_f32 v3, -v17, v13, v4
	v_fma_f32 v2, -v17, v12, v2
	v_mul_f32_e32 v4, v3, v3
	v_fmac_f32_e32 v4, v2, v2
	s_waitcnt lgkmcnt(0)
	v_add_f32_e32 v29, v29, v78
	ds_swizzle_b32 v78, v29 offset:swizzle(SWAP,2)
	v_fma_f32 v5, -v17, v11, v6
	v_fmac_f32_e32 v4, v5, v5
	v_fma_f32 v6, -v17, v10, v8
	v_fmac_f32_e32 v4, v6, v6
	s_waitcnt lgkmcnt(0)
	v_add_f32_e32 v29, v29, v78
	ds_swizzle_b32 v78, v29 offset:swizzle(SWAP,4)
	ds_swizzle_b32 v7, v4 offset:swizzle(SWAP,1)
	s_waitcnt lgkmcnt(1)
	v_add_f32_e32 v29, v29, v78
	ds_swizzle_b32 v78, v29 offset:swizzle(SWAP,8)
	s_waitcnt lgkmcnt(1)
	v_add_f32_e32 v4, v4, v7
	ds_swizzle_b32 v7, v4 offset:swizzle(SWAP,2)
	s_waitcnt lgkmcnt(1)
	v_add_f32_e32 v29, v29, v78
	ds_swizzle_b32 v78, v29 offset:swizzle(SWAP,16)
	s_waitcnt lgkmcnt(1)
	v_add_f32_e32 v4, v4, v7
	ds_swizzle_b32 v7, v4 offset:swizzle(SWAP,4)
	s_waitcnt lgkmcnt(1)
	v_add_f32_e32 v29, v29, v78
	v_fmamk_f32 v29, v29, 0x3c000000, v218
	v_cmp_gt_f32_e32 vcc, s68, v29
	v_mul_f32_e32 v78, 0x4f800000, v29
	s_waitcnt lgkmcnt(0)
	v_add_f32_e32 v4, v4, v7
	v_cndmask_b32_e32 v29, v29, v78, vcc
	v_sqrt_f32_e32 v78, v29
	ds_swizzle_b32 v7, v4 offset:swizzle(SWAP,8)
	v_add_u32_e32 v79, -1, v78
	v_fma_f32 v81, -v79, v78, v29
	v_cmp_ge_f32_e64 s[0:1], 0, v81
	v_add_u32_e32 v81, 1, v78
	s_waitcnt lgkmcnt(0)
	v_add_f32_e32 v4, v4, v7
	v_cndmask_b32_e64 v79, v78, v79, s[0:1]
	v_fma_f32 v78, -v81, v78, v29
	v_cmp_lt_f32_e64 s[0:1], 0, v78
	ds_swizzle_b32 v7, v4 offset:swizzle(SWAP,16)
	s_waitcnt lgkmcnt(0)
	v_add_f32_e32 v4, v4, v7
	v_cndmask_b32_e64 v78, v79, v81, s[0:1]
	v_mul_f32_e32 v79, 0x37800000, v78
	v_cndmask_b32_e32 v78, v78, v79, vcc
	v_cmp_class_f32_e32 vcc, v29, v219
	v_fmamk_f32 v4, v4, 0x3c000000, v218
	v_mul_f32_e32 v7, 0x4f800000, v4
	v_cndmask_b32_e32 v29, v78, v29, vcc
	v_div_scale_f32 v78, s[0:1], v29, v29, 1.0
	v_rcp_f32_e32 v79, v78
	s_nop 0
	v_fma_f32 v81, -v78, v79, 1.0
	v_fmac_f32_e32 v79, v81, v79
	v_div_scale_f32 v81, vcc, 1.0, v29, 1.0
	v_mul_f32_e32 v82, v81, v79
	v_fma_f32 v83, -v78, v82, v81
	v_fmac_f32_e32 v82, v83, v79
	v_fma_f32 v78, -v78, v82, v81
	v_div_fmas_f32 v78, v78, v79, v82
	v_cmp_gt_f32_e32 vcc, s68, v4
	v_div_fixup_f32 v78, v78, v29, 1.0
	v_mul_f32_e32 v29, v78, v0
	v_cndmask_b32_e32 v4, v4, v7, vcc
	v_sqrt_f32_e32 v7, v4
	v_mul_f32_e32 v29, v29, v28
	v_mul_f32_e32 v28, v78, v14
	v_mul_f32_e32 v28, v28, v80
	v_add_u32_e32 v8, -1, v7
	v_fma_f32 v9, -v8, v7, v4
	v_cmp_ge_f32_e64 s[0:1], 0, v9
	v_add_u32_e32 v9, 1, v7
	v_mul_f32_e32 v79, v78, v15
	v_cndmask_b32_e64 v8, v7, v8, s[0:1]
	v_fma_f32 v7, -v9, v7, v4
	v_cmp_lt_f32_e64 s[0:1], 0, v7
	v_mul_f32_e32 v27, v79, v27
	v_mul_f32_e32 v78, v78, v16
	v_cndmask_b32_e64 v7, v8, v9, s[0:1]
	v_mul_f32_e32 v8, 0x37800000, v7
	v_cndmask_b32_e32 v7, v7, v8, vcc
	v_cmp_class_f32_e32 vcc, v4, v219
	v_mul_f32_e32 v26, v78, v26
	s_nop 0
	v_cndmask_b32_e32 v4, v7, v4, vcc
	v_div_scale_f32 v7, s[0:1], v4, v4, 1.0
	v_rcp_f32_e32 v8, v7
	v_readlane_b32 s0, v254, 11
	v_fma_f32 v9, -v7, v8, 1.0
	v_fmac_f32_e32 v8, v9, v8
	v_div_scale_f32 v9, vcc, 1.0, v4, 1.0
	v_mul_f32_e32 v10, v9, v8
	v_fma_f32 v11, -v7, v10, v9
	v_fmac_f32_e32 v10, v11, v8
	v_fma_f32 v7, -v7, v10, v9
	v_div_fmas_f32 v7, v7, v8, v10
	v_div_fixup_f32 v4, v7, v4, 1.0
	v_mul_f32_e32 v0, v4, v0
	v_mul_f32_e32 v0, v0, v2
	v_mul_f32_e32 v2, v4, v14
	v_mul_f32_e32 v7, v2, v3
	v_mul_f32_e32 v2, v4, v15
	v_mul_f32_e32 v5, v2, v5
	v_mul_f32_e32 v2, v4, v16
	v_mul_f32_e32 v4, v2, v6
	v_mbcnt_lo_u32_b32 v6, -1, 0
	v_mbcnt_hi_u32_b32 v6, -1, v6
	s_nop 0
	v_lshl_add_u32 v9, v6, 7, s0
	v_and_b32_e32 v8, 31, v6
	v_and_b32_e32 v9, 0xffffe000, v9
	v_lshlrev_b32_e32 v10, 5, v6
	v_add_u32_e32 v9, 0, v9
	v_lshlrev_b32_e32 v8, 1, v8
	v_and_b32_e32 v10, 0x400, v10
	v_add3_u32 v8, v9, v8, v10
	v_bfe_u32 v10, v21, 16, 1
	v_add3_u32 v10, v21, v10, s33
	s_barrier
; __device__ __forceinline__ unsigned f2bf(float f) { unsigned u = __builtin_bit_cast(unsigned, f); return (u + 0x7fffu + ((u >> 16) & 1u)) >> 16; }
; __device__ __forceinline__ int crow(int r, int hi) { return (r & 3) + 8 * (r >> 2) + 4 * hi; }
; __device__ __forceinline__ void store_o_tile(const f32x16 (&o)[4], char* lds, bf16_t* Og, int wave_s) {
;     ...
;     bf16_t* stg = (bf16_t*)(lds + wid * 8192);
; #pragma unroll
;     for (int r = 0; r < 16; ++r) { const int orow = att::crow(r, hi);
; #pragma unroll
;         for (int d0 = 0; d0 < 4; ++d0) stg[orow * 128 + d0 * 32 + r32] = (bf16_t)f2bf(o[d0][r]); }
;     asm volatile("s_waitcnt lgkmcnt(0)" ::: "memory");
; #pragma unroll
	ds_write_b16_d16_hi v8, v10
	v_bfe_u32 v10, v20, 16, 1
	v_add3_u32 v10, v20, v10, s33
	ds_write_b16_d16_hi v8, v10 offset:64
	v_bfe_u32 v10, v19, 16, 1
	v_add3_u32 v10, v19, v10, s33
	ds_write_b16_d16_hi v8, v10 offset:128
	v_bfe_u32 v10, v18, 16, 1
	v_add3_u32 v10, v18, v10, s33
	ds_write_b16_d16_hi v8, v10 offset:192
	v_bfe_u32 v10, v25, 16, 1
	v_add3_u32 v10, v25, v10, s33
	ds_write_b16_d16_hi v8, v10 offset:256
	v_bfe_u32 v10, v24, 16, 1
	v_add3_u32 v10, v24, v10, s33
	ds_write_b16_d16_hi v8, v10 offset:320
	v_bfe_u32 v10, v23, 16, 1
	v_add3_u32 v10, v23, v10, s33
	ds_write_b16_d16_hi v8, v10 offset:384
	v_bfe_u32 v10, v22, 16, 1
	v_add3_u32 v10, v22, v10, s33
	ds_write_b16_d16_hi v8, v10 offset:448
	v_bfe_u32 v10, v33, 16, 1
	v_add3_u32 v10, v33, v10, s33
	ds_write_b16_d16_hi v8, v10 offset:512
	v_bfe_u32 v10, v32, 16, 1
	v_add3_u32 v10, v32, v10, s33
	ds_write_b16_d16_hi v8, v10 offset:576
	v_bfe_u32 v10, v31, 16, 1
	v_add3_u32 v10, v31, v10, s33
	ds_write_b16_d16_hi v8, v10 offset:640
	v_bfe_u32 v10, v30, 16, 1
	v_add3_u32 v10, v30, v10, s33
	ds_write_b16_d16_hi v8, v10 offset:704
	v_bfe_u32 v10, v41, 16, 1
	v_add3_u32 v10, v41, v10, s33
	ds_write_b16_d16_hi v8, v10 offset:768
	v_bfe_u32 v10, v40, 16, 1
	v_add3_u32 v10, v40, v10, s33
	ds_write_b16_d16_hi v8, v10 offset:832
	v_bfe_u32 v10, v39, 16, 1
	v_add3_u32 v10, v39, v10, s33
	ds_write_b16_d16_hi v8, v10 offset:896
	v_bfe_u32 v10, v38, 16, 1
	v_add3_u32 v10, v38, v10, s33
	ds_write_b16_d16_hi v8, v10 offset:960
	v_bfe_u32 v10, v47, 16, 1
	v_add3_u32 v10, v47, v10, s33
	ds_write_b16_d16_hi v8, v10 offset:2048
	v_bfe_u32 v10, v46, 16, 1
	v_add3_u32 v10, v46, v10, s33
	ds_write_b16_d16_hi v8, v10 offset:2112
	v_bfe_u32 v10, v45, 16, 1
	v_add3_u32 v10, v45, v10, s33
	ds_write_b16_d16_hi v8, v10 offset:2176
	v_bfe_u32 v10, v44, 16, 1
	v_add3_u32 v10, v44, v10, s33
	ds_write_b16_d16_hi v8, v10 offset:2240
	v_bfe_u32 v10, v57, 16, 1
	v_add3_u32 v10, v57, v10, s33
	ds_write_b16_d16_hi v8, v10 offset:2304
	v_bfe_u32 v10, v56, 16, 1
	v_add3_u32 v10, v56, v10, s33
	ds_write_b16_d16_hi v8, v10 offset:2368
	v_bfe_u32 v10, v55, 16, 1
	v_add3_u32 v10, v55, v10, s33
	ds_write_b16_d16_hi v8, v10 offset:2432
	v_bfe_u32 v10, v54, 16, 1
	v_add3_u32 v10, v54, v10, s33
	ds_write_b16_d16_hi v8, v10 offset:2496
	v_bfe_u32 v10, v62, 16, 1
	v_add3_u32 v10, v62, v10, s33
	ds_write_b16_d16_hi v8, v10 offset:2560
	v_bfe_u32 v10, v61, 16, 1
	v_add3_u32 v10, v61, v10, s33
	ds_write_b16_d16_hi v8, v10 offset:2624
	v_bfe_u32 v10, v60, 16, 1
	v_add3_u32 v10, v60, v10, s33
	ds_write_b16_d16_hi v8, v10 offset:2688
	v_bfe_u32 v10, v59, 16, 1
	v_add3_u32 v10, v59, v10, s33
	ds_write_b16_d16_hi v8, v10 offset:2752
	v_bfe_u32 v10, v73, 16, 1
	v_add3_u32 v10, v73, v10, s33
	ds_write_b16_d16_hi v8, v10 offset:2816
	v_bfe_u32 v10, v72, 16, 1
	v_add3_u32 v10, v72, v10, s33
	ds_write_b16_d16_hi v8, v10 offset:2880
	v_bfe_u32 v10, v71, 16, 1
	v_add3_u32 v10, v71, v10, s33
	ds_write_b16_d16_hi v8, v10 offset:2944
	v_bfe_u32 v10, v63, 16, 1
	v_add3_u32 v10, v63, v10, s33
	ds_write_b16_d16_hi v8, v10 offset:3008
	v_bfe_u32 v10, v77, 16, 1
	v_add3_u32 v10, v77, v10, s33
	ds_write_b16_d16_hi v8, v10 offset:4096
	v_bfe_u32 v10, v76, 16, 1
	v_add3_u32 v10, v76, v10, s33
	ds_write_b16_d16_hi v8, v10 offset:4160
	v_bfe_u32 v10, v75, 16, 1
	v_add3_u32 v10, v75, v10, s33
	ds_write_b16_d16_hi v8, v10 offset:4224
	v_bfe_u32 v10, v74, 16, 1
	v_add3_u32 v10, v74, v10, s33
	ds_write_b16_d16_hi v8, v10 offset:4288
	v_bfe_u32 v10, v70, 16, 1
	v_add3_u32 v10, v70, v10, s33
	ds_write_b16_d16_hi v8, v10 offset:4352
	v_bfe_u32 v10, v69, 16, 1
	v_add3_u32 v10, v69, v10, s33
	ds_write_b16_d16_hi v8, v10 offset:4416
	v_bfe_u32 v10, v68, 16, 1
	v_add3_u32 v10, v68, v10, s33
	ds_write_b16_d16_hi v8, v10 offset:4480
	v_bfe_u32 v10, v67, 16, 1
	v_add3_u32 v10, v67, v10, s33
	ds_write_b16_d16_hi v8, v10 offset:4544
	v_bfe_u32 v10, v66, 16, 1
	v_add3_u32 v10, v66, v10, s33
	ds_write_b16_d16_hi v8, v10 offset:4608
	v_bfe_u32 v10, v65, 16, 1
	v_add3_u32 v10, v65, v10, s33
	ds_write_b16_d16_hi v8, v10 offset:4672
	v_bfe_u32 v10, v64, 16, 1
	v_add3_u32 v10, v64, v10, s33
	ds_write_b16_d16_hi v8, v10 offset:4736
	v_bfe_u32 v10, v58, 16, 1
	v_add3_u32 v10, v58, v10, s33
	ds_write_b16_d16_hi v8, v10 offset:4800
	v_bfe_u32 v10, v53, 16, 1
	v_add3_u32 v10, v53, v10, s33
	ds_write_b16_d16_hi v8, v10 offset:4864
	v_bfe_u32 v10, v52, 16, 1
	v_add3_u32 v10, v52, v10, s33
	ds_write_b16_d16_hi v8, v10 offset:4928
	v_bfe_u32 v10, v51, 16, 1
	v_add3_u32 v10, v51, v10, s33
	ds_write_b16_d16_hi v8, v10 offset:4992
	v_bfe_u32 v10, v50, 16, 1
	v_add3_u32 v10, v50, v10, s33
	ds_write_b16_d16_hi v8, v10 offset:5056
	v_bfe_u32 v10, v49, 16, 1
	v_add3_u32 v10, v49, v10, s33
	ds_write_b16_d16_hi v8, v10 offset:6144
	v_bfe_u32 v10, v48, 16, 1
	v_add3_u32 v10, v48, v10, s33
	ds_write_b16_d16_hi v8, v10 offset:6208
	v_bfe_u32 v10, v43, 16, 1
	v_add3_u32 v10, v43, v10, s33
	ds_write_b16_d16_hi v8, v10 offset:6272
	v_bfe_u32 v10, v42, 16, 1
	v_add3_u32 v10, v42, v10, s33
	ds_write_b16_d16_hi v8, v10 offset:6336
	v_bfe_u32 v10, v37, 16, 1
	v_add3_u32 v10, v37, v10, s33
	ds_write_b16_d16_hi v8, v10 offset:6400
	v_bfe_u32 v10, v36, 16, 1
	v_add3_u32 v10, v36, v10, s33
	ds_write_b16_d16_hi v8, v10 offset:6464
	v_bfe_u32 v10, v35, 16, 1
	v_add3_u32 v10, v35, v10, s33
	ds_write_b16_d16_hi v8, v10 offset:6528
	v_bfe_u32 v10, v34, 16, 1
	v_add3_u32 v10, v34, v10, s33
	ds_write_b16_d16_hi v8, v10 offset:6592
	v_bfe_u32 v10, v29, 16, 1
	v_add3_u32 v10, v29, v10, s33
	ds_write_b16_d16_hi v8, v10 offset:6656
	v_bfe_u32 v10, v28, 16, 1
	v_add3_u32 v10, v28, v10, s33
	ds_write_b16_d16_hi v8, v10 offset:6720
	v_bfe_u32 v10, v27, 16, 1
	v_add3_u32 v10, v27, v10, s33
	ds_write_b16_d16_hi v8, v10 offset:6784
	v_bfe_u32 v10, v26, 16, 1
	v_add3_u32 v10, v26, v10, s33
	ds_write_b16_d16_hi v8, v10 offset:6848
	v_bfe_u32 v10, v0, 16, 1
	v_add3_u32 v0, v0, v10, s33
	ds_write_b16_d16_hi v8, v0 offset:6912
	v_bfe_u32 v0, v7, 16, 1
	v_add3_u32 v0, v7, v0, s33
	v_ashrrev_i32_e32 v2, 1, v226
	ds_write_b16_d16_hi v8, v0 offset:6976
	v_bfe_u32 v0, v5, 16, 1
	v_and_b32_e32 v2, 0xffffffe0, v2
	v_add3_u32 v0, v5, v0, s33
	v_add_u32_e32 v2, s64, v2
	ds_write_b16_d16_hi v8, v0 offset:7040
	v_bfe_u32 v0, v4, 16, 1
	v_ashrrev_i32_e32 v3, 31, v2
	v_add3_u32 v0, v4, v0, s33
	v_lshlrev_b64 v[2:3], 12, v[2:3]
	ds_write_b16_d16_hi v8, v0 offset:7104
	v_lshlrev_b32_e32 v0, 4, v6
	v_lshl_add_u64 v[2:3], s[6:7], 0, v[2:3]
	v_and_b32_e32 v0, 0xf0, v0
	v_lshl_add_u64 v[2:3], s[10:11], 1, v[2:3]
	v_bfe_u32 v10, v6, 4, 2
	v_add_u32_e32 v11, v9, v0
	s_waitcnt lgkmcnt(0)
; template <int NQ, int MODE> ...
;     ...
;     unsigned voK1[2], voK2, voV[2];
; #pragma unroll
;     for (int i = 0; i < 2; ++i) { const int p = wid + 8 * i, row = 4 * p + (lane >> 4), cbs = (lane & 15) ^ (row & 15); voK1[i] = (unsigned)(row * ldk0 + cbs * 8) * 2u; }
;     { const int row = 8 * wid + (lane >> 3), cbs = (lane & 7) ^ ((row >> 1) & 7); voK2 = (unsigned)(row * ldk2 + cbs * 8) * 2u; }
; #pragma unroll
;     for (int i = 0; i < 2; ++i) { const int p = wid + 8 * i, sub = 2 * p + (lane >> 5), kk = ((sub >> 2) << 3) | ((lane & 31) >> 2);
;         const int k = kk, c = (sub & 3) * 32 + (lane & 3) * 8; voV[i] = (unsigned)(k * ldv + c) * 2u; }
;     const char* gK1 = (const char*)(K0 + (size_t)kt0 * KVBLK * ldk0); const size_t stK1 = (size_t)KVBLK * ldk0 * 2;
;     const char* gK2 = (const char*)(K2 + (size_t)kt0 * KVBLK * ldk2); const size_t stK2 = (size_t)KVBLK * ldk2 * 2;
;     const char* gV = (const char*)(Vh + (size_t)kt0 * KVBLK * ldv); const size_t stV = (size_t)KVBLK * ldv * 2;
;     LAS unsigned char* K3 = (LAS unsigned char*)K_lds; LAS unsigned char* V3 = (LAS unsigned char*)V_lds;
;     ...
;     const char* pK1a = gK1 + voK1[0]; const char* pK1b = gK1 + voK1[1]; const char* pK2p = gK2 + voK2; const char* pVa = gV + voV[0]; const char* pVb = gV + voV[1];
;     ...
;     bf16x8 qr[NQ];
;     const bf16_t* Qw = Qb + (long)(wid * QBLK + r32) * ldq + hi * 8;
;     __syncthreads();
; #pragma unroll
;     for (int d0 = 0; d0 < NQ; ++d0) qr[d0] = *reinterpret_cast<const bf16x8*>(Qw + d0 * 16);
; __device__ __forceinline__ void store_o_tile(const f32x16 (&o)[4], char* lds, bf16_t* Og, int wave_s) {
;     ...
;     for (int i = 0; i < 8; ++i) { const int row = i * 4 + (lane >> 4), ch = lane & 15; const u32x4 v = *(const u32x4*)(stg + row * 128 + ch * 8); *(u32x4*)(Og + (size_t)row * DM + ch * 8) = v;
;         if (i & 1) asm volatile("" ::: "memory"); }
; __global__ void __launch_bounds__(NTHR, 2) mega_fwd(Args a) {
;     ...
;         for (int u = vcu; u < 256; u += G) { PH
;             const int hd = u >> 6, blk = u & 63, q0 = blk * 256;
;             f32x16 o[4];
;     ...
;             float* lut = (float*)(lds + att::OFF_LUT);
;             { UNIT_IDS att::attn_core<8, 0>(P + (size_t)q0 * INP + C_AQ + hd * 128, INP, P + C_AK + (hd >> 1) * 128, INP, nullptr, 0, P + C_AV + (hd >> 1) * 128, INP, 0, SEQ / 64, q0, nullptr, 0.f, 0.f, 0.f, 0.f, (char*)lds, o, wave_s);
	v_lshl_add_u64 v[6:7], v[2:3], 0, v[0:1]
	v_lshl_add_u32 v0, v10, 8, v11
	ds_read_b128 v[2:5], v0
	v_lshlrev_b32_e32 v0, 12, v10
	v_lshl_add_u64 v[8:9], v[6:7], 0, v[0:1]
	v_or_b32_e32 v0, 4, v10
	v_readlane_b32 s0, v254, 31
	s_waitcnt lgkmcnt(0)
	global_store_dwordx4 v[8:9], v[2:5], off offset:3072
	s_add_i32 s40, s40, s0
	s_cmpk_gt_i32 s41, 0xff
	v_lshl_add_u32 v2, v0, 8, v11
	ds_read_b128 v[2:5], v2
	v_lshlrev_b32_e32 v0, 12, v0
	v_lshl_add_u64 v[8:9], v[6:7], 0, v[0:1]
	v_or_b32_e32 v0, 8, v10
	s_waitcnt lgkmcnt(0)
	global_store_dwordx4 v[8:9], v[2:5], off offset:3072
	s_nop 1
	v_lshl_add_u32 v2, v0, 8, v11
	ds_read_b128 v[2:5], v2
	v_lshlrev_b32_e32 v0, 12, v0
	v_lshl_add_u64 v[8:9], v[6:7], 0, v[0:1]
	v_or_b32_e32 v0, 12, v10
	s_waitcnt lgkmcnt(0)
	global_store_dwordx4 v[8:9], v[2:5], off offset:3072
	s_nop 1
	v_lshl_add_u32 v2, v0, 8, v11
	ds_read_b128 v[2:5], v2
	v_lshlrev_b32_e32 v0, 12, v0
	v_lshl_add_u64 v[8:9], v[6:7], 0, v[0:1]
	v_or_b32_e32 v0, 16, v10
	s_waitcnt lgkmcnt(0)
	global_store_dwordx4 v[8:9], v[2:5], off offset:3072
	s_nop 1
	v_lshl_add_u32 v2, v0, 8, v11
	ds_read_b128 v[2:5], v2
	v_lshlrev_b32_e32 v0, 12, v0
	v_lshl_add_u64 v[8:9], v[6:7], 0, v[0:1]
	v_or_b32_e32 v0, 20, v10
	s_waitcnt lgkmcnt(0)
	global_store_dwordx4 v[8:9], v[2:5], off offset:3072
	s_nop 1
	v_lshl_add_u32 v2, v0, 8, v11
	ds_read_b128 v[2:5], v2
	v_lshlrev_b32_e32 v0, 12, v0
	v_lshl_add_u64 v[8:9], v[6:7], 0, v[0:1]
	v_or_b32_e32 v0, 24, v10
	s_waitcnt lgkmcnt(0)
	global_store_dwordx4 v[8:9], v[2:5], off offset:3072
	s_nop 1
	v_lshl_add_u32 v2, v0, 8, v11
	ds_read_b128 v[2:5], v2
	v_lshlrev_b32_e32 v0, 12, v0
	v_lshl_add_u64 v[8:9], v[6:7], 0, v[0:1]
	v_or_b32_e32 v0, 28, v10
	s_waitcnt lgkmcnt(0)
	global_store_dwordx4 v[8:9], v[2:5], off offset:3072
	s_nop 1
	v_lshl_add_u32 v2, v0, 8, v11
	ds_read_b128 v[2:5], v2
	v_lshlrev_b32_e32 v0, 12, v0
	v_lshl_add_u64 v[6:7], v[6:7], 0, v[0:1]
	s_waitcnt lgkmcnt(0)
	global_store_dwordx4 v[6:7], v[2:5], off offset:3072
	s_waitcnt lgkmcnt(0)
	s_cbranch_scc1 .LBB0_380
.LBB0_384:
	s_bfe_u32 s83, s40, 0x60008
	s_lshl_b32 s0, s41, 8
	s_lshl_b32 s37, s83, 8
	s_and_b32 s64, s0, 0x3f00
	s_max_i32 s39, s37, 0x80
	s_mov_b64 s[28:29], s[60:61]
	s_ashr_i32 s38, s41, 6
	s_mul_i32 s0, s64, 0x2200
	s_add_u32 s0, s28, s0
	s_addc_u32 s1, s29, 0
	s_mov_b32 s30, s84
	s_add_u32 s82, s0, 0x12000000
	v_mbcnt_lo_u32_b32 v192, -1, 0
	v_mbcnt_hi_u32_b32 v192, -1, v192
	s_addc_u32 s73, s1, 0
	s_lshl_b32 s10, s38, 7
	v_mbcnt_lo_u32_b32 v10, -1, 0
	v_mbcnt_hi_u32_b32 v10, -1, v10
	s_ashr_i32 s11, s10, 31
	v_bfe_u32 v0, v10, 4, 2
	v_or_b32_e32 v2, s50, v0
	v_bitop3_b32 v0, v0, v10, s50 bitop3:0x36
	s_lshl_b64 s[34:35], s[10:11], 1
	v_mul_lo_u32 v2, v2, s49
	v_lshlrev_b32_e32 v0, 3, v0
	s_movk_i32 s6, 0x78
	s_add_u32 s78, s82, s34
	v_bfe_u32 v11, v10, 5, 1
	v_and_or_b32 v0, v0, s6, v2
	v_readlane_b32 s6, v254, 34
	v_lshlrev_b32_e32 v5, 3, v10
	s_addc_u32 s79, s73, s35
	v_and_b32_e32 v64, 31, v10
	v_bfe_u32 v3, v10, 2, 3
	v_or_b32_e32 v4, s6, v11
	v_and_b32_e32 v5, 24, v5
	v_readlane_b32 s6, v254, 35
	v_lshl_or_b32 v5, v4, 5, v5
	v_or_b32_e32 v12, s80, v64
	v_or_b32_e32 v4, s6, v3
	v_readlane_b32 s6, v254, 0
	v_mov_b64_e32 v[8:9], s[78:79]
	v_lshlrev_b32_e32 v48, 4, v11
	v_or_b32_e32 v3, s6, v3
	v_mad_u64_u32 v[8:9], s[6:7], v12, s69, v[8:9]
	v_mov_b32_e32 v49, v1
	v_lshl_add_u64 v[8:9], v[8:9], 0, v[48:49]
	s_barrier
	global_load_dwordx4 v[172:175], v[8:9], off
	global_load_dwordx4 v[168:171], v[8:9], off offset:32
	global_load_dwordx4 v[164:167], v[8:9], off offset:64
	global_load_dwordx4 v[160:163], v[8:9], off offset:96
	global_load_dwordx4 v[156:159], v[8:9], off offset:128
	global_load_dwordx4 v[152:155], v[8:9], off offset:160
	global_load_dwordx4 v[148:151], v[8:9], off offset:192
	global_load_dwordx4 v[144:147], v[8:9], off offset:224
	s_and_b32 s0, s41, 0xffffff80
	s_ashr_i32 s1, s0, 31
	s_lshl_b64 s[56:57], s[0:1], 1
	s_add_u32 s4, s28, s56
	s_addc_u32 s5, s29, s57
	s_add_u32 s0, s4, 0x12000400
	s_addc_u32 s1, s5, 0
	s_add_u32 s4, s4, 0x12000600
	v_mul_lo_u32 v3, v3, s49
	s_mov_b32 m0, s81
	s_addc_u32 s5, s5, 0
	v_lshlrev_b32_e32 v0, 1, v0
	v_or_b32_e32 v3, v5, v3
	s_add_i32 s67, s81, 0x2000
	v_add_u32_e32 v2, 0x44000, v0
	v_lshlrev_b32_e32 v6, 1, v3
	v_mov_b32_e32 v3, v1
	global_load_lds_dwordx4 v0, s[0:1]
	s_mov_b32 m0, s67
	v_mul_lo_u32 v4, v4, s49
	v_lshl_add_u64 v[54:55], s[0:1], 0, v[0:1]
	v_lshl_add_u64 v[50:51], s[0:1], 0, v[2:3]
	global_load_lds_dwordx4 v2, s[0:1]
	s_add_i32 s31, 0, 0x12000
	v_readlane_b32 s0, v254, 47
	v_or_b32_e32 v4, v5, v4
	s_add_i32 s14, s31, s0
	v_lshlrev_b32_e32 v4, 1, v4
	s_mov_b32 m0, s14
	s_add_i32 s15, s14, 0x2000
	global_load_lds_dwordx4 v4, s[4:5]
	s_mov_b32 m0, s15
	s_add_i32 s70, s81, 0x4000
	v_lshl_add_u64 v[2:3], v[54:55], 0, s[74:75]
	global_load_lds_dwordx4 v6, s[4:5]
	s_mov_b32 m0, s70
	s_add_i32 s85, s81, 0x6000
	v_lshl_add_u64 v[8:9], v[50:51], 0, s[74:75]
	global_load_lds_dwordx4 v[2:3], off
	s_mov_b32 m0, s85
	s_add_i32 s87, s81, 0x8000
	global_load_lds_dwordx4 v[8:9], off
	v_mov_b32_e32 v5, v1
	s_waitcnt vmcnt(2) lgkmcnt(0)
	s_barrier
; #define DMA_K(t, st) do { if (HAS1) { GLDS(pK1a, K3 + (st) * SHM_KT + wid * 1024); GLDS(pK1b, K3 + (st) * SHM_KT + (wid + 8) * 1024); pK1a += stK1; pK1b += stK1; } \
;     if (HAS2) { GLDS(pK2p, K3 + (st) * SHM_KT + SHM_K1 + wid * 1024); pK2p += stK2; } } while (0)
; #define DMA_V(t, st) do { GLDS(pVa, V3 + (st) * SHM_V + wid * 1024); GLDS(pVb, V3 + (st) * SHM_V + (wid + 8) * 1024); pVa += stV; pVb += stV; } while (0)
; #define WAITB(n) do { if ((n) == 0) WAIT_BAR(0); else if ((n) == 1) WAIT_BAR(1); else if ((n) == 2) WAIT_BAR(2); else if ((n) == 3) WAIT_BAR(3); else if ((n) == 4) WAIT_BAR(4); else WAIT_BAR(5); } while (0)
; #define CINIT(t) do { TILEP(t); (void)relb; if (FOLD && __builtin_expect(dirty || cbT != cur_cb, 0)) { const float v_ = cbT - m_reg; _Pragma("unroll") for (int r = 0; r < 16; ++r) cinit[r] = v_; asm volatile("" : "+v"(cinit)); cur_cb = cbT; dirty = false; } } while (0)
; template <int NQ>
; __device__ __forceinline__ void qkt(f32x16& p0, f32x16& p1, const char* Ks, const int (&kq1)[2], const int (&kq2)[2], const bf16x8* qr, const f32x16& cinit) {
;     int kb1[8], kb2[4];
; #pragma unroll
;     for (int i = 0; i < 8; ++i) kb1[i] = kq1[0] + ((i ^ kq1[1]) << 5);
; #pragma unroll
;     for (int i = 0; i < 4; ++i) kb2[i] = kq2[0] + ((i ^ kq2[1]) << 5);
;     constexpr bool HAS1 = NQ >= 8, HAS2 = NQ != 8; constexpr int SHM_K1 = HAS1 ? 16384 : 0;
;     p0 = cinit; p1 = cinit;
;     if (HAS1) {
; #pragma unroll
;         for (int d0 = 0; d0 < 8; ++d0) { const char* a = Ks + kb1[d0];
;             const bf16x8 b0 = *reinterpret_cast<const bf16x8*>(a); const bf16x8 b1 = *reinterpret_cast<const bf16x8*>(a + 8192);
;             p0 = __builtin_amdgcn_mfma_f32_32x32x16_bf16(b0, qr[d0], p0, 0, 0, 0);
;             p1 = __builtin_amdgcn_mfma_f32_32x32x16_bf16(b1, qr[d0], p1, 0, 0, 0); } }
; template <int NQ, int MODE> ...
;     ...
;     WAITB(NLK);
;     if (2 < NT) DMA_K(2, 2); DMA_V(1, 1);
;     CINIT(0);
;     qkt<NQ>(pA0, pA1, K_lds, kb1, kb2, qr, cinit); { TILEP(0); (void)cbT; rsA = partialSM<MODE, true, FOLD>(pA0, pA1, m_reg, alA, relb, nearT, lut, cbT); dirty |= rsA; }
	v_lshl_add_u64 v[8:9], v[54:55], 0, s[46:47]
	s_mov_b32 m0, s87
	s_add_i32 s86, s81, 0xa000
	v_mov_b32_e32 v7, v1
	v_lshl_add_u64 v[56:57], s[4:5], 0, v[4:5]
	v_bitop3_b32 v0, v11, v10, 1 bitop3:0x78
	v_lshlrev_b32_e32 v11, 8, v64
	v_lshlrev_b32_e32 v12, 4, v10
	v_lshl_add_u64 v[2:3], v[50:51], 0, s[46:47]
	global_load_lds_dwordx4 v[8:9], off
	s_mov_b32 m0, s86
	s_add_i32 s71, s81, 0x16000
	v_lshl_add_u64 v[52:53], s[4:5], 0, v[6:7]
	v_lshl_add_u64 v[4:5], v[56:57], 0, s[74:75]
	global_load_lds_dwordx4 v[2:3], off
	s_mov_b32 m0, s71
	s_add_i32 s72, s81, 0x18000
	v_lshl_or_b32 v49, v0, 4, v11
	v_and_b32_e32 v65, 0xe0, v12
	v_lshl_add_u64 v[6:7], v[52:53], 0, s[74:75]
	global_load_lds_dwordx4 v[4:5], off
	s_mov_b32 m0, s72
	v_mov_b32_e32 v16, v1
	v_mov_b32_e32 v17, v1
	v_mov_b32_e32 v18, v1
	v_mov_b32_e32 v19, v1
	v_mov_b32_e32 v20, v1
	v_mov_b32_e32 v21, v1
	v_mov_b32_e32 v22, v1
	v_mov_b32_e32 v23, v1
	v_mov_b32_e32 v24, v1
	v_mov_b32_e32 v25, v1
	v_mov_b32_e32 v26, v1
	v_mov_b32_e32 v27, v1
	v_mov_b32_e32 v28, v1
	v_mov_b32_e32 v29, v1
	v_mov_b32_e32 v30, v1
	v_mov_b32_e32 v31, v1
	v_add3_u32 v0, 0, v65, v49
	global_load_lds_dwordx4 v[6:7], off
	ds_read_b128 v[2:5], v0
	ds_read_b128 v[6:9], v0 offset:8192
	s_waitcnt vmcnt(0) lgkmcnt(0)
	v_mfma_f32_32x32x16_bf16 v[32:47], v[2:5], v[172:175], v[16:31]
	v_bitop3_b32 v215, v12, 32, v221 bitop3:0x6c
	v_add3_u32 v0, 0, v215, v49
	v_bitop3_b32 v214, v12, 64, v221 bitop3:0x6c
	v_bitop3_b32 v213, v12, s45, v221 bitop3:0x6c
	s_movk_i32 s0, 0x80
	v_bitop3_b32 v212, v12, s0, v221 bitop3:0x6c
	s_movk_i32 s0, 0xa0
	v_mfma_f32_32x32x16_bf16 v[16:31], v[6:9], v[172:175], v[16:31]
	ds_read_b128 v[2:5], v0
	ds_read_b128 v[6:9], v0 offset:8192
	v_add3_u32 v0, 0, v214, v49
	v_bitop3_b32 v199, v12, s0, v221 bitop3:0x6c
	v_and_b32_e32 v66, 63, v10
	s_movk_i32 s0, 0xc0
	v_bitop3_b32 v198, v12, s0, v221 bitop3:0x6c
	v_add3_u32 v11, 0, v198, v49
	s_waitcnt lgkmcnt(0)
	v_mfma_f32_32x32x16_bf16 v[16:31], v[6:9], v[168:171], v[16:31]
	s_movk_i32 s0, 0xe0
	v_bitop3_b32 v197, v12, s0, v12 bitop3:0xc
	s_mov_b32 m0, s81
	v_lshl_add_u64 v[14:15], v[50:51], 0, s[76:77]
	s_add_i32 s65, s81, 0x1a000
	v_lshl_add_u64 v[62:63], v[56:57], 0, s[46:47]
	s_add_i32 s66, s81, 0x1c000
	v_mfma_f32_32x32x16_bf16 v[32:47], v[2:5], v[168:171], v[32:47]
	ds_read_b128 v[2:5], v0
	ds_read_b128 v[6:9], v0 offset:8192
	v_add3_u32 v0, 0, v213, v49
	s_mov_b64 s[4:5], 0x220000
	s_mov_b32 s12, 1
	s_mov_b32 s16, 0
	v_lshl_add_u64 v[184:185], v[54:55], 0, s[4:5]
	v_lshl_add_u64 v[186:187], v[56:57], 0, s[76:77]
	s_waitcnt lgkmcnt(0)
	v_mfma_f32_32x32x16_bf16 v[16:31], v[6:9], v[164:167], v[16:31]
	v_mfma_f32_32x32x16_bf16 v[32:47], v[2:5], v[164:167], v[32:47]
	ds_read_b128 v[2:5], v0
	ds_read_b128 v[6:9], v0 offset:8192
	v_add3_u32 v0, 0, v212, v49
	s_waitcnt lgkmcnt(0)
	v_mfma_f32_32x32x16_bf16 v[16:31], v[6:9], v[160:163], v[16:31]
	v_mfma_f32_32x32x16_bf16 v[32:47], v[2:5], v[160:163], v[32:47]
	ds_read_b128 v[2:5], v0
	ds_read_b128 v[6:9], v0 offset:8192
	v_add3_u32 v0, 0, v199, v49
	s_waitcnt lgkmcnt(0)
	v_mfma_f32_32x32x16_bf16 v[16:31], v[6:9], v[156:159], v[16:31]
	v_mfma_f32_32x32x16_bf16 v[32:47], v[2:5], v[156:159], v[32:47]
	ds_read_b128 v[2:5], v0
	ds_read_b128 v[6:9], v0 offset:8192
	v_lshlrev_b32_e32 v0, 3, v66
	s_waitcnt lgkmcnt(0)
	v_mfma_f32_32x32x16_bf16 v[16:31], v[6:9], v[152:155], v[16:31]
	v_and_b32_e32 v6, 0xc0, v12
	v_lshlrev_b32_e32 v7, 1, v10
	v_and_or_b32 v6, v0, 24, v6
	v_and_b32_e32 v7, 32, v7
	v_and_b32_e32 v0, 0x100, v0
	v_or3_b32 v67, v6, v7, v0
	ds_read_b128 v[6:9], v11 offset:8192
	v_mfma_f32_32x32x16_bf16 v[32:47], v[2:5], v[152:155], v[32:47]
	ds_read_b128 v[2:5], v11
	v_mov_b32_e32 v0, v1
	s_waitcnt lgkmcnt(1)
	v_mfma_f32_32x32x16_bf16 v[16:31], v[6:9], v[148:151], v[16:31]
	v_add3_u32 v6, 0, v197, v49
	ds_read_b128 v[10:13], v6
	ds_read_b128 v[58:61], v6 offset:8192
	s_waitcnt vmcnt(4) lgkmcnt(0)
	s_barrier
; #define DMA_V(t, st) do { GLDS(pVa, V3 + (st) * SHM_V + wid * 1024); GLDS(pVb, V3 + (st) * SHM_V + (wid + 8) * 1024); pVa += stV; pVb += stV; } while (0)
; template <int MODE, bool FIRST, bool FOLD>
; __device__ __forceinline__ bool partialSM(f32x16& p0, f32x16& p1, float& m_reg, float& alpha, int relbase, bool near, const float* lut, float cb) {
;     if (!FOLD) { const float off_ = cb - m_reg;
; #pragma unroll
;         for (int r = 0; r < 16; ++r) { p0[r] += off_; p1[r] += off_; } }
;     if (MODE != 0 && near) {
; #pragma unroll
;         for (int r = 0; r < 16; ++r) { const int rel = relbase + (r & 3) + 8 * (r >> 2), rel1 = rel + 32;
;             const int i0 = min(max(rel, -128), 128) + 128, i1 = min(max(rel1, -128), 128) + 128;
;             const float b0 = lut[i0], b1 = lut[i1];
;             if (MODE == 1) { p0[r] += b0; p1[r] += b1; }
;             else { p0[r] = (rel >= -128 && rel <= 128) ? p0[r] + b0 : -1e30f; p1[r] = (rel1 >= -128 && rel1 <= 128) ? p1[r] + b1 : -1e30f; } }
;     }
;     float pmax = p0[0];
; #pragma unroll
;     for (int r = 1; r < 16; ++r) pmax = fmaxf(pmax, p0[r]);
; #pragma unroll
;     for (int r = 0; r < 16; ++r) pmax = fmaxf(pmax, p1[r]);
;     { auto rr = __builtin_amdgcn_permlane32_swap(__float_as_uint(pmax), __float_as_uint(pmax), false, false);
;       pmax = fmaxf(__uint_as_float(rr[0]), __uint_as_float(rr[1])); }
;     bool resc;
;     if (FIRST && MODE != 2) resc = true; else resc = __any(pmax > THR2);
;     if (__builtin_expect(resc, FIRST && MODE != 2)) {
;         const float delta = (FIRST && MODE != 2) ? pmax : fmaxf(pmax, 0.f);
;         m_reg += delta; alpha = (FIRST && MODE != 2) ? 1.f : __builtin_amdgcn_exp2f(-delta);
; #pragma unroll
;         for (int r = 0; r < 16; ++r) { p0[r] -= delta; p1[r] -= delta; }
;     } else alpha = 1.f;
; #pragma unroll
;     for (int r = 0; r < 16; ++r) p0[r] = __builtin_amdgcn_exp2f(p0[r]);
; template <int NQ, int MODE> ...
;     ...
;     if (2 < NT) DMA_K(2, 2); DMA_V(1, 1);
;     CINIT(0);
;     qkt<NQ>(pA0, pA1, K_lds, kb1, kb2, qr, cinit); { TILEP(0); (void)cbT; rsA = partialSM<MODE, true, FOLD>(pA0, pA1, m_reg, alA, relb, nearT, lut, cbT); dirty |= rsA; }
;     l_reg *= alA;
;     if (2 < NT) WAITB(NL); else WAITB(NLV);
;     ...
;     int kc = 1, vp = 0;
;     ...
;     bf16x8 kfp0 = {}, kfp1 = {};
;     ...
;     DMA_K(3, 0); DMA_V(2, 2);
;     KPRE(kc); CINIT(1);
	v_mov_b32_e32 v6, v1
	v_mov_b32_e32 v7, v1
	v_mov_b32_e32 v8, v1
	v_mov_b32_e32 v9, v1
	s_waitcnt lgkmcnt(2)
	v_mfma_f32_32x32x16_bf16 v[32:47], v[2:5], v[148:151], v[32:47]
	v_lshl_add_u64 v[2:3], v[54:55], 0, s[76:77]
	global_load_lds_dwordx4 v[2:3], off
	s_mov_b32 m0, s67
	v_lshl_add_u64 v[4:5], v[52:53], 0, s[46:47]
	global_load_lds_dwordx4 v[14:15], off
	s_mov_b32 m0, s65
	s_waitcnt lgkmcnt(0)
	v_mfma_f32_32x32x16_bf16 v[32:47], v[10:13], v[144:147], v[32:47]
	global_load_lds_dwordx4 v[62:63], off
	s_mov_b32 m0, s66
	v_mov_b32_e32 v2, v1
	global_load_lds_dwordx4 v[4:5], off
	v_mov_b32_e32 v3, v1
	v_mfma_f32_32x32x16_bf16 v[16:31], v[58:61], v[144:147], v[16:31]
	s_nop 5
	v_max_f32_e32 v58, v33, v33
	v_max_f32_e32 v59, v32, v32
	v_max_f32_e32 v58, v59, v58
	v_max3_f32 v58, v58, v34, v35
	v_max3_f32 v58, v58, v36, v37
	v_max3_f32 v58, v58, v38, v39
	v_max3_f32 v58, v58, v40, v41
	v_max3_f32 v58, v58, v42, v43
	v_max3_f32 v58, v58, v44, v45
	v_max3_f32 v58, v58, v46, v47
	v_max3_f32 v58, v58, v16, v17
	v_max3_f32 v58, v58, v18, v19
	v_max3_f32 v58, v58, v20, v21
	v_max3_f32 v58, v58, v22, v23
	v_max3_f32 v58, v58, v24, v25
	v_max3_f32 v58, v58, v26, v27
	v_max3_f32 v58, v58, v28, v29
	v_max3_f32 v58, v58, v30, v31
	v_mov_b32_e32 v59, v58
	s_nop 1
	v_permlane32_swap_b32_e32 v58, v59
	v_max_f32_e32 v59, v59, v59
	v_max_f32_e32 v58, v58, v58
	v_max_f32_e32 v58, v58, v59
	v_sub_f32_e32 v32, v32, v58
	v_exp_f32_e32 v231, v32
	v_or_b32_e32 v32, v49, v65
	v_add_u32_e32 v216, 0, v32
	v_sub_f32_e32 v33, v33, v58
	v_sub_f32_e32 v34, v34, v58
	v_sub_f32_e32 v35, v35, v58
	v_sub_f32_e32 v36, v36, v58
	v_sub_f32_e32 v37, v37, v58
	v_sub_f32_e32 v38, v38, v58
	v_sub_f32_e32 v39, v39, v58
	v_sub_f32_e32 v40, v40, v58
	v_sub_f32_e32 v41, v41, v58
	v_sub_f32_e32 v42, v42, v58
	v_sub_f32_e32 v43, v43, v58
	v_sub_f32_e32 v44, v44, v58
	v_sub_f32_e32 v45, v45, v58
	v_sub_f32_e32 v46, v46, v58
	v_sub_f32_e32 v47, v47, v58
	ds_read_b128 v[180:183], v216 offset:16384
	ds_read_b128 v[176:179], v216 offset:24576
	v_exp_f32_e32 v232, v33
	v_exp_f32_e32 v233, v34
	v_exp_f32_e32 v235, v35
	v_exp_f32_e32 v234, v36
	v_exp_f32_e32 v236, v37
	v_exp_f32_e32 v237, v38
	v_exp_f32_e32 v238, v39
	v_exp_f32_e32 v200, v40
	v_exp_f32_e32 v201, v41
	v_exp_f32_e32 v202, v42
	v_exp_f32_e32 v225, v43
	v_exp_f32_e32 v203, v44
	v_exp_f32_e32 v228, v45
	v_exp_f32_e32 v229, v46
	v_exp_f32_e32 v230, v47
	v_add_f32_e32 v217, 0, v58
	v_mov_b32_e32 v4, v1
	v_mov_b32_e32 v5, v1
	v_mov_b32_e32 v10, v1
	v_mov_b32_e32 v11, v1
	v_mov_b32_e32 v12, v1
	v_mov_b32_e32 v13, v1
	v_mov_b32_e32 v14, v1
	v_mov_b32_e32 v15, v1
	s_cmp_lg_u32 s31, -1
	s_cselect_b32 s0, s31, 0
	s_cmp_lg_u32 0, -1
	v_add_u32_e32 v196, s0, v67
	s_cselect_b32 s0, 0, 0
	v_sub_f32_e32 v80, 0, v217
	v_sub_f32_e32 v111, v31, v58
	v_sub_f32_e32 v110, v30, v58
	v_sub_f32_e32 v109, v29, v58
	v_sub_f32_e32 v108, v28, v58
	v_sub_f32_e32 v107, v27, v58
	v_sub_f32_e32 v106, v26, v58
	v_sub_f32_e32 v105, v25, v58
	v_sub_f32_e32 v104, v24, v58
	v_sub_f32_e32 v103, v23, v58
	v_sub_f32_e32 v102, v22, v58
	v_sub_f32_e32 v101, v21, v58
	v_sub_f32_e32 v100, v20, v58
	v_sub_f32_e32 v99, v19, v58
	v_sub_f32_e32 v98, v18, v58
	v_sub_f32_e32 v97, v17, v58
	v_sub_f32_e32 v96, v16, v58
	v_lshl_add_u64 v[188:189], v[50:51], 0, s[4:5]
	v_lshl_add_u64 v[190:191], v[52:53], 0, s[76:77]
	v_add_u32_e32 v226, s0, v49
	v_cmp_gt_u32_e64 s[4:5], 32, v66
	v_lshl_add_u32 v194, v64, 2, s97
	v_add_u32_e32 v193, s97, v48
	v_mov_b64_e32 v[30:31], v[14:15]
	v_mov_b64_e32 v[46:47], v[14:15]
	v_mov_b64_e32 v[62:63], v[14:15]
	v_mov_b64_e32 v[78:79], v[14:15]
	s_mov_b64 s[90:91], 0x220000
	v_mov_b32_e32 v81, v80
	v_mov_b32_e32 v82, v80
	v_mov_b32_e32 v83, v80
	v_mov_b32_e32 v84, v80
	v_mov_b32_e32 v85, v80
	v_mov_b32_e32 v86, v80
	v_mov_b32_e32 v87, v80
	v_mov_b32_e32 v88, v80
	v_mov_b32_e32 v89, v80
	v_mov_b32_e32 v90, v80
	v_mov_b32_e32 v91, v80
	v_mov_b32_e32 v92, v80
	v_mov_b32_e32 v93, v80
	v_mov_b32_e32 v94, v80
	v_mov_b32_e32 v95, v80
	v_mov_b32_e32 v195, 0
	s_movk_i32 s17, 0xff04
	v_mov_b64_e32 v[28:29], v[12:13]
	v_mov_b64_e32 v[26:27], v[10:11]
	v_mov_b64_e32 v[24:25], v[8:9]
	v_mov_b64_e32 v[22:23], v[6:7]
	v_mov_b64_e32 v[20:21], v[4:5]
	v_mov_b64_e32 v[18:19], v[2:3]
	v_mov_b64_e32 v[16:17], v[0:1]
	v_mov_b64_e32 v[44:45], v[12:13]
	v_mov_b64_e32 v[42:43], v[10:11]
	v_mov_b64_e32 v[40:41], v[8:9]
	v_mov_b64_e32 v[38:39], v[6:7]
	v_mov_b64_e32 v[36:37], v[4:5]
	v_mov_b64_e32 v[34:35], v[2:3]
	v_mov_b64_e32 v[32:33], v[0:1]
	v_mov_b64_e32 v[60:61], v[12:13]
	v_mov_b64_e32 v[58:59], v[10:11]
	v_mov_b64_e32 v[56:57], v[8:9]
	v_mov_b64_e32 v[54:55], v[6:7]
	v_mov_b64_e32 v[52:53], v[4:5]
	v_mov_b64_e32 v[50:51], v[2:3]
	v_mov_b64_e32 v[48:49], v[0:1]
	v_mov_b64_e32 v[76:77], v[12:13]
	v_mov_b64_e32 v[74:75], v[10:11]
	v_mov_b64_e32 v[72:73], v[8:9]
	v_mov_b64_e32 v[70:71], v[6:7]
	v_mov_b64_e32 v[68:69], v[4:5]
	v_mov_b64_e32 v[66:67], v[2:3]
	v_mov_b64_e32 v[64:65], v[0:1]

; #define SBAR() __builtin_amdgcn_sched_barrier(0)
; #define PK4(P, BASE, OUT) do { u32x4 w = {cvtpk(P[BASE + 0], P[BASE + 1]), cvtpk(P[BASE + 2], P[BASE + 3]), cvtpk(P[BASE + 4], P[BASE + 5]), cvtpk(P[BASE + 6], P[BASE + 7])}; \
;     OUT = *reinterpret_cast<bf16x8*>(&w); } while (0)
; template <bool RSM> __device__ __forceinline__ void pv_d0(f32x16* o, f32x16& lacc, int vb, bf16x8 pa0, bf16x8 pa1, bf16x8 pa2, bf16x8 pa3) {
;     if (RSM) {
;         const bf16x8 ones = {0x3F80, 0x3F80, 0x3F80, 0x3F80, 0x3F80, 0x3F80, 0x3F80, 0x3F80};
;         lacc = __builtin_amdgcn_mfma_f32_32x32x16_bf16(pa0, ones, lacc, 0, 0, 0);
;         lacc = __builtin_amdgcn_mfma_f32_32x32x16_bf16(pa1, ones, lacc, 0, 0, 0);
;         lacc = __builtin_amdgcn_mfma_f32_32x32x16_bf16(pa2, ones, lacc, 0, 0, 0);
;         lacc = __builtin_amdgcn_mfma_f32_32x32x16_bf16(pa3, ones, lacc, 0, 0, 0); }
;     pv_one<0>(o[0], vb, pa0, pa1, pa2, pa3); pv_one<1>(o[1], vb, pa0, pa1, pa2, pa3); pv_one<2>(o[2], vb, pa0, pa1, pa2, pa3); pv_one<3>(o[3], vb, pa0, pa1, pa2, pa3);
; template <bool RSM> __device__ __forceinline__ void finishSM(f32x16& p0, f32x16& p1, float& l_reg, bf16x8& pa0, bf16x8& pa1, bf16x8& pa2, bf16x8& pa3) {
; #pragma unroll
;     for (int r = 0; r < 16; ++r) p1[r] = __builtin_amdgcn_exp2f(p1[r]);
;     float ps = 0;
;     if (!RSM) {
; #pragma unroll
;     for (int r = 0; r < 16; ++r) ps += p0[r];
; #pragma unroll
;     for (int r = 0; r < 16; ++r) ps += p1[r];
;     { auto rr = __builtin_amdgcn_permlane32_swap(__float_as_uint(ps), __float_as_uint(ps), false, false);
;       ps = __uint_as_float(rr[0]) + __uint_as_float(rr[1]); }
;     l_reg += ps; }
;     ...
;     PK4(p0, 0, pa0); PK4(p0, 8, pa1); PK4(p1, 0, pa2); PK4(p1, 8, pa3);
;     ...
; }
; template <int NQ, int MODE> ...
;     ...
;     finishSM<RSM>(pB0, pB1, l_reg, pa0, pa1, pa2, pa3); SBAR();
;     pv_d0<RSM>(o, lacc, vb0 + VST(vp + 1) * SHM_V, pa0, pa1, pa2, pa3);
;     (void)alA;
;     if (hi == 0) li_l[r32] = l_reg; asm volatile("s_waitcnt lgkmcnt(0)" ::: "memory");
.LBB0_436:
	v_exp_f32_e32 v5, v112
	v_exp_f32_e32 v6, v113
	v_exp_f32_e32 v7, v114
	v_exp_f32_e32 v8, v115
	v_exp_f32_e32 v9, v116
	v_add_f32_e32 v3, 0, v5
	v_exp_f32_e32 v10, v117
	v_add_f32_e32 v3, v6, v3
	v_exp_f32_e32 v11, v118
	v_add_f32_e32 v3, v7, v3
	v_exp_f32_e32 v12, v119
	v_add_f32_e32 v3, v8, v3
	v_exp_f32_e32 v13, v120
	v_add_f32_e32 v3, v9, v3
	v_exp_f32_e32 v15, v121
	v_add_f32_e32 v3, v10, v3
	v_exp_f32_e32 v96, v122
	v_add_f32_e32 v3, v11, v3
	v_exp_f32_e32 v97, v123
	v_add_f32_e32 v3, v12, v3
	v_exp_f32_e32 v98, v124
	v_add_f32_e32 v3, v13, v3
	v_exp_f32_e32 v99, v125
	v_add_f32_e32 v3, v15, v3
	v_exp_f32_e32 v100, v126
	v_add_f32_e32 v3, v96, v3
	v_exp_f32_e32 v101, v127
	v_add_f32_e32 v3, v97, v3
	v_exp_f32_e32 v80, v80
	v_add_f32_e32 v3, v98, v3
	v_exp_f32_e32 v81, v81
	v_add_f32_e32 v3, v99, v3
	v_exp_f32_e32 v82, v82
	v_add_f32_e32 v3, v100, v3
	v_exp_f32_e32 v83, v83
	v_add_f32_e32 v3, v101, v3
	v_exp_f32_e32 v84, v84
	v_add_f32_e32 v3, v80, v3
	v_exp_f32_e32 v85, v85
	v_add_f32_e32 v3, v81, v3
	v_exp_f32_e32 v86, v86
	v_add_f32_e32 v3, v82, v3
	v_exp_f32_e32 v87, v87
	v_add_f32_e32 v3, v83, v3
	v_exp_f32_e32 v88, v88
	v_add_f32_e32 v3, v84, v3
	v_exp_f32_e32 v89, v89
	v_add_f32_e32 v3, v85, v3
	v_exp_f32_e32 v90, v90
	v_add_f32_e32 v3, v86, v3
	v_exp_f32_e32 v91, v91
	v_add_f32_e32 v3, v87, v3
	v_exp_f32_e32 v92, v92
	v_add_f32_e32 v3, v88, v3
	v_exp_f32_e32 v93, v93
	v_add_f32_e32 v3, v89, v3
	v_exp_f32_e32 v94, v94
	v_add_f32_e32 v3, v90, v3
	v_exp_f32_e32 v95, v95
	v_add_f32_e32 v3, v91, v3
	v_add_f32_e32 v3, v92, v3
	v_add_f32_e32 v3, v93, v3
	v_add_f32_e32 v3, v94, v3
	v_add_f32_e32 v3, v95, v3
	v_mov_b32_e32 v4, v3
	s_nop 1
	v_permlane32_swap_b32_e32 v3, v4
	v_cvt_pk_bf16_f32 v6, v5, v6
	v_cvt_pk_bf16_f32 v7, v7, v8
	v_cvt_pk_bf16_f32 v8, v9, v10
	v_cvt_pk_bf16_f32 v9, v11, v12
	v_cvt_pk_bf16_f32 v10, v13, v15
	v_cvt_pk_bf16_f32 v11, v96, v97
	v_cvt_pk_bf16_f32 v12, v98, v99
	v_cvt_pk_bf16_f32 v13, v100, v101
	v_cvt_pk_bf16_f32 v80, v80, v81
	v_cvt_pk_bf16_f32 v81, v82, v83
	v_cvt_pk_bf16_f32 v82, v84, v85
	v_cvt_pk_bf16_f32 v83, v86, v87
	v_cvt_pk_bf16_f32 v84, v88, v89
	v_cvt_pk_bf16_f32 v85, v90, v91
	v_cvt_pk_bf16_f32 v86, v92, v93
	v_cvt_pk_bf16_f32 v87, v94, v95
	s_addk_i32 s12, 0x4000
	s_cmp_lt_i32 s16, 3
	s_cselect_b32 s6, s12, 0
	v_add_u32_e32 v5, s6, v196
	ds_read_b64_tr_b16 v[88:89], v5 offset:0
	ds_read_b64_tr_b16 v[90:91], v5 offset:0x800
	ds_read_b64_tr_b16 v[92:93], v5 offset:0x1000
	ds_read_b64_tr_b16 v[94:95], v5 offset:0x1800
	ds_read_b64_tr_b16 v[96:97], v5 offset:0x2000
	ds_read_b64_tr_b16 v[98:99], v5 offset:0x2800
	ds_read_b64_tr_b16 v[100:101], v5 offset:0x3000
	ds_read_b64_tr_b16 v[102:103], v5 offset:0x3800
	s_waitcnt lgkmcnt(0)
	s_nop 0
	v_mfma_f32_32x32x16_bf16 v[64:79], v[6:9], v[88:91], v[64:79]
	ds_read_b64_tr_b16 v[88:89], v5 offset:0x200
	ds_read_b64_tr_b16 v[90:91], v5 offset:0xa00
	v_mfma_f32_32x32x16_bf16 v[64:79], v[10:13], v[92:95], v[64:79]
	ds_read_b64_tr_b16 v[92:93], v5 offset:0x1200
	ds_read_b64_tr_b16 v[94:95], v5 offset:0x1a00
	v_mfma_f32_32x32x16_bf16 v[64:79], v[80:83], v[96:99], v[64:79]
	ds_read_b64_tr_b16 v[96:97], v5 offset:0x2200
	ds_read_b64_tr_b16 v[98:99], v5 offset:0x2a00
	v_mfma_f32_32x32x16_bf16 v[64:79], v[84:87], v[100:103], v[64:79]
	ds_read_b64_tr_b16 v[100:101], v5 offset:0x3200
	ds_read_b64_tr_b16 v[102:103], v5 offset:0x3a00
	s_waitcnt lgkmcnt(0)
	v_mfma_f32_32x32x16_bf16 v[48:63], v[6:9], v[88:91], v[48:63]
	ds_read_b64_tr_b16 v[88:89], v5 offset:0x400
	ds_read_b64_tr_b16 v[90:91], v5 offset:0xc00
	v_mfma_f32_32x32x16_bf16 v[48:63], v[10:13], v[92:95], v[48:63]
	ds_read_b64_tr_b16 v[92:93], v5 offset:0x1400
	ds_read_b64_tr_b16 v[94:95], v5 offset:0x1c00
	v_mfma_f32_32x32x16_bf16 v[48:63], v[80:83], v[96:99], v[48:63]
	ds_read_b64_tr_b16 v[96:97], v5 offset:0x2400
	ds_read_b64_tr_b16 v[98:99], v5 offset:0x2c00
	v_mfma_f32_32x32x16_bf16 v[48:63], v[84:87], v[100:103], v[48:63]
	ds_read_b64_tr_b16 v[100:101], v5 offset:0x3400
	ds_read_b64_tr_b16 v[102:103], v5 offset:0x3c00
	s_waitcnt lgkmcnt(0)
	v_mfma_f32_32x32x16_bf16 v[32:47], v[6:9], v[88:91], v[32:47]
	ds_read_b64_tr_b16 v[88:89], v5 offset:0x600
	ds_read_b64_tr_b16 v[90:91], v5 offset:0xe00
	v_mfma_f32_32x32x16_bf16 v[32:47], v[10:13], v[92:95], v[32:47]
	ds_read_b64_tr_b16 v[92:93], v5 offset:0x1600
	ds_read_b64_tr_b16 v[94:95], v5 offset:0x1e00
	v_mfma_f32_32x32x16_bf16 v[32:47], v[80:83], v[96:99], v[32:47]
	ds_read_b64_tr_b16 v[96:97], v5 offset:0x2600
	ds_read_b64_tr_b16 v[98:99], v5 offset:0x2e00
	v_mfma_f32_32x32x16_bf16 v[32:47], v[84:87], v[100:103], v[32:47]
	ds_read_b64_tr_b16 v[100:101], v5 offset:0x3600
	ds_read_b64_tr_b16 v[102:103], v5 offset:0x3e00
	s_waitcnt lgkmcnt(0)
	v_mfma_f32_32x32x16_bf16 v[16:31], v[6:9], v[88:91], v[16:31]
	v_mfma_f32_32x32x16_bf16 v[16:31], v[10:13], v[92:95], v[16:31]
	v_mfma_f32_32x32x16_bf16 v[16:31], v[80:83], v[96:99], v[16:31]
	v_mfma_f32_32x32x16_bf16 v[16:31], v[84:87], v[100:103], v[16:31]
	s_and_saveexec_b64 s[6:7], s[4:5]
	v_add_f32_e32 v0, v0, v14
	v_add_f32_e32 v0, v195, v0
	v_add_f32_e32 v3, v3, v4
	v_fmac_f32_e32 v3, v0, v2
	ds_write_b32 v194, v3
	s_or_b64 exec, exec, s[6:7]
	s_waitcnt lgkmcnt(0)
	ds_read_b128 v[2:5], v193
	ds_read_b128 v[6:9], v193 offset:32
	v_readlane_b32 s4, v254, 32
	s_add_u32 s6, s28, 0x1e000000
	s_addc_u32 s7, s29, 0
	s_waitcnt lgkmcnt(0)
; __device__ __forceinline__ int tid_of(int wave_s) { int l; asm volatile("v_mbcnt_lo_u32_b32 %0, -1, 0\n\tv_mbcnt_hi_u32_b32 %0, -1, %0" : "=v"(l)); return wave_s * 64 + l; }
; __device__ __forceinline__ unsigned f2bf(float f) { unsigned u = __builtin_bit_cast(unsigned, f); return (u + 0x7fffu + ((u >> 16) & 1u)) >> 16; }
; __device__ __forceinline__ int crow(int r, int hi) { return (r & 3) + 8 * (r >> 2) + 4 * hi; }
; template <int NQ, int MODE> ...
;     ...
;     for (int r = 0; r < 16; ++r) { const float rl = __builtin_amdgcn_rcpf(RSM ? lacc[r] : li_l[crow(r, hi)]);
; #pragma unroll
;         for (int d = 0; d < 4; ++d) o[d][r] *= rl; }
; __device__ __forceinline__ void store_o_tile(const f32x16 (&o)[4], char* lds, bf16_t* Og, int wave_s) {
;     int tid_ = tid_of(wave_s);
;     const int wid = tid_ >> 6, lane = tid_ & 63, r32 = lane & 31, hi = lane >> 5;
;     __syncthreads();
;     bf16_t* stg = (bf16_t*)(lds + wid * 8192);
; #pragma unroll
;     for (int r = 0; r < 16; ++r) { const int orow = att::crow(r, hi);
; #pragma unroll
;         for (int d0 = 0; d0 < 4; ++d0) stg[orow * 128 + d0 * 32 + r32] = (bf16_t)f2bf(o[d0][r]); }
	v_rcp_f32_e32 v0, v2
	v_rcp_f32_e32 v2, v3
	v_rcp_f32_e32 v3, v4
	v_add_u32_e32 v10, s4, v192
	v_mul_f32_e32 v11, v0, v64
	v_mul_f32_e32 v12, v0, v48
	v_mul_f32_e32 v13, v0, v32
	v_mul_f32_e32 v0, v0, v16
	v_mul_f32_e32 v14, v2, v65
	v_mul_f32_e32 v15, v2, v49
	v_mul_f32_e32 v16, v2, v33
	v_mul_f32_e32 v17, v2, v17
	v_rcp_f32_e32 v2, v5
	v_mul_f32_e32 v32, v3, v66
	v_mul_f32_e32 v33, v3, v50
	v_mul_f32_e32 v34, v3, v34
	v_mul_f32_e32 v18, v3, v18
	v_mul_f32_e32 v48, v2, v67
	v_rcp_f32_e32 v3, v6
	v_mul_f32_e32 v49, v2, v51
	v_mul_f32_e32 v35, v2, v35
	v_mul_f32_e32 v19, v2, v19
	v_rcp_f32_e32 v2, v7
	v_mul_f32_e32 v50, v3, v68
	v_mul_f32_e32 v51, v3, v52
	v_mul_f32_e32 v36, v3, v36
	v_mul_f32_e32 v20, v3, v20
	v_mul_f32_e32 v52, v2, v69
	v_mul_f32_e32 v53, v2, v53
	v_mul_f32_e32 v37, v2, v37
	v_mul_f32_e32 v21, v2, v21
	ds_read_b128 v[2:5], v193 offset:64
	v_rcp_f32_e32 v6, v8
	v_rcp_f32_e32 v65, v9
	v_readlane_b32 s4, v254, 11
	s_movk_i32 s16, 0xf0
	v_mul_f32_e32 v64, v6, v70
	v_mul_f32_e32 v54, v6, v54
	v_mul_f32_e32 v38, v6, v38
	v_mul_f32_e32 v22, v6, v22
	ds_read_b128 v[6:9], v193 offset:96
	s_waitcnt lgkmcnt(0)
	v_rcp_f32_e32 v2, v2
	v_rcp_f32_e32 v3, v3
	v_mul_f32_e32 v66, v65, v71
	v_mul_f32_e32 v55, v65, v55
	v_mul_f32_e32 v39, v65, v39
	v_mul_f32_e32 v23, v65, v23
	v_mul_f32_e32 v65, v2, v72
	v_mul_f32_e32 v56, v2, v56
	v_mul_f32_e32 v40, v2, v40
	v_mul_f32_e32 v24, v2, v24
	v_rcp_f32_e32 v2, v4
	v_mul_f32_e32 v67, v3, v73
	v_mul_f32_e32 v4, v3, v57
	v_mul_f32_e32 v41, v3, v41
	v_mul_f32_e32 v25, v3, v25
	v_rcp_f32_e32 v3, v5
	v_mul_f32_e32 v57, v2, v74
	v_mul_f32_e32 v5, v2, v58
	v_mul_f32_e32 v42, v2, v42
	v_mul_f32_e32 v26, v2, v26
	v_rcp_f32_e32 v2, v6
	v_mul_f32_e32 v58, v3, v75
	v_mul_f32_e32 v59, v3, v59
	v_mul_f32_e32 v43, v3, v43
	v_mul_f32_e32 v27, v3, v27
	v_rcp_f32_e32 v3, v7
	v_mul_f32_e32 v68, v2, v76
	v_mul_f32_e32 v60, v2, v60
	v_mul_f32_e32 v44, v2, v44
	v_mul_f32_e32 v28, v2, v28
	v_rcp_f32_e32 v2, v8
	v_mul_f32_e32 v69, v3, v77
	v_mul_f32_e32 v8, v3, v61
	v_mul_f32_e32 v45, v3, v45
	v_mul_f32_e32 v29, v3, v29
	v_rcp_f32_e32 v3, v9
	v_mul_f32_e32 v61, v2, v78
	v_mul_f32_e32 v9, v2, v62
	v_mul_f32_e32 v46, v2, v46
	v_mul_f32_e32 v30, v2, v30
	v_ashrrev_i32_e32 v2, 1, v10
	v_and_b32_e32 v2, 0xffffffe0, v2
	v_add_u32_e32 v2, s64, v2
	v_mul_f32_e32 v62, v3, v79
	v_mul_f32_e32 v63, v3, v63
	v_mul_f32_e32 v47, v3, v47
	v_mul_f32_e32 v31, v3, v31
	v_ashrrev_i32_e32 v3, 31, v2
	v_lshlrev_b64 v[2:3], 12, v[2:3]
	v_lshl_add_u64 v[6:7], s[6:7], 0, v[2:3]
	v_mbcnt_lo_u32_b32 v2, -1, 0
	v_mbcnt_hi_u32_b32 v2, -1, v2
	s_waitcnt vmcnt(0)
	v_lshl_add_u32 v10, v2, 7, s4
	v_and_b32_e32 v3, 31, v2
	v_and_b32_e32 v10, 0xffffe000, v10
	v_lshlrev_b32_e32 v70, 5, v2
	v_add_u32_e32 v10, 0, v10
	v_lshlrev_b32_e32 v3, 1, v3
	v_and_b32_e32 v70, 0x400, v70
	v_add3_u32 v3, v10, v3, v70
	v_bfe_u32 v70, v11, 16, 1
	v_add3_u32 v11, v11, v70, s33
	s_barrier
	ds_write_b16_d16_hi v3, v11
	v_bfe_u32 v11, v12, 16, 1
	v_add3_u32 v11, v12, v11, s33
	ds_write_b16_d16_hi v3, v11 offset:64
	v_bfe_u32 v11, v13, 16, 1
	v_add3_u32 v11, v13, v11, s33
	ds_write_b16_d16_hi v3, v11 offset:128
	v_bfe_u32 v11, v0, 16, 1
	v_add3_u32 v0, v0, v11, s33
	ds_write_b16_d16_hi v3, v0 offset:192
	v_bfe_u32 v0, v14, 16, 1
	v_add3_u32 v0, v14, v0, s33
	ds_write_b16_d16_hi v3, v0 offset:256
	v_bfe_u32 v0, v15, 16, 1
	v_add3_u32 v0, v15, v0, s33
	ds_write_b16_d16_hi v3, v0 offset:320
	v_bfe_u32 v0, v16, 16, 1
	v_add3_u32 v0, v16, v0, s33
	ds_write_b16_d16_hi v3, v0 offset:384
	v_bfe_u32 v0, v17, 16, 1
	v_add3_u32 v0, v17, v0, s33
	ds_write_b16_d16_hi v3, v0 offset:448
	v_bfe_u32 v0, v32, 16, 1
	v_add3_u32 v0, v32, v0, s33
	ds_write_b16_d16_hi v3, v0 offset:512
	v_bfe_u32 v0, v33, 16, 1
	v_add3_u32 v0, v33, v0, s33
	ds_write_b16_d16_hi v3, v0 offset:576
	v_bfe_u32 v0, v34, 16, 1
	v_add3_u32 v0, v34, v0, s33
	ds_write_b16_d16_hi v3, v0 offset:640
	v_bfe_u32 v0, v18, 16, 1
	v_add3_u32 v0, v18, v0, s33
	ds_write_b16_d16_hi v3, v0 offset:704
	v_bfe_u32 v0, v48, 16, 1
	v_add3_u32 v0, v48, v0, s33
	ds_write_b16_d16_hi v3, v0 offset:768
	v_bfe_u32 v0, v49, 16, 1
	v_add3_u32 v0, v49, v0, s33
	ds_write_b16_d16_hi v3, v0 offset:832
	v_bfe_u32 v0, v35, 16, 1
	v_add3_u32 v0, v35, v0, s33
	ds_write_b16_d16_hi v3, v0 offset:896
	v_bfe_u32 v0, v19, 16, 1
	v_add3_u32 v0, v19, v0, s33
	ds_write_b16_d16_hi v3, v0 offset:960
	v_bfe_u32 v0, v50, 16, 1
	v_add3_u32 v0, v50, v0, s33
	ds_write_b16_d16_hi v3, v0 offset:2048
	v_bfe_u32 v0, v51, 16, 1
	v_add3_u32 v0, v51, v0, s33
	ds_write_b16_d16_hi v3, v0 offset:2112
	v_bfe_u32 v0, v36, 16, 1
	v_add3_u32 v0, v36, v0, s33
	ds_write_b16_d16_hi v3, v0 offset:2176
	v_bfe_u32 v0, v20, 16, 1
	v_add3_u32 v0, v20, v0, s33
	ds_write_b16_d16_hi v3, v0 offset:2240
	v_bfe_u32 v0, v52, 16, 1
	v_add3_u32 v0, v52, v0, s33
	ds_write_b16_d16_hi v3, v0 offset:2304
	v_bfe_u32 v0, v53, 16, 1
	v_add3_u32 v0, v53, v0, s33
	ds_write_b16_d16_hi v3, v0 offset:2368
	v_bfe_u32 v0, v37, 16, 1
	v_add3_u32 v0, v37, v0, s33
	ds_write_b16_d16_hi v3, v0 offset:2432
	v_bfe_u32 v0, v21, 16, 1
	v_add3_u32 v0, v21, v0, s33
	ds_write_b16_d16_hi v3, v0 offset:2496
	v_bfe_u32 v0, v64, 16, 1
	v_add3_u32 v0, v64, v0, s33
	ds_write_b16_d16_hi v3, v0 offset:2560
	v_bfe_u32 v0, v54, 16, 1
	v_add3_u32 v0, v54, v0, s33
	ds_write_b16_d16_hi v3, v0 offset:2624
	v_bfe_u32 v0, v38, 16, 1
	v_add3_u32 v0, v38, v0, s33
	ds_write_b16_d16_hi v3, v0 offset:2688
	v_bfe_u32 v0, v22, 16, 1
	v_add3_u32 v0, v22, v0, s33
	ds_write_b16_d16_hi v3, v0 offset:2752
	v_bfe_u32 v0, v66, 16, 1
	v_add3_u32 v0, v66, v0, s33
	ds_write_b16_d16_hi v3, v0 offset:2816
	v_bfe_u32 v0, v55, 16, 1
	v_add3_u32 v0, v55, v0, s33
; __device__ __forceinline__ unsigned f2bf(float f) { unsigned u = __builtin_bit_cast(unsigned, f); return (u + 0x7fffu + ((u >> 16) & 1u)) >> 16; }
; __device__ __forceinline__ int crow(int r, int hi) { return (r & 3) + 8 * (r >> 2) + 4 * hi; }
; template <int NQ, int MODE> ...
;     ...
;     bf16x8 qr[NQ];
;     const bf16_t* Qw = Qb + (long)(wid * QBLK + r32) * ldq + hi * 8;
;     __syncthreads();
; #pragma unroll
;     for (int d0 = 0; d0 < NQ; ++d0) qr[d0] = *reinterpret_cast<const bf16x8*>(Qw + d0 * 16);
; __device__ __forceinline__ void store_o_tile(const f32x16 (&o)[4], char* lds, bf16_t* Og, int wave_s) {
;     ...
;     for (int r = 0; r < 16; ++r) { const int orow = att::crow(r, hi);
; #pragma unroll
;         for (int d0 = 0; d0 < 4; ++d0) stg[orow * 128 + d0 * 32 + r32] = (bf16_t)f2bf(o[d0][r]); }
;     asm volatile("s_waitcnt lgkmcnt(0)" ::: "memory");
; #pragma unroll
;     for (int i = 0; i < 8; ++i) { const int row = i * 4 + (lane >> 4), ch = lane & 15; const u32x4 v = *(const u32x4*)(stg + row * 128 + ch * 8); *(u32x4*)(Og + (size_t)row * DM + ch * 8) = v;
;         if (i & 1) asm volatile("" ::: "memory"); }
; __global__ void __launch_bounds__(NTHR, 2) mega_fwd(Args a) {
;     ...
;             { UNIT_IDS att::attn_core<12, 0>(QB + (size_t)q0 * 768 + hd * 192, 768, KVB + hd * 256, 1024, P + C_BKR, INP, KVB + hd * 256 + 128, 1024, 0, SEQ / 64, q0, nullptr, 0.f, 0.f, 0.f, 0.f, (char*)lds, o, wave_s);
	ds_write_b16_d16_hi v3, v0 offset:2880
	v_bfe_u32 v0, v39, 16, 1
	v_add3_u32 v0, v39, v0, s33
	ds_write_b16_d16_hi v3, v0 offset:2944
	v_bfe_u32 v0, v23, 16, 1
	v_add3_u32 v0, v23, v0, s33
	ds_write_b16_d16_hi v3, v0 offset:3008
	v_bfe_u32 v0, v65, 16, 1
	v_add3_u32 v0, v65, v0, s33
	ds_write_b16_d16_hi v3, v0 offset:4096
	v_bfe_u32 v0, v56, 16, 1
	v_add3_u32 v0, v56, v0, s33
	ds_write_b16_d16_hi v3, v0 offset:4160
	v_bfe_u32 v0, v40, 16, 1
	v_add3_u32 v0, v40, v0, s33
	ds_write_b16_d16_hi v3, v0 offset:4224
	v_bfe_u32 v0, v24, 16, 1
	v_add3_u32 v0, v24, v0, s33
	ds_write_b16_d16_hi v3, v0 offset:4288
	v_bfe_u32 v0, v67, 16, 1
	v_add3_u32 v0, v67, v0, s33
	ds_write_b16_d16_hi v3, v0 offset:4352
	v_bfe_u32 v0, v4, 16, 1
	v_add3_u32 v0, v4, v0, s33
	ds_write_b16_d16_hi v3, v0 offset:4416
	v_bfe_u32 v0, v41, 16, 1
	v_add3_u32 v0, v41, v0, s33
	ds_write_b16_d16_hi v3, v0 offset:4480
	v_bfe_u32 v0, v25, 16, 1
	v_add3_u32 v0, v25, v0, s33
	ds_write_b16_d16_hi v3, v0 offset:4544
	v_bfe_u32 v0, v57, 16, 1
	v_add3_u32 v0, v57, v0, s33
	ds_write_b16_d16_hi v3, v0 offset:4608
	v_bfe_u32 v0, v5, 16, 1
	v_add3_u32 v0, v5, v0, s33
	ds_write_b16_d16_hi v3, v0 offset:4672
	v_bfe_u32 v0, v42, 16, 1
	v_add3_u32 v0, v42, v0, s33
	ds_write_b16_d16_hi v3, v0 offset:4736
	v_bfe_u32 v0, v26, 16, 1
	v_add3_u32 v0, v26, v0, s33
	ds_write_b16_d16_hi v3, v0 offset:4800
	v_bfe_u32 v0, v58, 16, 1
	v_add3_u32 v0, v58, v0, s33
	ds_write_b16_d16_hi v3, v0 offset:4864
	v_bfe_u32 v0, v59, 16, 1
	v_add3_u32 v0, v59, v0, s33
	ds_write_b16_d16_hi v3, v0 offset:4928
	v_bfe_u32 v0, v43, 16, 1
	v_add3_u32 v0, v43, v0, s33
	ds_write_b16_d16_hi v3, v0 offset:4992
	v_bfe_u32 v0, v27, 16, 1
	v_add3_u32 v0, v27, v0, s33
	ds_write_b16_d16_hi v3, v0 offset:5056
	v_bfe_u32 v0, v68, 16, 1
	v_add3_u32 v0, v68, v0, s33
	ds_write_b16_d16_hi v3, v0 offset:6144
	v_bfe_u32 v0, v60, 16, 1
	v_add3_u32 v0, v60, v0, s33
	ds_write_b16_d16_hi v3, v0 offset:6208
	v_bfe_u32 v0, v44, 16, 1
	v_add3_u32 v0, v44, v0, s33
	ds_write_b16_d16_hi v3, v0 offset:6272
	v_bfe_u32 v0, v28, 16, 1
	v_add3_u32 v0, v28, v0, s33
	ds_write_b16_d16_hi v3, v0 offset:6336
	v_bfe_u32 v0, v69, 16, 1
	v_add3_u32 v0, v69, v0, s33
	ds_write_b16_d16_hi v3, v0 offset:6400
	v_bfe_u32 v0, v8, 16, 1
	v_add3_u32 v0, v8, v0, s33
	ds_write_b16_d16_hi v3, v0 offset:6464
	v_bfe_u32 v0, v45, 16, 1
	v_add3_u32 v0, v45, v0, s33
	ds_write_b16_d16_hi v3, v0 offset:6528
	v_bfe_u32 v0, v29, 16, 1
	v_add3_u32 v0, v29, v0, s33
	ds_write_b16_d16_hi v3, v0 offset:6592
	v_bfe_u32 v0, v61, 16, 1
	v_add3_u32 v0, v61, v0, s33
	ds_write_b16_d16_hi v3, v0 offset:6656
	v_bfe_u32 v0, v9, 16, 1
	v_add3_u32 v0, v9, v0, s33
	ds_write_b16_d16_hi v3, v0 offset:6720
	v_bfe_u32 v0, v46, 16, 1
	v_add3_u32 v0, v46, v0, s33
	ds_write_b16_d16_hi v3, v0 offset:6784
	v_bfe_u32 v0, v30, 16, 1
	v_add3_u32 v0, v30, v0, s33
	ds_write_b16_d16_hi v3, v0 offset:6848
	v_bfe_u32 v0, v62, 16, 1
	v_add3_u32 v0, v62, v0, s33
	ds_write_b16_d16_hi v3, v0 offset:6912
	v_bfe_u32 v0, v63, 16, 1
	v_add3_u32 v0, v63, v0, s33
	ds_write_b16_d16_hi v3, v0 offset:6976
	v_bfe_u32 v0, v47, 16, 1
	v_add3_u32 v0, v47, v0, s33
	ds_write_b16_d16_hi v3, v0 offset:7040
	v_bfe_u32 v0, v31, 16, 1
	v_add3_u32 v0, v31, v0, s33
	ds_write_b16_d16_hi v3, v0 offset:7104
	v_lshlrev_b32_e32 v0, 4, v2
	v_and_b32_e32 v0, 0xf0, v0
	v_bfe_u32 v11, v2, 4, 2
	v_add_u32_e32 v10, v10, v0
	s_waitcnt lgkmcnt(0)
	v_lshl_add_u32 v2, v11, 8, v10
	ds_read_b128 v[2:5], v2
	v_lshl_add_u64 v[6:7], s[10:11], 1, v[6:7]
	v_lshl_add_u64 v[6:7], v[6:7], 0, v[0:1]
	v_lshlrev_b32_e32 v0, 12, v11
	v_lshl_add_u64 v[8:9], v[6:7], 0, v[0:1]
	v_or_b32_e32 v0, 4, v11
	s_waitcnt lgkmcnt(0)
	global_store_dwordx4 v[8:9], v[2:5], off
	s_mul_i32 s4, s64, 0x600
	s_add_u32 s12, s28, s4
	v_lshl_add_u32 v2, v0, 8, v10
	ds_read_b128 v[2:5], v2
	v_lshlrev_b32_e32 v0, 12, v0
	v_lshl_add_u64 v[8:9], v[6:7], 0, v[0:1]
	v_or_b32_e32 v0, 8, v11
	s_mul_i32 s4, s38, 0xc0
	s_waitcnt lgkmcnt(0)
	global_store_dwordx4 v[8:9], v[2:5], off
	s_addc_u32 s13, s29, 0
	s_ashr_i32 s5, s4, 31
	v_lshl_add_u32 v2, v0, 8, v10
	ds_read_b128 v[2:5], v2
	v_lshlrev_b32_e32 v0, 12, v0
	v_lshl_add_u64 v[8:9], v[6:7], 0, v[0:1]
	v_or_b32_e32 v0, 12, v11
	s_lshl_b64 s[4:5], s[4:5], 1
	s_waitcnt lgkmcnt(0)
	global_store_dwordx4 v[8:9], v[2:5], off
	s_add_u32 s4, s12, s4
	s_addc_u32 s5, s13, s5
	v_lshl_add_u32 v2, v0, 8, v10
	ds_read_b128 v[2:5], v2
	v_lshlrev_b32_e32 v0, 12, v0
	v_lshl_add_u64 v[8:9], v[6:7], 0, v[0:1]
	v_or_b32_e32 v0, 16, v11
	s_add_u32 s4, s4, 0x1a800000
	s_waitcnt lgkmcnt(0)
	global_store_dwordx4 v[8:9], v[2:5], off
	s_addc_u32 s5, s5, 0
	v_mov_b32_e32 v51, v1
	v_lshl_add_u32 v2, v0, 8, v10
	ds_read_b128 v[2:5], v2
	v_lshlrev_b32_e32 v0, 12, v0
	v_lshl_add_u64 v[8:9], v[6:7], 0, v[0:1]
	v_or_b32_e32 v0, 20, v11
	s_lshl_b32 s12, s38, 8
	s_waitcnt lgkmcnt(0)
	global_store_dwordx4 v[8:9], v[2:5], off
	s_ashr_i32 s13, s12, 31
	s_lshl_b64 s[12:13], s[12:13], 1
	v_lshl_add_u32 v2, v0, 8, v10
	ds_read_b128 v[2:5], v2
	v_lshlrev_b32_e32 v0, 12, v0
	v_lshl_add_u64 v[8:9], v[6:7], 0, v[0:1]
	v_or_b32_e32 v0, 24, v11
	s_add_u32 s12, s28, s12
	s_waitcnt lgkmcnt(0)
	global_store_dwordx4 v[8:9], v[2:5], off
	s_addc_u32 s13, s29, s13
	s_add_u32 s12, s12, 0x1c000000
	v_lshl_add_u32 v2, v0, 8, v10
	ds_read_b128 v[2:5], v2
	v_lshlrev_b32_e32 v0, 12, v0
	v_lshl_add_u64 v[8:9], v[6:7], 0, v[0:1]
	v_or_b32_e32 v0, 28, v11
	s_mov_b32 m0, s81
	s_waitcnt lgkmcnt(0)
	global_store_dwordx4 v[8:9], v[2:5], off
	s_addc_u32 s13, s13, 0
	v_mov_b32_e32 v9, v1
	v_lshl_add_u32 v2, v0, 8, v10
	ds_read_b128 v[2:5], v2
	v_lshlrev_b32_e32 v0, 12, v0
	v_lshl_add_u64 v[6:7], v[6:7], 0, v[0:1]
	v_mov_b64_e32 v[10:11], s[4:5]
	s_movk_i32 s4, 0x600
	s_waitcnt lgkmcnt(0)
	global_store_dwordx4 v[6:7], v[2:5], off
	s_waitcnt lgkmcnt(0)
	v_mbcnt_lo_u32_b32 v176, -1, 0
	v_mbcnt_hi_u32_b32 v176, -1, v176
	v_mbcnt_lo_u32_b32 v12, -1, 0
	v_mbcnt_hi_u32_b32 v12, -1, v12
	s_waitcnt lgkmcnt(0)
	v_and_b32_e32 v62, 31, v12
	v_bfe_u32 v13, v12, 5, 1
	v_or_b32_e32 v15, s80, v62
	v_mad_u64_u32 v[10:11], s[4:5], v15, s4, v[10:11]
	v_lshlrev_b32_e32 v50, 4, v13
	v_lshl_add_u64 v[10:11], v[10:11], 0, v[50:51]
	s_barrier
; #define DMA_K(t, st) do { if (HAS1) { GLDS(pK1a, K3 + (st) * SHM_KT + wid * 1024); GLDS(pK1b, K3 + (st) * SHM_KT + (wid + 8) * 1024); pK1a += stK1; pK1b += stK1; } \
;     if (HAS2) { GLDS(pK2p, K3 + (st) * SHM_KT + SHM_K1 + wid * 1024); pK2p += stK2; } } while (0)
; #define DMA_V(t, st) do { GLDS(pVa, V3 + (st) * SHM_V + wid * 1024); GLDS(pVb, V3 + (st) * SHM_V + (wid + 8) * 1024); pVa += stV; pVb += stV; } while (0)
; template <int NQ>
; __device__ __forceinline__ void qkt(f32x16& p0, f32x16& p1, const char* Ks, const int (&kq1)[2], const int (&kq2)[2], const bf16x8* qr, const f32x16& cinit) {
;     int kb1[8], kb2[4];
; #pragma unroll
;     for (int i = 0; i < 8; ++i) kb1[i] = kq1[0] + ((i ^ kq1[1]) << 5);
; #pragma unroll
;     for (int i = 0; i < 4; ++i) kb2[i] = kq2[0] + ((i ^ kq2[1]) << 5);
;     constexpr bool HAS1 = NQ >= 8, HAS2 = NQ != 8; constexpr int SHM_K1 = HAS1 ? 16384 : 0;
;     p0 = cinit; p1 = cinit;
;     if (HAS1) {
; #pragma unroll
;         for (int d0 = 0; d0 < 8; ++d0) { const char* a = Ks + kb1[d0];
;             const bf16x8 b0 = *reinterpret_cast<const bf16x8*>(a); const bf16x8 b1 = *reinterpret_cast<const bf16x8*>(a + 8192);
;             p0 = __builtin_amdgcn_mfma_f32_32x32x16_bf16(b0, qr[d0], p0, 0, 0, 0);
;             p1 = __builtin_amdgcn_mfma_f32_32x32x16_bf16(b1, qr[d0], p1, 0, 0, 0); } }
;     if (HAS2) {
; #pragma unroll
;         for (int d = 0; d < 4; ++d) { const char* a = Ks + SHM_K1 + kb2[d];
;             const bf16x8 b0 = *reinterpret_cast<const bf16x8*>(a); const bf16x8 b1 = *reinterpret_cast<const bf16x8*>(a + 4096);
;             p0 = __builtin_amdgcn_mfma_f32_32x32x16_bf16(b0, qr[(NQ == 12 ? 8 : 0) + d], p0, 0, 0, 0);
;             p1 = __builtin_amdgcn_mfma_f32_32x32x16_bf16(b1, qr[(NQ == 12 ? 8 : 0) + d], p1, 0, 0, 0); } }
; template <int NQ, int MODE> ...
;     ...
;     for (int d0 = 0; d0 < NQ; ++d0) qr[d0] = *reinterpret_cast<const bf16x8*>(Qw + d0 * 16);
;     DMA_K(0, 0); DMA_V(0, 0); DMA_K(1, 1);
;     ...
;     WAITB(NLK);
;     if (2 < NT) DMA_K(2, 2); DMA_V(1, 1);
;     CINIT(0);
;     qkt<NQ>(pA0, pA1, K_lds, kb1, kb2, qr, cinit); { TILEP(0); (void)cbT; rsA = partialSM<MODE, true, FOLD>(pA0, pA1, m_reg, alA, relb, nearT, lut, cbT); dirty |= rsA; }
	global_load_dwordx4 v[142:145], v[10:11], off
	global_load_dwordx4 v[138:141], v[10:11], off offset:32
	global_load_dwordx4 v[134:137], v[10:11], off offset:64
	global_load_dwordx4 v[130:133], v[10:11], off offset:96
	global_load_dwordx4 v[126:129], v[10:11], off offset:128
	global_load_dwordx4 v[122:125], v[10:11], off offset:160
	global_load_dwordx4 v[118:121], v[10:11], off offset:192
	global_load_dwordx4 v[114:117], v[10:11], off offset:224
	global_load_dwordx4 v[110:113], v[10:11], off offset:256
	global_load_dwordx4 v[106:109], v[10:11], off offset:288
	global_load_dwordx4 v[102:105], v[10:11], off offset:320
	global_load_dwordx4 v[98:101], v[10:11], off offset:352
	v_bfe_u32 v0, v12, 4, 2
	v_or_b32_e32 v2, s50, v0
	v_bitop3_b32 v0, v0, v12, s50 bitop3:0x36
	v_lshlrev_b32_e32 v2, 11, v2
	v_lshlrev_b32_e32 v0, 4, v0
	v_and_or_b32 v0, v0, s16, v2
	v_bfe_u32 v3, v12, 3, 3
	v_readlane_b32 s16, v254, 33
	v_lshlrev_b32_e32 v14, 4, v12
	v_bfe_u32 v5, v12, 2, 3
	v_or_b32_e32 v3, s16, v3
	v_lshrrev_b32_e32 v4, 1, v3
	v_xor_b32_e32 v4, v4, v12
	v_mul_lo_u32 v3, v3, s49
	v_lshlrev_b32_e32 v4, 3, v4
	v_readlane_b32 s16, v254, 34
	v_and_or_b32 v3, v4, 56, v3
	v_and_b32_e32 v6, 48, v14
	v_or_b32_e32 v4, s16, v13
	v_readlane_b32 s16, v254, 48
	v_lshl_or_b32 v6, v4, 6, v6
	v_lshlrev_b32_e32 v8, 1, v3
	v_or_b32_e32 v4, s16, v5
	v_readlane_b32 s16, v254, 49
	v_add_u32_e32 v2, 0x10000, v0
	v_lshl_or_b32 v4, v4, 11, v6
	v_or_b32_e32 v5, s16, v5
	v_lshl_or_b32 v6, v5, 11, v6
	v_mov_b32_e32 v5, v1
	v_lshl_add_u64 v[52:53], s[28:29], 0, v[8:9]
	s_mov_b64 s[4:5], 0x12000d00
	global_load_lds_dwordx4 v0, s[12:13]
	s_mov_b32 m0, s67
	v_mov_b32_e32 v7, v1
	v_lshl_add_u64 v[8:9], v[52:53], 0, s[4:5]
	v_lshl_add_u64 v[56:57], s[12:13], 0, v[4:5]
	s_mov_b64 s[4:5], 0x100
	global_load_lds_dwordx4 v2, s[12:13]
	s_mov_b32 m0, s70
	v_lshl_add_u64 v[4:5], v[56:57], 0, s[4:5]
	v_lshl_add_u64 v[60:61], s[12:13], 0, v[6:7]
	global_load_lds_dwordx4 v[8:9], off
	s_mov_b32 m0, s14
	v_mov_b32_e32 v3, v1
	v_lshl_add_u64 v[58:59], s[12:13], 0, v[0:1]
	v_lshl_add_u64 v[6:7], v[60:61], 0, s[4:5]
	global_load_lds_dwordx4 v[4:5], off
	s_mov_b32 m0, s15
	v_lshl_add_u64 v[54:55], s[12:13], 0, v[2:3]
	v_lshl_add_u64 v[2:3], v[58:59], 0, s[94:95]
	s_mov_b64 s[4:5], 0x12088d00
	global_load_lds_dwordx4 v[6:7], off
	s_mov_b32 m0, s85
	v_lshl_add_u64 v[10:11], v[54:55], 0, s[94:95]
	v_lshl_add_u64 v[8:9], v[52:53], 0, s[4:5]
	s_mov_b64 s[4:5], 0x20100
	global_load_lds_dwordx4 v[2:3], off
	s_mov_b32 m0, s87
	v_lshl_add_u64 v[4:5], v[56:57], 0, s[4:5]
	v_lshl_add_u64 v[6:7], v[60:61], 0, s[4:5]
	global_load_lds_dwordx4 v[10:11], off
	s_mov_b32 m0, s86
	v_bitop3_b32 v0, v13, v12, 1 bitop3:0x78
	v_lshlrev_b32_e32 v2, 8, v62
	s_mov_b64 s[4:5], 0x12110d00
	global_load_lds_dwordx4 v[8:9], off
	v_lshl_or_b32 v187, v0, 4, v2
	s_cmp_lg_u32 s31, -1
	v_lshl_add_u64 v[2:3], v[52:53], 0, s[4:5]
	s_mov_b64 s[4:5], 0x40000
	s_cselect_b32 s13, s31, 0
	s_waitcnt vmcnt(3) lgkmcnt(0)
	s_barrier
	v_lshl_add_u64 v[10:11], v[58:59], 0, s[4:5]
	s_add_i32 m0, s81, 0xc000
	v_lshl_add_u64 v[8:9], v[54:55], 0, s[4:5]
	global_load_lds_dwordx4 v[10:11], off
	s_add_i32 m0, s81, 0xe000
	v_and_b32_e32 v189, 0xe0, v14
	global_load_lds_dwordx4 v[8:9], off
	s_add_i32 m0, s81, 0x10000
	v_add3_u32 v0, 0, v189, v187
	global_load_lds_dwordx4 v[2:3], off
	s_mov_b32 m0, s71
	v_bitop3_b32 v194, v14, 32, v221 bitop3:0x6c
	global_load_lds_dwordx4 v[4:5], off
	s_mov_b32 m0, s72
	v_bitop3_b32 v193, v14, 64, v221 bitop3:0x6c
	global_load_lds_dwordx4 v[6:7], off
	ds_read_b128 v[2:5], v0
	ds_read_b128 v[6:9], v0 offset:8192
	s_waitcnt vmcnt(0) lgkmcnt(0)
	v_mfma_f32_32x32x16_bf16 v[34:49], v[2:5], v[142:145], 0
	v_add3_u32 v0, 0, v194, v187
	s_movk_i32 s14, 0x60
	v_bitop3_b32 v192, v14, s14, v221 bitop3:0x6c
	s_movk_i32 s4, 0x80
	v_bitop3_b32 v191, v14, s4, v221 bitop3:0x6c
	s_movk_i32 s4, 0xa0
	v_bitop3_b32 v190, v14, s4, v221 bitop3:0x6c
	v_mfma_f32_32x32x16_bf16 v[18:33], v[6:9], v[142:145], 0
	ds_read_b128 v[2:5], v0
	ds_read_b128 v[6:9], v0 offset:8192
	v_add3_u32 v0, 0, v193, v187
	s_movk_i32 s4, 0xc0
	v_bitop3_b32 v188, v14, s4, v221 bitop3:0x6c
	s_movk_i32 s4, 0xe0
	v_bitop3_b32 v186, v14, s4, v14 bitop3:0xc
	v_and_b32_e32 v51, 63, v12
	s_waitcnt lgkmcnt(1)
	v_mfma_f32_32x32x16_bf16 v[34:49], v[2:5], v[138:141], v[34:49]
	v_lshlrev_b32_e32 v10, 3, v51
	s_mov_b64 s[4:5], 0x60000
	v_lshl_add_u64 v[68:69], v[58:59], 0, s[4:5]
	s_mov_b32 m0, s81
	v_lshl_add_u64 v[70:71], v[54:55], 0, s[4:5]
	s_mov_b64 s[4:5], 0x12198d00
	v_lshl_add_u64 v[72:73], v[52:53], 0, s[4:5]
	s_waitcnt lgkmcnt(0)
	v_mfma_f32_32x32x16_bf16 v[18:33], v[6:9], v[138:141], v[18:33]
	ds_read_b128 v[2:5], v0
	ds_read_b128 v[6:9], v0 offset:8192
	v_add3_u32 v0, 0, v192, v187
	s_mov_b64 s[4:5], 0x40100
	v_lshl_add_u64 v[74:75], v[56:57], 0, s[4:5]
	v_lshl_add_u64 v[76:77], v[60:61], 0, s[4:5]
	s_mov_b32 s12, 0
	s_mov_b64 s[4:5], 0x80000
	s_waitcnt lgkmcnt(1)
	v_mfma_f32_32x32x16_bf16 v[34:49], v[2:5], v[134:137], v[34:49]
	s_mov_b32 s15, s12
	s_mov_b32 s16, s12
	s_mov_b32 s17, s12
	s_mov_b32 s18, s12
	s_mov_b32 s19, s12
	s_mov_b32 s20, s12
	s_mov_b32 s21, s12
	s_waitcnt lgkmcnt(0)
	v_mfma_f32_32x32x16_bf16 v[18:33], v[6:9], v[134:137], v[18:33]
	ds_read_b128 v[2:5], v0
	ds_read_b128 v[6:9], v0 offset:8192
	v_add3_u32 v0, 0, v191, v187
	s_mov_b32 s22, s12
	s_mov_b32 s23, s12
	s_mov_b32 s24, s12
	s_mov_b32 s25, s12
	s_mov_b32 s26, s12
	s_waitcnt lgkmcnt(1)
	v_mfma_f32_32x32x16_bf16 v[34:49], v[2:5], v[130:133], v[34:49]
	s_mov_b32 s27, s12
	v_lshl_add_u64 v[162:163], v[58:59], 0, s[4:5]
	v_lshl_add_u64 v[164:165], v[54:55], 0, s[4:5]
	s_mov_b64 s[4:5], 0x12220d00
	v_lshl_add_u64 v[166:167], v[52:53], 0, s[4:5]
	s_mov_b64 s[4:5], 0x60100
	v_lshl_add_u64 v[170:171], v[56:57], 0, s[4:5]
	s_waitcnt lgkmcnt(0)
; template <int NQ>
; __device__ __forceinline__ void qkt(f32x16& p0, f32x16& p1, const char* Ks, const int (&kq1)[2], const int (&kq2)[2], const bf16x8* qr, const f32x16& cinit) {
;     ...
;     if (HAS1) {
; #pragma unroll
;         for (int d0 = 0; d0 < 8; ++d0) { const char* a = Ks + kb1[d0];
;             const bf16x8 b0 = *reinterpret_cast<const bf16x8*>(a); const bf16x8 b1 = *reinterpret_cast<const bf16x8*>(a + 8192);
;             p0 = __builtin_amdgcn_mfma_f32_32x32x16_bf16(b0, qr[d0], p0, 0, 0, 0);
;             p1 = __builtin_amdgcn_mfma_f32_32x32x16_bf16(b1, qr[d0], p1, 0, 0, 0); } }
;     if (HAS2) {
; #pragma unroll
;         for (int d = 0; d < 4; ++d) { const char* a = Ks + SHM_K1 + kb2[d];
;             const bf16x8 b0 = *reinterpret_cast<const bf16x8*>(a); const bf16x8 b1 = *reinterpret_cast<const bf16x8*>(a + 4096);
;             p0 = __builtin_amdgcn_mfma_f32_32x32x16_bf16(b0, qr[(NQ == 12 ? 8 : 0) + d], p0, 0, 0, 0);
;             p1 = __builtin_amdgcn_mfma_f32_32x32x16_bf16(b1, qr[(NQ == 12 ? 8 : 0) + d], p1, 0, 0, 0); } }
	v_mfma_f32_32x32x16_bf16 v[18:33], v[6:9], v[130:133], v[18:33]
	ds_read_b128 v[2:5], v0
	ds_read_b128 v[6:9], v0 offset:8192
	v_add3_u32 v0, 0, v190, v187
	v_lshl_add_u64 v[168:169], v[60:61], 0, s[4:5]
	v_cmp_gt_u32_e64 s[4:5], 32, v51
	v_lshl_add_u32 v178, v62, 2, s97
	s_mov_b32 s88, 1
	s_movk_i32 s45, 0x60
	s_waitcnt lgkmcnt(1)
	v_mfma_f32_32x32x16_bf16 v[34:49], v[2:5], v[126:129], v[34:49]
	v_mov_b32_e32 v179, 0
	s_waitcnt lgkmcnt(0)
	v_mfma_f32_32x32x16_bf16 v[18:33], v[6:9], v[126:129], v[18:33]
	ds_read_b128 v[2:5], v0
	ds_read_b128 v[6:9], v0 offset:8192
	v_add3_u32 v0, 0, v188, v187
	s_waitcnt lgkmcnt(1)
	v_mfma_f32_32x32x16_bf16 v[34:49], v[2:5], v[122:125], v[34:49]
	s_waitcnt lgkmcnt(0)
	v_mfma_f32_32x32x16_bf16 v[18:33], v[6:9], v[122:125], v[18:33]
	ds_read_b128 v[2:5], v0
	ds_read_b128 v[6:9], v0 offset:8192
	v_add3_u32 v0, 0, v186, v187
	s_waitcnt lgkmcnt(1)
	v_mfma_f32_32x32x16_bf16 v[34:49], v[2:5], v[118:121], v[34:49]
	s_waitcnt lgkmcnt(0)
	v_mfma_f32_32x32x16_bf16 v[18:33], v[6:9], v[118:121], v[18:33]
	ds_read_b128 v[2:5], v0
	ds_read_b128 v[6:9], v0 offset:8192
	v_lshrrev_b32_e32 v0, 1, v12
	v_bitop3_b32 v0, v0, v13, 1 bitop3:0x6c
	s_waitcnt lgkmcnt(1)
	v_mfma_f32_32x32x16_bf16 v[34:49], v[2:5], v[114:117], v[34:49]
	v_lshlrev_b32_e32 v2, 7, v62
	v_lshl_or_b32 v184, v0, 4, v2
	v_lshlrev_b32_e32 v0, 3, v12
	v_and_b32_e32 v185, 0x60, v0
	v_bitop3_b32 v181, v0, 32, v222 bitop3:0x6c
	v_bitop3_b32 v182, v0, 64, v222 bitop3:0x6c
	v_bitop3_b32 v183, v0, s14, v0 bitop3:0xc
	s_waitcnt lgkmcnt(0)
	v_mfma_f32_32x32x16_bf16 v[18:33], v[6:9], v[114:117], v[18:33]
	v_add3_u32 v6, 0, v185, v184
	ds_read_b128 v[2:5], v6 offset:16384
	ds_read_b128 v[6:9], v6 offset:20480
	v_add3_u32 v0, 0, v183, v184
	ds_read_b128 v[64:67], v0 offset:20480
	s_mov_b32 s14, s12
	s_waitcnt lgkmcnt(1)
	v_mfma_f32_32x32x16_bf16 v[18:33], v[6:9], v[110:113], v[18:33]
	v_add3_u32 v6, 0, v181, v184
	v_and_b32_e32 v7, 0xc0, v14
	v_and_or_b32 v11, v10, 24, v7
	v_mfma_f32_32x32x16_bf16 v[34:49], v[2:5], v[110:113], v[34:49]
	ds_read_b128 v[2:5], v6 offset:16384
	ds_read_b128 v[6:9], v6 offset:20480
	s_waitcnt lgkmcnt(1)
	v_mfma_f32_32x32x16_bf16 v[34:49], v[2:5], v[106:109], v[34:49]
	v_lshlrev_b32_e32 v2, 1, v12
	v_and_b32_e32 v2, 32, v2
	v_and_b32_e32 v3, 0x100, v10
	v_or3_b32 v10, v11, v2, v3
	v_add3_u32 v11, 0, v182, v184
	ds_read_b128 v[2:5], v11 offset:16384
	v_add_u32_e32 v177, s13, v10
	s_waitcnt lgkmcnt(1)
	v_mfma_f32_32x32x16_bf16 v[18:33], v[6:9], v[106:109], v[18:33]
	ds_read_b128 v[6:9], v11 offset:20480
	s_mov_b32 s13, s12
	s_waitcnt lgkmcnt(1)
	v_mfma_f32_32x32x16_bf16 v[34:49], v[2:5], v[102:105], v[34:49]
	ds_read_b128 v[2:5], v0 offset:16384
	s_waitcnt vmcnt(5) lgkmcnt(0)
	s_barrier
; #define DMA_K(t, st) do { if (HAS1) { GLDS(pK1a, K3 + (st) * SHM_KT + wid * 1024); GLDS(pK1b, K3 + (st) * SHM_KT + (wid + 8) * 1024); pK1a += stK1; pK1b += stK1; } \
;     if (HAS2) { GLDS(pK2p, K3 + (st) * SHM_KT + SHM_K1 + wid * 1024); pK2p += stK2; } } while (0)
; template <int MODE, bool FIRST, bool FOLD>
; __device__ __forceinline__ bool partialSM(f32x16& p0, f32x16& p1, float& m_reg, float& alpha, int relbase, bool near, const float* lut, float cb) {
;     if (!FOLD) { const float off_ = cb - m_reg;
; #pragma unroll
;         for (int r = 0; r < 16; ++r) { p0[r] += off_; p1[r] += off_; } }
;     if (MODE != 0 && near) {
; #pragma unroll
;         for (int r = 0; r < 16; ++r) { const int rel = relbase + (r & 3) + 8 * (r >> 2), rel1 = rel + 32;
;             const int i0 = min(max(rel, -128), 128) + 128, i1 = min(max(rel1, -128), 128) + 128;
;             const float b0 = lut[i0], b1 = lut[i1];
;             if (MODE == 1) { p0[r] += b0; p1[r] += b1; }
;             else { p0[r] = (rel >= -128 && rel <= 128) ? p0[r] + b0 : -1e30f; p1[r] = (rel1 >= -128 && rel1 <= 128) ? p1[r] + b1 : -1e30f; } }
;     }
;     float pmax = p0[0];
; #pragma unroll
;     for (int r = 1; r < 16; ++r) pmax = fmaxf(pmax, p0[r]);
; #pragma unroll
;     for (int r = 0; r < 16; ++r) pmax = fmaxf(pmax, p1[r]);
;     { auto rr = __builtin_amdgcn_permlane32_swap(__float_as_uint(pmax), __float_as_uint(pmax), false, false);
;       pmax = fmaxf(__uint_as_float(rr[0]), __uint_as_float(rr[1])); }
;     bool resc;
;     if (FIRST && MODE != 2) resc = true; else resc = __any(pmax > THR2);
;     if (__builtin_expect(resc, FIRST && MODE != 2)) {
;         const float delta = (FIRST && MODE != 2) ? pmax : fmaxf(pmax, 0.f);
;         m_reg += delta; alpha = (FIRST && MODE != 2) ? 1.f : __builtin_amdgcn_exp2f(-delta);
; #pragma unroll
;         for (int r = 0; r < 16; ++r) { p0[r] -= delta; p1[r] -= delta; }
;     } else alpha = 1.f;
; #pragma unroll
;     for (int r = 0; r < 16; ++r) p0[r] = __builtin_amdgcn_exp2f(p0[r]);
; template <int NQ, int MODE> ...
;     ...
;     if (2 < NT) DMA_K(2, 2); DMA_V(1, 1);
;     CINIT(0);
;     qkt<NQ>(pA0, pA1, K_lds, kb1, kb2, qr, cinit); { TILEP(0); (void)cbT; rsA = partialSM<MODE, true, FOLD>(pA0, pA1, m_reg, alA, relb, nearT, lut, cbT); dirty |= rsA; }
;     l_reg *= alA;
	global_load_lds_dwordx4 v[68:69], off
	s_mov_b32 m0, s67
	s_nop 0
	global_load_lds_dwordx4 v[70:71], off
	s_mov_b32 m0, s70
	s_waitcnt lgkmcnt(0)
	v_mfma_f32_32x32x16_bf16 v[18:33], v[6:9], v[102:105], v[18:33]
	global_load_lds_dwordx4 v[72:73], off
	s_mov_b32 m0, s65
	s_nop 0
	global_load_lds_dwordx4 v[74:75], off
	s_mov_b32 m0, s66
	v_mfma_f32_32x32x16_bf16 v[34:49], v[2:5], v[98:101], v[34:49]
	global_load_lds_dwordx4 v[76:77], off
	v_mov_b64_e32 v[2:3], s[12:13]
	v_mov_b64_e32 v[16:17], s[26:27]
	v_mov_b64_e32 v[4:5], s[14:15]
	v_mov_b64_e32 v[6:7], s[16:17]
	v_mov_b64_e32 v[8:9], s[18:19]
	v_mfma_f32_32x32x16_bf16 v[18:33], v[64:67], v[98:101], v[18:33]
	s_nop 4
	v_add_f32_e32 v0, 0, v34
	v_add_f32_e32 v34, 0, v35
	v_add_f32_e32 v35, 0, v36
	v_add_f32_e32 v36, 0, v37
	v_add_f32_e32 v37, 0, v38
	v_add_f32_e32 v38, 0, v39
	v_add_f32_e32 v39, 0, v40
	v_add_f32_e32 v40, 0, v41
	v_add_f32_e32 v41, 0, v42
	v_add_f32_e32 v42, 0, v43
	v_add_f32_e32 v43, 0, v44
	v_add_f32_e32 v44, 0, v45
	v_add_f32_e32 v45, 0, v46
	v_add_f32_e32 v46, 0, v47
	v_add_f32_e32 v47, 0, v48
	v_add_f32_e32 v48, 0, v49
	v_max_f32_e32 v49, v0, v34
	v_max3_f32 v49, v49, v35, v36
	v_max3_f32 v49, v49, v37, v38
	v_max3_f32 v49, v49, v39, v40
	v_max3_f32 v49, v49, v41, v42
	v_max3_f32 v49, v49, v43, v44
	v_max3_f32 v49, v49, v45, v46
	v_max3_f32 v49, v49, v47, v48
	v_pk_add_f32 v[18:19], v[18:19], 0 op_sel_hi:[1,0]
	v_pk_add_f32 v[20:21], v[20:21], 0 op_sel_hi:[1,0]
	v_max3_f32 v49, v49, v18, v19
	v_max3_f32 v49, v49, v20, v21
	v_pk_add_f32 v[22:23], v[22:23], 0 op_sel_hi:[1,0]
	v_pk_add_f32 v[24:25], v[24:25], 0 op_sel_hi:[1,0]
	v_max3_f32 v49, v49, v22, v23
	v_max3_f32 v49, v49, v24, v25
	v_pk_add_f32 v[26:27], v[26:27], 0 op_sel_hi:[1,0]
	v_pk_add_f32 v[28:29], v[28:29], 0 op_sel_hi:[1,0]
	v_max3_f32 v49, v49, v26, v27
	v_max3_f32 v49, v49, v28, v29
	v_pk_add_f32 v[30:31], v[30:31], 0 op_sel_hi:[1,0]
	v_pk_add_f32 v[32:33], v[32:33], 0 op_sel_hi:[1,0]
	v_max3_f32 v49, v49, v30, v31
	v_max3_f32 v49, v49, v32, v33
	v_mov_b32_e32 v63, v49
	s_nop 1
	v_permlane32_swap_b32_e32 v49, v63
	v_max_f32_e32 v63, v63, v63
	v_max_f32_e32 v49, v49, v49
	v_max_f32_e32 v49, v49, v63
	v_sub_f32_e32 v0, v0, v49
	v_sub_f32_e32 v34, v34, v49
	v_sub_f32_e32 v35, v35, v49
	v_sub_f32_e32 v36, v36, v49
	v_sub_f32_e32 v37, v37, v49
	v_sub_f32_e32 v38, v38, v49
	v_sub_f32_e32 v39, v39, v49
	v_sub_f32_e32 v40, v40, v49
	v_sub_f32_e32 v41, v41, v49
	v_sub_f32_e32 v42, v42, v49
	v_sub_f32_e32 v43, v43, v49
	v_sub_f32_e32 v44, v44, v49
	v_sub_f32_e32 v45, v45, v49
	v_sub_f32_e32 v46, v46, v49
	v_sub_f32_e32 v47, v47, v49
	v_sub_f32_e32 v48, v48, v49
	v_exp_f32_e32 v200, v0
	v_exp_f32_e32 v201, v34
	v_exp_f32_e32 v202, v35
	v_exp_f32_e32 v212, v36
	v_exp_f32_e32 v203, v37
	v_exp_f32_e32 v213, v38
	v_exp_f32_e32 v214, v39
	v_exp_f32_e32 v215, v40
	v_exp_f32_e32 v158, v41
	v_exp_f32_e32 v159, v42
	v_exp_f32_e32 v160, v43
	v_exp_f32_e32 v175, v44
	v_exp_f32_e32 v161, v45
	v_exp_f32_e32 v197, v46
	v_exp_f32_e32 v198, v47
	v_exp_f32_e32 v199, v48
	v_mov_b64_e32 v[10:11], s[20:21]
	v_mov_b64_e32 v[12:13], s[22:23]
	v_mov_b64_e32 v[14:15], s[24:25]
	v_add_f32_e32 v180, 0, v49
	v_sub_f32_e32 v149, v33, v49
	v_sub_f32_e32 v148, v32, v49
	v_sub_f32_e32 v147, v31, v49
	v_sub_f32_e32 v146, v30, v49
	v_sub_f32_e32 v153, v29, v49
	v_sub_f32_e32 v152, v28, v49
	v_sub_f32_e32 v151, v27, v49
	v_sub_f32_e32 v150, v26, v49
	v_sub_f32_e32 v157, v25, v49
	v_sub_f32_e32 v156, v24, v49
	v_sub_f32_e32 v155, v23, v49
	v_sub_f32_e32 v154, v22, v49
	v_sub_f32_e32 v85, v21, v49
	v_sub_f32_e32 v84, v20, v49
	v_sub_f32_e32 v83, v19, v49
	v_sub_f32_e32 v82, v18, v49
	v_add_u32_e32 v0, s97, v50
	v_mov_b64_e32 v[32:33], v[16:17]
	v_mov_b64_e32 v[48:49], v[16:17]
	v_mov_b64_e32 v[64:65], v[16:17]
	s_movk_i32 s16, 0xff04
	v_mov_b64_e32 v[30:31], v[14:15]
	v_mov_b64_e32 v[28:29], v[12:13]
	v_mov_b64_e32 v[26:27], v[10:11]
	v_mov_b64_e32 v[24:25], v[8:9]
	v_mov_b64_e32 v[22:23], v[6:7]
	v_mov_b64_e32 v[20:21], v[4:5]
	v_mov_b64_e32 v[18:19], v[2:3]
	v_mov_b64_e32 v[46:47], v[14:15]
	v_mov_b64_e32 v[44:45], v[12:13]
	v_mov_b64_e32 v[42:43], v[10:11]
	v_mov_b64_e32 v[40:41], v[8:9]
	v_mov_b64_e32 v[38:39], v[6:7]
	v_mov_b64_e32 v[36:37], v[4:5]
	v_mov_b64_e32 v[34:35], v[2:3]
	v_mov_b64_e32 v[62:63], v[14:15]
	v_mov_b64_e32 v[60:61], v[12:13]
	v_mov_b64_e32 v[58:59], v[10:11]
	v_mov_b64_e32 v[56:57], v[8:9]
	v_mov_b64_e32 v[54:55], v[6:7]
	v_mov_b64_e32 v[52:53], v[4:5]
	v_mov_b64_e32 v[50:51], v[2:3]

; #define SBAR() __builtin_amdgcn_sched_barrier(0)
; #define PK4(P, BASE, OUT) do { u32x4 w = {cvtpk(P[BASE + 0], P[BASE + 1]), cvtpk(P[BASE + 2], P[BASE + 3]), cvtpk(P[BASE + 4], P[BASE + 5]), cvtpk(P[BASE + 6], P[BASE + 7])}; \
;     OUT = *reinterpret_cast<bf16x8*>(&w); } while (0)
; template <bool RSM> __device__ __forceinline__ void pv_d0(f32x16* o, f32x16& lacc, int vb, bf16x8 pa0, bf16x8 pa1, bf16x8 pa2, bf16x8 pa3) {
;     if (RSM) {
;         const bf16x8 ones = {0x3F80, 0x3F80, 0x3F80, 0x3F80, 0x3F80, 0x3F80, 0x3F80, 0x3F80};
;         lacc = __builtin_amdgcn_mfma_f32_32x32x16_bf16(pa0, ones, lacc, 0, 0, 0);
;         lacc = __builtin_amdgcn_mfma_f32_32x32x16_bf16(pa1, ones, lacc, 0, 0, 0);
;         lacc = __builtin_amdgcn_mfma_f32_32x32x16_bf16(pa2, ones, lacc, 0, 0, 0);
;         lacc = __builtin_amdgcn_mfma_f32_32x32x16_bf16(pa3, ones, lacc, 0, 0, 0); }
;     pv_one<0>(o[0], vb, pa0, pa1, pa2, pa3); pv_one<1>(o[1], vb, pa0, pa1, pa2, pa3); pv_one<2>(o[2], vb, pa0, pa1, pa2, pa3); pv_one<3>(o[3], vb, pa0, pa1, pa2, pa3);
; template <bool RSM> __device__ __forceinline__ void finishSM(f32x16& p0, f32x16& p1, float& l_reg, bf16x8& pa0, bf16x8& pa1, bf16x8& pa2, bf16x8& pa3) {
; #pragma unroll
;     for (int r = 0; r < 16; ++r) p1[r] = __builtin_amdgcn_exp2f(p1[r]);
;     float ps = 0;
;     if (!RSM) {
; #pragma unroll
;     for (int r = 0; r < 16; ++r) ps += p0[r];
; #pragma unroll
;     for (int r = 0; r < 16; ++r) ps += p1[r];
;     { auto rr = __builtin_amdgcn_permlane32_swap(__float_as_uint(ps), __float_as_uint(ps), false, false);
;       ps = __uint_as_float(rr[0]) + __uint_as_float(rr[1]); }
;     l_reg += ps; }
;     ...
;     PK4(p0, 0, pa0); PK4(p0, 8, pa1); PK4(p1, 0, pa2); PK4(p1, 8, pa3);
;     ...
; }
; template <int NQ, int MODE> ...
;     ...
;     finishSM<RSM>(pB0, pB1, l_reg, pa0, pa1, pa2, pa3); SBAR();
;     pv_d0<RSM>(o, lacc, vb0 + VST(vp + 1) * SHM_V, pa0, pa1, pa2, pa3);
;     (void)alA;
;     if (hi == 0) li_l[r32] = l_reg; asm volatile("s_waitcnt lgkmcnt(0)" ::: "memory");
.LBB0_488:
	v_exp_f32_e32 v97, v98
	v_exp_f32_e32 v98, v99
	v_exp_f32_e32 v82, v82
	v_exp_f32_e32 v83, v83
	v_exp_f32_e32 v84, v84
	v_exp_f32_e32 v99, v66
	v_add_f32_e32 v66, 0, v97
	v_exp_f32_e32 v85, v85
	v_add_f32_e32 v66, v98, v66
	v_exp_f32_e32 v86, v86
	v_add_f32_e32 v66, v82, v66
	v_exp_f32_e32 v87, v87
	v_add_f32_e32 v66, v83, v66
	v_exp_f32_e32 v88, v88
	v_add_f32_e32 v66, v84, v66
	v_exp_f32_e32 v89, v89
	v_add_f32_e32 v66, v85, v66
	v_exp_f32_e32 v90, v90
	v_add_f32_e32 v66, v86, v66
	v_exp_f32_e32 v91, v91
	v_add_f32_e32 v66, v87, v66
	v_exp_f32_e32 v92, v92
	v_add_f32_e32 v66, v88, v66
	v_exp_f32_e32 v93, v93
	v_add_f32_e32 v66, v89, v66
	v_exp_f32_e32 v94, v94
	v_add_f32_e32 v66, v90, v66
	v_exp_f32_e32 v95, v95
	v_add_f32_e32 v66, v91, v66
	v_add_f32_e32 v66, v92, v66
	v_exp_f32_e32 v100, v67
	v_add_f32_e32 v66, v93, v66
	v_exp_f32_e32 v101, v68
	v_add_f32_e32 v66, v94, v66
	v_exp_f32_e32 v102, v69
	v_add_f32_e32 v66, v95, v66
	v_exp_f32_e32 v103, v70
	v_add_f32_e32 v66, v99, v66
	v_exp_f32_e32 v104, v71
	v_add_f32_e32 v66, v100, v66
	v_exp_f32_e32 v105, v72
	v_add_f32_e32 v66, v101, v66
	v_exp_f32_e32 v106, v73
	v_add_f32_e32 v66, v102, v66
	v_exp_f32_e32 v107, v74
	v_add_f32_e32 v66, v103, v66
	v_exp_f32_e32 v108, v75
	v_add_f32_e32 v66, v104, v66
	v_exp_f32_e32 v109, v76
	v_add_f32_e32 v66, v105, v66
	v_exp_f32_e32 v110, v77
	v_add_f32_e32 v66, v106, v66
	v_exp_f32_e32 v111, v78
	v_add_f32_e32 v66, v107, v66
	v_exp_f32_e32 v112, v79
	v_add_f32_e32 v66, v108, v66
	v_exp_f32_e32 v113, v80
	v_add_f32_e32 v66, v109, v66
	v_exp_f32_e32 v114, v81
	v_add_f32_e32 v66, v110, v66
	v_add_f32_e32 v66, v111, v66
	v_add_f32_e32 v66, v112, v66
	v_add_f32_e32 v66, v113, v66
	v_add_f32_e32 v66, v114, v66
	v_mov_b32_e32 v67, v66
	s_nop 1
	v_permlane32_swap_b32_e32 v66, v67
	v_cvt_pk_bf16_f32 v68, v97, v98
	v_cvt_pk_bf16_f32 v69, v82, v83
	v_cvt_pk_bf16_f32 v70, v84, v85
	v_cvt_pk_bf16_f32 v71, v86, v87
	v_cvt_pk_bf16_f32 v72, v88, v89
	v_cvt_pk_bf16_f32 v73, v90, v91
	v_cvt_pk_bf16_f32 v74, v92, v93
	v_cvt_pk_bf16_f32 v75, v94, v95
	v_cvt_pk_bf16_f32 v76, v99, v100
	v_cvt_pk_bf16_f32 v77, v101, v102
	v_cvt_pk_bf16_f32 v78, v103, v104
	v_cvt_pk_bf16_f32 v79, v105, v106
	v_cvt_pk_bf16_f32 v80, v107, v108
	v_cvt_pk_bf16_f32 v81, v109, v110
	v_cvt_pk_bf16_f32 v82, v111, v112
	v_cvt_pk_bf16_f32 v83, v113, v114
	s_addk_i32 s13, 0x4000
	s_cmp_lt_i32 s12, 3
	s_cselect_b32 s12, s13, 0
	v_add_u32_e32 v97, s12, v177
	ds_read_b64_tr_b16 v[84:85], v97 offset:0
	ds_read_b64_tr_b16 v[86:87], v97 offset:0x800
	ds_read_b64_tr_b16 v[88:89], v97 offset:0x1000
	ds_read_b64_tr_b16 v[90:91], v97 offset:0x1800
	ds_read_b64_tr_b16 v[92:93], v97 offset:0x2000
	ds_read_b64_tr_b16 v[94:95], v97 offset:0x2800
	ds_read_b64_tr_b16 v[98:99], v97 offset:0x3000
	ds_read_b64_tr_b16 v[100:101], v97 offset:0x3800
	s_waitcnt lgkmcnt(0)
	s_nop 0
	v_mfma_f32_32x32x16_bf16 v[50:65], v[68:71], v[84:87], v[50:65]
	ds_read_b64_tr_b16 v[84:85], v97 offset:0x200
	ds_read_b64_tr_b16 v[86:87], v97 offset:0xa00
	v_mfma_f32_32x32x16_bf16 v[50:65], v[72:75], v[88:91], v[50:65]
	ds_read_b64_tr_b16 v[88:89], v97 offset:0x1200
	ds_read_b64_tr_b16 v[90:91], v97 offset:0x1a00
	v_mfma_f32_32x32x16_bf16 v[50:65], v[76:79], v[92:95], v[50:65]
	ds_read_b64_tr_b16 v[92:93], v97 offset:0x2200
	ds_read_b64_tr_b16 v[94:95], v97 offset:0x2a00
	v_mfma_f32_32x32x16_bf16 v[50:65], v[80:83], v[98:101], v[50:65]
	ds_read_b64_tr_b16 v[98:99], v97 offset:0x3200
	ds_read_b64_tr_b16 v[100:101], v97 offset:0x3a00
	s_waitcnt lgkmcnt(0)
	v_mfma_f32_32x32x16_bf16 v[34:49], v[68:71], v[84:87], v[34:49]
	ds_read_b64_tr_b16 v[84:85], v97 offset:0x400
	ds_read_b64_tr_b16 v[86:87], v97 offset:0xc00
	v_mfma_f32_32x32x16_bf16 v[34:49], v[72:75], v[88:91], v[34:49]
	ds_read_b64_tr_b16 v[88:89], v97 offset:0x1400
	ds_read_b64_tr_b16 v[90:91], v97 offset:0x1c00
	v_mfma_f32_32x32x16_bf16 v[34:49], v[76:79], v[92:95], v[34:49]
	ds_read_b64_tr_b16 v[92:93], v97 offset:0x2400
	ds_read_b64_tr_b16 v[94:95], v97 offset:0x2c00
	v_mfma_f32_32x32x16_bf16 v[34:49], v[80:83], v[98:101], v[34:49]
	ds_read_b64_tr_b16 v[98:99], v97 offset:0x3400
	ds_read_b64_tr_b16 v[100:101], v97 offset:0x3c00
	s_waitcnt lgkmcnt(0)
	v_mfma_f32_32x32x16_bf16 v[18:33], v[68:71], v[84:87], v[18:33]
	ds_read_b64_tr_b16 v[84:85], v97 offset:0x600
	ds_read_b64_tr_b16 v[86:87], v97 offset:0xe00
	v_mfma_f32_32x32x16_bf16 v[18:33], v[72:75], v[88:91], v[18:33]
	ds_read_b64_tr_b16 v[88:89], v97 offset:0x1600
	ds_read_b64_tr_b16 v[90:91], v97 offset:0x1e00
	v_mfma_f32_32x32x16_bf16 v[18:33], v[76:79], v[92:95], v[18:33]
	ds_read_b64_tr_b16 v[92:93], v97 offset:0x2600
	ds_read_b64_tr_b16 v[94:95], v97 offset:0x2e00
	v_mfma_f32_32x32x16_bf16 v[18:33], v[80:83], v[98:101], v[18:33]
	ds_read_b64_tr_b16 v[98:99], v97 offset:0x3600
	ds_read_b64_tr_b16 v[100:101], v97 offset:0x3e00
	s_waitcnt lgkmcnt(0)
	v_mfma_f32_32x32x16_bf16 v[2:17], v[68:71], v[84:87], v[2:17]
	v_mfma_f32_32x32x16_bf16 v[2:17], v[72:75], v[88:91], v[2:17]
	v_mfma_f32_32x32x16_bf16 v[2:17], v[76:79], v[92:95], v[2:17]
	v_mfma_f32_32x32x16_bf16 v[2:17], v[80:83], v[98:101], v[2:17]
	s_and_saveexec_b64 s[12:13], s[4:5]
	v_add_f32_e32 v68, v130, v131
	v_add_f32_e32 v68, v179, v68
	v_add_f32_e32 v66, v66, v67
	v_fmac_f32_e32 v66, v68, v96
	ds_write_b32 v178, v66
	s_or_b64 exec, exec, s[12:13]
	s_waitcnt lgkmcnt(0)
	ds_read_b128 v[66:69], v0
	ds_read_b128 v[70:73], v0 offset:32
	v_readlane_b32 s4, v254, 32
	v_readlane_b32 s5, v254, 11
	s_waitcnt lgkmcnt(0)
; __device__ __forceinline__ int tid_of(int wave_s) { int l; asm volatile("v_mbcnt_lo_u32_b32 %0, -1, 0\n\tv_mbcnt_hi_u32_b32 %0, -1, %0" : "=v"(l)); return wave_s * 64 + l; }
; __device__ __forceinline__ unsigned f2bf(float f) { unsigned u = __builtin_bit_cast(unsigned, f); return (u + 0x7fffu + ((u >> 16) & 1u)) >> 16; }
; __device__ __forceinline__ int crow(int r, int hi) { return (r & 3) + 8 * (r >> 2) + 4 * hi; }
; template <int NQ, int MODE> ...
;     ...
;     for (int r = 0; r < 16; ++r) { const float rl = __builtin_amdgcn_rcpf(RSM ? lacc[r] : li_l[crow(r, hi)]);
; #pragma unroll
;         for (int d = 0; d < 4; ++d) o[d][r] *= rl; }
; __device__ __forceinline__ void store_o_tile(const f32x16 (&o)[4], char* lds, bf16_t* Og, int wave_s) {
;     int tid_ = tid_of(wave_s);
;     const int wid = tid_ >> 6, lane = tid_ & 63, r32 = lane & 31, hi = lane >> 5;
;     __syncthreads();
;     bf16_t* stg = (bf16_t*)(lds + wid * 8192);
; #pragma unroll
;     for (int r = 0; r < 16; ++r) { const int orow = att::crow(r, hi);
; #pragma unroll
;         for (int d0 = 0; d0 < 4; ++d0) stg[orow * 128 + d0 * 32 + r32] = (bf16_t)f2bf(o[d0][r]); }
	v_rcp_f32_e32 v66, v66
	v_rcp_f32_e32 v67, v67
	v_add_u32_e32 v74, s4, v176
	v_mul_f32_e32 v50, v66, v50
	v_mul_f32_e32 v34, v66, v34
	v_mul_f32_e32 v75, v66, v18
	v_mul_f32_e32 v66, v66, v2
	v_mul_f32_e32 v51, v67, v51
	v_rcp_f32_e32 v2, v68
	v_mul_f32_e32 v35, v67, v35
	v_mul_f32_e32 v68, v67, v19
	v_mul_f32_e32 v67, v67, v3
	v_rcp_f32_e32 v3, v69
	v_mul_f32_e32 v52, v2, v52
	v_mul_f32_e32 v36, v2, v36
	v_mul_f32_e32 v69, v2, v20
	v_mul_f32_e32 v76, v2, v4
	v_mul_f32_e32 v53, v3, v53
	v_rcp_f32_e32 v2, v70
	v_mul_f32_e32 v37, v3, v37
	v_mul_f32_e32 v70, v3, v21
	v_mul_f32_e32 v77, v3, v5
	v_rcp_f32_e32 v3, v71
	v_mul_f32_e32 v54, v2, v54
	v_mul_f32_e32 v38, v2, v38
	v_mul_f32_e32 v22, v2, v22
	v_mul_f32_e32 v71, v2, v6
	v_mul_f32_e32 v55, v3, v55
	v_rcp_f32_e32 v6, v72
	v_mul_f32_e32 v39, v3, v39
	v_mul_f32_e32 v23, v3, v23
	v_mul_f32_e32 v72, v3, v7
	ds_read_b128 v[2:5], v0 offset:64
	ds_read_b128 v[18:21], v0 offset:96
	v_rcp_f32_e32 v7, v73
	v_mul_f32_e32 v56, v6, v56
	v_mul_f32_e32 v40, v6, v40
	s_waitcnt lgkmcnt(0)
	v_rcp_f32_e32 v0, v2
	v_rcp_f32_e32 v2, v3
	v_rcp_f32_e32 v3, v4
	v_mul_f32_e32 v24, v6, v24
	v_mul_f32_e32 v58, v0, v58
	v_mul_f32_e32 v42, v0, v42
	v_mul_f32_e32 v26, v0, v26
	v_mul_f32_e32 v0, v0, v10
	v_mul_f32_e32 v10, v2, v59
	v_mul_f32_e32 v4, v2, v43
	v_mul_f32_e32 v27, v2, v27
	v_mul_f32_e32 v11, v2, v11
	v_rcp_f32_e32 v2, v5
	v_mul_f32_e32 v43, v3, v60
	v_mul_f32_e32 v5, v3, v44
	v_mul_f32_e32 v28, v3, v28
	v_mul_f32_e32 v12, v3, v12
	v_mul_f32_e32 v44, v2, v61
	v_rcp_f32_e32 v3, v18
	v_mul_f32_e32 v18, v2, v45
	v_mul_f32_e32 v29, v2, v29
	v_mul_f32_e32 v13, v2, v13
	v_rcp_f32_e32 v2, v19
	v_mul_f32_e32 v45, v3, v62
	v_mul_f32_e32 v19, v3, v46
	v_mul_f32_e32 v30, v3, v30
	v_mul_f32_e32 v14, v3, v14
	v_mul_f32_e32 v46, v2, v63
	v_rcp_f32_e32 v3, v20
	v_mul_f32_e32 v20, v2, v47
	v_mul_f32_e32 v31, v2, v31
	v_mul_f32_e32 v15, v2, v15
	v_rcp_f32_e32 v2, v21
	v_mul_f32_e32 v21, v3, v48
	v_mul_f32_e32 v47, v3, v64
	v_mul_f32_e32 v32, v3, v32
	v_mul_f32_e32 v48, v2, v65
	v_mul_f32_e32 v49, v2, v49
	v_mul_f32_e32 v33, v2, v33
	v_mul_f32_e32 v17, v2, v17
	v_ashrrev_i32_e32 v2, 1, v74
	v_and_b32_e32 v2, 0xffffffe0, v2
	v_add_u32_e32 v2, s64, v2
	v_mul_f32_e32 v16, v3, v16
	v_ashrrev_i32_e32 v3, 31, v2
	v_lshlrev_b64 v[2:3], 12, v[2:3]
	v_mul_f32_e32 v8, v6, v8
	v_mul_f32_e32 v57, v7, v57
	v_mul_f32_e32 v41, v7, v41
	v_mul_f32_e32 v25, v7, v25
	v_mul_f32_e32 v9, v7, v9
	v_lshl_add_u64 v[6:7], s[6:7], 0, v[2:3]
	v_mbcnt_lo_u32_b32 v2, -1, 0
	v_mbcnt_hi_u32_b32 v2, -1, v2
	s_waitcnt vmcnt(0)
	v_lshl_add_u32 v59, v2, 7, s5
	v_and_b32_e32 v3, 31, v2
	v_and_b32_e32 v59, 0xffffe000, v59
	v_lshlrev_b32_e32 v60, 5, v2
	v_add_u32_e32 v59, 0, v59
	v_lshlrev_b32_e32 v3, 1, v3
	v_and_b32_e32 v60, 0x400, v60
	v_add3_u32 v3, v59, v3, v60
	v_bfe_u32 v60, v50, 16, 1
	v_add3_u32 v50, v50, v60, s33
	s_barrier
	ds_write_b16_d16_hi v3, v50
	v_bfe_u32 v50, v34, 16, 1
	v_add3_u32 v34, v34, v50, s33
	ds_write_b16_d16_hi v3, v34 offset:64
	v_bfe_u32 v34, v75, 16, 1
	v_add3_u32 v34, v75, v34, s33
	ds_write_b16_d16_hi v3, v34 offset:128
	v_bfe_u32 v34, v66, 16, 1
	v_add3_u32 v34, v66, v34, s33
	ds_write_b16_d16_hi v3, v34 offset:192
	v_bfe_u32 v34, v51, 16, 1
	v_add3_u32 v34, v51, v34, s33
	ds_write_b16_d16_hi v3, v34 offset:256
	v_bfe_u32 v34, v35, 16, 1
	v_add3_u32 v34, v35, v34, s33
	ds_write_b16_d16_hi v3, v34 offset:320
	v_bfe_u32 v34, v68, 16, 1
	v_add3_u32 v34, v68, v34, s33
	ds_write_b16_d16_hi v3, v34 offset:384
	v_bfe_u32 v34, v67, 16, 1
	v_add3_u32 v34, v67, v34, s33
	ds_write_b16_d16_hi v3, v34 offset:448
	v_bfe_u32 v34, v52, 16, 1
	v_add3_u32 v34, v52, v34, s33
	ds_write_b16_d16_hi v3, v34 offset:512
	v_bfe_u32 v34, v36, 16, 1
	v_add3_u32 v34, v36, v34, s33
	ds_write_b16_d16_hi v3, v34 offset:576
	v_bfe_u32 v34, v69, 16, 1
	v_add3_u32 v34, v69, v34, s33
	ds_write_b16_d16_hi v3, v34 offset:640
	v_bfe_u32 v34, v76, 16, 1
	v_add3_u32 v34, v76, v34, s33
	ds_write_b16_d16_hi v3, v34 offset:704
	v_bfe_u32 v34, v53, 16, 1
	v_add3_u32 v34, v53, v34, s33
	ds_write_b16_d16_hi v3, v34 offset:768
	v_bfe_u32 v34, v37, 16, 1
	v_add3_u32 v34, v37, v34, s33
	ds_write_b16_d16_hi v3, v34 offset:832
	v_bfe_u32 v34, v70, 16, 1
	v_add3_u32 v34, v70, v34, s33
	ds_write_b16_d16_hi v3, v34 offset:896
	v_bfe_u32 v34, v77, 16, 1
	v_add3_u32 v34, v77, v34, s33
	ds_write_b16_d16_hi v3, v34 offset:960
	v_bfe_u32 v34, v54, 16, 1
	v_add3_u32 v34, v54, v34, s33
	ds_write_b16_d16_hi v3, v34 offset:2048
	v_bfe_u32 v34, v38, 16, 1
	v_add3_u32 v34, v38, v34, s33
	ds_write_b16_d16_hi v3, v34 offset:2112
	v_bfe_u32 v34, v22, 16, 1
	v_add3_u32 v22, v22, v34, s33
	ds_write_b16_d16_hi v3, v22 offset:2176
	v_bfe_u32 v22, v71, 16, 1
	v_add3_u32 v22, v71, v22, s33
	ds_write_b16_d16_hi v3, v22 offset:2240
	v_bfe_u32 v22, v55, 16, 1
	v_add3_u32 v22, v55, v22, s33
	ds_write_b16_d16_hi v3, v22 offset:2304
	v_bfe_u32 v22, v39, 16, 1
	v_add3_u32 v22, v39, v22, s33
	ds_write_b16_d16_hi v3, v22 offset:2368
	v_bfe_u32 v22, v23, 16, 1
	v_add3_u32 v22, v23, v22, s33
	ds_write_b16_d16_hi v3, v22 offset:2432
	v_bfe_u32 v22, v72, 16, 1
	v_add3_u32 v22, v72, v22, s33
	ds_write_b16_d16_hi v3, v22 offset:2496
	v_bfe_u32 v22, v56, 16, 1
	v_add3_u32 v22, v56, v22, s33
	ds_write_b16_d16_hi v3, v22 offset:2560
	v_bfe_u32 v22, v40, 16, 1
	v_add3_u32 v22, v40, v22, s33
	ds_write_b16_d16_hi v3, v22 offset:2624
	v_bfe_u32 v22, v24, 16, 1
	v_add3_u32 v22, v24, v22, s33
	ds_write_b16_d16_hi v3, v22 offset:2688
	v_bfe_u32 v22, v8, 16, 1
	v_add3_u32 v8, v8, v22, s33
	ds_write_b16_d16_hi v3, v8 offset:2752
	v_bfe_u32 v8, v57, 16, 1
	v_add3_u32 v8, v57, v8, s33
	ds_write_b16_d16_hi v3, v8 offset:2816
; __device__ __forceinline__ unsigned f2bf(float f) { unsigned u = __builtin_bit_cast(unsigned, f); return (u + 0x7fffu + ((u >> 16) & 1u)) >> 16; }
; __device__ __forceinline__ int crow(int r, int hi) { return (r & 3) + 8 * (r >> 2) + 4 * hi; }
; __device__ __forceinline__ int t5_bucket(int rel) {
;     const int n = rel < 0 ? -rel : rel;
;     int b = n < 8 ? n : min(15, 2 + (31 - __clz(n * n)));
;     return b + (rel > 0 ? 16 : 0);
; }
; __device__ __forceinline__ void store_o_tile(const f32x16 (&o)[4], char* lds, bf16_t* Og, int wave_s) {
;     ...
;     for (int r = 0; r < 16; ++r) { const int orow = att::crow(r, hi);
; #pragma unroll
;         for (int d0 = 0; d0 < 4; ++d0) stg[orow * 128 + d0 * 32 + r32] = (bf16_t)f2bf(o[d0][r]); }
;     asm volatile("s_waitcnt lgkmcnt(0)" ::: "memory");
; #pragma unroll
;     for (int i = 0; i < 8; ++i) { const int row = i * 4 + (lane >> 4), ch = lane & 15; const u32x4 v = *(const u32x4*)(stg + row * 128 + ch * 8); *(u32x4*)(Og + (size_t)row * DM + ch * 8) = v;
;         if (i & 1) asm volatile("" ::: "memory"); }
; __global__ void __launch_bounds__(NTHR, 2) mega_fwd(Args a) {
;     ...
;             { UNIT_IDS __syncthreads();
;               if (tid < 257) lut[tid] = SMV[SM_RB + t5_bucket(tid - 128) * 8 + hd] * LOG2E;
	v_bfe_u32 v8, v41, 16, 1
	v_add3_u32 v8, v41, v8, s33
	ds_write_b16_d16_hi v3, v8 offset:2880
	v_bfe_u32 v8, v25, 16, 1
	v_add3_u32 v8, v25, v8, s33
	ds_write_b16_d16_hi v3, v8 offset:2944
	v_bfe_u32 v8, v9, 16, 1
	v_add3_u32 v8, v9, v8, s33
	ds_write_b16_d16_hi v3, v8 offset:3008
	v_bfe_u32 v8, v58, 16, 1
	v_add3_u32 v8, v58, v8, s33
	ds_write_b16_d16_hi v3, v8 offset:4096
	v_bfe_u32 v8, v42, 16, 1
	v_add3_u32 v8, v42, v8, s33
	ds_write_b16_d16_hi v3, v8 offset:4160
	v_bfe_u32 v8, v26, 16, 1
	v_add3_u32 v8, v26, v8, s33
	ds_write_b16_d16_hi v3, v8 offset:4224
	v_bfe_u32 v8, v0, 16, 1
	v_add3_u32 v0, v0, v8, s33
	ds_write_b16_d16_hi v3, v0 offset:4288
	v_bfe_u32 v0, v10, 16, 1
	v_add3_u32 v0, v10, v0, s33
	ds_write_b16_d16_hi v3, v0 offset:4352
	v_bfe_u32 v0, v4, 16, 1
	v_add3_u32 v0, v4, v0, s33
	ds_write_b16_d16_hi v3, v0 offset:4416
	v_bfe_u32 v0, v27, 16, 1
	v_add3_u32 v0, v27, v0, s33
	ds_write_b16_d16_hi v3, v0 offset:4480
	v_bfe_u32 v0, v11, 16, 1
	v_add3_u32 v0, v11, v0, s33
	ds_write_b16_d16_hi v3, v0 offset:4544
	v_bfe_u32 v0, v43, 16, 1
	v_add3_u32 v0, v43, v0, s33
	ds_write_b16_d16_hi v3, v0 offset:4608
	v_bfe_u32 v0, v5, 16, 1
	v_add3_u32 v0, v5, v0, s33
	ds_write_b16_d16_hi v3, v0 offset:4672
	v_bfe_u32 v0, v28, 16, 1
	v_add3_u32 v0, v28, v0, s33
	ds_write_b16_d16_hi v3, v0 offset:4736
	v_bfe_u32 v0, v12, 16, 1
	v_add3_u32 v0, v12, v0, s33
	ds_write_b16_d16_hi v3, v0 offset:4800
	v_bfe_u32 v0, v44, 16, 1
	v_add3_u32 v0, v44, v0, s33
	ds_write_b16_d16_hi v3, v0 offset:4864
	v_bfe_u32 v0, v18, 16, 1
	v_add3_u32 v0, v18, v0, s33
	ds_write_b16_d16_hi v3, v0 offset:4928
	v_bfe_u32 v0, v29, 16, 1
	v_add3_u32 v0, v29, v0, s33
	ds_write_b16_d16_hi v3, v0 offset:4992
	v_bfe_u32 v0, v13, 16, 1
	v_add3_u32 v0, v13, v0, s33
	ds_write_b16_d16_hi v3, v0 offset:5056
	v_bfe_u32 v0, v45, 16, 1
	v_add3_u32 v0, v45, v0, s33
	ds_write_b16_d16_hi v3, v0 offset:6144
	v_bfe_u32 v0, v19, 16, 1
	v_add3_u32 v0, v19, v0, s33
	ds_write_b16_d16_hi v3, v0 offset:6208
	v_bfe_u32 v0, v30, 16, 1
	v_add3_u32 v0, v30, v0, s33
	ds_write_b16_d16_hi v3, v0 offset:6272
	v_bfe_u32 v0, v14, 16, 1
	v_add3_u32 v0, v14, v0, s33
	ds_write_b16_d16_hi v3, v0 offset:6336
	v_bfe_u32 v0, v46, 16, 1
	v_add3_u32 v0, v46, v0, s33
	ds_write_b16_d16_hi v3, v0 offset:6400
	v_bfe_u32 v0, v20, 16, 1
	v_add3_u32 v0, v20, v0, s33
	ds_write_b16_d16_hi v3, v0 offset:6464
	v_bfe_u32 v0, v31, 16, 1
	v_add3_u32 v0, v31, v0, s33
	ds_write_b16_d16_hi v3, v0 offset:6528
	v_bfe_u32 v0, v15, 16, 1
	v_add3_u32 v0, v15, v0, s33
	ds_write_b16_d16_hi v3, v0 offset:6592
	v_bfe_u32 v0, v47, 16, 1
	v_add3_u32 v0, v47, v0, s33
	ds_write_b16_d16_hi v3, v0 offset:6656
	v_bfe_u32 v0, v21, 16, 1
	v_add3_u32 v0, v21, v0, s33
	ds_write_b16_d16_hi v3, v0 offset:6720
	v_bfe_u32 v0, v32, 16, 1
	v_add3_u32 v0, v32, v0, s33
	ds_write_b16_d16_hi v3, v0 offset:6784
	v_bfe_u32 v0, v16, 16, 1
	v_add3_u32 v0, v16, v0, s33
	ds_write_b16_d16_hi v3, v0 offset:6848
	v_bfe_u32 v0, v48, 16, 1
	v_add3_u32 v0, v48, v0, s33
	ds_write_b16_d16_hi v3, v0 offset:6912
	v_bfe_u32 v0, v49, 16, 1
	v_add3_u32 v0, v49, v0, s33
	ds_write_b16_d16_hi v3, v0 offset:6976
	v_bfe_u32 v0, v33, 16, 1
	v_add3_u32 v0, v33, v0, s33
	ds_write_b16_d16_hi v3, v0 offset:7040
	v_bfe_u32 v0, v17, 16, 1
	v_add3_u32 v0, v17, v0, s33
	ds_write_b16_d16_hi v3, v0 offset:7104
	v_lshlrev_b32_e32 v0, 4, v2
	v_and_b32_e32 v0, 0xf0, v0
	v_bfe_u32 v10, v2, 4, 2
	v_add_u32_e32 v11, v59, v0
	s_waitcnt lgkmcnt(0)
	v_lshl_add_u32 v2, v10, 8, v11
	ds_read_b128 v[2:5], v2
	v_lshl_add_u64 v[6:7], s[10:11], 1, v[6:7]
	v_lshl_add_u64 v[6:7], v[6:7], 0, v[0:1]
	v_lshlrev_b32_e32 v0, 12, v10
	v_lshl_add_u64 v[8:9], v[6:7], 0, v[0:1]
	v_or_b32_e32 v0, 4, v10
	s_waitcnt lgkmcnt(0)
	global_store_dwordx4 v[8:9], v[2:5], off offset:1024
	s_nop 1
	v_lshl_add_u32 v2, v0, 8, v11
	ds_read_b128 v[2:5], v2
	v_lshlrev_b32_e32 v0, 12, v0
	v_lshl_add_u64 v[8:9], v[6:7], 0, v[0:1]
	v_or_b32_e32 v0, 8, v10
	s_waitcnt lgkmcnt(0)
	global_store_dwordx4 v[8:9], v[2:5], off offset:1024
	s_nop 1
	v_lshl_add_u32 v2, v0, 8, v11
	ds_read_b128 v[2:5], v2
	v_lshlrev_b32_e32 v0, 12, v0
	v_lshl_add_u64 v[8:9], v[6:7], 0, v[0:1]
	v_or_b32_e32 v0, 12, v10
	s_waitcnt lgkmcnt(0)
	global_store_dwordx4 v[8:9], v[2:5], off offset:1024
	s_nop 1
	v_lshl_add_u32 v2, v0, 8, v11
	ds_read_b128 v[2:5], v2
	v_lshlrev_b32_e32 v0, 12, v0
	v_lshl_add_u64 v[8:9], v[6:7], 0, v[0:1]
	v_or_b32_e32 v0, 16, v10
	s_waitcnt lgkmcnt(0)
	global_store_dwordx4 v[8:9], v[2:5], off offset:1024
	s_nop 1
	v_lshl_add_u32 v2, v0, 8, v11
	ds_read_b128 v[2:5], v2
	v_lshlrev_b32_e32 v0, 12, v0
	v_lshl_add_u64 v[8:9], v[6:7], 0, v[0:1]
	v_or_b32_e32 v0, 20, v10
	s_waitcnt lgkmcnt(0)
	global_store_dwordx4 v[8:9], v[2:5], off offset:1024
	s_nop 1
	v_lshl_add_u32 v2, v0, 8, v11
	ds_read_b128 v[2:5], v2
	v_lshlrev_b32_e32 v0, 12, v0
	v_lshl_add_u64 v[8:9], v[6:7], 0, v[0:1]
	v_or_b32_e32 v0, 24, v10
	s_waitcnt lgkmcnt(0)
	global_store_dwordx4 v[8:9], v[2:5], off offset:1024
	s_nop 1
	v_lshl_add_u32 v2, v0, 8, v11
	ds_read_b128 v[2:5], v2
	v_lshlrev_b32_e32 v0, 12, v0
	v_lshl_add_u64 v[8:9], v[6:7], 0, v[0:1]
	v_or_b32_e32 v0, 28, v10
	s_waitcnt lgkmcnt(0)
	global_store_dwordx4 v[8:9], v[2:5], off offset:1024
	s_nop 1
	v_lshl_add_u32 v2, v0, 8, v11
	ds_read_b128 v[2:5], v2
	v_lshlrev_b32_e32 v0, 12, v0
	v_lshl_add_u64 v[6:7], v[6:7], 0, v[0:1]
	s_waitcnt lgkmcnt(0)
	global_store_dwordx4 v[6:7], v[2:5], off offset:1024
	s_waitcnt lgkmcnt(0)
	v_mbcnt_lo_u32_b32 v0, -1, 0
	v_mbcnt_hi_u32_b32 v0, -1, v0
	s_waitcnt lgkmcnt(0)
	v_add_u32_e32 v128, s4, v0
	v_cmp_gt_i32_e32 vcc, s2, v128
	s_barrier
	s_and_saveexec_b64 s[4:5], vcc
	s_cbranch_execz .LBB0_492
	v_add_u32_e32 v0, 0xffffff80, v128
	v_sub_u32_e32 v2, 0, v0
	v_max_i32_e32 v2, v0, v2
	v_mul_lo_u32 v0, v0, v0
	v_ffbh_u32_e32 v0, v0
	v_sub_u32_e32 v0, 33, v0
	v_min_u32_e32 v0, 15, v0
	v_cmp_gt_u32_e32 vcc, 8, v2
	s_movk_i32 s12, 0x80
	s_nop 0
	v_cndmask_b32_e32 v0, v0, v2, vcc
	v_cmp_lt_i32_e32 vcc, s12, v128
	s_add_i32 s12, s38, 0x2b10
	s_nop 0
	v_cndmask_b32_e64 v2, 0, 16, vcc
	v_add_u32_e32 v0, v0, v2
	v_lshl_add_u32 v2, v0, 3, s12
	v_ashrrev_i32_e32 v3, 31, v2
	v_lshl_add_u64 v[2:3], v[2:3], 2, s[28:29]
	v_add_co_u32_e32 v2, vcc, 0x20000, v2
	s_nop 1
	v_addc_co_u32_e32 v3, vcc, 0, v3, vcc
	global_load_dword v0, v[2:3], off
	v_lshl_add_u32 v2, v128, 2, 0
	v_add_u32_e32 v2, 0x22800, v2
	s_waitcnt vmcnt(0) lgkmcnt(0)
	v_mul_f32_e32 v0, 0x3fb8aa3b, v0
	ds_write_b32 v2, v0
; #define LAS __attribute__((address_space(3)))
; #define DMA_K(t, st) do { if (HAS1) { GLDS(pK1a, K3 + (st) * SHM_KT + wid * 1024); GLDS(pK1b, K3 + (st) * SHM_KT + (wid + 8) * 1024); pK1a += stK1; pK1b += stK1; } \
;     if (HAS2) { GLDS(pK2p, K3 + (st) * SHM_KT + SHM_K1 + wid * 1024); pK2p += stK2; } } while (0)
; template <int NQ, int MODE> ...
;     ...
;     unsigned voK1[2], voK2, voV[2];
; #pragma unroll
;     for (int i = 0; i < 2; ++i) { const int p = wid + 8 * i, row = 4 * p + (lane >> 4), cbs = (lane & 15) ^ (row & 15); voK1[i] = (unsigned)(row * ldk0 + cbs * 8) * 2u; }
;     { const int row = 8 * wid + (lane >> 3), cbs = (lane & 7) ^ ((row >> 1) & 7); voK2 = (unsigned)(row * ldk2 + cbs * 8) * 2u; }
; #pragma unroll
;     for (int i = 0; i < 2; ++i) { const int p = wid + 8 * i, sub = 2 * p + (lane >> 5), kk = ((sub >> 2) << 3) | ((lane & 31) >> 2);
;         const int k = kk, c = (sub & 3) * 32 + (lane & 3) * 8; voV[i] = (unsigned)(k * ldv + c) * 2u; }
;     const char* gK1 = (const char*)(K0 + (size_t)kt0 * KVBLK * ldk0); const size_t stK1 = (size_t)KVBLK * ldk0 * 2;
;     const char* gK2 = (const char*)(K2 + (size_t)kt0 * KVBLK * ldk2); const size_t stK2 = (size_t)KVBLK * ldk2 * 2;
;     const char* gV = (const char*)(Vh + (size_t)kt0 * KVBLK * ldv); const size_t stV = (size_t)KVBLK * ldv * 2;
;     LAS unsigned char* K3 = (LAS unsigned char*)K_lds; LAS unsigned char* V3 = (LAS unsigned char*)V_lds;
;     ...
;     const char* pK1a = gK1 + voK1[0]; const char* pK1b = gK1 + voK1[1]; const char* pK2p = gK2 + voK2; const char* pVa = gV + voV[0]; const char* pVb = gV + voV[1];
;     ...
;     bf16x8 qr[NQ];
;     const bf16_t* Qw = Qb + (long)(wid * QBLK + r32) * ldq + hi * 8;
;     __syncthreads();
; #pragma unroll
;     for (int d0 = 0; d0 < NQ; ++d0) qr[d0] = *reinterpret_cast<const bf16x8*>(Qw + d0 * 16);
;     DMA_K(0, 0); DMA_V(0, 0); DMA_K(1, 1);
; __global__ void __launch_bounds__(NTHR, 2) mega_fwd(Args a) {
;     ...
;               const int ks = q0 - 128 < 0 ? 0 : q0 - 128, ke = q0 + 384 > SEQ ? SEQ : q0 + 384;
;               const float sink = SMV[SM_CS + lq * 4 + hd] * LOG2E;
;               att::attn_core<8, 2>(P + (size_t)q0 * INP + C_CQ + hd * 128, INP, P + C_CK + (hd >> 1) * 128, INP, nullptr, 0, P + C_CV + (hd >> 1) * 128, INP, ks / 64, (ke - ks) / 64, q0, lut, 0.f, 0.f, sink, 1.f, (char*)lds, o, wave_s);
.LBB0_492:
	s_or_b64 exec, exec, s[4:5]
	s_max_i32 s14, s64, 0x80
	s_add_i32 s18, s14, 0xffffff80
	s_min_u32 s15, s64, 0x3e80
	s_add_u32 s12, s28, 0x20000
	s_addc_u32 s13, s29, 0
	s_lshl_b32 s4, s30, 2
	s_add_i32 s4, s38, s4
	s_addk_i32 s4, 0x2b00
	s_ashr_i32 s5, s4, 31
	s_lshl_b64 s[4:5], s[4:5], 2
	s_add_u32 s4, s12, s4
	s_addc_u32 s5, s13, s5
	v_mov_b64_e32 v[2:3], s[4:5]
	s_add_u32 s4, s28, s56
	global_load_dword v62, v[2:3], off
	s_addc_u32 s5, s29, s57
	s_sub_i32 s14, s15, s14
	v_mbcnt_lo_u32_b32 v59, -1, 0
	v_mbcnt_hi_u32_b32 v59, -1, v59
	s_addk_i32 s14, 0x200
	v_bfe_u32 v0, v59, 4, 2
	v_or_b32_e32 v2, s50, v0
	v_bitop3_b32 v0, v0, v59, s50 bitop3:0x36
	s_ashr_i32 s17, s14, 6
	v_mul_lo_u32 v2, v2, s49
	v_lshlrev_b32_e32 v0, 3, v0
	s_movk_i32 s14, 0x78
	v_bfe_u32 v58, v59, 5, 1
	v_and_or_b32 v0, v0, s14, v2
	v_readlane_b32 s14, v254, 34
	v_lshlrev_b32_e32 v4, 3, v59
	v_bfe_u32 v3, v59, 2, 3
	v_or_b32_e32 v2, s14, v58
	v_and_b32_e32 v4, 24, v4
	v_readlane_b32 s14, v254, 35
	v_lshl_or_b32 v4, v2, 5, v4
	s_lshr_b32 s16, s18, 6
	v_or_b32_e32 v2, s14, v3
	v_readlane_b32 s14, v254, 0
	v_and_b32_e32 v174, 31, v59
	v_mul_lo_u32 v2, v2, s49
	v_or_b32_e32 v3, s14, v3
	v_mul_lo_u32 v3, v3, s49
	v_or_b32_e32 v3, v4, v3
	s_mul_i32 s15, s16, 0x88000
	v_or_b32_e32 v2, v4, v2
	v_lshlrev_b32_e32 v4, 1, v3
	s_mul_hi_u32 s14, s16, 0x88000
	s_add_u32 s19, s4, s15
	v_or_b32_e32 v3, s80, v174
	v_mov_b64_e32 v[6:7], s[78:79]
	s_addc_u32 s20, s5, s14
	v_mad_u64_u32 v[6:7], s[14:15], v3, s69, v[6:7]
	v_lshlrev_b32_e32 v8, 4, v58
	v_mov_b32_e32 v9, v1
	v_lshl_add_u64 v[6:7], v[6:7], 0, v[8:9]
	s_add_u32 s4, s19, 0x12001180
	s_waitcnt lgkmcnt(0)
	s_barrier
	global_load_dwordx4 v[158:161], v[6:7], off offset:3456
	global_load_dwordx4 v[154:157], v[6:7], off offset:3488
	global_load_dwordx4 v[150:153], v[6:7], off offset:3520
	global_load_dwordx4 v[146:149], v[6:7], off offset:3552
	global_load_dwordx4 v[142:145], v[6:7], off offset:3584
	global_load_dwordx4 v[138:141], v[6:7], off offset:3616
	global_load_dwordx4 v[134:137], v[6:7], off offset:3648
	global_load_dwordx4 v[130:133], v[6:7], off offset:3680
	s_mov_b32 m0, s81
	v_lshlrev_b32_e32 v0, 1, v0
	s_addc_u32 s5, s20, 0
	v_add_u32_e32 v10, 0x44000, v0
	s_add_u32 s14, s19, 0x12001380
	global_load_lds_dwordx4 v0, s[4:5]
	s_mov_b32 m0, s67
	v_lshlrev_b32_e32 v2, 1, v2
	s_addc_u32 s15, s20, 0
	global_load_lds_dwordx4 v10, s[4:5]
	s_mov_b32 m0, s63
	s_add_i32 s26, s81, 0x14000
	v_mov_b32_e32 v11, v1
	v_lshl_add_u64 v[6:7], s[4:5], 0, v[0:1]
	global_load_lds_dwordx4 v2, s[14:15]
	s_mov_b32 m0, s26
	v_lshl_add_u64 v[8:9], s[4:5], 0, v[10:11]
	v_lshl_add_u64 v[10:11], v[6:7], 0, s[74:75]
	global_load_lds_dwordx4 v4, s[14:15]
	s_mov_b32 m0, s70
	v_lshl_add_u64 v[12:13], v[8:9], 0, s[74:75]
	global_load_lds_dwordx4 v[10:11], off
	s_mov_b32 m0, s85
	s_cmp_lt_i32 s17, 3
	global_load_lds_dwordx4 v[12:13], off
	s_waitcnt vmcnt(2) lgkmcnt(0)
	s_barrier
	s_cselect_b64 s[4:5], -1, 0
	v_lshl_add_u64 v[52:53], v[6:7], 0, s[46:47]
	v_lshl_add_u64 v[50:51], v[8:9], 0, s[46:47]
	s_and_b64 vcc, exec, s[4:5]
	s_cbranch_vccnz .LBB0_494
	s_mov_b32 m0, s87
	s_nop 0
	global_load_lds_dwordx4 v[52:53], off
	s_mov_b32 m0, s86
	v_lshl_add_u64 v[52:53], v[6:7], 0, s[76:77]
	global_load_lds_dwordx4 v[50:51], off
	v_lshl_add_u64 v[50:51], v[8:9], 0, s[76:77]

; __device__ __forceinline__ int tid_of(int wave_s) { int l; asm volatile("v_mbcnt_lo_u32_b32 %0, -1, 0\n\tv_mbcnt_hi_u32_b32 %0, -1, %0" : "=v"(l)); return wave_s * 64 + l; }
; __device__ __forceinline__ unsigned f2bf(float f) { unsigned u = __builtin_bit_cast(unsigned, f); return (u + 0x7fffu + ((u >> 16) & 1u)) >> 16; }
; __device__ __forceinline__ int crow(int r, int hi) { return (r & 3) + 8 * (r >> 2) + 4 * hi; }
; template <int NQ, int MODE> ...
;     ...
;     if (hi == 0) li_l[r32] = l_reg; asm volatile("s_waitcnt lgkmcnt(0)" ::: "memory");
; #pragma unroll
;     for (int r = 0; r < 16; ++r) { const float rl = __builtin_amdgcn_rcpf(RSM ? lacc[r] : li_l[crow(r, hi)]);
; #pragma unroll
;         for (int d = 0; d < 4; ++d) o[d][r] *= rl; }
; __device__ __forceinline__ void store_o_tile(const f32x16 (&o)[4], char* lds, bf16_t* Og, int wave_s) {
;     int tid_ = tid_of(wave_s);
;     const int wid = tid_ >> 6, lane = tid_ & 63, r32 = lane & 31, hi = lane >> 5;
;     __syncthreads();
;     bf16_t* stg = (bf16_t*)(lds + wid * 8192);
; #pragma unroll
;     for (int r = 0; r < 16; ++r) { const int orow = att::crow(r, hi);
; #pragma unroll
;         for (int d0 = 0; d0 < 4; ++d0) stg[orow * 128 + d0 * 32 + r32] = (bf16_t)f2bf(o[d0][r]); }
.LBB0_694:
	s_or_b64 exec, exec, s[4:5]
	s_waitcnt lgkmcnt(0)
	ds_read_b128 v[66:69], v176
	ds_read_b128 v[70:73], v176 offset:32
	v_readlane_b32 s4, v254, 11
	s_waitcnt lgkmcnt(0)
	v_rcp_f32_e32 v0, v66
	v_rcp_f32_e32 v66, v67
	v_rcp_f32_e32 v67, v68
	v_mul_f32_e32 v68, v0, v18
	v_mul_f32_e32 v50, v0, v50
	v_mul_f32_e32 v34, v0, v34
	v_mul_f32_e32 v0, v0, v2
	v_rcp_f32_e32 v2, v69
	v_mul_f32_e32 v74, v66, v19
	v_mul_f32_e32 v51, v66, v51
	v_mul_f32_e32 v35, v66, v35
	v_mul_f32_e32 v66, v66, v3
	v_mul_f32_e32 v69, v2, v21
	v_rcp_f32_e32 v3, v70
	v_mul_f32_e32 v53, v2, v53
	v_mul_f32_e32 v37, v2, v37
	v_mul_f32_e32 v70, v2, v5
	v_rcp_f32_e32 v2, v71
	v_mul_f32_e32 v75, v67, v20
	v_mul_f32_e32 v52, v67, v52
	v_mul_f32_e32 v36, v67, v36
	v_mul_f32_e32 v67, v67, v4
	v_mul_f32_e32 v22, v3, v22
	v_mul_f32_e32 v54, v3, v54
	v_mul_f32_e32 v38, v3, v38
	v_mul_f32_e32 v71, v3, v6
	v_mul_f32_e32 v23, v2, v23
	v_rcp_f32_e32 v6, v72
	v_mul_f32_e32 v55, v2, v55
	v_mul_f32_e32 v39, v2, v39
	v_mul_f32_e32 v72, v2, v7
	ds_read_b128 v[2:5], v176 offset:64
	ds_read_b128 v[18:21], v176 offset:96
	v_rcp_f32_e32 v7, v73
	v_mul_f32_e32 v24, v6, v24
	v_mul_f32_e32 v56, v6, v56
	s_waitcnt lgkmcnt(0)
	v_rcp_f32_e32 v2, v2
	v_rcp_f32_e32 v3, v3
	v_mul_f32_e32 v40, v6, v40
	v_mul_f32_e32 v8, v6, v8
	v_mul_f32_e32 v26, v2, v26
	v_mul_f32_e32 v58, v2, v58
	v_mul_f32_e32 v42, v2, v42
	v_mul_f32_e32 v10, v2, v10
	v_rcp_f32_e32 v2, v4
	v_mul_f32_e32 v27, v3, v27
	v_mul_f32_e32 v4, v3, v59
	v_mul_f32_e32 v43, v3, v43
	v_mul_f32_e32 v11, v3, v11
	v_rcp_f32_e32 v3, v5
	v_mul_f32_e32 v28, v2, v28
	v_mul_f32_e32 v5, v2, v60
	v_mul_f32_e32 v44, v2, v44
	v_mul_f32_e32 v12, v2, v12
	v_rcp_f32_e32 v2, v18
	v_mul_f32_e32 v29, v3, v29
	v_mul_f32_e32 v18, v3, v61
	v_mul_f32_e32 v45, v3, v45
	v_mul_f32_e32 v13, v3, v13
	v_rcp_f32_e32 v3, v19
	v_mul_f32_e32 v30, v2, v30
	v_mul_f32_e32 v19, v2, v62
	v_mul_f32_e32 v46, v2, v46
	v_mul_f32_e32 v14, v2, v14
	v_rcp_f32_e32 v2, v20
	v_mul_f32_e32 v31, v3, v31
	v_mul_f32_e32 v20, v3, v63
	v_mul_f32_e32 v47, v3, v47
	v_mul_f32_e32 v15, v3, v15
	v_rcp_f32_e32 v3, v21
	v_mul_f32_e32 v32, v2, v32
	v_mul_f32_e32 v21, v2, v64
	v_mul_f32_e32 v48, v2, v48
	v_mul_f32_e32 v16, v2, v16
	v_ashrrev_i32_e32 v2, 1, v128
	v_and_b32_e32 v2, 0xffffffe0, v2
	v_add_u32_e32 v2, s64, v2
	v_mul_f32_e32 v33, v3, v33
	v_mul_f32_e32 v59, v3, v65
	v_mul_f32_e32 v49, v3, v49
	v_mul_f32_e32 v17, v3, v17
	v_ashrrev_i32_e32 v3, 31, v2
	v_lshlrev_b64 v[2:3], 12, v[2:3]
	v_mul_f32_e32 v25, v7, v25
	v_mul_f32_e32 v57, v7, v57
	v_mul_f32_e32 v41, v7, v41
	v_mul_f32_e32 v9, v7, v9
	v_lshl_add_u64 v[6:7], s[6:7], 0, v[2:3]
	v_mbcnt_lo_u32_b32 v2, -1, 0
	v_mbcnt_hi_u32_b32 v2, -1, v2
	s_waitcnt vmcnt(0)
	v_lshl_add_u32 v60, v2, 7, s4
	v_and_b32_e32 v3, 31, v2
	v_and_b32_e32 v60, 0xffffe000, v60
	v_lshlrev_b32_e32 v61, 5, v2
	v_add_u32_e32 v60, 0, v60
	v_lshlrev_b32_e32 v3, 1, v3
	v_and_b32_e32 v61, 0x400, v61
	v_add3_u32 v3, v60, v3, v61
	v_bfe_u32 v61, v68, 16, 1
	v_add3_u32 v61, v68, v61, s33
	s_barrier
	ds_write_b16_d16_hi v3, v61
	v_bfe_u32 v61, v50, 16, 1
	v_add3_u32 v50, v50, v61, s33
	ds_write_b16_d16_hi v3, v50 offset:64
	v_bfe_u32 v50, v34, 16, 1
	v_add3_u32 v34, v34, v50, s33
	ds_write_b16_d16_hi v3, v34 offset:128
	v_bfe_u32 v34, v0, 16, 1
	v_add3_u32 v0, v0, v34, s33
	ds_write_b16_d16_hi v3, v0 offset:192
	v_bfe_u32 v0, v74, 16, 1
	v_add3_u32 v0, v74, v0, s33
	ds_write_b16_d16_hi v3, v0 offset:256
	v_bfe_u32 v0, v51, 16, 1
	v_add3_u32 v0, v51, v0, s33
	ds_write_b16_d16_hi v3, v0 offset:320
	v_bfe_u32 v0, v35, 16, 1
	v_add3_u32 v0, v35, v0, s33
	ds_write_b16_d16_hi v3, v0 offset:384
	v_bfe_u32 v0, v66, 16, 1
	v_add3_u32 v0, v66, v0, s33
	ds_write_b16_d16_hi v3, v0 offset:448
	v_bfe_u32 v0, v75, 16, 1
	v_add3_u32 v0, v75, v0, s33
	ds_write_b16_d16_hi v3, v0 offset:512
	v_bfe_u32 v0, v52, 16, 1
	v_add3_u32 v0, v52, v0, s33
	ds_write_b16_d16_hi v3, v0 offset:576
	v_bfe_u32 v0, v36, 16, 1
	v_add3_u32 v0, v36, v0, s33
	ds_write_b16_d16_hi v3, v0 offset:640
	v_bfe_u32 v0, v67, 16, 1
	v_add3_u32 v0, v67, v0, s33
	ds_write_b16_d16_hi v3, v0 offset:704
	v_bfe_u32 v0, v69, 16, 1
	v_add3_u32 v0, v69, v0, s33
	ds_write_b16_d16_hi v3, v0 offset:768
	v_bfe_u32 v0, v53, 16, 1
	v_add3_u32 v0, v53, v0, s33
	ds_write_b16_d16_hi v3, v0 offset:832
	v_bfe_u32 v0, v37, 16, 1
	v_add3_u32 v0, v37, v0, s33
	ds_write_b16_d16_hi v3, v0 offset:896
	v_bfe_u32 v0, v70, 16, 1
	v_add3_u32 v0, v70, v0, s33
	ds_write_b16_d16_hi v3, v0 offset:960
	v_bfe_u32 v0, v22, 16, 1
	v_add3_u32 v0, v22, v0, s33
	ds_write_b16_d16_hi v3, v0 offset:2048
	v_bfe_u32 v0, v54, 16, 1
	v_add3_u32 v0, v54, v0, s33
	ds_write_b16_d16_hi v3, v0 offset:2112
	v_bfe_u32 v0, v38, 16, 1
	v_add3_u32 v0, v38, v0, s33
	ds_write_b16_d16_hi v3, v0 offset:2176
	v_bfe_u32 v0, v71, 16, 1
	v_add3_u32 v0, v71, v0, s33
	ds_write_b16_d16_hi v3, v0 offset:2240
	v_bfe_u32 v0, v23, 16, 1
	v_add3_u32 v0, v23, v0, s33
	ds_write_b16_d16_hi v3, v0 offset:2304
	v_bfe_u32 v0, v55, 16, 1
	v_add3_u32 v0, v55, v0, s33
	ds_write_b16_d16_hi v3, v0 offset:2368
	v_bfe_u32 v0, v39, 16, 1
	v_add3_u32 v0, v39, v0, s33
	ds_write_b16_d16_hi v3, v0 offset:2432
	v_bfe_u32 v0, v72, 16, 1
	v_add3_u32 v0, v72, v0, s33
	ds_write_b16_d16_hi v3, v0 offset:2496
	v_bfe_u32 v0, v24, 16, 1
	v_add3_u32 v0, v24, v0, s33
	ds_write_b16_d16_hi v3, v0 offset:2560
	v_bfe_u32 v0, v56, 16, 1
	v_add3_u32 v0, v56, v0, s33
	ds_write_b16_d16_hi v3, v0 offset:2624
	v_bfe_u32 v0, v40, 16, 1
	v_add3_u32 v0, v40, v0, s33
	ds_write_b16_d16_hi v3, v0 offset:2688
	v_bfe_u32 v0, v8, 16, 1
	v_add3_u32 v0, v8, v0, s33
	ds_write_b16_d16_hi v3, v0 offset:2752
	v_bfe_u32 v0, v25, 16, 1
; __device__ __forceinline__ unsigned f2bf(float f) { unsigned u = __builtin_bit_cast(unsigned, f); return (u + 0x7fffu + ((u >> 16) & 1u)) >> 16; }
; __device__ __forceinline__ int crow(int r, int hi) { return (r & 3) + 8 * (r >> 2) + 4 * hi; }
; __device__ __forceinline__ void store_o_tile(const f32x16 (&o)[4], char* lds, bf16_t* Og, int wave_s) {
;     ...
;     for (int r = 0; r < 16; ++r) { const int orow = att::crow(r, hi);
; #pragma unroll
;         for (int d0 = 0; d0 < 4; ++d0) stg[orow * 128 + d0 * 32 + r32] = (bf16_t)f2bf(o[d0][r]); }
;     asm volatile("s_waitcnt lgkmcnt(0)" ::: "memory");
; #pragma unroll
;     for (int i = 0; i < 8; ++i) { const int row = i * 4 + (lane >> 4), ch = lane & 15; const u32x4 v = *(const u32x4*)(stg + row * 128 + ch * 8); *(u32x4*)(Og + (size_t)row * DM + ch * 8) = v;
;         if (i & 1) asm volatile("" ::: "memory"); }
; __global__ void __launch_bounds__(NTHR, 2) mega_fwd(Args a) {
;     ...
;             { UNIT_IDS __syncthreads();
;               if (tid < 257) lut[tid] = SMV[SM_RB + t5_bucket(tid - 128) * 8 + 4 + hd] * LOG2E;
	v_add3_u32 v0, v25, v0, s33
	ds_write_b16_d16_hi v3, v0 offset:2816
	v_bfe_u32 v0, v57, 16, 1
	v_add3_u32 v0, v57, v0, s33
	ds_write_b16_d16_hi v3, v0 offset:2880
	v_bfe_u32 v0, v41, 16, 1
	v_add3_u32 v0, v41, v0, s33
	ds_write_b16_d16_hi v3, v0 offset:2944
	v_bfe_u32 v0, v9, 16, 1
	v_add3_u32 v0, v9, v0, s33
	ds_write_b16_d16_hi v3, v0 offset:3008
	v_bfe_u32 v0, v26, 16, 1
	v_add3_u32 v0, v26, v0, s33
	ds_write_b16_d16_hi v3, v0 offset:4096
	v_bfe_u32 v0, v58, 16, 1
	v_add3_u32 v0, v58, v0, s33
	ds_write_b16_d16_hi v3, v0 offset:4160
	v_bfe_u32 v0, v42, 16, 1
	v_add3_u32 v0, v42, v0, s33
	ds_write_b16_d16_hi v3, v0 offset:4224
	v_bfe_u32 v0, v10, 16, 1
	v_add3_u32 v0, v10, v0, s33
	ds_write_b16_d16_hi v3, v0 offset:4288
	v_bfe_u32 v0, v27, 16, 1
	v_add3_u32 v0, v27, v0, s33
	ds_write_b16_d16_hi v3, v0 offset:4352
	v_bfe_u32 v0, v4, 16, 1
	v_add3_u32 v0, v4, v0, s33
	ds_write_b16_d16_hi v3, v0 offset:4416
	v_bfe_u32 v0, v43, 16, 1
	v_add3_u32 v0, v43, v0, s33
	ds_write_b16_d16_hi v3, v0 offset:4480
	v_bfe_u32 v0, v11, 16, 1
	v_add3_u32 v0, v11, v0, s33
	ds_write_b16_d16_hi v3, v0 offset:4544
	v_bfe_u32 v0, v28, 16, 1
	v_add3_u32 v0, v28, v0, s33
	ds_write_b16_d16_hi v3, v0 offset:4608
	v_bfe_u32 v0, v5, 16, 1
	v_add3_u32 v0, v5, v0, s33
	ds_write_b16_d16_hi v3, v0 offset:4672
	v_bfe_u32 v0, v44, 16, 1
	v_add3_u32 v0, v44, v0, s33
	ds_write_b16_d16_hi v3, v0 offset:4736
	v_bfe_u32 v0, v12, 16, 1
	v_add3_u32 v0, v12, v0, s33
	ds_write_b16_d16_hi v3, v0 offset:4800
	v_bfe_u32 v0, v29, 16, 1
	v_add3_u32 v0, v29, v0, s33
	ds_write_b16_d16_hi v3, v0 offset:4864
	v_bfe_u32 v0, v18, 16, 1
	v_add3_u32 v0, v18, v0, s33
	ds_write_b16_d16_hi v3, v0 offset:4928
	v_bfe_u32 v0, v45, 16, 1
	v_add3_u32 v0, v45, v0, s33
	ds_write_b16_d16_hi v3, v0 offset:4992
	v_bfe_u32 v0, v13, 16, 1
	v_add3_u32 v0, v13, v0, s33
	ds_write_b16_d16_hi v3, v0 offset:5056
	v_bfe_u32 v0, v30, 16, 1
	v_add3_u32 v0, v30, v0, s33
	ds_write_b16_d16_hi v3, v0 offset:6144
	v_bfe_u32 v0, v19, 16, 1
	v_add3_u32 v0, v19, v0, s33
	ds_write_b16_d16_hi v3, v0 offset:6208
	v_bfe_u32 v0, v46, 16, 1
	v_add3_u32 v0, v46, v0, s33
	ds_write_b16_d16_hi v3, v0 offset:6272
	v_bfe_u32 v0, v14, 16, 1
	v_add3_u32 v0, v14, v0, s33
	ds_write_b16_d16_hi v3, v0 offset:6336
	v_bfe_u32 v0, v31, 16, 1
	v_add3_u32 v0, v31, v0, s33
	ds_write_b16_d16_hi v3, v0 offset:6400
	v_bfe_u32 v0, v20, 16, 1
	v_add3_u32 v0, v20, v0, s33
	ds_write_b16_d16_hi v3, v0 offset:6464
	v_bfe_u32 v0, v47, 16, 1
	v_add3_u32 v0, v47, v0, s33
	ds_write_b16_d16_hi v3, v0 offset:6528
	v_bfe_u32 v0, v15, 16, 1
	v_add3_u32 v0, v15, v0, s33
	ds_write_b16_d16_hi v3, v0 offset:6592
	v_bfe_u32 v0, v32, 16, 1
	v_add3_u32 v0, v32, v0, s33
	ds_write_b16_d16_hi v3, v0 offset:6656
	v_bfe_u32 v0, v21, 16, 1
	v_add3_u32 v0, v21, v0, s33
	ds_write_b16_d16_hi v3, v0 offset:6720
	v_bfe_u32 v0, v48, 16, 1
	v_add3_u32 v0, v48, v0, s33
	ds_write_b16_d16_hi v3, v0 offset:6784
	v_bfe_u32 v0, v16, 16, 1
	v_add3_u32 v0, v16, v0, s33
	ds_write_b16_d16_hi v3, v0 offset:6848
	v_bfe_u32 v0, v33, 16, 1
	v_add3_u32 v0, v33, v0, s33
	ds_write_b16_d16_hi v3, v0 offset:6912
	v_bfe_u32 v0, v59, 16, 1
	v_add3_u32 v0, v59, v0, s33
	ds_write_b16_d16_hi v3, v0 offset:6976
	v_bfe_u32 v0, v49, 16, 1
	v_add3_u32 v0, v49, v0, s33
	ds_write_b16_d16_hi v3, v0 offset:7040
	v_bfe_u32 v0, v17, 16, 1
	v_add3_u32 v0, v17, v0, s33
	ds_write_b16_d16_hi v3, v0 offset:7104
	v_lshlrev_b32_e32 v0, 4, v2
	v_and_b32_e32 v0, 0xf0, v0
	v_bfe_u32 v10, v2, 4, 2
	v_add_u32_e32 v11, v60, v0
	s_waitcnt lgkmcnt(0)
	v_lshl_add_u32 v2, v10, 8, v11
	ds_read_b128 v[2:5], v2
	v_lshl_add_u64 v[6:7], s[10:11], 1, v[6:7]
	v_lshl_add_u64 v[6:7], v[6:7], 0, v[0:1]
	v_lshlrev_b32_e32 v0, 12, v10
	v_lshl_add_u64 v[8:9], v[6:7], 0, v[0:1]
	v_or_b32_e32 v0, 4, v10
	s_waitcnt lgkmcnt(0)
	global_store_dwordx4 v[8:9], v[2:5], off offset:2048
	v_readlane_b32 s4, v254, 32
	s_nop 0
	v_lshl_add_u32 v2, v0, 8, v11
	ds_read_b128 v[2:5], v2
	v_lshlrev_b32_e32 v0, 12, v0
	v_lshl_add_u64 v[8:9], v[6:7], 0, v[0:1]
	v_or_b32_e32 v0, 8, v10
	s_waitcnt lgkmcnt(0)
	global_store_dwordx4 v[8:9], v[2:5], off offset:2048
	s_nop 1
	v_lshl_add_u32 v2, v0, 8, v11
	ds_read_b128 v[2:5], v2
	v_lshlrev_b32_e32 v0, 12, v0
	v_lshl_add_u64 v[8:9], v[6:7], 0, v[0:1]
	v_or_b32_e32 v0, 12, v10
	s_waitcnt lgkmcnt(0)
	global_store_dwordx4 v[8:9], v[2:5], off offset:2048
	s_nop 1
	v_lshl_add_u32 v2, v0, 8, v11
	ds_read_b128 v[2:5], v2
	v_lshlrev_b32_e32 v0, 12, v0
	v_lshl_add_u64 v[8:9], v[6:7], 0, v[0:1]
	v_or_b32_e32 v0, 16, v10
	s_waitcnt lgkmcnt(0)
	global_store_dwordx4 v[8:9], v[2:5], off offset:2048
	s_nop 1
	v_lshl_add_u32 v2, v0, 8, v11
	ds_read_b128 v[2:5], v2
	v_lshlrev_b32_e32 v0, 12, v0
	v_lshl_add_u64 v[8:9], v[6:7], 0, v[0:1]
	v_or_b32_e32 v0, 20, v10
	s_waitcnt lgkmcnt(0)
	global_store_dwordx4 v[8:9], v[2:5], off offset:2048
	s_nop 1
	v_lshl_add_u32 v2, v0, 8, v11
	ds_read_b128 v[2:5], v2
	v_lshlrev_b32_e32 v0, 12, v0
	v_lshl_add_u64 v[8:9], v[6:7], 0, v[0:1]
	v_or_b32_e32 v0, 24, v10
	s_waitcnt lgkmcnt(0)
	global_store_dwordx4 v[8:9], v[2:5], off offset:2048
	s_nop 1
	v_lshl_add_u32 v2, v0, 8, v11
	ds_read_b128 v[2:5], v2
	v_lshlrev_b32_e32 v0, 12, v0
	v_lshl_add_u64 v[8:9], v[6:7], 0, v[0:1]
	v_or_b32_e32 v0, 28, v10
	s_waitcnt lgkmcnt(0)
	global_store_dwordx4 v[8:9], v[2:5], off offset:2048
	s_nop 1
	v_lshl_add_u32 v2, v0, 8, v11
	ds_read_b128 v[2:5], v2
	v_lshlrev_b32_e32 v0, 12, v0
	v_lshl_add_u64 v[6:7], v[6:7], 0, v[0:1]
	s_waitcnt lgkmcnt(0)
	global_store_dwordx4 v[6:7], v[2:5], off offset:2048
	s_waitcnt lgkmcnt(0)
	v_mbcnt_lo_u32_b32 v0, -1, 0
	v_mbcnt_hi_u32_b32 v0, -1, v0
	s_waitcnt lgkmcnt(0)
	v_add_u32_e32 v226, s4, v0
	v_cmp_gt_i32_e32 vcc, s2, v226
	s_barrier
	s_and_saveexec_b64 s[4:5], vcc
	s_cbranch_execz .LBB0_696
	v_add_u32_e32 v0, 0xffffff80, v226
	v_sub_u32_e32 v2, 0, v0
	v_max_i32_e32 v2, v0, v2
	v_mul_lo_u32 v0, v0, v0
	v_ffbh_u32_e32 v0, v0
	v_sub_u32_e32 v0, 33, v0
	v_min_u32_e32 v0, 15, v0
	v_cmp_gt_u32_e32 vcc, 8, v2
	s_movk_i32 s14, 0x80
	s_nop 0
	v_cndmask_b32_e32 v0, v0, v2, vcc
	v_cmp_lt_i32_e32 vcc, s14, v226
	s_add_i32 s14, s38, 0x2b14
	s_nop 0
	v_cndmask_b32_e64 v2, 0, 16, vcc
	v_add_u32_e32 v0, v0, v2
	v_lshl_add_u32 v2, v0, 3, s14
	v_ashrrev_i32_e32 v3, 31, v2
	v_lshl_add_u64 v[2:3], v[2:3], 2, s[12:13]
	global_load_dword v0, v[2:3], off
	v_lshl_add_u32 v2, v226, 2, 0
	v_add_u32_e32 v2, 0x22800, v2
	s_waitcnt vmcnt(0) lgkmcnt(0)
	v_mul_f32_e32 v0, 0x3fb8aa3b, v0
	ds_write_b32 v2, v0
; __device__ __forceinline__ int v_rd_base(int lane) { return ((lane & 3) << 3) | (((lane >> 2) & 3) << 6) | (((lane >> 4) & 1) << 5) | (((lane >> 5) & 1) << 8); }
; template <int NQ>
; __device__ __forceinline__ void qkt(f32x16& p0, f32x16& p1, const char* Ks, const int (&kq1)[2], const int (&kq2)[2], const bf16x8* qr, const f32x16& cinit) {
;     ...
;     if (HAS2) {
; #pragma unroll
;         for (int d = 0; d < 4; ++d) { const char* a = Ks + SHM_K1 + kb2[d];
;             const bf16x8 b0 = *reinterpret_cast<const bf16x8*>(a); const bf16x8 b1 = *reinterpret_cast<const bf16x8*>(a + 4096);
;             p0 = __builtin_amdgcn_mfma_f32_32x32x16_bf16(b0, qr[(NQ == 12 ? 8 : 0) + d], p0, 0, 0, 0);
;             p1 = __builtin_amdgcn_mfma_f32_32x32x16_bf16(b1, qr[(NQ == 12 ? 8 : 0) + d], p1, 0, 0, 0); } }
; template <int NQ, int MODE> ...
;     ...
;     bf16x8 qr[NQ];
;     const bf16_t* Qw = Qb + (long)(wid * QBLK + r32) * ldq + hi * 8;
;     __syncthreads();
; #pragma unroll
;     for (int d0 = 0; d0 < NQ; ++d0) qr[d0] = *reinterpret_cast<const bf16x8*>(Qw + d0 * 16);
;     DMA_K(0, 0); DMA_V(0, 0); DMA_K(1, 1);
;     const int lo1 = (hi ^ (r32 & 1)) << 4, s3 = (r32 >> 1) & 7, b1_ = r32 * 256 + lo1;
;     const int kb1[2] = {b1_, s3};
;     const int lo2 = (hi ^ ((r32 >> 1) & 1)) << 4, s2 = (r32 >> 2) & 3, b2_ = r32 * 128 + lo2;
;     const int kb2[2] = {b2_, s2};
;     const int vb0 = (int)(uintptr_t)V_lds + v_rd_base(lane);
;     const int kl0 = (int)(uintptr_t)K_lds;
;     const int qw = q0 + wid * QBLK;
;     ...
;     f32x16 cinit = f32x16{}; float cur_cb = 0.f; bool dirty = true;
;     ...
;     f32x16 pA0, pA1, pB0, pB1; float alA, alB; bool rsA, rsB; bf16x8 pa0, pa1, pa2, pa3;
;     WAITB(NLK);
;     if (2 < NT) DMA_K(2, 2); DMA_V(1, 1);
;     CINIT(0);
;     qkt<NQ>(pA0, pA1, K_lds, kb1, kb2, qr, cinit); { TILEP(0); (void)cbT; rsA = partialSM<MODE, true, FOLD>(pA0, pA1, m_reg, alA, relb, nearT, lut, cbT); dirty |= rsA; }
; __global__ void __launch_bounds__(NTHR, 2) mega_fwd(Args a) {
;     ...
;               const float cbL = SMV[SM_RB + 15 * 8 + 4 + hd] * LOG2E, cbR = SMV[SM_RB + 31 * 8 + 4 + hd] * LOG2E;
;               att::attn_core<4, 1>(P + (size_t)q0 * INP + C_DQ + hd * 128, INP, P + C_DK + hd * 128, INP, nullptr, 0, P + C_DV + hd * 128, INP, 0, SEQ / 64, q0, lut, cbL, cbR, 0.f, 0.f, (char*)lds, o, wave_s);
.LBB0_696:
	s_or_b64 exec, exec, s[4:5]
	s_ashr_i32 s39, s38, 31
	s_lshl_b64 s[4:5], s[38:39], 2
	s_add_u32 s4, s12, s4
	s_addc_u32 s5, s13, s5
	v_mov_b32_e32 v0, s4
	v_add_co_u32_e32 v2, vcc, 0xa000, v0
	v_mov_b32_e32 v5, s5
	s_nop 0
	v_addc_co_u32_e32 v3, vcc, 0, v5, vcc
	global_load_dword v15, v[2:3], off offset:3632
	s_add_u32 s4, s82, s34
	v_add_co_u32_e32 v4, vcc, 0xb000, v0
	s_addc_u32 s5, s73, s35
	s_nop 0
	v_addc_co_u32_e32 v5, vcc, 0, v5, vcc
	s_add_u32 s12, s4, 0x1580
	global_load_dword v8, v[4:5], off offset:48
	v_mbcnt_lo_u32_b32 v9, -1, 0
	v_mbcnt_hi_u32_b32 v9, -1, v9
	v_readlane_b32 s4, v254, 33
	v_bfe_u32 v0, v9, 3, 3
	v_bfe_u32 v65, v9, 5, 1
	v_or_b32_e32 v0, s4, v0
	v_readlane_b32 s4, v254, 34
	s_addc_u32 s13, s5, 0
	v_and_b32_e32 v14, 31, v9
	v_bfe_u32 v2, v9, 2, 3
	v_or_b32_e32 v6, s4, v65
	v_readlane_b32 s4, v254, 35
	v_mov_b64_e32 v[4:5], s[12:13]
	v_or_b32_e32 v16, s80, v14
	v_or_b32_e32 v10, s4, v2
	v_readlane_b32 s4, v254, 0
	v_mov_b32_e32 v3, v1
	s_waitcnt lgkmcnt(0)
	v_or_b32_e32 v12, s4, v2
	v_lshlrev_b32_e32 v2, 4, v65
	v_mad_u64_u32 v[4:5], s[4:5], v16, s69, v[4:5]
	v_lshl_add_u64 v[2:3], v[4:5], 0, v[2:3]
	s_barrier
	global_load_dwordx4 v[188:191], v[2:3], off
	global_load_dwordx4 v[184:187], v[2:3], off offset:32
	global_load_dwordx4 v[180:183], v[2:3], off offset:64
	global_load_dwordx4 v[176:179], v[2:3], off offset:96
	v_lshlrev_b32_e32 v66, 3, v9
	s_add_u32 s14, s28, s34
	v_and_b32_e32 v7, 24, v66
	v_lshrrev_b32_e32 v17, 1, v0
	s_addc_u32 s15, s29, s35
	v_lshl_or_b32 v6, v6, 5, v7
	v_mul_lo_u32 v4, v10, s49
	v_mul_lo_u32 v5, v12, s49
	v_xor_b32_e32 v7, v17, v9
	s_add_u32 s16, s14, 0x12001980
	v_mul_lo_u32 v0, v0, s49
	v_or_b32_e32 v4, v6, v4
	v_or_b32_e32 v5, v6, v5
	v_lshlrev_b32_e32 v6, 3, v7
	s_addc_u32 s17, s15, 0
	v_and_or_b32 v0, v6, 56, v0
	s_mov_b32 m0, s81
	s_add_u32 s18, s14, 0x12001d80
	v_lshlrev_b32_e32 v0, 1, v0
	v_lshlrev_b32_e32 v10, 1, v4
	s_addc_u32 s19, s15, 0
	global_load_lds_dwordx4 v0, s[16:17]
	s_mov_b32 m0, s63
	v_lshlrev_b32_e32 v12, 1, v5
	v_lshl_add_u64 v[4:5], s[16:17], 0, v[0:1]
	global_load_lds_dwordx4 v10, s[18:19]
	s_mov_b32 m0, s26
	v_lshl_add_u64 v[20:21], v[4:5], 0, s[74:75]
	global_load_lds_dwordx4 v12, s[18:19]
	s_mov_b32 m0, s67
	v_mov_b32_e32 v11, v1
	global_load_lds_dwordx4 v[20:21], off
	v_lshl_add_u64 v[6:7], s[18:19], 0, v[10:11]
	s_waitcnt vmcnt(1) lgkmcnt(0)
	s_barrier
	v_lshl_add_u64 v[10:11], v[4:5], 0, s[46:47]
	s_mov_b32 m0, s70
	s_cmpk_lt_u32 s25, 0x9a
	v_mov_b32_e32 v13, v1
	v_lshl_add_u64 v[16:17], v[6:7], 0, s[74:75]
	global_load_lds_dwordx4 v[10:11], off
	s_waitcnt vmcnt(0)
	v_mul_f32_e32 v227, 0x3fb8aa3b, v15
	s_mov_b32 m0, s71
	s_cselect_b64 s[14:15], -1, 0
	v_lshrrev_b32_e32 v22, 1, v9
	v_lshl_add_u64 v[2:3], s[18:19], 0, v[12:13]
	global_load_lds_dwordx4 v[16:17], off
	v_cndmask_b32_e64 v16, v227, 0, s[14:15]
	v_lshl_add_u64 v[18:19], v[2:3], 0, s[74:75]
	v_bitop3_b32 v0, v65, v22, 1 bitop3:0x78
	v_lshlrev_b32_e32 v12, 7, v14
	s_mov_b32 m0, s72
	v_mov_b32_e32 v30, v16
	v_mov_b32_e32 v31, v16
	global_load_lds_dwordx4 v[18:19], off
	v_mov_b32_e32 v17, v16
	v_mov_b32_e32 v18, v16
	v_mov_b32_e32 v19, v16
	v_mov_b32_e32 v20, v16
	v_mov_b32_e32 v21, v16
	v_mov_b32_e32 v22, v16
	v_mov_b32_e32 v23, v16
	v_mov_b32_e32 v24, v16
	v_mov_b32_e32 v25, v16
	v_mov_b32_e32 v26, v16
	v_mov_b32_e32 v27, v16
	v_mov_b32_e32 v28, v16
	v_mov_b32_e32 v29, v16
	v_lshl_or_b32 v0, v0, 4, v12
	v_mov_b64_e32 v[46:47], v[30:31]
	v_and_b32_e32 v64, 0x60, v66
	v_mov_b64_e32 v[44:45], v[28:29]
	v_mov_b64_e32 v[42:43], v[26:27]
	v_mov_b64_e32 v[40:41], v[24:25]
	v_mov_b64_e32 v[38:39], v[22:23]
	v_mov_b64_e32 v[36:37], v[20:21]
	v_mov_b64_e32 v[34:35], v[18:19]
	v_mov_b64_e32 v[32:33], v[16:17]
	v_add3_u32 v15, 0, v64, v0
	ds_read_b128 v[10:13], v15
	s_waitcnt lgkmcnt(0)
	v_mfma_f32_32x32x16_bf16 v[48:63], v[10:13], v[188:191], v[32:47]
	ds_read_b128 v[10:13], v15 offset:4096
	v_bitop3_b32 v236, v66, 32, v222 bitop3:0x6c
	v_add3_u32 v15, 0, v236, v0
	v_bitop3_b32 v235, v66, 64, v222 bitop3:0x6c
	v_bitop3_b32 v234, v66, s45, v66 bitop3:0xc
	s_cmpk_gt_u32 s25, 0x99
	s_waitcnt lgkmcnt(0)
	v_mfma_f32_32x32x16_bf16 v[32:47], v[10:13], v[188:191], v[32:47]
	ds_read_b128 v[10:13], v15
	s_waitcnt lgkmcnt(0)
	v_mfma_f32_32x32x16_bf16 v[48:63], v[10:13], v[184:187], v[48:63]
	ds_read_b128 v[10:13], v15 offset:4096
	v_add3_u32 v15, 0, v235, v0
	s_waitcnt lgkmcnt(0)
	v_mfma_f32_32x32x16_bf16 v[32:47], v[10:13], v[184:187], v[32:47]
	ds_read_b128 v[10:13], v15
	s_waitcnt lgkmcnt(0)
	v_mfma_f32_32x32x16_bf16 v[48:63], v[10:13], v[180:183], v[48:63]
	ds_read_b128 v[10:13], v15 offset:4096
	v_add3_u32 v15, 0, v234, v0
	s_waitcnt lgkmcnt(0)
	v_mfma_f32_32x32x16_bf16 v[32:47], v[10:13], v[180:183], v[32:47]
	ds_read_b128 v[10:13], v15
	s_waitcnt lgkmcnt(0)
	v_mfma_f32_32x32x16_bf16 v[48:63], v[10:13], v[176:179], v[48:63]
	ds_read_b128 v[10:13], v15 offset:4096
	v_lshlrev_b32_e32 v15, 2, v65
	v_or_b32_e32 v65, s25, v14
	v_sub_u32_e32 v231, v15, v65
	s_waitcnt lgkmcnt(0)
	v_mfma_f32_32x32x16_bf16 v[32:47], v[10:13], v[176:179], v[32:47]
	s_cbranch_scc1 .LBB0_698
; template <int MODE, bool FIRST, bool FOLD>
; __device__ __forceinline__ bool partialSM(f32x16& p0, f32x16& p1, float& m_reg, float& alpha, int relbase, bool near, const float* lut, float cb) {
;     ...
;     if (MODE != 0 && near) {
; #pragma unroll
;         for (int r = 0; r < 16; ++r) { const int rel = relbase + (r & 3) + 8 * (r >> 2), rel1 = rel + 32;
;             const int i0 = min(max(rel, -128), 128) + 128, i1 = min(max(rel1, -128), 128) + 128;
;             const float b0 = lut[i0], b1 = lut[i1];
;             if (MODE == 1) { p0[r] += b0; p1[r] += b1; }
;             else { p0[r] = (rel >= -128 && rel <= 128) ? p0[r] + b0 : -1e30f; p1[r] = (rel1 >= -128 && rel1 <= 128) ? p1[r] + b1 : -1e30f; } }
;     }
	v_add_u32_e32 v12, 1, v231
	v_med3_i32 v13, v12, s3, v223
	v_med3_i32 v12, v12, s96, v222
	v_lshl_add_u32 v65, v12, 2, s24
	v_add_u32_e32 v12, 2, v231
	v_med3_i32 v66, v12, s3, v223
	v_med3_i32 v12, v12, s96, v222
	v_add_u32_e32 v71, 9, v231
	v_lshl_add_u32 v67, v12, 2, s24
	v_add_u32_e32 v12, 3, v231
	v_med3_i32 v72, v71, s3, v223
	v_med3_i32 v71, v71, s96, v222
	v_med3_i32 v10, v231, s3, v223
	v_med3_i32 v11, v231, s96, v222
	v_med3_i32 v68, v12, s3, v223
	v_lshl_add_u32 v74, v71, 2, s24
	v_add_u32_e32 v71, 10, v231
	v_lshl_add_u32 v10, v10, 2, s24
	v_lshl_add_u32 v11, v11, 2, s24
	v_lshl_add_u32 v13, v13, 2, s24
	v_lshl_add_u32 v66, v66, 2, s24
	v_med3_i32 v12, v12, s96, v222
	v_lshl_add_u32 v69, v68, 2, s24
	v_lshl_add_u32 v73, v72, 2, s24
	v_med3_i32 v72, v71, s3, v223
	v_med3_i32 v71, v71, s96, v222
	v_add_u32_e32 v79, 17, v231
	v_lshl_add_u32 v70, v12, 2, s24
	ds_read_b32 v10, v10 offset:512
	ds_read_b32 v12, v11 offset:640
	ds_read_b32 v11, v13 offset:512
	ds_read_b32 v13, v65 offset:640
	ds_read_b32 v66, v66 offset:512
	ds_read_b32 v68, v67 offset:640
	ds_read_b32 v67, v69 offset:512
	ds_read_b32 v69, v70 offset:640
	v_add_u32_e32 v65, 8, v231
	v_lshl_add_u32 v76, v71, 2, s24
	v_add_u32_e32 v71, 11, v231
	v_med3_i32 v80, v79, s3, v223
	v_med3_i32 v79, v79, s96, v222
	v_med3_i32 v70, v65, s3, v223
	v_med3_i32 v65, v65, s96, v222
	v_lshl_add_u32 v75, v72, 2, s24
	v_med3_i32 v72, v71, s3, v223
	v_lshl_add_u32 v82, v79, 2, s24
	v_add_u32_e32 v79, 18, v231
	v_lshl_add_u32 v70, v70, 2, s24
	v_lshl_add_u32 v65, v65, 2, s24
	v_med3_i32 v71, v71, s96, v222
	v_lshl_add_u32 v77, v72, 2, s24
	v_lshl_add_u32 v81, v80, 2, s24
	v_med3_i32 v80, v79, s3, v223
	v_med3_i32 v79, v79, s96, v222
	v_add_u32_e32 v87, 25, v231
	v_lshl_add_u32 v78, v71, 2, s24
	ds_read_b32 v70, v70 offset:512
	ds_read_b32 v72, v65 offset:640
	ds_read_b32 v71, v73 offset:512
	ds_read_b32 v73, v74 offset:640
	ds_read_b32 v74, v75 offset:512
	ds_read_b32 v76, v76 offset:640
	ds_read_b32 v75, v77 offset:512
	ds_read_b32 v77, v78 offset:640
	v_add_u32_e32 v65, 16, v231
	v_lshl_add_u32 v84, v79, 2, s24
	v_add_u32_e32 v79, 19, v231
	v_med3_i32 v88, v87, s3, v223
	v_med3_i32 v87, v87, s96, v222
	v_med3_i32 v78, v65, s3, v223
	v_med3_i32 v65, v65, s96, v222
	v_lshl_add_u32 v83, v80, 2, s24
	v_med3_i32 v80, v79, s3, v223
	v_lshl_add_u32 v94, v87, 2, s24
	v_add_u32_e32 v87, 26, v231
	v_lshl_add_u32 v78, v78, 2, s24
	v_lshl_add_u32 v65, v65, 2, s24
	v_med3_i32 v79, v79, s96, v222
	v_lshl_add_u32 v85, v80, 2, s24
	v_lshl_add_u32 v89, v88, 2, s24
	v_med3_i32 v88, v87, s3, v223
	v_med3_i32 v87, v87, s96, v222
	v_lshl_add_u32 v86, v79, 2, s24
	ds_read_b32 v78, v78 offset:512
	ds_read_b32 v80, v65 offset:640
	ds_read_b32 v79, v81 offset:512
	ds_read_b32 v81, v82 offset:640
	ds_read_b32 v82, v83 offset:512
	ds_read_b32 v84, v84 offset:640
	ds_read_b32 v83, v85 offset:512
	ds_read_b32 v85, v86 offset:640
	v_add_u32_e32 v65, 24, v231
	v_lshl_add_u32 v92, v87, 2, s24
	v_add_u32_e32 v87, 27, v231
	v_med3_i32 v86, v65, s3, v223
	v_lshl_add_u32 v90, v88, 2, s24
	v_med3_i32 v88, v87, s3, v223
	v_med3_i32 v87, v87, s96, v222
	v_med3_i32 v65, v65, s96, v222
	v_lshl_add_u32 v86, v86, 2, s24
	v_lshl_add_u32 v91, v88, 2, s24
	v_lshl_add_u32 v93, v87, 2, s24
	v_lshl_add_u32 v65, v65, 2, s24
	ds_read_b32 v86, v86 offset:512
	ds_read_b32 v88, v65 offset:640
	ds_read_b32 v90, v90 offset:512
	ds_read_b32 v91, v91 offset:512
	ds_read_b32 v87, v89 offset:512
	ds_read_b32 v93, v93 offset:640
	ds_read_b32 v92, v92 offset:640
	ds_read_b32 v89, v94 offset:640
	s_waitcnt lgkmcnt(0)
	v_pk_add_f32 v[62:63], v[62:63], v[90:91]
	v_pk_add_f32 v[60:61], v[60:61], v[86:87]
	v_pk_add_f32 v[58:59], v[58:59], v[82:83]
	v_pk_add_f32 v[56:57], v[56:57], v[78:79]
	v_pk_add_f32 v[54:55], v[54:55], v[74:75]
	v_pk_add_f32 v[52:53], v[52:53], v[70:71]
	v_pk_add_f32 v[50:51], v[50:51], v[66:67]
	v_pk_add_f32 v[48:49], v[48:49], v[10:11]
	v_pk_add_f32 v[46:47], v[46:47], v[92:93]
	v_pk_add_f32 v[44:45], v[44:45], v[88:89]
	v_pk_add_f32 v[42:43], v[42:43], v[84:85]
	v_pk_add_f32 v[40:41], v[40:41], v[80:81]
	v_pk_add_f32 v[38:39], v[38:39], v[76:77]
	v_pk_add_f32 v[36:37], v[36:37], v[72:73]
	v_pk_add_f32 v[34:35], v[34:35], v[68:69]
	v_pk_add_f32 v[32:33], v[32:33], v[12:13]

; #define SBAR() __builtin_amdgcn_sched_barrier(0)
; __device__ __forceinline__ int crow(int r, int hi) { return (r & 3) + 8 * (r >> 2) + 4 * hi; }
; #define PK4(P, BASE, OUT) do { u32x4 w = {cvtpk(P[BASE + 0], P[BASE + 1]), cvtpk(P[BASE + 2], P[BASE + 3]), cvtpk(P[BASE + 4], P[BASE + 5]), cvtpk(P[BASE + 6], P[BASE + 7])}; \
;     OUT = *reinterpret_cast<bf16x8*>(&w); } while (0)
; template <bool RSM> __device__ __forceinline__ void pv_d0(f32x16* o, f32x16& lacc, int vb, bf16x8 pa0, bf16x8 pa1, bf16x8 pa2, bf16x8 pa3) {
;     if (RSM) {
;         const bf16x8 ones = {0x3F80, 0x3F80, 0x3F80, 0x3F80, 0x3F80, 0x3F80, 0x3F80, 0x3F80};
;         lacc = __builtin_amdgcn_mfma_f32_32x32x16_bf16(pa0, ones, lacc, 0, 0, 0);
;         lacc = __builtin_amdgcn_mfma_f32_32x32x16_bf16(pa1, ones, lacc, 0, 0, 0);
;         lacc = __builtin_amdgcn_mfma_f32_32x32x16_bf16(pa2, ones, lacc, 0, 0, 0);
;         lacc = __builtin_amdgcn_mfma_f32_32x32x16_bf16(pa3, ones, lacc, 0, 0, 0); }
;     pv_one<0>(o[0], vb, pa0, pa1, pa2, pa3); pv_one<1>(o[1], vb, pa0, pa1, pa2, pa3); pv_one<2>(o[2], vb, pa0, pa1, pa2, pa3); pv_one<3>(o[3], vb, pa0, pa1, pa2, pa3);
; template <bool RSM> __device__ __forceinline__ void finishSM(f32x16& p0, f32x16& p1, float& l_reg, bf16x8& pa0, bf16x8& pa1, bf16x8& pa2, bf16x8& pa3) {
; #pragma unroll
;     for (int r = 0; r < 16; ++r) p1[r] = __builtin_amdgcn_exp2f(p1[r]);
;     float ps = 0;
;     if (!RSM) {
; #pragma unroll
;     for (int r = 0; r < 16; ++r) ps += p0[r];
; #pragma unroll
;     for (int r = 0; r < 16; ++r) ps += p1[r];
;     { auto rr = __builtin_amdgcn_permlane32_swap(__float_as_uint(ps), __float_as_uint(ps), false, false);
;       ps = __uint_as_float(rr[0]) + __uint_as_float(rr[1]); }
;     l_reg += ps; }
;     ...
;     PK4(p0, 0, pa0); PK4(p0, 8, pa1); PK4(p1, 0, pa2); PK4(p1, 8, pa3);
;     ...
; }
; template <int NQ, int MODE> ...
;     ...
;     finishSM<RSM>(pB0, pB1, l_reg, pa0, pa1, pa2, pa3); SBAR();
;     pv_d0<RSM>(o, lacc, vb0 + VST(vp + 1) * SHM_V, pa0, pa1, pa2, pa3);
;     (void)alA;
;     if (hi == 0) li_l[r32] = l_reg; asm volatile("s_waitcnt lgkmcnt(0)" ::: "memory");
; #pragma unroll
;     for (int r = 0; r < 16; ++r) { const float rl = __builtin_amdgcn_rcpf(RSM ? lacc[r] : li_l[crow(r, hi)]);
; #pragma unroll
;         for (int d = 0; d < 4; ++d) o[d][r] *= rl; }
.LBB0_769:
	v_exp_f32_e32 v2, v144
	v_exp_f32_e32 v3, v145
	v_exp_f32_e32 v4, v146
	v_exp_f32_e32 v5, v147
	v_exp_f32_e32 v6, v148
	v_exp_f32_e32 v7, v149
	v_exp_f32_e32 v8, v150
	v_exp_f32_e32 v9, v151
	v_exp_f32_e32 v10, v152
	v_exp_f32_e32 v11, v153
	v_exp_f32_e32 v12, v154
	v_exp_f32_e32 v13, v155
	v_exp_f32_e32 v112, v112
	v_exp_f32_e32 v113, v113
	v_exp_f32_e32 v114, v114
	v_exp_f32_e32 v115, v115
	v_exp_f32_e32 v14, v156
	v_exp_f32_e32 v15, v157
	v_exp_f32_e32 v128, v158
	v_exp_f32_e32 v129, v159
	v_exp_f32_e32 v116, v116
	v_exp_f32_e32 v117, v117
	v_exp_f32_e32 v118, v118
	v_exp_f32_e32 v119, v119
	v_exp_f32_e32 v120, v120
	v_exp_f32_e32 v121, v121
	v_exp_f32_e32 v122, v122
	v_exp_f32_e32 v123, v123
	v_exp_f32_e32 v124, v124
	v_exp_f32_e32 v125, v125
	v_exp_f32_e32 v126, v126
	v_exp_f32_e32 v127, v127
	v_cvt_pk_bf16_f32 v2, v2, v3
	v_cvt_pk_bf16_f32 v3, v4, v5
	v_cvt_pk_bf16_f32 v4, v6, v7
	v_cvt_pk_bf16_f32 v5, v8, v9
	v_cvt_pk_bf16_f32 v6, v10, v11
	v_cvt_pk_bf16_f32 v7, v12, v13
	v_cvt_pk_bf16_f32 v8, v14, v15
	v_cvt_pk_bf16_f32 v9, v128, v129
	v_cvt_pk_bf16_f32 v10, v112, v113
	v_cvt_pk_bf16_f32 v11, v114, v115
	v_cvt_pk_bf16_f32 v12, v116, v117
	v_cvt_pk_bf16_f32 v13, v118, v119
	v_cvt_pk_bf16_f32 v112, v120, v121
	v_cvt_pk_bf16_f32 v113, v122, v123
	v_cvt_pk_bf16_f32 v114, v124, v125
	v_cvt_pk_bf16_f32 v115, v126, v127
	s_addk_i32 s37, 0x4000
	s_cmp_lt_i32 s35, 3
	s_mov_b32 s38, s36
	s_mov_b32 s39, s36
	s_cselect_b32 s20, s37, 0
	s_mov_b32 s37, s36
	v_mov_b64_e32 v[118:119], s[38:39]
	v_mov_b64_e32 v[116:117], s[36:37]
	v_add_u32_e32 v14, s20, v230
	s_nop 0
	v_mfma_f32_32x32x16_bf16 v[96:111], v[2:5], v[116:119], v[96:111]
	v_mfma_f32_32x32x16_bf16 v[96:111], v[6:9], v[116:119], v[96:111]
	v_mfma_f32_32x32x16_bf16 v[96:111], v[10:13], v[116:119], v[96:111]
	v_mfma_f32_32x32x16_bf16 v[96:111], v[112:115], v[116:119], v[96:111]
	ds_read_b64_tr_b16 v[116:117], v14 offset:0
	ds_read_b64_tr_b16 v[118:119], v14 offset:0x800
	ds_read_b64_tr_b16 v[120:121], v14 offset:0x1000
	ds_read_b64_tr_b16 v[122:123], v14 offset:0x1800
	ds_read_b64_tr_b16 v[124:125], v14 offset:0x2000
	ds_read_b64_tr_b16 v[126:127], v14 offset:0x2800
	ds_read_b64_tr_b16 v[128:129], v14 offset:0x3000
	ds_read_b64_tr_b16 v[130:131], v14 offset:0x3800
	s_waitcnt lgkmcnt(0)
	s_nop 0
	v_mfma_f32_32x32x16_bf16 v[80:95], v[2:5], v[116:119], v[80:95]
	ds_read_b64_tr_b16 v[116:117], v14 offset:0x200
	ds_read_b64_tr_b16 v[118:119], v14 offset:0xa00
	v_mfma_f32_32x32x16_bf16 v[80:95], v[6:9], v[120:123], v[80:95]
	ds_read_b64_tr_b16 v[120:121], v14 offset:0x1200
	ds_read_b64_tr_b16 v[122:123], v14 offset:0x1a00
	v_mfma_f32_32x32x16_bf16 v[80:95], v[10:13], v[124:127], v[80:95]
	ds_read_b64_tr_b16 v[124:125], v14 offset:0x2200
	ds_read_b64_tr_b16 v[126:127], v14 offset:0x2a00
	v_mfma_f32_32x32x16_bf16 v[80:95], v[112:115], v[128:131], v[80:95]
	ds_read_b64_tr_b16 v[128:129], v14 offset:0x3200
	ds_read_b64_tr_b16 v[130:131], v14 offset:0x3a00
	s_waitcnt lgkmcnt(0)
	v_mfma_f32_32x32x16_bf16 v[64:79], v[2:5], v[116:119], v[64:79]
	ds_read_b64_tr_b16 v[116:117], v14 offset:0x400
	ds_read_b64_tr_b16 v[118:119], v14 offset:0xc00
	v_mfma_f32_32x32x16_bf16 v[64:79], v[6:9], v[120:123], v[64:79]
	ds_read_b64_tr_b16 v[120:121], v14 offset:0x1400
	ds_read_b64_tr_b16 v[122:123], v14 offset:0x1c00
	v_mfma_f32_32x32x16_bf16 v[64:79], v[10:13], v[124:127], v[64:79]
	ds_read_b64_tr_b16 v[124:125], v14 offset:0x2400
	ds_read_b64_tr_b16 v[126:127], v14 offset:0x2c00
	v_mfma_f32_32x32x16_bf16 v[64:79], v[112:115], v[128:131], v[64:79]
	ds_read_b64_tr_b16 v[128:129], v14 offset:0x3400
	ds_read_b64_tr_b16 v[130:131], v14 offset:0x3c00
	s_waitcnt lgkmcnt(0)
	v_mfma_f32_32x32x16_bf16 v[48:63], v[2:5], v[116:119], v[48:63]
	ds_read_b64_tr_b16 v[116:117], v14 offset:0x600
	ds_read_b64_tr_b16 v[118:119], v14 offset:0xe00
	v_mfma_f32_32x32x16_bf16 v[48:63], v[6:9], v[120:123], v[48:63]
	ds_read_b64_tr_b16 v[120:121], v14 offset:0x1600
	ds_read_b64_tr_b16 v[122:123], v14 offset:0x1e00
	v_mfma_f32_32x32x16_bf16 v[48:63], v[10:13], v[124:127], v[48:63]
	ds_read_b64_tr_b16 v[124:125], v14 offset:0x2600
	ds_read_b64_tr_b16 v[126:127], v14 offset:0x2e00
	v_mfma_f32_32x32x16_bf16 v[48:63], v[112:115], v[128:131], v[48:63]
	ds_read_b64_tr_b16 v[128:129], v14 offset:0x3600
	ds_read_b64_tr_b16 v[130:131], v14 offset:0x3e00
	s_waitcnt lgkmcnt(0)
	v_mfma_f32_32x32x16_bf16 v[32:47], v[2:5], v[116:119], v[32:47]
	v_mfma_f32_32x32x16_bf16 v[32:47], v[6:9], v[120:123], v[32:47]
	v_mfma_f32_32x32x16_bf16 v[32:47], v[10:13], v[124:127], v[32:47]
	v_mfma_f32_32x32x16_bf16 v[32:47], v[112:115], v[128:131], v[32:47]
	s_and_saveexec_b64 s[20:21], s[4:5]
	v_mul_f32_e32 v0, v233, v0
	ds_write_b32 v232, v0
	s_or_b64 exec, exec, s[20:21]
	v_rcp_f32_e32 v0, v96
	v_rcp_f32_e32 v2, v97
	s_lshl_b32 s4, s41, 3
	s_add_i32 s4, s4, s86
	v_mul_f32_e32 v4, v0, v80
	v_mul_f32_e32 v6, v0, v64
	v_mul_f32_e32 v7, v0, v48
	s_nop 0
	v_mul_f32_e32 v8, v0, v32
	v_rcp_f32_e32 v0, v98
	v_mul_f32_e32 v5, v2, v81
	v_mul_f32_e32 v9, v2, v65
	v_mul_f32_e32 v10, v2, v49
	v_mul_f32_e32 v11, v2, v33
	v_rcp_f32_e32 v2, v99
	v_mul_f32_e32 v12, v0, v82
	v_mul_f32_e32 v13, v0, v66
	v_mul_f32_e32 v14, v0, v50
	v_mul_f32_e32 v15, v0, v34
	v_rcp_f32_e32 v0, v100
	v_mul_f32_e32 v32, v2, v83
	v_mul_f32_e32 v33, v2, v67
	v_mul_f32_e32 v34, v2, v51
	v_mul_f32_e32 v35, v2, v35
	v_rcp_f32_e32 v2, v101
	v_mul_f32_e32 v48, v0, v84
	v_mul_f32_e32 v49, v0, v68
	v_mul_f32_e32 v50, v0, v52
	v_mul_f32_e32 v36, v0, v36
	v_rcp_f32_e32 v0, v102
	v_mul_f32_e32 v51, v2, v85
	v_mul_f32_e32 v52, v2, v69
	v_mul_f32_e32 v53, v2, v53
	v_mul_f32_e32 v37, v2, v37
	v_rcp_f32_e32 v2, v103
	v_mul_f32_e32 v64, v0, v86
	v_mul_f32_e32 v65, v0, v70
	v_mul_f32_e32 v54, v0, v54
	v_mul_f32_e32 v38, v0, v38
	v_rcp_f32_e32 v0, v104
	v_mul_f32_e32 v66, v2, v87
	v_mul_f32_e32 v67, v2, v71
	v_mul_f32_e32 v55, v2, v55
	v_mul_f32_e32 v39, v2, v39
	v_rcp_f32_e32 v2, v105
	v_mul_f32_e32 v68, v0, v88
	v_mul_f32_e32 v69, v0, v72
	v_mul_f32_e32 v56, v0, v56
	v_mul_f32_e32 v40, v0, v40
	v_rcp_f32_e32 v0, v106
	v_mul_f32_e32 v70, v2, v89
	v_mul_f32_e32 v71, v2, v73
	v_mul_f32_e32 v57, v2, v57
	v_mul_f32_e32 v41, v2, v41
	v_rcp_f32_e32 v2, v107
	v_mul_f32_e32 v72, v0, v90
	v_mul_f32_e32 v73, v0, v74
	v_mul_f32_e32 v58, v0, v58
	v_mul_f32_e32 v42, v0, v42
	v_rcp_f32_e32 v0, v108
	v_mul_f32_e32 v74, v2, v91
	v_mul_f32_e32 v75, v2, v75
	v_mul_f32_e32 v59, v2, v59
	v_mul_f32_e32 v43, v2, v43
	v_rcp_f32_e32 v2, v109
	v_mul_f32_e32 v80, v0, v92
	v_mul_f32_e32 v76, v0, v76
	v_mul_f32_e32 v60, v0, v60
	v_mul_f32_e32 v44, v0, v44
	v_rcp_f32_e32 v0, v110
	s_ashr_i32 s5, s4, 31
	s_lshl_b64 s[4:5], s[4:5], 14
	v_mul_f32_e32 v81, v2, v93
	v_mul_f32_e32 v77, v2, v77
	v_mul_f32_e32 v61, v2, v61
	v_mul_f32_e32 v45, v2, v45
	v_rcp_f32_e32 v2, v111
	s_add_u32 s4, s28, s4
	s_waitcnt lgkmcnt(0)
; __device__ __forceinline__ int tid_of(int wave_s) { int l; asm volatile("v_mbcnt_lo_u32_b32 %0, -1, 0\n\tv_mbcnt_hi_u32_b32 %0, -1, %0" : "=v"(l)); return wave_s * 64 + l; }
; #define DMA_K(t, st) do { if (HAS1) { GLDS(pK1a, K3 + (st) * SHM_KT + wid * 1024); GLDS(pK1b, K3 + (st) * SHM_KT + (wid + 8) * 1024); pK1a += stK1; pK1b += stK1; } \
;     if (HAS2) { GLDS(pK2p, K3 + (st) * SHM_KT + SHM_K1 + wid * 1024); pK2p += stK2; } } while (0)
; #define DMA_V(t, st) do { GLDS(pVa, V3 + (st) * SHM_V + wid * 1024); GLDS(pVb, V3 + (st) * SHM_V + (wid + 8) * 1024); pVa += stV; pVb += stV; } while (0)
; template <int NQ, int MODE> ...
;     ...
;     bf16x8 qr[NQ];
;     const bf16_t* Qw = Qb + (long)(wid * QBLK + r32) * ldq + hi * 8;
;     __syncthreads();
; #pragma unroll
;     for (int d0 = 0; d0 < NQ; ++d0) qr[d0] = *reinterpret_cast<const bf16x8*>(Qw + d0 * 16);
;     DMA_K(0, 0); DMA_V(0, 0); DMA_K(1, 1);
; __global__ void __launch_bounds__(NTHR, 2) mega_fwd(Args a) {
;     ...
;               { float* scrp = DSCR + ((size_t)(u * 8 + wave_s) * 64) * 64 + (tid_of(wave_s) & 63);
; #pragma unroll
;               for (int d0 = 0; d0 < 4; ++d0)
; #pragma unroll
;                   for (int r = 0; r < 16; ++r) scrp[(d0 * 16 + r) * 64] = o[d0][r]; }
;               att::attn_core<4, 1>(P + (size_t)q0 * INP + C_DQ + hd * 128 + 64, INP, P + C_DK + hd * 128 + 64, INP, nullptr, 0, P + C_DV + hd * 128, INP, 0, SEQ / 64, q0, lut, cbL, cbR, 0.f, 0.f, (char*)lds, o, wave_s);
	v_mul_f32_e32 v82, v0, v94
	v_mul_f32_e32 v78, v0, v78
	v_mul_f32_e32 v62, v0, v62
	v_mul_f32_e32 v46, v0, v46
	s_addc_u32 s5, s29, s5
	v_mbcnt_lo_u32_b32 v0, -1, 0
	v_mbcnt_hi_u32_b32 v0, -1, v0
	s_add_u32 s20, s4, 0xfe00000
	v_and_b32_e32 v0, 63, v0
	s_addc_u32 s21, s5, 0
	v_lshlrev_b32_e32 v0, 2, v0
	v_mul_f32_e32 v83, v2, v95
	v_mul_f32_e32 v79, v2, v79
	v_mul_f32_e32 v63, v2, v63
	v_mul_f32_e32 v47, v2, v47
	v_lshl_add_u64 v[2:3], s[20:21], 0, v[0:1]
	s_movk_i32 s4, 0x1000
	global_store_dword v[2:3], v4, off
	global_store_dword v[2:3], v5, off offset:256
	global_store_dword v[2:3], v12, off offset:512
	global_store_dword v[2:3], v32, off offset:768
	global_store_dword v[2:3], v48, off offset:1024
	global_store_dword v[2:3], v51, off offset:1280
	global_store_dword v[2:3], v64, off offset:1536
	global_store_dword v[2:3], v66, off offset:1792
	global_store_dword v[2:3], v68, off offset:2048
	global_store_dword v[2:3], v70, off offset:2304
	global_store_dword v[2:3], v72, off offset:2560
	global_store_dword v[2:3], v74, off offset:2816
	global_store_dword v[2:3], v80, off offset:3072
	global_store_dword v[2:3], v81, off offset:3328
	global_store_dword v[2:3], v82, off offset:3584
	global_store_dword v[2:3], v83, off offset:3840
	v_add_co_u32_e32 v4, vcc, s4, v2
	s_movk_i32 s4, 0x2000
	s_nop 0
	v_addc_co_u32_e32 v5, vcc, 0, v3, vcc
	global_store_dword v[4:5], v6, off
	global_store_dword v[4:5], v9, off offset:256
	global_store_dword v[4:5], v13, off offset:512
	global_store_dword v[4:5], v33, off offset:768
	global_store_dword v[4:5], v49, off offset:1024
	global_store_dword v[4:5], v52, off offset:1280
	global_store_dword v[4:5], v65, off offset:1536
	global_store_dword v[4:5], v67, off offset:1792
	global_store_dword v[4:5], v69, off offset:2048
	global_store_dword v[4:5], v71, off offset:2304
	global_store_dword v[4:5], v73, off offset:2560
	global_store_dword v[4:5], v75, off offset:2816
	global_store_dword v[4:5], v76, off offset:3072
	global_store_dword v[4:5], v77, off offset:3328
	global_store_dword v[4:5], v78, off offset:3584
	global_store_dword v[4:5], v79, off offset:3840
	v_add_co_u32_e32 v4, vcc, s4, v2
	s_movk_i32 s4, 0x3000
	s_nop 0
	v_addc_co_u32_e32 v5, vcc, 0, v3, vcc
	v_add_co_u32_e32 v2, vcc, s4, v2
	global_store_dword v[4:5], v7, off
	global_store_dword v[4:5], v10, off offset:256
	global_store_dword v[4:5], v14, off offset:512
	global_store_dword v[4:5], v34, off offset:768
	global_store_dword v[4:5], v50, off offset:1024
	global_store_dword v[4:5], v53, off offset:1280
	global_store_dword v[4:5], v54, off offset:1536
	global_store_dword v[4:5], v55, off offset:1792
	global_store_dword v[4:5], v56, off offset:2048
	global_store_dword v[4:5], v57, off offset:2304
	global_store_dword v[4:5], v58, off offset:2560
	global_store_dword v[4:5], v59, off offset:2816
	global_store_dword v[4:5], v60, off offset:3072
	global_store_dword v[4:5], v61, off offset:3328
	global_store_dword v[4:5], v62, off offset:3584
	global_store_dword v[4:5], v63, off offset:3840
	v_addc_co_u32_e32 v3, vcc, 0, v3, vcc
	global_store_dword v[2:3], v8, off
	global_store_dword v[2:3], v11, off offset:256
	global_store_dword v[2:3], v15, off offset:512
	global_store_dword v[2:3], v35, off offset:768
	global_store_dword v[2:3], v36, off offset:1024
	global_store_dword v[2:3], v37, off offset:1280
	global_store_dword v[2:3], v38, off offset:1536
	global_store_dword v[2:3], v39, off offset:1792
	global_store_dword v[2:3], v40, off offset:2048
	global_store_dword v[2:3], v41, off offset:2304
	global_store_dword v[2:3], v42, off offset:2560
	global_store_dword v[2:3], v43, off offset:2816
	global_store_dword v[2:3], v44, off offset:3072
	global_store_dword v[2:3], v45, off offset:3328
	global_store_dword v[2:3], v46, off offset:3584
	global_store_dword v[2:3], v47, off offset:3840
	v_mbcnt_lo_u32_b32 v9, -1, 0
	v_mbcnt_hi_u32_b32 v9, -1, v9
	v_mov_b64_e32 v[2:3], s[12:13]
	v_and_b32_e32 v8, 31, v9
	v_bfe_u32 v52, v9, 5, 1
	v_or_b32_e32 v0, s80, v8
	v_mad_u64_u32 v[2:3], s[4:5], v0, s69, v[2:3]
	v_lshlrev_b32_e32 v4, 4, v52
	v_mov_b32_e32 v5, v1
	v_lshl_add_u64 v[2:3], v[2:3], 0, v[4:5]
	s_waitcnt vmcnt(0) lgkmcnt(0)
	s_barrier
	global_load_dwordx4 v[172:175], v[2:3], off offset:128
	global_load_dwordx4 v[164:167], v[2:3], off offset:160
	v_bfe_u32 v0, v9, 3, 3
	v_readlane_b32 s4, v254, 33
	global_load_dwordx4 v[168:171], v[2:3], off offset:192
	global_load_dwordx4 v[160:163], v[2:3], off offset:224
	v_or_b32_e32 v0, s4, v0
	v_lshrrev_b32_e32 v4, 1, v0
	v_xor_b32_e32 v4, v4, v9
	v_mul_lo_u32 v0, v0, s49
	v_lshlrev_b32_e32 v4, 3, v4
	v_readlane_b32 s4, v254, 34
	v_lshlrev_b32_e32 v53, 3, v9
	v_and_or_b32 v0, v4, 56, v0
	v_bfe_u32 v4, v9, 2, 3
	v_or_b32_e32 v5, s4, v52
	v_and_b32_e32 v6, 24, v53
	v_readlane_b32 s4, v254, 35
	v_lshl_or_b32 v5, v5, 5, v6
	v_lshlrev_b32_e32 v0, 1, v0
	v_or_b32_e32 v6, s4, v4
	v_readlane_b32 s4, v254, 0
	v_mul_lo_u32 v6, v6, s49
	v_lshl_add_u64 v[14:15], s[16:17], 0, v[0:1]
	v_or_b32_e32 v4, s4, v4
	s_mov_b32 m0, s81
	v_or_b32_e32 v6, v5, v6
	v_mul_lo_u32 v4, v4, s49
	v_lshl_add_u64 v[2:3], v[14:15], 0, s[42:43]
	v_lshlrev_b32_e32 v10, 1, v6
	v_or_b32_e32 v4, v5, v4
	global_load_lds_dwordx4 v[2:3], off
	s_mov_b32 m0, s63
	v_lshlrev_b32_e32 v12, 1, v4
	s_mov_b64 s[4:5], 0x88080
	global_load_lds_dwordx4 v10, s[18:19]
	s_mov_b32 m0, s26
	v_lshl_add_u64 v[32:33], v[14:15], 0, s[4:5]
	global_load_lds_dwordx4 v12, s[18:19]
	s_mov_b32 m0, s67
	v_mov_b32_e32 v11, v1
	global_load_lds_dwordx4 v[32:33], off
	s_mov_b64 s[4:5], 0x110080
	v_mov_b32_e32 v13, v1
	v_lshl_add_u64 v[6:7], s[18:19], 0, v[10:11]
	s_waitcnt vmcnt(1) lgkmcnt(0)
	s_barrier
; template <int MODE, bool FIRST, bool FOLD>
; __device__ __forceinline__ bool partialSM(f32x16& p0, f32x16& p1, float& m_reg, float& alpha, int relbase, bool near, const float* lut, float cb) {
;     ...
;     if (MODE != 0 && near) {
; #pragma unroll
;         for (int r = 0; r < 16; ++r) { const int rel = relbase + (r & 3) + 8 * (r >> 2), rel1 = rel + 32;
;             const int i0 = min(max(rel, -128), 128) + 128, i1 = min(max(rel1, -128), 128) + 128;
;             const float b0 = lut[i0], b1 = lut[i1];
;             if (MODE == 1) { p0[r] += b0; p1[r] += b1; }
;             else { p0[r] = (rel >= -128 && rel <= 128) ? p0[r] + b0 : -1e30f; p1[r] = (rel1 >= -128 && rel1 <= 128) ? p1[r] + b1 : -1e30f; } }
;     }
; template <int NQ>
; __device__ __forceinline__ void qkt(f32x16& p0, f32x16& p1, const char* Ks, const int (&kq1)[2], const int (&kq2)[2], const bf16x8* qr, const f32x16& cinit) {
;     ...
;     p0 = cinit; p1 = cinit;
;     if (HAS1) {
; #pragma unroll
;         for (int d0 = 0; d0 < 8; ++d0) { const char* a = Ks + kb1[d0];
;             const bf16x8 b0 = *reinterpret_cast<const bf16x8*>(a); const bf16x8 b1 = *reinterpret_cast<const bf16x8*>(a + 8192);
;             p0 = __builtin_amdgcn_mfma_f32_32x32x16_bf16(b0, qr[d0], p0, 0, 0, 0);
;             p1 = __builtin_amdgcn_mfma_f32_32x32x16_bf16(b1, qr[d0], p1, 0, 0, 0); } }
;     if (HAS2) {
; #pragma unroll
;         for (int d = 0; d < 4; ++d) { const char* a = Ks + SHM_K1 + kb2[d];
;             const bf16x8 b0 = *reinterpret_cast<const bf16x8*>(a); const bf16x8 b1 = *reinterpret_cast<const bf16x8*>(a + 4096);
;             p0 = __builtin_amdgcn_mfma_f32_32x32x16_bf16(b0, qr[(NQ == 12 ? 8 : 0) + d], p0, 0, 0, 0);
;             p1 = __builtin_amdgcn_mfma_f32_32x32x16_bf16(b1, qr[(NQ == 12 ? 8 : 0) + d], p1, 0, 0, 0); } }
	v_lshl_add_u64 v[14:15], v[14:15], 0, s[4:5]
	s_mov_b32 m0, s70
	v_lshl_add_u64 v[4:5], s[18:19], 0, v[12:13]
	v_lshl_add_u64 v[10:11], v[6:7], 0, s[74:75]
	global_load_lds_dwordx4 v[14:15], off
	s_mov_b32 m0, s71
	v_lshl_add_u64 v[12:13], v[4:5], 0, s[74:75]
	global_load_lds_dwordx4 v[10:11], off
	s_mov_b32 m0, s72
	v_lshrrev_b32_e32 v0, 1, v9
	global_load_lds_dwordx4 v[12:13], off
	v_bitop3_b32 v0, v52, v0, 1 bitop3:0x78
	v_lshlrev_b32_e32 v32, 7, v8
	v_lshl_or_b32 v0, v0, 4, v32
	v_and_b32_e32 v11, 0x60, v53
	v_add3_u32 v10, 0, v11, v0
	ds_read_b128 v[12:15], v10
	ds_read_b128 v[48:51], v10 offset:4096
	s_waitcnt vmcnt(0) lgkmcnt(0)
	v_mfma_f32_32x32x16_bf16 v[32:47], v[12:15], v[172:175], v[16:31]
	v_bitop3_b32 v197, v53, 32, v222 bitop3:0x6c
	v_add3_u32 v10, 0, v197, v0
	v_bitop3_b32 v196, v53, 64, v222 bitop3:0x6c
	v_bitop3_b32 v195, v53, s45, v53 bitop3:0xc
	s_andn2_b64 vcc, exec, s[14:15]
	v_mfma_f32_32x32x16_bf16 v[16:31], v[48:51], v[172:175], v[16:31]
	ds_read_b128 v[12:15], v10
	ds_read_b128 v[48:51], v10 offset:4096
	v_add3_u32 v10, 0, v196, v0
	s_waitcnt lgkmcnt(1)
	v_mfma_f32_32x32x16_bf16 v[32:47], v[12:15], v[164:167], v[32:47]
	s_waitcnt lgkmcnt(0)
	v_mfma_f32_32x32x16_bf16 v[16:31], v[48:51], v[164:167], v[16:31]
	ds_read_b128 v[12:15], v10
	ds_read_b128 v[48:51], v10 offset:4096
	v_add3_u32 v10, 0, v195, v0
	s_waitcnt lgkmcnt(1)
	v_mfma_f32_32x32x16_bf16 v[32:47], v[12:15], v[168:171], v[32:47]
	s_waitcnt lgkmcnt(0)
	v_mfma_f32_32x32x16_bf16 v[16:31], v[48:51], v[168:171], v[16:31]
	ds_read_b128 v[12:15], v10
	ds_read_b128 v[48:51], v10 offset:4096
	v_lshlrev_b32_e32 v10, 2, v52
	s_waitcnt lgkmcnt(1)
	v_mfma_f32_32x32x16_bf16 v[32:47], v[12:15], v[160:163], v[32:47]
	v_or_b32_e32 v12, s25, v8
	v_sub_u32_e32 v193, v10, v12
	s_waitcnt lgkmcnt(0)
	v_mfma_f32_32x32x16_bf16 v[16:31], v[48:51], v[160:163], v[16:31]
	s_cbranch_vccnz .LBB0_773
	v_add_u32_e32 v14, 1, v193
	v_med3_i32 v15, v14, s3, v223
	v_med3_i32 v14, v14, s96, v222
	v_lshl_add_u32 v48, v14, 2, s24
	v_add_u32_e32 v14, 2, v193
	v_med3_i32 v49, v14, s3, v223
	v_med3_i32 v14, v14, s96, v222
	v_lshl_add_u32 v50, v14, 2, s24
	v_add_u32_e32 v14, 3, v193
	v_med3_i32 v12, v193, s3, v223
	v_med3_i32 v13, v193, s96, v222
	v_med3_i32 v51, v14, s3, v223
	v_med3_i32 v14, v14, s96, v222
	v_lshl_add_u32 v12, v12, 2, s24
	v_lshl_add_u32 v13, v13, 2, s24
	v_lshl_add_u32 v15, v15, 2, s24
	v_lshl_add_u32 v49, v49, 2, s24
	v_lshl_add_u32 v51, v51, 2, s24
	v_lshl_add_u32 v52, v14, 2, s24
	ds_read_b32 v12, v12 offset:512
	ds_read_b32 v14, v13 offset:640
	ds_read_b32 v13, v15 offset:512
	ds_read_b32 v15, v48 offset:640
	ds_read_b32 v48, v49 offset:512
	ds_read_b32 v50, v50 offset:640
	ds_read_b32 v49, v51 offset:512
	ds_read_b32 v51, v52 offset:640
	v_add_u32_e32 v52, 8, v193
	v_med3_i32 v53, v52, s3, v223
	v_med3_i32 v52, v52, s96, v222
	v_lshl_add_u32 v54, v52, 2, s24
	v_add_u32_e32 v52, 9, v193
	v_med3_i32 v55, v52, s3, v223
	v_med3_i32 v52, v52, s96, v222
	v_lshl_add_u32 v56, v52, 2, s24
	v_add_u32_e32 v52, 10, v193
	v_med3_i32 v57, v52, s3, v223
	v_med3_i32 v52, v52, s96, v222
	v_lshl_add_u32 v58, v52, 2, s24
	v_add_u32_e32 v52, 11, v193
	v_med3_i32 v59, v52, s3, v223
	v_med3_i32 v52, v52, s96, v222
	v_lshl_add_u32 v53, v53, 2, s24
	v_lshl_add_u32 v55, v55, 2, s24
	v_lshl_add_u32 v57, v57, 2, s24
	v_lshl_add_u32 v59, v59, 2, s24
	v_lshl_add_u32 v60, v52, 2, s24
	ds_read_b32 v52, v53 offset:512
	ds_read_b32 v54, v54 offset:640
	ds_read_b32 v53, v55 offset:512
	ds_read_b32 v55, v56 offset:640
	ds_read_b32 v56, v57 offset:512
	ds_read_b32 v58, v58 offset:640
	ds_read_b32 v57, v59 offset:512
	ds_read_b32 v59, v60 offset:640
	v_add_u32_e32 v60, 16, v193
	v_med3_i32 v61, v60, s3, v223
	v_med3_i32 v60, v60, s96, v222
	v_lshl_add_u32 v62, v60, 2, s24
	v_add_u32_e32 v60, 17, v193
	v_med3_i32 v63, v60, s3, v223
	v_med3_i32 v60, v60, s96, v222
	v_lshl_add_u32 v64, v60, 2, s24
	v_add_u32_e32 v60, 18, v193
	v_med3_i32 v65, v60, s3, v223
	v_med3_i32 v60, v60, s96, v222
	v_lshl_add_u32 v66, v60, 2, s24
	v_add_u32_e32 v60, 19, v193
	v_med3_i32 v67, v60, s3, v223
	v_med3_i32 v60, v60, s96, v222
	v_lshl_add_u32 v61, v61, 2, s24
	v_lshl_add_u32 v63, v63, 2, s24
	v_lshl_add_u32 v65, v65, 2, s24
	v_lshl_add_u32 v67, v67, 2, s24
	v_lshl_add_u32 v68, v60, 2, s24
	ds_read_b32 v60, v61 offset:512
	ds_read_b32 v62, v62 offset:640
	ds_read_b32 v61, v63 offset:512
	ds_read_b32 v63, v64 offset:640
	ds_read_b32 v64, v65 offset:512
	ds_read_b32 v66, v66 offset:640
	ds_read_b32 v65, v67 offset:512
	ds_read_b32 v67, v68 offset:640
	v_add_u32_e32 v68, 24, v193
	v_med3_i32 v69, v68, s3, v223
	v_med3_i32 v68, v68, s96, v222
	v_lshl_add_u32 v70, v68, 2, s24
	v_add_u32_e32 v68, 25, v193
	v_med3_i32 v71, v68, s3, v223
	v_med3_i32 v68, v68, s96, v222
	v_lshl_add_u32 v76, v68, 2, s24
	v_add_u32_e32 v68, 26, v193
	v_med3_i32 v72, v68, s3, v223
	v_med3_i32 v68, v68, s96, v222
	v_lshl_add_u32 v74, v68, 2, s24
	v_add_u32_e32 v68, 27, v193
	v_med3_i32 v73, v68, s3, v223
	v_med3_i32 v68, v68, s96, v222
	v_lshl_add_u32 v69, v69, 2, s24
	v_lshl_add_u32 v71, v71, 2, s24
	v_lshl_add_u32 v72, v72, 2, s24
	v_lshl_add_u32 v73, v73, 2, s24
	v_lshl_add_u32 v75, v68, 2, s24
	ds_read_b32 v68, v69 offset:512
	ds_read_b32 v70, v70 offset:640
	ds_read_b32 v72, v72 offset:512
	ds_read_b32 v73, v73 offset:512
	ds_read_b32 v69, v71 offset:512
	ds_read_b32 v75, v75 offset:640
	ds_read_b32 v74, v74 offset:640
	ds_read_b32 v71, v76 offset:640
	s_waitcnt lgkmcnt(4)
	v_pk_add_f32 v[46:47], v[46:47], v[72:73]
	s_waitcnt lgkmcnt(3)
	v_pk_add_f32 v[44:45], v[44:45], v[68:69]
	v_pk_add_f32 v[42:43], v[42:43], v[64:65]
	v_pk_add_f32 v[40:41], v[40:41], v[60:61]
	v_pk_add_f32 v[38:39], v[38:39], v[56:57]
	v_pk_add_f32 v[36:37], v[36:37], v[52:53]
	v_pk_add_f32 v[34:35], v[34:35], v[48:49]
	v_pk_add_f32 v[32:33], v[32:33], v[12:13]
	s_waitcnt lgkmcnt(1)
	v_pk_add_f32 v[30:31], v[30:31], v[74:75]
	s_waitcnt lgkmcnt(0)
	v_pk_add_f32 v[28:29], v[28:29], v[70:71]
	v_pk_add_f32 v[26:27], v[26:27], v[66:67]
	v_pk_add_f32 v[24:25], v[24:25], v[62:63]
	v_pk_add_f32 v[22:23], v[22:23], v[58:59]
	v_pk_add_f32 v[20:21], v[20:21], v[54:55]
	v_pk_add_f32 v[18:19], v[18:19], v[50:51]
	v_pk_add_f32 v[16:17], v[16:17], v[14:15]

;     __device__ __forceinline__ void operator()(const f32x4 (&acc)[2][2][4][2], const Unit& u, int wr, int wc, int fr, int fq) const {
;         const int col0 = u.pn * BM + wc * 32 + 4 * fq;
;         f32x4 gv[2][2];
; #pragma unroll
;         for (int bj = 0; bj < 2; ++bj)
; #pragma unroll
;             for (int n = 0; n < 2; ++n) gv[bj][n] = *(const f32x4*)(gate + col0 + bj * HALF + n * 16);
; #pragma unroll
;         for (int ai = 0; ai < 2; ++ai) {
;             f32x4 bs[4][2][2];
; #pragma unroll
;             for (int m = 0; m < 4; ++m) { const size_t off = (size_t)(u.pm * BM + ai * HALF + wr * 64 + m * 16 + fr) * ldc + col0;
; #pragma unroll
;                 for (int bj = 0; bj < 2; ++bj)
; #pragma unroll
;                     for (int n = 0; n < 2; ++n) bs[m][bj][n] = *(const f32x4*)(res + off + bj * HALF + n * 16); }
;             asm volatile("" ::: "memory");
; #pragma unroll
;             for (int m = 0; m < 4; ++m) { const size_t off = (size_t)(u.pm * BM + ai * HALF + wr * 64 + m * 16 + fr) * ldc + col0;
; #pragma unroll
;                 for (int bj = 0; bj < 2; ++bj)
; #pragma unroll
;                     for (int n = 0; n < 2; ++n) *(f32x4*)(out + off + bj * HALF + n * 16) = bs[m][bj][n] + gv[bj][n] * acc[ai][bj][m][n]; }
.LBB0_924:
	v_mbcnt_lo_u32_b32 v154, -1, 0
	v_mbcnt_hi_u32_b32 v154, -1, v154
	s_lshl_b32 s15, s66, 8
	v_lshrrev_b32_e32 v130, 2, v154
	v_and_or_b32 v130, v130, 12, s15
	s_lshl_b32 s15, s65, 8
	s_add_i32 s15, s15, s41
	v_or_b32_e32 v130, s56, v130
	v_and_or_b32 v156, v154, 15, s15
	v_ashrrev_i32_e32 v131, 31, v130
	v_or_b32_e32 v176, 16, v156
	v_or_b32_e32 v192, 32, v156
	v_lshlrev_b64 v[152:153], 2, v[130:131]
	v_ashrrev_i32_e32 v157, 31, v156
	v_ashrrev_i32_e32 v177, 31, v176
	v_ashrrev_i32_e32 v193, 31, v192
	v_lshl_add_u64 v[154:155], s[8:9], 0, v[152:153]
	v_lshlrev_b64 v[204:205], 13, v[156:157]
	v_lshlrev_b64 v[206:207], 13, v[176:177]
	v_lshlrev_b64 v[216:217], 13, v[192:193]
	v_or_b32_e32 v212, 48, v156
	v_lshl_add_u64 v[130:131], s[10:11], 0, v[152:153]
	v_lshl_add_u64 v[172:173], v[154:155], 0, v[204:205]
	v_lshl_add_u64 v[188:189], v[154:155], 0, v[206:207]
	v_lshl_add_u64 v[208:209], v[154:155], 0, v[216:217]
	v_ashrrev_i32_e32 v213, 31, v212
	global_load_dwordx4 v[142:145], v[130:131], off
	global_load_dwordx4 v[138:141], v[130:131], off offset:64
	global_load_dwordx4 v[134:137], v[130:131], off offset:512
	s_nop 0
	global_load_dwordx4 v[130:133], v[130:131], off offset:576
	s_nop 0
	global_load_dwordx4 v[160:163], v[172:173], off
	global_load_dwordx4 v[164:167], v[172:173], off offset:64
	global_load_dwordx4 v[168:171], v[172:173], off offset:512
	s_nop 0
	global_load_dwordx4 v[172:175], v[172:173], off offset:576
	s_nop 0
	global_load_dwordx4 v[176:179], v[188:189], off
	global_load_dwordx4 v[180:183], v[188:189], off offset:64
	global_load_dwordx4 v[184:187], v[188:189], off offset:512
	s_nop 0
	global_load_dwordx4 v[188:191], v[188:189], off offset:576
	s_nop 0
	global_load_dwordx4 v[192:195], v[208:209], off
	global_load_dwordx4 v[196:199], v[208:209], off offset:64
	global_load_dwordx4 v[200:203], v[208:209], off offset:512
	s_nop 0
	global_load_dwordx4 v[208:211], v[208:209], off offset:576
	v_lshlrev_b64 v[238:239], 13, v[212:213]
	v_lshl_add_u64 v[234:235], v[154:155], 0, v[238:239]
	global_load_dwordx4 v[212:215], v[234:235], off
	global_load_dwordx4 v[226:229], v[234:235], off offset:64
	global_load_dwordx4 v[230:233], v[234:235], off offset:512
	s_nop 0
	global_load_dwordx4 v[234:237], v[234:235], off offset:576
	v_lshl_add_u64 v[204:205], s[58:59], 0, v[204:205]
	v_lshl_add_u64 v[204:205], v[204:205], 0, v[152:153]
	v_lshl_add_u64 v[206:207], s[58:59], 0, v[206:207]
	v_lshl_add_u64 v[216:217], s[58:59], 0, v[216:217]
	v_lshl_add_u64 v[206:207], v[206:207], 0, v[152:153]
	v_lshl_add_u64 v[216:217], v[216:217], 0, v[152:153]
	s_andn2_b64 vcc, exec, s[4:5]
	s_mov_b64 s[4:5], -1
	s_waitcnt vmcnt(0) lgkmcnt(0)
	v_pk_fma_f32 v[128:129], v[128:129], v[144:145], v[162:163]
	v_pk_fma_f32 v[126:127], v[126:127], v[142:143], v[160:161]
	v_pk_fma_f32 v[124:125], v[124:125], v[140:141], v[166:167]
	v_pk_fma_f32 v[122:123], v[122:123], v[138:139], v[164:165]
	v_pk_fma_f32 v[108:109], v[108:109], v[136:137], v[170:171]
	v_pk_fma_f32 v[78:79], v[78:79], v[130:131], v[208:209]
	v_pk_fma_f32 v[106:107], v[106:107], v[134:135], v[168:169]
	v_pk_fma_f32 v[104:105], v[104:105], v[132:133], v[174:175]
	v_pk_fma_f32 v[102:103], v[102:103], v[130:131], v[172:173]
	v_pk_fma_f32 v[120:121], v[120:121], v[144:145], v[178:179]
	v_pk_fma_f32 v[118:119], v[118:119], v[142:143], v[176:177]
	v_pk_fma_f32 v[116:117], v[116:117], v[140:141], v[182:183]
	v_pk_fma_f32 v[114:115], v[114:115], v[138:139], v[180:181]
	v_pk_fma_f32 v[96:97], v[96:97], v[136:137], v[186:187]
	v_pk_fma_f32 v[94:95], v[94:95], v[134:135], v[184:185]
	v_pk_fma_f32 v[92:93], v[92:93], v[132:133], v[190:191]
	v_pk_fma_f32 v[90:91], v[90:91], v[130:131], v[188:189]
	v_pk_fma_f32 v[112:113], v[112:113], v[144:145], v[194:195]
	v_pk_fma_f32 v[110:111], v[110:111], v[142:143], v[192:193]
	v_pk_fma_f32 v[100:101], v[100:101], v[140:141], v[198:199]
	v_pk_fma_f32 v[98:99], v[98:99], v[138:139], v[196:197]
	v_pk_fma_f32 v[88:89], v[88:89], v[136:137], v[202:203]
	v_pk_fma_f32 v[86:87], v[86:87], v[134:135], v[200:201]
	v_pk_fma_f32 v[80:81], v[80:81], v[132:133], v[210:211]
	global_store_dwordx4 v[204:205], v[126:129], off
	global_store_dwordx4 v[204:205], v[122:125], off offset:64
	global_store_dwordx4 v[204:205], v[106:109], off offset:512
	global_store_dwordx4 v[204:205], v[102:105], off offset:576
	global_store_dwordx4 v[206:207], v[118:121], off
	global_store_dwordx4 v[206:207], v[114:117], off offset:64
	global_store_dwordx4 v[206:207], v[94:97], off offset:512
	global_store_dwordx4 v[206:207], v[90:93], off offset:576
	global_store_dwordx4 v[216:217], v[110:113], off
	global_store_dwordx4 v[216:217], v[98:101], off offset:64
	global_store_dwordx4 v[216:217], v[86:89], off offset:512
	global_store_dwordx4 v[216:217], v[78:81], off offset:576
	v_pk_fma_f32 v[76:77], v[76:77], v[140:141], v[228:229]
	v_pk_fma_f32 v[74:75], v[74:75], v[138:139], v[226:227]
	v_pk_fma_f32 v[78:79], v[82:83], v[142:143], v[212:213]
	v_lshl_add_u64 v[82:83], s[58:59], 0, v[238:239]
	v_pk_fma_f32 v[80:81], v[84:85], v[144:145], v[214:215]
	v_lshl_add_u64 v[82:83], v[82:83], 0, v[152:153]
	v_pk_fma_f32 v[72:73], v[72:73], v[136:137], v[232:233]
	v_pk_fma_f32 v[70:71], v[70:71], v[134:135], v[230:231]
; __device__ __forceinline__ int tid_of(int wave_s) { int l; asm volatile("v_mbcnt_lo_u32_b32 %0, -1, 0\n\tv_mbcnt_hi_u32_b32 %0, -1, %0" : "=v"(l)); return wave_s * 64 + l; }
; #define PG8_BAR __builtin_amdgcn_s_barrier()
;     __device__ __forceinline__ void operator()(const f32x4 (&acc)[2][2][4][2], const Unit& u, int wr, int wc, int fr, int fq) const {
;     ...
;         for (int ai = 0; ai < 2; ++ai) {
;             f32x4 bs[4][2][2];
; #pragma unroll
;             for (int m = 0; m < 4; ++m) { const size_t off = (size_t)(u.pm * BM + ai * HALF + wr * 64 + m * 16 + fr) * ldc + col0;
; #pragma unroll
;                 for (int bj = 0; bj < 2; ++bj)
; #pragma unroll
;                     for (int n = 0; n < 2; ++n) bs[m][bj][n] = *(const f32x4*)(res + off + bj * HALF + n * 16); }
;             asm volatile("" ::: "memory");
; #pragma unroll
;             for (int m = 0; m < 4; ++m) { const size_t off = (size_t)(u.pm * BM + ai * HALF + wr * 64 + m * 16 + fr) * ldc + col0;
; #pragma unroll
;                 for (int bj = 0; bj < 2; ++bj)
; #pragma unroll
;                     for (int n = 0; n < 2; ++n) *(f32x4*)(out + off + bj * HALF + n * 16) = bs[m][bj][n] + gv[bj][n] * acc[ai][bj][m][n]; }
;             asm volatile("" ::: "memory");
; template <class Epi>
; __device__ __forceinline__ void gemm_phase(LAS unsigned char* lds, const Gemm g, const StaticOrder& S, const Epi& E, int wave_s) {
;     ...
;         if (wr == 0) PG8_BAR;
;         { const int l2_ = tid_of(wave_s) & 63; E(acc, cur, wr, wc, l2_ & 15, l2_ >> 4); }
;         if (!has_next) break;
; #pragma unroll
;         for (int a = 0; a < 2; ++a)
; #pragma unroll
;             for (int b = 0; b < 2; ++b)
; #pragma unroll
;                 for (int m = 0; m < 4; ++m)
; #pragma unroll
;                     for (int n = 0; n < 2; ++n) acc[a][b][m][n] = (f32x4){0.f, 0.f, 0.f, 0.f};
;         cur = nxt; cA = nA; cB = nB; ++ui;
;         if (wr == 1) PG8_BAR;
	v_pk_fma_f32 v[68:69], v[68:69], v[132:133], v[236:237]
	v_pk_fma_f32 v[66:67], v[66:67], v[130:131], v[234:235]
	global_store_dwordx4 v[82:83], v[78:81], off
	global_store_dwordx4 v[82:83], v[74:77], off offset:64
	global_store_dwordx4 v[82:83], v[70:73], off offset:512
	global_store_dwordx4 v[82:83], v[66:69], off offset:576
	v_add_u32_e32 v82, 0x90, v156
	v_add_u32_e32 v98, 0xa0, v156
	v_add_u32_e32 v66, 0x80, v156
	v_ashrrev_i32_e32 v67, 31, v66
	v_ashrrev_i32_e32 v83, 31, v82
	v_ashrrev_i32_e32 v99, 31, v98
	v_lshlrev_b64 v[160:161], 13, v[66:67]
	v_lshlrev_b64 v[162:163], 13, v[82:83]
	v_lshlrev_b64 v[164:165], 13, v[98:99]
	v_add_u32_e32 v114, 0xb0, v156
	v_lshl_add_u64 v[78:79], v[154:155], 0, v[160:161]
	v_lshl_add_u64 v[94:95], v[154:155], 0, v[162:163]
	v_lshl_add_u64 v[110:111], v[154:155], 0, v[164:165]
	v_ashrrev_i32_e32 v115, 31, v114
	global_load_dwordx4 v[66:69], v[78:79], off
	global_load_dwordx4 v[70:73], v[78:79], off offset:64
	global_load_dwordx4 v[74:77], v[78:79], off offset:512
	s_nop 0
	global_load_dwordx4 v[78:81], v[78:79], off offset:576
	s_nop 0
	global_load_dwordx4 v[82:85], v[94:95], off
	global_load_dwordx4 v[86:89], v[94:95], off offset:64
	global_load_dwordx4 v[90:93], v[94:95], off offset:512
	s_nop 0
	global_load_dwordx4 v[94:97], v[94:95], off offset:576
	s_nop 0
	global_load_dwordx4 v[98:101], v[110:111], off
	global_load_dwordx4 v[102:105], v[110:111], off offset:64
	global_load_dwordx4 v[106:109], v[110:111], off offset:512
	s_nop 0
	global_load_dwordx4 v[110:113], v[110:111], off offset:576
	v_lshlrev_b64 v[156:157], 13, v[114:115]
	v_lshl_add_u64 v[126:127], v[154:155], 0, v[156:157]
	global_load_dwordx4 v[114:117], v[126:127], off
	global_load_dwordx4 v[118:121], v[126:127], off offset:64
	global_load_dwordx4 v[122:125], v[126:127], off offset:512
	s_nop 0
	global_load_dwordx4 v[126:129], v[126:127], off offset:576
	v_lshl_add_u64 v[154:155], s[58:59], 0, v[160:161]
	v_lshl_add_u64 v[160:161], s[58:59], 0, v[162:163]
	v_lshl_add_u64 v[162:163], s[58:59], 0, v[164:165]
	v_lshl_add_u64 v[154:155], v[154:155], 0, v[152:153]
	v_lshl_add_u64 v[162:163], v[162:163], 0, v[152:153]
	v_lshl_add_u64 v[160:161], v[160:161], 0, v[152:153]
	s_waitcnt vmcnt(15)
	v_pk_fma_f32 v[64:65], v[64:65], v[144:145], v[68:69]
	v_pk_fma_f32 v[62:63], v[62:63], v[142:143], v[66:67]
	s_waitcnt vmcnt(14)
	v_pk_fma_f32 v[60:61], v[60:61], v[140:141], v[72:73]
	v_pk_fma_f32 v[58:59], v[58:59], v[138:139], v[70:71]
	s_waitcnt vmcnt(5)
	v_pk_fma_f32 v[20:21], v[20:21], v[136:137], v[108:109]
	v_pk_fma_f32 v[18:19], v[18:19], v[134:135], v[106:107]
	v_pk_fma_f32 v[44:45], v[44:45], v[136:137], v[76:77]
	v_pk_fma_f32 v[42:43], v[42:43], v[134:135], v[74:75]
	v_pk_fma_f32 v[40:41], v[40:41], v[132:133], v[80:81]
	v_pk_fma_f32 v[38:39], v[38:39], v[130:131], v[78:79]
	v_pk_fma_f32 v[56:57], v[56:57], v[144:145], v[84:85]
	v_pk_fma_f32 v[54:55], v[54:55], v[142:143], v[82:83]
	v_pk_fma_f32 v[52:53], v[52:53], v[140:141], v[88:89]
	v_pk_fma_f32 v[50:51], v[50:51], v[138:139], v[86:87]
	v_pk_fma_f32 v[32:33], v[32:33], v[136:137], v[92:93]
	v_pk_fma_f32 v[30:31], v[30:31], v[134:135], v[90:91]
	v_pk_fma_f32 v[28:29], v[28:29], v[132:133], v[96:97]
	v_pk_fma_f32 v[26:27], v[26:27], v[130:131], v[94:95]
	v_pk_fma_f32 v[48:49], v[48:49], v[144:145], v[100:101]
	v_pk_fma_f32 v[46:47], v[46:47], v[142:143], v[98:99]
	v_pk_fma_f32 v[36:37], v[36:37], v[140:141], v[104:105]
	v_pk_fma_f32 v[34:35], v[34:35], v[138:139], v[102:103]
	global_store_dwordx4 v[154:155], v[62:65], off
	global_store_dwordx4 v[154:155], v[58:61], off offset:64
	global_store_dwordx4 v[154:155], v[42:45], off offset:512
	global_store_dwordx4 v[154:155], v[38:41], off offset:576
	global_store_dwordx4 v[160:161], v[54:57], off
	global_store_dwordx4 v[160:161], v[50:53], off offset:64
	global_store_dwordx4 v[160:161], v[30:33], off offset:512
	global_store_dwordx4 v[160:161], v[26:29], off offset:576
	global_store_dwordx4 v[162:163], v[46:49], off
	global_store_dwordx4 v[162:163], v[34:37], off offset:64
	global_store_dwordx4 v[162:163], v[18:21], off offset:512
	s_waitcnt vmcnt(15)
	v_pk_fma_f32 v[12:13], v[12:13], v[132:133], v[112:113]
	v_pk_fma_f32 v[10:11], v[10:11], v[130:131], v[110:111]
	v_lshl_add_u64 v[18:19], s[58:59], 0, v[156:157]
	global_store_dwordx4 v[162:163], v[10:13], off offset:576
	v_lshl_add_u64 v[18:19], v[18:19], 0, v[152:153]
	s_waitcnt vmcnt(13)
	v_pk_fma_f32 v[8:9], v[8:9], v[136:137], v[124:125]
	v_pk_fma_f32 v[12:13], v[24:25], v[144:145], v[116:117]
	v_pk_fma_f32 v[10:11], v[22:23], v[142:143], v[114:115]
	global_store_dwordx4 v[18:19], v[10:13], off
	v_pk_fma_f32 v[6:7], v[6:7], v[134:135], v[122:123]
	s_waitcnt vmcnt(13)
	v_pk_fma_f32 v[4:5], v[4:5], v[132:133], v[128:129]
	v_pk_fma_f32 v[12:13], v[16:17], v[140:141], v[120:121]
	v_pk_fma_f32 v[10:11], v[14:15], v[138:139], v[118:119]
	v_pk_fma_f32 v[2:3], v[2:3], v[130:131], v[126:127]
	global_store_dwordx4 v[18:19], v[10:13], off offset:64
	global_store_dwordx4 v[18:19], v[6:9], off offset:512
	global_store_dwordx4 v[18:19], v[2:5], off offset:576
	s_cbranch_vccnz .LBB0_913
	s_andn2_b64 vcc, exec, s[6:7]
	s_cbranch_vccnz .LBB0_912
	s_barrier
	s_branch .LBB0_912

; __device__ __forceinline__ unsigned xb_ld(unsigned* p)              { return __hip_atomic_load(p, __ATOMIC_RELAXED, __HIP_MEMORY_SCOPE_AGENT); }
; __device__ __forceinline__ void xcd_barrier_complete(unsigned* bar, unsigned x, unsigned& nloc, unsigned& nx) {
;     const unsigned G = gridDim.x * gridDim.y * gridDim.z;
;     unsigned sum, cnt, mine, sp = 0u;
;     for (;;) {
;         sum = 0u; cnt = 0u; mine = 0u;
; #pragma unroll
;         for (unsigned j = 0; j < 16; ++j) { const unsigned c = xb_ld(&bar[XB_XCNT(j)]); sum += c; cnt += (c > 0u) ? 1u : 0u; mine = (j == x) ? c : mine; }
;         if (sum == G) break;
;         __builtin_amdgcn_s_sleep(1);
;         if ((++sp & 255u) == 0u) { if (xb_ld(&bar[XB_TMO])) break; if (sp > XB_SPIN_CAP) { atomicAdd(&bar[XB_TMO], 1u); break; } }
;     }
.LBB0_933:
	v_mov_b64_e32 v[2:3], s[6:7]
	s_waitcnt lgkmcnt(0)
	global_load_dword v0, v[2:3], off sc1
	v_mov_b64_e32 v[2:3], s[8:9]
	global_load_dword v2, v[2:3], off sc1
	v_mov_b64_e32 v[4:5], s[10:11]
	global_load_dword v3, v[4:5], off sc1
	v_mov_b64_e32 v[4:5], s[12:13]
	global_load_dword v4, v[4:5], off sc1
	v_readlane_b32 s40, v254, 8
	s_or_b64 s[88:89], s[88:89], exec
	s_or_b64 s[86:87], s[86:87], exec
	s_waitcnt vmcnt(0) lgkmcnt(0)
	v_add_u32_e32 v6, v2, v0
	v_add_u32_e32 v6, v6, v3
	v_add_u32_e32 v8, v6, v4
	v_mov_b64_e32 v[6:7], s[14:15]
	global_load_dword v5, v[6:7], off sc1
	v_mov_b64_e32 v[6:7], s[16:17]
	global_load_dword v6, v[6:7], off sc1
	s_waitcnt vmcnt(0) lgkmcnt(0)
	v_add_u32_e32 v8, v8, v5
	v_add_u32_e32 v10, v8, v6
	v_mov_b64_e32 v[8:9], s[18:19]
	global_load_dword v7, v[8:9], off sc1
	v_mov_b64_e32 v[8:9], s[20:21]
	global_load_dword v8, v[8:9], off sc1
	s_waitcnt vmcnt(0) lgkmcnt(0)
	v_add_u32_e32 v10, v10, v7
	v_add_u32_e32 v12, v10, v8
	v_mov_b64_e32 v[10:11], s[22:23]
	global_load_dword v9, v[10:11], off sc1
	v_mov_b64_e32 v[10:11], s[24:25]
	global_load_dword v10, v[10:11], off sc1
	s_waitcnt vmcnt(0) lgkmcnt(0)
	v_add_u32_e32 v12, v12, v9
	v_add_u32_e32 v14, v12, v10
	v_mov_b64_e32 v[12:13], s[26:27]
	global_load_dword v11, v[12:13], off sc1
	v_mov_b64_e32 v[12:13], s[28:29]
	global_load_dword v12, v[12:13], off sc1
	s_waitcnt vmcnt(0) lgkmcnt(0)
	v_add_u32_e32 v14, v14, v11
	v_add_u32_e32 v16, v14, v12
	v_mov_b64_e32 v[14:15], s[30:31]
	global_load_dword v13, v[14:15], off sc1
	v_mov_b64_e32 v[14:15], s[34:35]
	global_load_dword v14, v[14:15], off sc1
	s_waitcnt vmcnt(0) lgkmcnt(0)
	v_add_u32_e32 v16, v16, v13
	v_add_u32_e32 v18, v16, v14
	v_mov_b64_e32 v[16:17], s[78:79]
	global_load_dword v15, v[16:17], off sc1
	v_mov_b64_e32 v[16:17], s[92:93]
	global_load_dword v16, v[16:17], off sc1
	s_waitcnt vmcnt(0) lgkmcnt(0)
	v_add_u32_e32 v18, v18, v15
	v_add_u32_e32 v17, v18, v16
	v_cmp_ne_u32_e32 vcc, s40, v17
	s_and_saveexec_b64 s[90:91], vcc
	s_cbranch_execz .LBB0_932
	s_and_b32 s40, s85, 0xff
	s_mov_b64 s[64:65], -1
	s_cmp_eq_u32 s40, 0
	s_mov_b64 s[72:73], -1
	s_mov_b64 s[40:41], -1
	s_sleep 1
	s_cbranch_scc1 .LBB0_936
	s_and_saveexec_b64 s[70:71], s[72:73]
	s_cbranch_execz .LBB0_931
	s_branch .LBB0_939
.LBB0_936:
	v_mov_b64_e32 v[18:19], s[4:5]
	global_load_dword v17, v[18:19], off sc1
	s_mov_b64 s[72:73], 0
	s_waitcnt vmcnt(0) lgkmcnt(0)
	v_cmp_eq_u32_e32 vcc, 0, v17
	s_and_saveexec_b64 s[70:71], vcc
	s_cmp_lt_u32 s85, 0x400001
	s_cselect_b64 s[72:73], -1, 0
	s_xor_b64 s[40:41], exec, -1
	s_and_b64 s[72:73], s[72:73], exec
	s_or_b64 exec, exec, s[70:71]
	s_and_saveexec_b64 s[70:71], s[72:73]
	s_cbranch_execz .LBB0_931

; __device__ __forceinline__ unsigned xb_ld(unsigned* p)              { return __hip_atomic_load(p, __ATOMIC_RELAXED, __HIP_MEMORY_SCOPE_AGENT); }
; __device__ __forceinline__ unsigned xb_add(unsigned* p, unsigned v) { return __hip_atomic_fetch_add(p, v, __ATOMIC_RELAXED, __HIP_MEMORY_SCOPE_AGENT); }
; #define XB_SPIN(cond, bar) do { unsigned _sp = 0; while (cond) {     \
;     if ((++_sp & 255u) == 0u) { if (xb_ld(&(bar)[XB_TMO])) break; if (_sp > XB_SPIN_CAP) { atomicAdd(&(bar)[XB_TMO], 1u); break; } } } } while (0)
; __device__ __forceinline__ void xcd_barrier(const XcdBarrier& b, int wave_s) {
;     ...
;         const unsigned old = xb_add(&bar[XB_XSUB(b.x)], 1u);
;         const unsigned gen = old / nloc;
;         if (old + 1u == (gen + 1u) * nloc) {
;             __builtin_amdgcn_fence(__ATOMIC_RELEASE, "agent");
;             asm volatile("s_waitcnt vmcnt(0)" ::: "memory");
;             const unsigned og = xb_add(&bar[XB_TOP], 1u);
;             const unsigned tg = og / nx;
;             if (og + 1u == (tg + 1u) * nx) xb_add(&bar[XB_TOPGEN], 1u);
;             else XB_SPIN(xb_ld(&bar[XB_TOPGEN]) == tg, bar);
;             __builtin_amdgcn_fence(__ATOMIC_ACQUIRE, "agent");
;             xb_add(&bar[XB_XGEN(b.x)], 1u);
;             asm volatile("s_waitcnt vmcnt(0)" ::: "memory");
;         } else {
;             XB_SPIN(xb_ld(&bar[XB_XGEN(b.x)]) == gen, bar);
.LBB0_943:
	s_lshl_b32 s4, s37, 8
	s_add_u32 s4, s56, s4
	s_addc_u32 s5, s57, 0
	v_mov_b32_e32 v3, s4
	v_add_co_u32_e32 v4, vcc, 0x11000, v3
	v_mov_b32_e32 v3, s5
	s_nop 0
	v_addc_co_u32_e32 v5, vcc, 0, v3, vcc
	flat_atomic_add v4, v[4:5], v220 offset:1024 sc0
	v_cvt_f32_u32_e32 v3, v2
	v_sub_u32_e32 v5, 0, v2
	s_add_u32 s27, s4, 0x10000
	s_addc_u32 s26, s5, 0
	v_rcp_iflag_f32_e32 v3, v3
	s_nop 0
	v_mul_f32_e32 v3, 0x4f7ffffe, v3
	v_cvt_u32_f32_e32 v3, v3
	v_mul_lo_u32 v5, v5, v3
	v_mul_hi_u32 v5, v3, v5
	v_add_u32_e32 v3, v3, v5
	s_waitcnt vmcnt(0) lgkmcnt(0)
	v_mul_hi_u32 v3, v4, v3
	v_mul_lo_u32 v5, v3, v2
	v_sub_u32_e32 v5, v4, v5
	v_cmp_ge_u32_e32 vcc, v5, v2
	v_add_u32_e32 v6, 1, v3
	s_nop 0
	v_cndmask_b32_e32 v3, v3, v6, vcc
	v_sub_u32_e32 v6, v5, v2
	v_cndmask_b32_e32 v5, v5, v6, vcc
	v_cmp_ge_u32_e32 vcc, v5, v2
	v_add_u32_e32 v5, 1, v3
	v_add_u32_e32 v6, 1, v4
	v_cndmask_b32_e32 v3, v3, v5, vcc
	v_mad_u64_u32 v[4:5], s[4:5], v2, v3, v[2:3]
	v_cmp_ne_u32_e32 vcc, v6, v4
	s_and_saveexec_b64 s[4:5], vcc
	s_xor_b64 s[4:5], exec, s[4:5]
	s_cbranch_execz .LBB0_956
	v_mov_b32_e32 v0, s27
	v_add_co_u32_e32 v4, vcc, 0x2000, v0
	v_mov_b32_e32 v0, s26
	s_nop 0
	v_addc_co_u32_e32 v5, vcc, 0, v0, vcc
	global_load_dword v0, v[4:5], off offset:1024 sc1
	s_add_u32 s8, s27, 0x2400
	s_addc_u32 s9, s26, 0
	s_waitcnt vmcnt(0) lgkmcnt(0)
	v_cmp_eq_u32_e32 vcc, v0, v3
	s_and_saveexec_b64 s[6:7], vcc
	s_cbranch_execz .LBB0_955
	s_add_u32 s10, s56, 0x10200
	s_addc_u32 s11, s57, 0
	s_mov_b32 s28, 1
	s_mov_b64 s[12:13], 0
	s_branch .LBB0_947

; __device__ __forceinline__ unsigned xb_ld(unsigned* p)              { return __hip_atomic_load(p, __ATOMIC_RELAXED, __HIP_MEMORY_SCOPE_AGENT); }
; #define XB_SPIN(cond, bar) do { unsigned _sp = 0; while (cond) {     \
;     if ((++_sp & 255u) == 0u) { if (xb_ld(&(bar)[XB_TMO])) break; if (_sp > XB_SPIN_CAP) { atomicAdd(&(bar)[XB_TMO], 1u); break; } } } } while (0)
; __device__ __forceinline__ void xcd_barrier(const XcdBarrier& b, int wave_s) {
;     ...
;             XB_SPIN(xb_ld(&bar[XB_XGEN(b.x)]) == gen, bar);
.LBB0_947:
	s_and_b32 s20, s28, 0xff
	s_mov_b64 s[18:19], -1
	s_cmp_lg_u32 s20, 0
	s_mov_b64 s[20:21], -1
	s_cbranch_scc1 .LBB0_951
	v_mov_b64_e32 v[4:5], s[10:11]
	global_load_dword v0, v[4:5], off sc1
	s_mov_b64 s[20:21], 0
	s_mov_b64 s[22:23], -1
	s_waitcnt vmcnt(0) lgkmcnt(0)
	v_cmp_eq_u32_e32 vcc, 0, v0
	s_and_saveexec_b64 s[24:25], vcc
	s_cmp_lt_u32 s28, 0x400001
	s_cselect_b64 s[20:21], -1, 0
	s_xor_b64 s[22:23], exec, -1
	s_and_b64 s[20:21], s[20:21], exec
	s_or_b64 exec, exec, s[24:25]
.LBB0_951:
	s_andn2_b64 s[16:17], s[16:17], exec
	s_and_b64 s[22:23], s[22:23], exec
	s_or_b64 s[16:17], s[16:17], s[22:23]
	s_and_saveexec_b64 s[22:23], s[20:21]
	s_cbranch_execz .LBB0_946
	v_mov_b64_e32 v[4:5], s[8:9]
	global_load_dword v0, v[4:5], off sc1
	s_add_i32 s28, s28, 1
	s_or_b64 s[16:17], s[16:17], exec
	s_waitcnt vmcnt(0) lgkmcnt(0)
	v_cmp_ne_u32_e32 vcc, v0, v3
	s_orn2_b64 s[18:19], vcc, exec
	s_branch .LBB0_946

; __device__ __forceinline__ unsigned xb_ld(unsigned* p)              { return __hip_atomic_load(p, __ATOMIC_RELAXED, __HIP_MEMORY_SCOPE_AGENT); }
; __device__ __forceinline__ unsigned xb_add(unsigned* p, unsigned v) { return __hip_atomic_fetch_add(p, v, __ATOMIC_RELAXED, __HIP_MEMORY_SCOPE_AGENT); }
; #define XB_SPIN(cond, bar) do { unsigned _sp = 0; while (cond) {     \
;     if ((++_sp & 255u) == 0u) { if (xb_ld(&(bar)[XB_TMO])) break; if (_sp > XB_SPIN_CAP) { atomicAdd(&(bar)[XB_TMO], 1u); break; } } } } while (0)
; __device__ __forceinline__ void xcd_barrier(const XcdBarrier& b, int wave_s) {
;     ...
;         if (old + 1u == (gen + 1u) * nloc) {
;             __builtin_amdgcn_fence(__ATOMIC_RELEASE, "agent");
;             asm volatile("s_waitcnt vmcnt(0)" ::: "memory");
;             const unsigned og = xb_add(&bar[XB_TOP], 1u);
;             const unsigned tg = og / nx;
;             if (og + 1u == (tg + 1u) * nx) xb_add(&bar[XB_TOPGEN], 1u);
;             else XB_SPIN(xb_ld(&bar[XB_TOPGEN]) == tg, bar);
.LBB0_956:
	s_andn2_saveexec_b64 s[4:5], s[4:5]
	s_cbranch_execz .LBB0_972
	v_mov_b32_e32 v2, s56
	v_add_co_u32_e32 v2, vcc, 0x13000, v2
	v_mov_b32_e32 v3, s57
	buffer_wbl2 sc1
	s_waitcnt vmcnt(0)
	v_addc_co_u32_e32 v3, vcc, 0, v3, vcc
	flat_atomic_add v2, v[2:3], v220 offset:1024 sc0
	v_cvt_f32_u32_e32 v3, v0
	v_sub_u32_e32 v4, 0, v0
	s_mov_b64 s[8:9], -1
	v_rcp_iflag_f32_e32 v3, v3
	s_nop 0
	v_mul_f32_e32 v3, 0x4f7ffffe, v3
	v_cvt_u32_f32_e32 v3, v3
	v_mul_lo_u32 v4, v4, v3
	v_mul_hi_u32 v4, v3, v4
	v_add_u32_e32 v3, v3, v4
	s_waitcnt vmcnt(0) lgkmcnt(0)
	v_mul_hi_u32 v3, v2, v3
	v_mul_lo_u32 v4, v3, v0
	v_sub_u32_e32 v4, v2, v4
	v_cmp_ge_u32_e32 vcc, v4, v0
	v_add_u32_e32 v5, 1, v3
	s_nop 0
	v_cndmask_b32_e32 v3, v3, v5, vcc
	v_sub_u32_e32 v5, v4, v0
	v_cndmask_b32_e32 v4, v4, v5, vcc
	v_cmp_ge_u32_e32 vcc, v4, v0
	v_add_u32_e32 v4, 1, v3
	v_add_u32_e32 v5, 1, v2
	v_cndmask_b32_e32 v4, v3, v4, vcc
	v_mad_u64_u32 v[2:3], s[4:5], v0, v4, v[0:1]
	s_add_u32 s4, s56, 0x13500
	s_addc_u32 s5, s57, 0
	v_cmp_ne_u32_e32 vcc, v5, v2
	v_mov_b64_e32 v[2:3], s[4:5]
	s_and_saveexec_b64 s[6:7], vcc
	s_cbranch_execz .LBB0_969
	v_mov_b64_e32 v[2:3], s[4:5]
	global_load_dword v0, v[2:3], off sc1
	s_mov_b64 s[12:13], 0
	s_waitcnt vmcnt(0) lgkmcnt(0)
	v_cmp_eq_u32_e32 vcc, v0, v4
	s_and_saveexec_b64 s[10:11], vcc
	s_cbranch_execz .LBB0_968
	s_add_u32 s8, s56, 0x10200
	s_addc_u32 s9, s57, 0
	s_mov_b32 s24, 1
	s_branch .LBB0_961

; __device__ __forceinline__ unsigned xb_ld(unsigned* p)              { return __hip_atomic_load(p, __ATOMIC_RELAXED, __HIP_MEMORY_SCOPE_AGENT); }
; __device__ __forceinline__ unsigned xb_add(unsigned* p, unsigned v) { return __hip_atomic_fetch_add(p, v, __ATOMIC_RELAXED, __HIP_MEMORY_SCOPE_AGENT); }
; #define XB_SPIN(cond, bar) do { unsigned _sp = 0; while (cond) {     \
;     if ((++_sp & 255u) == 0u) { if (xb_ld(&(bar)[XB_TMO])) break; if (_sp > XB_SPIN_CAP) { atomicAdd(&(bar)[XB_TMO], 1u); break; } } } } while (0)
; __device__ __forceinline__ void xcd_barrier(const XcdBarrier& b, int wave_s) {
;     ...
;             if (og + 1u == (tg + 1u) * nx) xb_add(&bar[XB_TOPGEN], 1u);
;             else XB_SPIN(xb_ld(&bar[XB_TOPGEN]) == tg, bar);
.LBB0_963:
	v_mov_b64_e32 v[2:3], s[8:9]
	global_load_dword v0, v[2:3], off sc1
	s_mov_b64 s[20:21], 0
	s_mov_b64 s[18:19], -1
	s_waitcnt vmcnt(0) lgkmcnt(0)
	v_cmp_eq_u32_e32 vcc, 0, v0
	s_and_saveexec_b64 s[22:23], vcc
	s_cmp_lt_u32 s24, 0x400001
	s_cselect_b64 s[20:21], -1, 0
	s_xor_b64 s[18:19], exec, -1
	s_and_b64 s[20:21], s[20:21], exec
	s_or_b64 exec, exec, s[22:23]
	s_and_saveexec_b64 s[22:23], s[20:21]
	s_cbranch_execz .LBB0_960
.LBB0_966:
	v_mov_b64_e32 v[2:3], s[4:5]
	global_load_dword v0, v[2:3], off sc1
	s_add_i32 s24, s24, 1
	s_or_b64 s[18:19], s[18:19], exec
	s_waitcnt vmcnt(0) lgkmcnt(0)
	v_cmp_ne_u32_e32 vcc, v0, v4
	s_orn2_b64 s[16:17], vcc, exec
	s_branch .LBB0_960

; #define PH unsigned char* ws = a.ws; asm volatile("" : "+s"(ws)); int lq = l; asm volatile("" : "+s"(lq)); (void)lq;
; template <bool FINAL>
; __device__ __forceinline__ void norm_pass(const float* X, const float* g, const float* scale, const float* shift, bf16_t* H, float* OUTF, int vcu_, int NGW_, int wave_s) {
;     ...
;     f32x4 gm[8], sh[8];
; #pragma unroll
;     for (int j = 0; j < 8; ++j) { const f32x4 gv = ((const f32x4*)g)[64 * j + lane];
;         if (!FINAL) { const f32x4 s = ((const f32x4*)scale)[64 * j + lane]; gm[j] = gv * (1.f + s); sh[j] = ((const f32x4*)shift)[64 * j + lane]; } else { gm[j] = gv; sh[j] = (f32x4){0.f, 0.f, 0.f, 0.f}; } }
;     f32x4 nv[8];
;     { const f32x4* xr = (const f32x4*)(X + (size_t)gw * DM) + lane;
; #pragma unroll
;         for (int j = 0; j < 8; ++j) nv[j] = xr[64 * j]; }
;     for (int m = gw; m < SEQ; m += NGW) {
;         f32x4 v[8]; float ss = 0.f;
; #pragma unroll
;         for (int j = 0; j < 8; ++j) v[j] = nv[j];
;         if (m + NGW < SEQ) { const f32x4* xn = (const f32x4*)(X + (size_t)(m + NGW) * DM) + lane;
; #pragma unroll
;             for (int j = 0; j < 8; ++j) nv[j] = xn[64 * j]; }
; __global__ void __launch_bounds__(NTHR, 2) mega_fwd(Args a) {
;     ...
;         { PH const float* mod = MOD + lq * 12288; norm_pass<false>(a.out, SMV + SM_N2 + lq * DM, mod + 4 * DM, mod + 3 * DM, H, nullptr, vcu, NGW, wave_s); }
.LBB0_972:
	s_or_b64 exec, exec, s[38:39]
	s_mov_b64 s[4:5], s[60:61]
	s_mov_b32 s7, s84
	v_readlane_b32 s8, v255, 31
	s_mov_b32 s6, s92
	s_waitcnt lgkmcnt(0)
	s_barrier
	s_lshl_b32 s16, s8, 3
	s_add_i32 s8, s16, s86
	s_cmpk_gt_i32 s8, 0x3fff
	v_mbcnt_lo_u32_b32 v0, -1, 0
	v_mbcnt_hi_u32_b32 v0, -1, v0
	s_cbranch_scc1 .LBB0_977
	s_mul_i32 s10, s7, 0x3000
	s_ashr_i32 s11, s10, 31
	s_lshl_b64 s[10:11], s[10:11], 2
	s_add_u32 s9, s4, s10
	s_addc_u32 s17, s5, s11
	s_lshl_b32 s10, s7, 11
	s_ashr_i32 s11, s10, 31
	s_lshl_b64 s[10:11], s[10:11], 2
	s_add_u32 s7, s4, s10
	s_addc_u32 s10, s5, s11
	s_add_u32 s12, s7, 0x24000
	s_addc_u32 s13, s10, 0
	s_add_u32 s14, s9, 0x108000
	s_addc_u32 s15, s17, 0
	v_and_b32_e32 v148, 63, v0
	s_add_u32 s10, s9, 0x106000
	v_lshlrev_b32_e32 v0, 4, v148
	s_addc_u32 s11, s17, 0
	v_or_b32_e32 v14, 0x400, v0
	v_mov_b32_e32 v15, v1
	v_lshl_add_u64 v[2:3], s[14:15], 0, v[0:1]
	v_lshl_add_u64 v[4:5], s[10:11], 0, v[0:1]
	v_lshl_add_u64 v[8:9], s[14:15], 0, v[14:15]
	v_or_b32_e32 v18, 0x800, v0
	v_mov_b32_e32 v19, v1
	v_lshl_add_u64 v[6:7], s[12:13], 0, v[0:1]
	global_load_dwordx4 v[42:45], v[2:3], off
	s_nop 0
	global_load_dwordx4 v[2:5], v[4:5], off
	s_nop 0
	global_load_dwordx4 v[46:49], v[6:7], off
	global_load_dwordx4 v[50:53], v[6:7], off offset:1024
	global_load_dwordx4 v[54:57], v[8:9], off
	v_lshl_add_u64 v[8:9], s[14:15], 0, v[18:19]
	v_or_b32_e32 v22, 0xc00, v0
	v_mov_b32_e32 v23, v1
	global_load_dwordx4 v[58:61], v[8:9], off
	global_load_dwordx4 v[62:65], v[6:7], off offset:2048
	global_load_dwordx4 v[66:69], v[6:7], off offset:3072
	v_lshl_add_u64 v[6:7], s[14:15], 0, v[22:23]
	global_load_dwordx4 v[70:73], v[6:7], off
	v_or_b32_e32 v6, 0x1000, v0
	v_mov_b32_e32 v7, v1
	v_lshl_add_u64 v[8:9], s[12:13], 0, v[6:7]
	v_lshl_add_u64 v[10:11], s[14:15], 0, v[6:7]
	v_or_b32_e32 v26, 0x1400, v0
	v_mov_b32_e32 v27, v1
	global_load_dwordx4 v[116:119], v[8:9], off
	global_load_dwordx4 v[120:123], v[10:11], off
	v_lshl_add_u64 v[6:7], s[10:11], 0, v[6:7]
	v_lshl_add_u64 v[10:11], s[12:13], 0, v[26:27]
	global_load_dwordx4 v[6:9], v[6:7], off
	s_nop 0
	global_load_dwordx4 v[124:127], v[10:11], off
	v_lshl_add_u64 v[10:11], s[14:15], 0, v[26:27]
	global_load_dwordx4 v[128:131], v[10:11], off
	v_or_b32_e32 v10, 0x1800, v0
	v_mov_b32_e32 v11, v1
	v_lshl_add_u64 v[12:13], s[12:13], 0, v[10:11]
	v_lshl_add_u64 v[16:17], s[14:15], 0, v[10:11]
	global_load_dwordx4 v[132:135], v[12:13], off
	global_load_dwordx4 v[136:139], v[16:17], off
	v_or_b32_e32 v30, 0x1c00, v0
	v_mov_b32_e32 v31, v1
	v_lshl_add_u64 v[10:11], s[10:11], 0, v[10:11]
	v_lshl_add_u64 v[12:13], s[14:15], 0, v[30:31]
	v_lshl_add_u64 v[16:17], s[12:13], 0, v[30:31]
	global_load_dwordx4 v[140:143], v[12:13], off
	s_nop 0
	global_load_dwordx4 v[10:13], v[10:11], off
	s_nop 0
	global_load_dwordx4 v[144:147], v[16:17], off
	s_ashr_i32 s9, s8, 31
	v_lshl_add_u64 v[14:15], s[10:11], 0, v[14:15]
	v_lshl_add_u64 v[18:19], s[10:11], 0, v[18:19]
	v_lshl_add_u64 v[22:23], s[10:11], 0, v[22:23]
	v_lshl_add_u64 v[26:27], s[10:11], 0, v[26:27]
	v_lshl_add_u64 v[30:31], s[10:11], 0, v[30:31]
	s_lshl_b64 s[10:11], s[8:9], 13
	s_add_u32 s10, s58, s10
	s_addc_u32 s11, s59, s11
	v_lshl_add_u64 v[32:33], s[10:11], 0, v[0:1]
	s_movk_i32 s7, 0x1000
	v_add_co_u32_e32 v32, vcc, s7, v32
	global_load_dwordx4 v[14:17], v[14:15], off
	s_nop 0
	v_addc_co_u32_e32 v33, vcc, 0, v33, vcc
	global_load_dwordx4 v[18:21], v[18:19], off
	s_waitcnt vmcnt(0) lgkmcnt(0)
	v_pk_add_f32 v[42:43], v[42:43], 1.0 op_sel_hi:[1,0]
	global_load_dwordx4 v[22:25], v[22:23], off
	v_pk_mul_f32 v[100:101], v[46:47], v[42:43]
	global_load_dwordx4 v[26:29], v[26:27], off
	s_nop 0
	global_load_dwordx4 v[34:37], v[32:33], off offset:3072
	global_load_dwordx4 v[38:41], v[32:33], off offset:2048
	global_load_dwordx4 v[74:77], v[32:33], off offset:1024
	global_load_dwordx4 v[78:81], v[32:33], off
	global_load_dwordx4 v[82:85], v0, s[10:11] offset:3072
	global_load_dwordx4 v[86:89], v0, s[10:11] offset:2048
	global_load_dwordx4 v[90:93], v0, s[10:11] offset:1024
	global_load_dwordx4 v[94:97], v0, s[10:11]
	s_nop 0
	global_load_dwordx4 v[30:33], v[30:31], off
	v_pk_add_f32 v[42:43], v[56:57], 1.0 op_sel_hi:[1,0]
	s_lshl_b64 s[10:11], s[8:9], 12
	v_pk_mul_f32 v[102:103], v[52:53], v[42:43]
	v_pk_add_f32 v[42:43], v[60:61], 1.0 op_sel_hi:[1,0]
	v_pk_add_f32 v[44:45], v[44:45], 1.0 op_sel_hi:[1,0]
	v_pk_mul_f32 v[106:107], v[64:65], v[42:43]
	v_pk_add_f32 v[42:43], v[72:73], 1.0 op_sel_hi:[1,0]
	s_add_u32 s4, s4, s10
	v_pk_mul_f32 v[110:111], v[68:69], v[42:43]
	v_pk_mul_f32 v[98:99], v[48:49], v[44:45]
	v_pk_add_f32 v[44:45], v[54:55], 1.0 op_sel_hi:[1,0]
	s_addc_u32 s5, s5, s11
	v_pk_add_f32 v[42:43], v[122:123], 1.0 op_sel_hi:[1,0]
	v_pk_mul_f32 v[104:105], v[50:51], v[44:45]
	v_pk_mul_f32 v[114:115], v[118:119], v[42:43]
	v_pk_add_f32 v[44:45], v[58:59], 1.0 op_sel_hi:[1,0]
	s_ashr_i32 s7, s6, 31
	v_pk_add_f32 v[42:43], v[130:131], 1.0 op_sel_hi:[1,0]
	v_pk_mul_f32 v[108:109], v[62:63], v[44:45]
	v_pk_mul_f32 v[118:119], v[126:127], v[42:43]
	v_pk_add_f32 v[44:45], v[70:71], 1.0 op_sel_hi:[1,0]
	s_lshl_b64 s[10:11], s[6:7], 12
	v_pk_add_f32 v[42:43], v[138:139], 1.0 op_sel_hi:[1,0]
	v_pk_mul_f32 v[112:113], v[66:67], v[44:45]
	v_pk_mul_f32 v[122:123], v[134:135], v[42:43]
	v_pk_add_f32 v[44:45], v[120:121], 1.0 op_sel_hi:[1,0]
	v_pk_add_f32 v[42:43], v[142:143], 1.0 op_sel_hi:[1,0]
	v_pk_mul_f32 v[116:117], v[116:117], v[44:45]
	v_pk_mul_f32 v[126:127], v[146:147], v[42:43]
	v_lshlrev_b32_e32 v42, 3, v148
	v_mov_b32_e32 v43, v1
	v_lshl_add_u64 v[42:43], s[4:5], 0, v[42:43]
	s_mov_b64 s[4:5], 0xbe00000
	v_lshl_add_u64 v[130:131], v[42:43], 0, s[4:5]
	s_add_i32 s4, s86, s6
	s_add_i32 s4, s4, s16
	v_pk_add_f32 v[44:45], v[128:129], 1.0 op_sel_hi:[1,0]
	s_ashr_i32 s5, s4, 31
	v_pk_mul_f32 v[120:121], v[124:125], v[44:45]
	v_pk_add_f32 v[44:45], v[136:137], 1.0 op_sel_hi:[1,0]
	s_lshl_b64 s[4:5], s[4:5], 13
	v_readlane_b32 s9, v255, 37
	v_pk_mul_f32 v[124:125], v[132:133], v[44:45]
	v_pk_add_f32 v[44:45], v[140:141], 1.0 op_sel_hi:[1,0]
	s_add_u32 s4, s9, s4
	v_readlane_b32 s9, v255, 38
	v_pk_mul_f32 v[128:129], v[144:145], v[44:45]
	s_addc_u32 s5, s9, s5
	v_lshl_add_u64 v[132:133], s[4:5], 0, v[0:1]
	s_lshl_b64 s[12:13], s[6:7], 13
	s_waitcnt vmcnt(0)
	v_mov_b64_e32 v[44:45], v[36:37]
	v_mov_b64_e32 v[48:49], v[40:41]
	v_mov_b64_e32 v[50:51], v[74:75]
	v_mov_b64_e32 v[54:55], v[78:79]
	v_mov_b64_e32 v[58:59], v[82:83]
	v_mov_b64_e32 v[62:63], v[86:87]
	v_mov_b64_e32 v[66:67], v[90:91]
	v_mov_b64_e32 v[70:71], v[94:95]
	v_mov_b64_e32 v[42:43], v[34:35]
	v_mov_b64_e32 v[46:47], v[38:39]
	v_mov_b64_e32 v[52:53], v[76:77]
	v_mov_b64_e32 v[56:57], v[80:81]
	v_mov_b64_e32 v[60:61], v[84:85]
	v_mov_b64_e32 v[64:65], v[88:89]
	v_mov_b64_e32 v[68:69], v[92:93]
	v_mov_b64_e32 v[72:73], v[96:97]
	s_branch .LBB0_975

; __device__ __forceinline__ unsigned cvtpk(float lo, float hi) { unsigned r; asm volatile("v_cvt_pk_bf16_f32 %0, %1, %2" : "=v"(r) : "v"(lo), "v"(hi)); return r; }
;     __device__ __forceinline__ void operator()(const f32x4 (&acc)[2][2][4][2], const Unit& u, int wr, int wc, int fr, int fq) const {
;     ...
;             for (int m = 2 * (am & 1); m < 2 * (am & 1) + 2; ++m) { const int row = row0 + ai * HALF + m * 16; bf16_t* rowp = O + (size_t)row * ldc + col0;
;                 const float rsvv = rsv[ai][m];
; #pragma unroll
;                 for (int bj = 0; bj < 2; ++bj) { f32x4 v0 = acc[ai][bj][m][0], v1 = acc[ai][bj][m][1];
;                     if (MODE == 1) {
; #pragma unroll
;                         for (int e = 0; e < 4; ++e) { float a = fmaxf(v0[e], 0.f), b = fmaxf(v1[e], 0.f); v0[e] = a * a; v1[e] = b * b; } }
;                     if (MODE >= 2) { v0 = v0 * rsvv; v1 = v1 * rsvv; }
;                     if (MODE == 3) { const f32x4 a0 = t0[m][bj], a1 = t1[m][bj]; f32x4 w0, w1;
;                         w0[0] = v0[0] * a0[0] - v0[1] * a0[1]; w0[1] = v0[1] * a0[0] + v0[0] * a0[1]; w0[2] = v0[2] * a0[2] - v0[3] * a0[3]; w0[3] = v0[3] * a0[2] + v0[2] * a0[3];
;                         w1[0] = v1[0] * a1[0] - v1[1] * a1[1]; w1[1] = v1[1] * a1[0] + v1[0] * a1[1]; w1[2] = v1[2] * a1[2] - v1[3] * a1[3]; w1[3] = v1[3] * a1[2] + v1[2] * a1[3];
;                         v0 = w0; v1 = w1; }
;                     u32x4 w; w.x = cvtpk(v0[0], v0[1]); w.y = cvtpk(v0[2], v0[3]); w.z = cvtpk(v1[0], v1[1]); w.w = cvtpk(v1[2], v1[3]);
;                     *(u32x4*)(rowp + bj * HALF) = w; } }
.LBB0_1037:
	s_lshl_b32 s13, s64, 8
	v_mbcnt_lo_u32_b32 v140, -1, 0
	v_mbcnt_hi_u32_b32 v140, -1, v140
	s_add_i32 s13, s13, s38
	v_and_or_b32 v144, v140, 15, s13
	v_lshrrev_b32_e32 v140, 1, v140
	s_lshl_b32 s13, s57, 8
	v_max_f32_e32 v122, v122, v122
	v_and_or_b32 v140, v140, 24, s13
	v_ashrrev_i32_e32 v145, 31, v144
	v_max_f32_e32 v122, 0, v122
	v_max_f32_e32 v123, v123, v123
	v_max_f32_e32 v124, v124, v124
	v_or_b32_e32 v140, s39, v140
	v_lshlrev_b64 v[146:147], 14, v[144:145]
	v_mul_f32_e32 v145, v122, v122
	v_max_f32_e32 v122, v127, v127
	v_max_f32_e32 v123, 0, v123
	v_max_f32_e32 v124, 0, v124
	v_ashrrev_i32_e32 v141, 31, v140
	v_max_f32_e32 v126, v126, v126
	v_max_f32_e32 v122, 0, v122
	v_mul_f32_e32 v127, v123, v123
	v_max_f32_e32 v123, v128, v128
	v_mul_f32_e32 v128, v124, v124
	v_max_f32_e32 v124, v129, v129
	v_max_f32_e32 v125, v125, v125
	v_lshl_add_u64 v[146:147], s[8:9], 0, v[146:147]
	v_lshlrev_b64 v[148:149], 1, v[140:141]
	v_max_f32_e32 v126, 0, v126
	v_mul_f32_e32 v122, v122, v122
	v_max_f32_e32 v123, 0, v123
	v_max_f32_e32 v124, 0, v124
	v_max_f32_e32 v125, 0, v125
	v_max_f32_e32 v114, v114, v114
	v_lshl_add_u64 v[140:141], v[146:147], 0, v[148:149]
	v_mul_f32_e32 v126, v126, v126
	v_mul_f32_e32 v123, v123, v123
	v_mul_f32_e32 v124, v124, v124
	v_mul_f32_e32 v125, v125, v125
	v_cvt_pk_bf16_f32 v122, v126, v122
	v_max_f32_e32 v114, 0, v114
	v_max_f32_e32 v115, v115, v115
	v_max_f32_e32 v116, v116, v116
	v_cvt_pk_bf16_f32 v123, v123, v124
	v_cvt_pk_bf16_f32 v124, v145, v127
	v_cvt_pk_bf16_f32 v125, v128, v125
	global_store_dwordx4 v[140:141], v[122:125], off
	v_max_f32_e32 v115, 0, v115
	v_max_f32_e32 v116, 0, v116
	v_mul_f32_e32 v122, v114, v114
	v_max_f32_e32 v114, v119, v119
	v_max_f32_e32 v118, v118, v118
	v_max_f32_e32 v114, 0, v114
	v_mul_f32_e32 v119, v115, v115
	v_max_f32_e32 v115, v120, v120
	v_mul_f32_e32 v120, v116, v116
	v_max_f32_e32 v116, v121, v121
	v_max_f32_e32 v117, v117, v117
	v_max_f32_e32 v118, 0, v118
	v_mul_f32_e32 v114, v114, v114
	v_max_f32_e32 v115, 0, v115
	v_max_f32_e32 v116, 0, v116
	v_max_f32_e32 v117, 0, v117
	v_mul_f32_e32 v118, v118, v118
	v_mul_f32_e32 v115, v115, v115
	v_mul_f32_e32 v116, v116, v116
	v_mul_f32_e32 v117, v117, v117
	v_cvt_pk_bf16_f32 v114, v118, v114
	v_max_f32_e32 v106, v106, v106
	v_cvt_pk_bf16_f32 v115, v115, v116
	v_cvt_pk_bf16_f32 v116, v122, v119
	v_cvt_pk_bf16_f32 v117, v120, v117
	global_store_dwordx4 v[140:141], v[114:117], off offset:256
	v_max_f32_e32 v106, 0, v106
	v_max_f32_e32 v107, v107, v107
	v_or_b32_e32 v114, 16, v144
	v_max_f32_e32 v108, v108, v108
	v_ashrrev_i32_e32 v115, 31, v114
	v_mul_f32_e32 v116, v106, v106
	v_max_f32_e32 v106, v111, v111
	v_max_f32_e32 v107, 0, v107
	v_max_f32_e32 v108, 0, v108
	v_lshlrev_b64 v[114:115], 14, v[114:115]
	v_max_f32_e32 v110, v110, v110
	v_max_f32_e32 v106, 0, v106
	v_mul_f32_e32 v111, v107, v107
	v_max_f32_e32 v107, v112, v112
	v_mul_f32_e32 v112, v108, v108
	v_max_f32_e32 v108, v113, v113
	v_max_f32_e32 v109, v109, v109
	v_lshl_add_u64 v[114:115], s[8:9], 0, v[114:115]
	v_max_f32_e32 v110, 0, v110
	v_mul_f32_e32 v106, v106, v106
	v_max_f32_e32 v107, 0, v107
	v_max_f32_e32 v108, 0, v108
	v_max_f32_e32 v109, 0, v109
	v_max_f32_e32 v98, v98, v98
	v_lshl_add_u64 v[114:115], v[114:115], 0, v[148:149]
	v_mul_f32_e32 v110, v110, v110
	v_mul_f32_e32 v107, v107, v107
	v_mul_f32_e32 v108, v108, v108
	v_mul_f32_e32 v109, v109, v109
	v_cvt_pk_bf16_f32 v106, v110, v106
	v_max_f32_e32 v98, 0, v98
	v_max_f32_e32 v99, v99, v99
	v_max_f32_e32 v100, v100, v100
	v_cvt_pk_bf16_f32 v107, v107, v108
	v_cvt_pk_bf16_f32 v108, v116, v111
	v_cvt_pk_bf16_f32 v109, v112, v109
	global_store_dwordx4 v[114:115], v[106:109], off
	v_max_f32_e32 v99, 0, v99
	v_max_f32_e32 v100, 0, v100
	v_mul_f32_e32 v106, v98, v98
	v_max_f32_e32 v98, v103, v103
	v_max_f32_e32 v102, v102, v102
	v_max_f32_e32 v98, 0, v98
	v_mul_f32_e32 v103, v99, v99
	v_max_f32_e32 v99, v104, v104
	v_mul_f32_e32 v104, v100, v100
	v_max_f32_e32 v100, v105, v105
	v_max_f32_e32 v101, v101, v101
	v_max_f32_e32 v102, 0, v102
	v_mul_f32_e32 v98, v98, v98
	v_max_f32_e32 v99, 0, v99
	v_max_f32_e32 v100, 0, v100
	v_max_f32_e32 v101, 0, v101
	v_mul_f32_e32 v102, v102, v102
	v_mul_f32_e32 v99, v99, v99
	v_mul_f32_e32 v100, v100, v100
	v_mul_f32_e32 v101, v101, v101
	v_cvt_pk_bf16_f32 v98, v102, v98
	v_max_f32_e32 v90, v90, v90
	v_cvt_pk_bf16_f32 v99, v99, v100
	v_cvt_pk_bf16_f32 v100, v106, v103
	v_cvt_pk_bf16_f32 v101, v104, v101
	global_store_dwordx4 v[114:115], v[98:101], off offset:256
	v_max_f32_e32 v90, 0, v90
	v_max_f32_e32 v91, v91, v91
	v_or_b32_e32 v98, 32, v144
	v_max_f32_e32 v92, v92, v92
	v_ashrrev_i32_e32 v99, 31, v98
	v_mul_f32_e32 v100, v90, v90
	v_max_f32_e32 v90, v95, v95
	v_max_f32_e32 v91, 0, v91
	v_max_f32_e32 v92, 0, v92
	v_lshlrev_b64 v[98:99], 14, v[98:99]
	v_max_f32_e32 v94, v94, v94
	v_max_f32_e32 v90, 0, v90
	v_mul_f32_e32 v95, v91, v91
	v_max_f32_e32 v91, v96, v96
	v_mul_f32_e32 v96, v92, v92
	v_max_f32_e32 v92, v97, v97
	v_max_f32_e32 v93, v93, v93
	v_lshl_add_u64 v[98:99], s[8:9], 0, v[98:99]
	v_max_f32_e32 v94, 0, v94
	v_mul_f32_e32 v90, v90, v90
	v_max_f32_e32 v91, 0, v91
	v_max_f32_e32 v92, 0, v92
	v_max_f32_e32 v93, 0, v93
	v_max_f32_e32 v82, v82, v82
	v_lshl_add_u64 v[98:99], v[98:99], 0, v[148:149]
	v_mul_f32_e32 v94, v94, v94
	v_mul_f32_e32 v91, v91, v91
	v_mul_f32_e32 v92, v92, v92
	v_mul_f32_e32 v93, v93, v93
	v_cvt_pk_bf16_f32 v90, v94, v90
	v_max_f32_e32 v82, 0, v82
	v_max_f32_e32 v83, v83, v83
	v_max_f32_e32 v84, v84, v84
	v_cvt_pk_bf16_f32 v91, v91, v92
	v_cvt_pk_bf16_f32 v92, v100, v95
	v_cvt_pk_bf16_f32 v93, v96, v93
	global_store_dwordx4 v[98:99], v[90:93], off
; __device__ __forceinline__ unsigned cvtpk(float lo, float hi) { unsigned r; asm volatile("v_cvt_pk_bf16_f32 %0, %1, %2" : "=v"(r) : "v"(lo), "v"(hi)); return r; }
;     __device__ __forceinline__ void operator()(const f32x4 (&acc)[2][2][4][2], const Unit& u, int wr, int wc, int fr, int fq) const {
;     ...
;             for (int m = 2 * (am & 1); m < 2 * (am & 1) + 2; ++m) { const int row = row0 + ai * HALF + m * 16; bf16_t* rowp = O + (size_t)row * ldc + col0;
;                 const float rsvv = rsv[ai][m];
; #pragma unroll
;                 for (int bj = 0; bj < 2; ++bj) { f32x4 v0 = acc[ai][bj][m][0], v1 = acc[ai][bj][m][1];
;                     if (MODE == 1) {
; #pragma unroll
;                         for (int e = 0; e < 4; ++e) { float a = fmaxf(v0[e], 0.f), b = fmaxf(v1[e], 0.f); v0[e] = a * a; v1[e] = b * b; } }
;                     if (MODE >= 2) { v0 = v0 * rsvv; v1 = v1 * rsvv; }
;                     if (MODE == 3) { const f32x4 a0 = t0[m][bj], a1 = t1[m][bj]; f32x4 w0, w1;
;                         w0[0] = v0[0] * a0[0] - v0[1] * a0[1]; w0[1] = v0[1] * a0[0] + v0[0] * a0[1]; w0[2] = v0[2] * a0[2] - v0[3] * a0[3]; w0[3] = v0[3] * a0[2] + v0[2] * a0[3];
;                         w1[0] = v1[0] * a1[0] - v1[1] * a1[1]; w1[1] = v1[1] * a1[0] + v1[0] * a1[1]; w1[2] = v1[2] * a1[2] - v1[3] * a1[3]; w1[3] = v1[3] * a1[2] + v1[2] * a1[3];
;                         v0 = w0; v1 = w1; }
;                     u32x4 w; w.x = cvtpk(v0[0], v0[1]); w.y = cvtpk(v0[2], v0[3]); w.z = cvtpk(v1[0], v1[1]); w.w = cvtpk(v1[2], v1[3]);
;                     *(u32x4*)(rowp + bj * HALF) = w; } }
	v_max_f32_e32 v83, 0, v83
	v_max_f32_e32 v84, 0, v84
	v_mul_f32_e32 v90, v82, v82
	v_max_f32_e32 v82, v87, v87
	v_max_f32_e32 v86, v86, v86
	v_max_f32_e32 v82, 0, v82
	v_mul_f32_e32 v87, v83, v83
	v_max_f32_e32 v83, v88, v88
	v_mul_f32_e32 v88, v84, v84
	v_max_f32_e32 v84, v89, v89
	v_max_f32_e32 v85, v85, v85
	v_max_f32_e32 v86, 0, v86
	v_mul_f32_e32 v82, v82, v82
	v_max_f32_e32 v83, 0, v83
	v_max_f32_e32 v84, 0, v84
	v_max_f32_e32 v85, 0, v85
	v_mul_f32_e32 v86, v86, v86
	v_mul_f32_e32 v83, v83, v83
	v_mul_f32_e32 v84, v84, v84
	v_mul_f32_e32 v85, v85, v85
	v_cvt_pk_bf16_f32 v82, v86, v82
	v_max_f32_e32 v74, v74, v74
	v_cvt_pk_bf16_f32 v83, v83, v84
	v_cvt_pk_bf16_f32 v84, v90, v87
	v_cvt_pk_bf16_f32 v85, v88, v85
	global_store_dwordx4 v[98:99], v[82:85], off offset:256
	v_max_f32_e32 v74, 0, v74
	v_max_f32_e32 v75, v75, v75
	v_or_b32_e32 v82, 48, v144
	v_max_f32_e32 v76, v76, v76
	v_ashrrev_i32_e32 v83, 31, v82
	v_mul_f32_e32 v84, v74, v74
	v_max_f32_e32 v74, v79, v79
	v_max_f32_e32 v75, 0, v75
	v_max_f32_e32 v76, 0, v76
	v_lshlrev_b64 v[82:83], 14, v[82:83]
	v_max_f32_e32 v78, v78, v78
	v_max_f32_e32 v74, 0, v74
	v_mul_f32_e32 v79, v75, v75
	v_max_f32_e32 v75, v80, v80
	v_mul_f32_e32 v80, v76, v76
	v_max_f32_e32 v76, v81, v81
	v_max_f32_e32 v77, v77, v77
	v_lshl_add_u64 v[82:83], s[8:9], 0, v[82:83]
	v_max_f32_e32 v78, 0, v78
	v_mul_f32_e32 v74, v74, v74
	v_max_f32_e32 v75, 0, v75
	v_max_f32_e32 v76, 0, v76
	v_max_f32_e32 v77, 0, v77
	v_max_f32_e32 v66, v66, v66
	v_max_f32_e32 v67, v67, v67
	v_max_f32_e32 v68, v68, v68
	v_lshl_add_u64 v[82:83], v[82:83], 0, v[148:149]
	v_mul_f32_e32 v78, v78, v78
	v_mul_f32_e32 v75, v75, v75
	v_mul_f32_e32 v76, v76, v76
	v_mul_f32_e32 v77, v77, v77
	v_cvt_pk_bf16_f32 v74, v78, v74
	v_max_f32_e32 v66, 0, v66
	v_max_f32_e32 v67, 0, v67
	v_max_f32_e32 v68, 0, v68
	v_cvt_pk_bf16_f32 v75, v75, v76
	v_cvt_pk_bf16_f32 v76, v84, v79
	v_cvt_pk_bf16_f32 v77, v80, v77
	global_store_dwordx4 v[82:83], v[74:77], off
	v_max_f32_e32 v70, v70, v70
	v_max_f32_e32 v69, v69, v69
	v_mul_f32_e32 v74, v66, v66
	v_max_f32_e32 v66, v71, v71
	v_mul_f32_e32 v71, v67, v67
	v_max_f32_e32 v67, v72, v72
	v_mul_f32_e32 v72, v68, v68
	v_max_f32_e32 v68, v73, v73
	v_max_f32_e32 v66, 0, v66
	v_max_f32_e32 v67, 0, v67
	v_max_f32_e32 v68, 0, v68
	v_max_f32_e32 v70, 0, v70
	v_mul_f32_e32 v66, v66, v66
	v_mul_f32_e32 v67, v67, v67
	v_max_f32_e32 v69, 0, v69
	v_mul_f32_e32 v68, v68, v68
	v_max_f32_e32 v58, v58, v58
	v_mul_f32_e32 v70, v70, v70
	v_mul_f32_e32 v69, v69, v69
	v_cvt_pk_bf16_f32 v66, v70, v66
	v_cvt_pk_bf16_f32 v67, v67, v68
	v_cvt_pk_bf16_f32 v68, v74, v71
	v_max_f32_e32 v58, 0, v58
	v_max_f32_e32 v59, v59, v59
	v_max_f32_e32 v60, v60, v60
	v_cvt_pk_bf16_f32 v69, v72, v69
	global_store_dwordx4 v[82:83], v[66:69], off offset:256
	v_max_f32_e32 v62, v62, v62
	v_max_f32_e32 v59, 0, v59
	v_mul_f32_e32 v68, v58, v58
	v_max_f32_e32 v58, v63, v63
	v_max_f32_e32 v60, 0, v60
	v_max_f32_e32 v62, 0, v62
	v_max_f32_e32 v58, 0, v58
	v_mul_f32_e32 v63, v59, v59
	v_max_f32_e32 v59, v64, v64
	v_mul_f32_e32 v64, v60, v60
	v_max_f32_e32 v60, v65, v65
	v_mul_f32_e32 v62, v62, v62
	v_mul_f32_e32 v58, v58, v58
	v_max_f32_e32 v59, 0, v59
	v_max_f32_e32 v60, 0, v60
	v_max_f32_e32 v61, v61, v61
	s_mov_b32 s13, 0x200000
	v_mul_f32_e32 v59, v59, v59
	v_max_f32_e32 v61, 0, v61
	v_mul_f32_e32 v60, v60, v60
	v_cvt_pk_bf16_f32 v58, v62, v58
	v_add_co_u32_e32 v62, vcc, s13, v140
	v_max_f32_e32 v50, v50, v50
	v_max_f32_e32 v51, v51, v51
	v_max_f32_e32 v52, v52, v52
	v_mul_f32_e32 v61, v61, v61
	v_cvt_pk_bf16_f32 v59, v59, v60
	v_cvt_pk_bf16_f32 v60, v68, v63
	v_addc_co_u32_e32 v63, vcc, 0, v141, vcc
	v_max_f32_e32 v50, 0, v50
	v_max_f32_e32 v51, 0, v51
	v_max_f32_e32 v52, 0, v52
	v_cvt_pk_bf16_f32 v61, v64, v61
	global_store_dwordx4 v[62:63], v[58:61], off
	v_max_f32_e32 v54, v54, v54
	v_max_f32_e32 v53, v53, v53
	v_mul_f32_e32 v58, v50, v50
	v_max_f32_e32 v50, v55, v55
	v_mul_f32_e32 v55, v51, v51
	v_max_f32_e32 v51, v56, v56
	v_mul_f32_e32 v56, v52, v52
	v_max_f32_e32 v52, v57, v57
	v_max_f32_e32 v50, 0, v50
	v_max_f32_e32 v51, 0, v51
	v_max_f32_e32 v52, 0, v52
	s_mov_b64 s[20:21], 0x200000
	v_max_f32_e32 v54, 0, v54
	v_mul_f32_e32 v50, v50, v50
	v_mul_f32_e32 v51, v51, v51
	v_max_f32_e32 v53, 0, v53
	v_mul_f32_e32 v52, v52, v52
	v_max_f32_e32 v42, v42, v42
	v_lshl_add_u64 v[66:67], v[140:141], 0, s[20:21]
	v_mul_f32_e32 v54, v54, v54
	v_mul_f32_e32 v53, v53, v53
	v_cvt_pk_bf16_f32 v50, v54, v50
	v_cvt_pk_bf16_f32 v51, v51, v52
	v_cvt_pk_bf16_f32 v52, v58, v55
	v_max_f32_e32 v42, 0, v42
	v_max_f32_e32 v43, v43, v43
	v_max_f32_e32 v44, v44, v44
	v_cvt_pk_bf16_f32 v53, v56, v53
	global_store_dwordx4 v[66:67], v[50:53], off offset:256
	v_max_f32_e32 v46, v46, v46
	v_max_f32_e32 v43, 0, v43
	v_mul_f32_e32 v52, v42, v42
	v_max_f32_e32 v42, v47, v47
	v_max_f32_e32 v44, 0, v44
	v_max_f32_e32 v46, 0, v46
	v_max_f32_e32 v42, 0, v42
	v_mul_f32_e32 v47, v43, v43
	v_max_f32_e32 v43, v48, v48
	v_mul_f32_e32 v48, v44, v44
	v_max_f32_e32 v44, v49, v49
	v_mul_f32_e32 v46, v46, v46
	v_mul_f32_e32 v42, v42, v42
	v_max_f32_e32 v43, 0, v43
	v_max_f32_e32 v44, 0, v44
	v_max_f32_e32 v45, v45, v45
	s_mov_b32 s13, 0x240000
	v_mul_f32_e32 v43, v43, v43
; __device__ __forceinline__ int tid_of(int wave_s) { int l; asm volatile("v_mbcnt_lo_u32_b32 %0, -1, 0\n\tv_mbcnt_hi_u32_b32 %0, -1, %0" : "=v"(l)); return wave_s * 64 + l; }
; #define PG8_BAR __builtin_amdgcn_s_barrier()
;     __device__ __forceinline__ void operator()(const f32x4 (&acc)[2][2][4][2], const Unit& u, int wr, int wc, int fr, int fq) const {
;     ...
;             for (int m = 2 * (am & 1); m < 2 * (am & 1) + 2; ++m) { const int row = row0 + ai * HALF + m * 16; bf16_t* rowp = O + (size_t)row * ldc + col0;
;                 const float rsvv = rsv[ai][m];
; #pragma unroll
;                 for (int bj = 0; bj < 2; ++bj) { f32x4 v0 = acc[ai][bj][m][0], v1 = acc[ai][bj][m][1];
;                     if (MODE == 1) {
; #pragma unroll
;                         for (int e = 0; e < 4; ++e) { float a = fmaxf(v0[e], 0.f), b = fmaxf(v1[e], 0.f); v0[e] = a * a; v1[e] = b * b; } }
;                     if (MODE >= 2) { v0 = v0 * rsvv; v1 = v1 * rsvv; }
;                     if (MODE == 3) { const f32x4 a0 = t0[m][bj], a1 = t1[m][bj]; f32x4 w0, w1;
;                         w0[0] = v0[0] * a0[0] - v0[1] * a0[1]; w0[1] = v0[1] * a0[0] + v0[0] * a0[1]; w0[2] = v0[2] * a0[2] - v0[3] * a0[3]; w0[3] = v0[3] * a0[2] + v0[2] * a0[3];
;                         w1[0] = v1[0] * a1[0] - v1[1] * a1[1]; w1[1] = v1[1] * a1[0] + v1[0] * a1[1]; w1[2] = v1[2] * a1[2] - v1[3] * a1[3]; w1[3] = v1[3] * a1[2] + v1[2] * a1[3];
;                         v0 = w0; v1 = w1; }
;                     u32x4 w; w.x = cvtpk(v0[0], v0[1]); w.y = cvtpk(v0[2], v0[3]); w.z = cvtpk(v1[0], v1[1]); w.w = cvtpk(v1[2], v1[3]);
;                     *(u32x4*)(rowp + bj * HALF) = w; } }
; template <class Epi>
; __device__ __forceinline__ void gemm_phase(LAS unsigned char* lds, const Gemm g, const StaticOrder& S, const Epi& E, int wave_s) {
;     ...
;         if (wr == 0) PG8_BAR;
;         { const int l2_ = tid_of(wave_s) & 63; E(acc, cur, wr, wc, l2_ & 15, l2_ >> 4); }
;         if (!has_next) break;
; #pragma unroll
;         for (int a = 0; a < 2; ++a)
; #pragma unroll
;             for (int b = 0; b < 2; ++b)
; #pragma unroll
;                 for (int m = 0; m < 4; ++m)
; #pragma unroll
;                     for (int n = 0; n < 2; ++n) acc[a][b][m][n] = (f32x4){0.f, 0.f, 0.f, 0.f};
;         cur = nxt; cA = nA; cB = nB; ++ui;
;         if (wr == 1) PG8_BAR;
	v_max_f32_e32 v45, 0, v45
	v_mul_f32_e32 v44, v44, v44
	v_cvt_pk_bf16_f32 v42, v46, v42
	v_add_co_u32_e32 v46, vcc, s13, v140
	v_max_f32_e32 v34, v34, v34
	v_max_f32_e32 v35, v35, v35
	v_max_f32_e32 v36, v36, v36
	v_mul_f32_e32 v45, v45, v45
	v_cvt_pk_bf16_f32 v43, v43, v44
	v_cvt_pk_bf16_f32 v44, v52, v47
	v_addc_co_u32_e32 v47, vcc, 0, v141, vcc
	v_max_f32_e32 v34, 0, v34
	v_max_f32_e32 v35, 0, v35
	v_max_f32_e32 v36, 0, v36
	v_cvt_pk_bf16_f32 v45, v48, v45
	global_store_dwordx4 v[46:47], v[42:45], off
	v_max_f32_e32 v38, v38, v38
	v_max_f32_e32 v37, v37, v37
	v_mul_f32_e32 v42, v34, v34
	v_max_f32_e32 v34, v39, v39
	v_mul_f32_e32 v39, v35, v35
	v_max_f32_e32 v35, v40, v40
	v_mul_f32_e32 v40, v36, v36
	v_max_f32_e32 v36, v41, v41
	v_max_f32_e32 v34, 0, v34
	v_max_f32_e32 v35, 0, v35
	v_max_f32_e32 v36, 0, v36
	s_mov_b64 s[20:21], 0x240000
	v_max_f32_e32 v38, 0, v38
	v_mul_f32_e32 v34, v34, v34
	v_mul_f32_e32 v35, v35, v35
	v_max_f32_e32 v37, 0, v37
	v_mul_f32_e32 v36, v36, v36
	v_max_f32_e32 v26, v26, v26
	v_lshl_add_u64 v[50:51], v[140:141], 0, s[20:21]
	v_mul_f32_e32 v38, v38, v38
	v_mul_f32_e32 v37, v37, v37
	v_cvt_pk_bf16_f32 v34, v38, v34
	v_cvt_pk_bf16_f32 v35, v35, v36
	v_cvt_pk_bf16_f32 v36, v42, v39
	v_max_f32_e32 v26, 0, v26
	v_max_f32_e32 v27, v27, v27
	v_max_f32_e32 v28, v28, v28
	v_cvt_pk_bf16_f32 v37, v40, v37
	global_store_dwordx4 v[50:51], v[34:37], off offset:256
	v_max_f32_e32 v30, v30, v30
	v_max_f32_e32 v27, 0, v27
	v_mul_f32_e32 v36, v26, v26
	v_max_f32_e32 v26, v31, v31
	v_max_f32_e32 v28, 0, v28
	v_max_f32_e32 v30, 0, v30
	v_max_f32_e32 v26, 0, v26
	v_mul_f32_e32 v31, v27, v27
	v_max_f32_e32 v27, v32, v32
	v_mul_f32_e32 v32, v28, v28
	v_max_f32_e32 v28, v33, v33
	v_mul_f32_e32 v30, v30, v30
	v_mul_f32_e32 v26, v26, v26
	v_max_f32_e32 v27, 0, v27
	v_max_f32_e32 v28, 0, v28
	v_max_f32_e32 v29, v29, v29
	s_mov_b32 s13, 0x280000
	v_mul_f32_e32 v27, v27, v27
	v_max_f32_e32 v29, 0, v29
	v_mul_f32_e32 v28, v28, v28
	v_cvt_pk_bf16_f32 v26, v30, v26
	v_add_co_u32_e32 v30, vcc, s13, v140
	v_max_f32_e32 v18, v18, v18
	v_max_f32_e32 v19, v19, v19
	v_max_f32_e32 v20, v20, v20
	v_mul_f32_e32 v29, v29, v29
	v_cvt_pk_bf16_f32 v27, v27, v28
	v_cvt_pk_bf16_f32 v28, v36, v31
	v_addc_co_u32_e32 v31, vcc, 0, v141, vcc
	v_max_f32_e32 v18, 0, v18
	v_max_f32_e32 v19, 0, v19
	v_max_f32_e32 v20, 0, v20
	v_cvt_pk_bf16_f32 v29, v32, v29
	global_store_dwordx4 v[30:31], v[26:29], off
	v_max_f32_e32 v22, v22, v22
	v_max_f32_e32 v21, v21, v21
	v_mul_f32_e32 v26, v18, v18
	v_max_f32_e32 v18, v23, v23
	v_mul_f32_e32 v23, v19, v19
	v_max_f32_e32 v19, v24, v24
	v_mul_f32_e32 v24, v20, v20
	v_max_f32_e32 v20, v25, v25
	v_max_f32_e32 v18, 0, v18
	v_max_f32_e32 v19, 0, v19
	v_max_f32_e32 v20, 0, v20
	s_mov_b64 s[20:21], 0x280000
	v_max_f32_e32 v22, 0, v22
	v_mul_f32_e32 v18, v18, v18
	v_mul_f32_e32 v19, v19, v19
	v_max_f32_e32 v21, 0, v21
	v_mul_f32_e32 v20, v20, v20
	v_max_f32_e32 v10, v10, v10
	v_lshl_add_u64 v[34:35], v[140:141], 0, s[20:21]
	v_mul_f32_e32 v22, v22, v22
	v_mul_f32_e32 v21, v21, v21
	v_cvt_pk_bf16_f32 v18, v22, v18
	v_cvt_pk_bf16_f32 v19, v19, v20
	v_cvt_pk_bf16_f32 v20, v26, v23
	v_max_f32_e32 v10, 0, v10
	v_max_f32_e32 v11, v11, v11
	v_max_f32_e32 v12, v12, v12
	v_cvt_pk_bf16_f32 v21, v24, v21
	global_store_dwordx4 v[34:35], v[18:21], off offset:256
	v_max_f32_e32 v14, v14, v14
	v_max_f32_e32 v11, 0, v11
	v_mul_f32_e32 v20, v10, v10
	v_max_f32_e32 v10, v15, v15
	v_max_f32_e32 v12, 0, v12
	v_max_f32_e32 v14, 0, v14
	v_max_f32_e32 v10, 0, v10
	v_mul_f32_e32 v15, v11, v11
	v_max_f32_e32 v11, v16, v16
	v_mul_f32_e32 v16, v12, v12
	v_max_f32_e32 v12, v17, v17
	v_mul_f32_e32 v14, v14, v14
	v_mul_f32_e32 v10, v10, v10
	v_max_f32_e32 v11, 0, v11
	v_max_f32_e32 v12, 0, v12
	v_max_f32_e32 v13, v13, v13
	s_mov_b32 s13, 0x2c0000
	v_mul_f32_e32 v11, v11, v11
	v_max_f32_e32 v13, 0, v13
	v_mul_f32_e32 v12, v12, v12
	v_cvt_pk_bf16_f32 v10, v14, v10
	v_add_co_u32_e32 v14, vcc, s13, v140
	v_max_f32_e32 v2, v2, v2
	v_max_f32_e32 v3, v3, v3
	v_max_f32_e32 v4, v4, v4
	v_mul_f32_e32 v13, v13, v13
	v_cvt_pk_bf16_f32 v11, v11, v12
	v_cvt_pk_bf16_f32 v12, v20, v15
	v_addc_co_u32_e32 v15, vcc, 0, v141, vcc
	v_max_f32_e32 v2, 0, v2
	v_max_f32_e32 v3, 0, v3
	v_max_f32_e32 v4, 0, v4
	v_cvt_pk_bf16_f32 v13, v16, v13
	global_store_dwordx4 v[14:15], v[10:13], off
	v_max_f32_e32 v5, v5, v5
	s_mov_b64 s[20:21], 0x2c0000
	v_mul_f32_e32 v10, v2, v2
	v_max_f32_e32 v2, v7, v7
	v_mul_f32_e32 v7, v3, v3
	v_max_f32_e32 v3, v8, v8
	v_mul_f32_e32 v8, v4, v4
	v_max_f32_e32 v4, v9, v9
	v_max_f32_e32 v6, v6, v6
	v_max_f32_e32 v2, 0, v2
	v_max_f32_e32 v3, 0, v3
	v_max_f32_e32 v4, 0, v4
	v_max_f32_e32 v5, 0, v5
	v_lshl_add_u64 v[18:19], v[140:141], 0, s[20:21]
	v_max_f32_e32 v6, 0, v6
	v_mul_f32_e32 v2, v2, v2
	v_mul_f32_e32 v3, v3, v3
	v_mul_f32_e32 v4, v4, v4
	v_mul_f32_e32 v5, v5, v5
	s_andn2_b64 vcc, exec, s[4:5]
	s_mov_b64 s[4:5], -1
	v_mul_f32_e32 v6, v6, v6
	v_cvt_pk_bf16_f32 v2, v6, v2
	v_cvt_pk_bf16_f32 v3, v3, v4
	v_cvt_pk_bf16_f32 v4, v10, v7
	v_cvt_pk_bf16_f32 v5, v8, v5
	global_store_dwordx4 v[18:19], v[2:5], off offset:256
	s_cbranch_vccnz .LBB0_1026
	s_andn2_b64 vcc, exec, s[6:7]
	s_cbranch_vccnz .LBB0_1025
	s_barrier
	s_branch .LBB0_1025

;     __device__ __forceinline__ void operator()(const f32x4 (&acc)[2][2][4][2], const Unit& u, int wr, int wc, int fr, int fq) const {
;         const int col0 = u.pn * BM + wc * 32 + 4 * fq;
;         f32x4 gv[2][2];
; #pragma unroll
;         for (int bj = 0; bj < 2; ++bj)
; #pragma unroll
;             for (int n = 0; n < 2; ++n) gv[bj][n] = *(const f32x4*)(gate + col0 + bj * HALF + n * 16);
; #pragma unroll
;         for (int ai = 0; ai < 2; ++ai) {
;             f32x4 bs[4][2][2];
; #pragma unroll
;             for (int m = 0; m < 4; ++m) { const size_t off = (size_t)(u.pm * BM + ai * HALF + wr * 64 + m * 16 + fr) * ldc + col0;
; #pragma unroll
;                 for (int bj = 0; bj < 2; ++bj)
; #pragma unroll
;                     for (int n = 0; n < 2; ++n) bs[m][bj][n] = *(const f32x4*)(res + off + bj * HALF + n * 16); }
;             asm volatile("" ::: "memory");
; #pragma unroll
;             for (int m = 0; m < 4; ++m) { const size_t off = (size_t)(u.pm * BM + ai * HALF + wr * 64 + m * 16 + fr) * ldc + col0;
; #pragma unroll
;                 for (int bj = 0; bj < 2; ++bj)
; #pragma unroll
;                     for (int n = 0; n < 2; ++n) *(f32x4*)(out + off + bj * HALF + n * 16) = bs[m][bj][n] + gv[bj][n] * acc[ai][bj][m][n]; }
.LBB0_1101:
	v_mbcnt_lo_u32_b32 v154, -1, 0
	v_mbcnt_hi_u32_b32 v154, -1, v154
	s_lshl_b32 s11, s56, 8
	v_lshrrev_b32_e32 v130, 2, v154
	v_and_or_b32 v130, v130, 12, s11
	s_lshl_b32 s11, s41, 8
	s_add_i32 s11, s11, s35
	v_or_b32_e32 v130, s37, v130
	v_and_or_b32 v156, v154, 15, s11
	v_ashrrev_i32_e32 v131, 31, v130
	v_or_b32_e32 v176, 16, v156
	v_or_b32_e32 v192, 32, v156
	v_lshlrev_b64 v[152:153], 2, v[130:131]
	v_ashrrev_i32_e32 v157, 31, v156
	v_ashrrev_i32_e32 v177, 31, v176
	v_ashrrev_i32_e32 v193, 31, v192
	v_lshl_add_u64 v[154:155], s[58:59], 0, v[152:153]
	v_lshlrev_b64 v[204:205], 13, v[156:157]
	v_lshlrev_b64 v[206:207], 13, v[176:177]
	v_lshlrev_b64 v[216:217], 13, v[192:193]
	v_or_b32_e32 v212, 48, v156
	v_lshl_add_u64 v[130:131], s[6:7], 0, v[152:153]
	v_lshl_add_u64 v[172:173], v[154:155], 0, v[204:205]
	v_lshl_add_u64 v[188:189], v[154:155], 0, v[206:207]
	v_lshl_add_u64 v[208:209], v[154:155], 0, v[216:217]
	v_ashrrev_i32_e32 v213, 31, v212
	global_load_dwordx4 v[142:145], v[130:131], off
	global_load_dwordx4 v[138:141], v[130:131], off offset:64
	global_load_dwordx4 v[134:137], v[130:131], off offset:512
	s_nop 0
	global_load_dwordx4 v[130:133], v[130:131], off offset:576
	s_nop 0
	global_load_dwordx4 v[160:163], v[172:173], off
	global_load_dwordx4 v[164:167], v[172:173], off offset:64
	global_load_dwordx4 v[168:171], v[172:173], off offset:512
	s_nop 0
	global_load_dwordx4 v[172:175], v[172:173], off offset:576
	s_nop 0
	global_load_dwordx4 v[176:179], v[188:189], off
	global_load_dwordx4 v[180:183], v[188:189], off offset:64
	global_load_dwordx4 v[184:187], v[188:189], off offset:512
	s_nop 0
	global_load_dwordx4 v[188:191], v[188:189], off offset:576
	s_nop 0
	global_load_dwordx4 v[192:195], v[208:209], off
	global_load_dwordx4 v[196:199], v[208:209], off offset:64
	global_load_dwordx4 v[200:203], v[208:209], off offset:512
	s_nop 0
	global_load_dwordx4 v[208:211], v[208:209], off offset:576
	v_lshlrev_b64 v[238:239], 13, v[212:213]
	v_lshl_add_u64 v[234:235], v[154:155], 0, v[238:239]
	global_load_dwordx4 v[212:215], v[234:235], off
	global_load_dwordx4 v[226:229], v[234:235], off offset:64
	global_load_dwordx4 v[230:233], v[234:235], off offset:512
	s_nop 0
	global_load_dwordx4 v[234:237], v[234:235], off offset:576
	v_lshl_add_u64 v[204:205], s[58:59], 0, v[204:205]
	v_lshl_add_u64 v[204:205], v[204:205], 0, v[152:153]
	v_lshl_add_u64 v[206:207], s[58:59], 0, v[206:207]
	v_lshl_add_u64 v[216:217], s[58:59], 0, v[216:217]
	v_lshl_add_u64 v[206:207], v[206:207], 0, v[152:153]
	v_lshl_add_u64 v[216:217], v[216:217], 0, v[152:153]
	s_andn2_b64 vcc, exec, s[0:1]
	s_mov_b64 s[0:1], -1
	s_waitcnt vmcnt(0) lgkmcnt(0)
	v_pk_fma_f32 v[128:129], v[128:129], v[144:145], v[162:163]
	v_pk_fma_f32 v[126:127], v[126:127], v[142:143], v[160:161]
	v_pk_fma_f32 v[124:125], v[124:125], v[140:141], v[166:167]
	v_pk_fma_f32 v[122:123], v[122:123], v[138:139], v[164:165]
	v_pk_fma_f32 v[108:109], v[108:109], v[136:137], v[170:171]
	v_pk_fma_f32 v[78:79], v[78:79], v[130:131], v[208:209]
	v_pk_fma_f32 v[106:107], v[106:107], v[134:135], v[168:169]
	v_pk_fma_f32 v[104:105], v[104:105], v[132:133], v[174:175]
	v_pk_fma_f32 v[102:103], v[102:103], v[130:131], v[172:173]
	v_pk_fma_f32 v[120:121], v[120:121], v[144:145], v[178:179]
	v_pk_fma_f32 v[118:119], v[118:119], v[142:143], v[176:177]
	v_pk_fma_f32 v[116:117], v[116:117], v[140:141], v[182:183]
	v_pk_fma_f32 v[114:115], v[114:115], v[138:139], v[180:181]
	v_pk_fma_f32 v[96:97], v[96:97], v[136:137], v[186:187]
	v_pk_fma_f32 v[94:95], v[94:95], v[134:135], v[184:185]
	v_pk_fma_f32 v[92:93], v[92:93], v[132:133], v[190:191]
	v_pk_fma_f32 v[90:91], v[90:91], v[130:131], v[188:189]
	v_pk_fma_f32 v[112:113], v[112:113], v[144:145], v[194:195]
	v_pk_fma_f32 v[110:111], v[110:111], v[142:143], v[192:193]
	v_pk_fma_f32 v[100:101], v[100:101], v[140:141], v[198:199]
	v_pk_fma_f32 v[98:99], v[98:99], v[138:139], v[196:197]
	v_pk_fma_f32 v[88:89], v[88:89], v[136:137], v[202:203]
	v_pk_fma_f32 v[86:87], v[86:87], v[134:135], v[200:201]
	v_pk_fma_f32 v[80:81], v[80:81], v[132:133], v[210:211]
	global_store_dwordx4 v[204:205], v[126:129], off
	global_store_dwordx4 v[204:205], v[122:125], off offset:64
	global_store_dwordx4 v[204:205], v[106:109], off offset:512
	global_store_dwordx4 v[204:205], v[102:105], off offset:576
	global_store_dwordx4 v[206:207], v[118:121], off
	global_store_dwordx4 v[206:207], v[114:117], off offset:64
	global_store_dwordx4 v[206:207], v[94:97], off offset:512
	global_store_dwordx4 v[206:207], v[90:93], off offset:576
	global_store_dwordx4 v[216:217], v[110:113], off
	global_store_dwordx4 v[216:217], v[98:101], off offset:64
	global_store_dwordx4 v[216:217], v[86:89], off offset:512
	global_store_dwordx4 v[216:217], v[78:81], off offset:576
	v_pk_fma_f32 v[76:77], v[76:77], v[140:141], v[228:229]
	v_pk_fma_f32 v[74:75], v[74:75], v[138:139], v[226:227]
	v_pk_fma_f32 v[78:79], v[82:83], v[142:143], v[212:213]
	v_lshl_add_u64 v[82:83], s[58:59], 0, v[238:239]
	v_pk_fma_f32 v[80:81], v[84:85], v[144:145], v[214:215]
	v_lshl_add_u64 v[82:83], v[82:83], 0, v[152:153]
	v_pk_fma_f32 v[72:73], v[72:73], v[136:137], v[232:233]
	v_pk_fma_f32 v[70:71], v[70:71], v[134:135], v[230:231]
; __device__ __forceinline__ int tid_of(int wave_s) { int l; asm volatile("v_mbcnt_lo_u32_b32 %0, -1, 0\n\tv_mbcnt_hi_u32_b32 %0, -1, %0" : "=v"(l)); return wave_s * 64 + l; }
; #define PG8_BAR __builtin_amdgcn_s_barrier()
;     __device__ __forceinline__ void operator()(const f32x4 (&acc)[2][2][4][2], const Unit& u, int wr, int wc, int fr, int fq) const {
;     ...
;         for (int ai = 0; ai < 2; ++ai) {
;             f32x4 bs[4][2][2];
; #pragma unroll
;             for (int m = 0; m < 4; ++m) { const size_t off = (size_t)(u.pm * BM + ai * HALF + wr * 64 + m * 16 + fr) * ldc + col0;
; #pragma unroll
;                 for (int bj = 0; bj < 2; ++bj)
; #pragma unroll
;                     for (int n = 0; n < 2; ++n) bs[m][bj][n] = *(const f32x4*)(res + off + bj * HALF + n * 16); }
;             asm volatile("" ::: "memory");
; #pragma unroll
;             for (int m = 0; m < 4; ++m) { const size_t off = (size_t)(u.pm * BM + ai * HALF + wr * 64 + m * 16 + fr) * ldc + col0;
; #pragma unroll
;                 for (int bj = 0; bj < 2; ++bj)
; #pragma unroll
;                     for (int n = 0; n < 2; ++n) *(f32x4*)(out + off + bj * HALF + n * 16) = bs[m][bj][n] + gv[bj][n] * acc[ai][bj][m][n]; }
;             asm volatile("" ::: "memory");
; template <class Epi>
; __device__ __forceinline__ void gemm_phase(LAS unsigned char* lds, const Gemm g, const StaticOrder& S, const Epi& E, int wave_s) {
;     ...
;         if (wr == 0) PG8_BAR;
;         { const int l2_ = tid_of(wave_s) & 63; E(acc, cur, wr, wc, l2_ & 15, l2_ >> 4); }
;         if (!has_next) break;
; #pragma unroll
;         for (int a = 0; a < 2; ++a)
; #pragma unroll
;             for (int b = 0; b < 2; ++b)
; #pragma unroll
;                 for (int m = 0; m < 4; ++m)
; #pragma unroll
;                     for (int n = 0; n < 2; ++n) acc[a][b][m][n] = (f32x4){0.f, 0.f, 0.f, 0.f};
;         cur = nxt; cA = nA; cB = nB; ++ui;
;         if (wr == 1) PG8_BAR;
	v_pk_fma_f32 v[68:69], v[68:69], v[132:133], v[236:237]
	v_pk_fma_f32 v[66:67], v[66:67], v[130:131], v[234:235]
	global_store_dwordx4 v[82:83], v[78:81], off
	global_store_dwordx4 v[82:83], v[74:77], off offset:64
	global_store_dwordx4 v[82:83], v[70:73], off offset:512
	global_store_dwordx4 v[82:83], v[66:69], off offset:576
	v_add_u32_e32 v82, 0x90, v156
	v_add_u32_e32 v98, 0xa0, v156
	v_add_u32_e32 v66, 0x80, v156
	v_ashrrev_i32_e32 v67, 31, v66
	v_ashrrev_i32_e32 v83, 31, v82
	v_ashrrev_i32_e32 v99, 31, v98
	v_lshlrev_b64 v[160:161], 13, v[66:67]
	v_lshlrev_b64 v[162:163], 13, v[82:83]
	v_lshlrev_b64 v[164:165], 13, v[98:99]
	v_add_u32_e32 v114, 0xb0, v156
	v_lshl_add_u64 v[78:79], v[154:155], 0, v[160:161]
	v_lshl_add_u64 v[94:95], v[154:155], 0, v[162:163]
	v_lshl_add_u64 v[110:111], v[154:155], 0, v[164:165]
	v_ashrrev_i32_e32 v115, 31, v114
	global_load_dwordx4 v[66:69], v[78:79], off
	global_load_dwordx4 v[70:73], v[78:79], off offset:64
	global_load_dwordx4 v[74:77], v[78:79], off offset:512
	s_nop 0
	global_load_dwordx4 v[78:81], v[78:79], off offset:576
	s_nop 0
	global_load_dwordx4 v[82:85], v[94:95], off
	global_load_dwordx4 v[86:89], v[94:95], off offset:64
	global_load_dwordx4 v[90:93], v[94:95], off offset:512
	s_nop 0
	global_load_dwordx4 v[94:97], v[94:95], off offset:576
	s_nop 0
	global_load_dwordx4 v[98:101], v[110:111], off
	global_load_dwordx4 v[102:105], v[110:111], off offset:64
	global_load_dwordx4 v[106:109], v[110:111], off offset:512
	s_nop 0
	global_load_dwordx4 v[110:113], v[110:111], off offset:576
	v_lshlrev_b64 v[156:157], 13, v[114:115]
	v_lshl_add_u64 v[126:127], v[154:155], 0, v[156:157]
	global_load_dwordx4 v[114:117], v[126:127], off
	global_load_dwordx4 v[118:121], v[126:127], off offset:64
	global_load_dwordx4 v[122:125], v[126:127], off offset:512
	s_nop 0
	global_load_dwordx4 v[126:129], v[126:127], off offset:576
	v_lshl_add_u64 v[154:155], s[58:59], 0, v[160:161]
	v_lshl_add_u64 v[160:161], s[58:59], 0, v[162:163]
	v_lshl_add_u64 v[162:163], s[58:59], 0, v[164:165]
	v_lshl_add_u64 v[154:155], v[154:155], 0, v[152:153]
	v_lshl_add_u64 v[162:163], v[162:163], 0, v[152:153]
	v_lshl_add_u64 v[160:161], v[160:161], 0, v[152:153]
	s_waitcnt vmcnt(15)
	v_pk_fma_f32 v[64:65], v[64:65], v[144:145], v[68:69]
	v_pk_fma_f32 v[62:63], v[62:63], v[142:143], v[66:67]
	s_waitcnt vmcnt(14)
	v_pk_fma_f32 v[60:61], v[60:61], v[140:141], v[72:73]
	v_pk_fma_f32 v[58:59], v[58:59], v[138:139], v[70:71]
	s_waitcnt vmcnt(5)
	v_pk_fma_f32 v[20:21], v[20:21], v[136:137], v[108:109]
	v_pk_fma_f32 v[18:19], v[18:19], v[134:135], v[106:107]
	v_pk_fma_f32 v[44:45], v[44:45], v[136:137], v[76:77]
	v_pk_fma_f32 v[42:43], v[42:43], v[134:135], v[74:75]
	v_pk_fma_f32 v[40:41], v[40:41], v[132:133], v[80:81]
	v_pk_fma_f32 v[38:39], v[38:39], v[130:131], v[78:79]
	v_pk_fma_f32 v[56:57], v[56:57], v[144:145], v[84:85]
	v_pk_fma_f32 v[54:55], v[54:55], v[142:143], v[82:83]
	v_pk_fma_f32 v[52:53], v[52:53], v[140:141], v[88:89]
	v_pk_fma_f32 v[50:51], v[50:51], v[138:139], v[86:87]
	v_pk_fma_f32 v[32:33], v[32:33], v[136:137], v[92:93]
	v_pk_fma_f32 v[30:31], v[30:31], v[134:135], v[90:91]
	v_pk_fma_f32 v[28:29], v[28:29], v[132:133], v[96:97]
	v_pk_fma_f32 v[26:27], v[26:27], v[130:131], v[94:95]
	v_pk_fma_f32 v[48:49], v[48:49], v[144:145], v[100:101]
	v_pk_fma_f32 v[46:47], v[46:47], v[142:143], v[98:99]
	v_pk_fma_f32 v[36:37], v[36:37], v[140:141], v[104:105]
	v_pk_fma_f32 v[34:35], v[34:35], v[138:139], v[102:103]
	global_store_dwordx4 v[154:155], v[62:65], off
	global_store_dwordx4 v[154:155], v[58:61], off offset:64
	global_store_dwordx4 v[154:155], v[42:45], off offset:512
	global_store_dwordx4 v[154:155], v[38:41], off offset:576
	global_store_dwordx4 v[160:161], v[54:57], off
	global_store_dwordx4 v[160:161], v[50:53], off offset:64
	global_store_dwordx4 v[160:161], v[30:33], off offset:512
	global_store_dwordx4 v[160:161], v[26:29], off offset:576
	global_store_dwordx4 v[162:163], v[46:49], off
	global_store_dwordx4 v[162:163], v[34:37], off offset:64
	global_store_dwordx4 v[162:163], v[18:21], off offset:512
	s_waitcnt vmcnt(15)
	v_pk_fma_f32 v[12:13], v[12:13], v[132:133], v[112:113]
	v_pk_fma_f32 v[10:11], v[10:11], v[130:131], v[110:111]
	v_lshl_add_u64 v[18:19], s[58:59], 0, v[156:157]
	global_store_dwordx4 v[162:163], v[10:13], off offset:576
	v_lshl_add_u64 v[18:19], v[18:19], 0, v[152:153]
	s_waitcnt vmcnt(13)
	v_pk_fma_f32 v[8:9], v[8:9], v[136:137], v[124:125]
	v_pk_fma_f32 v[12:13], v[24:25], v[144:145], v[116:117]
	v_pk_fma_f32 v[10:11], v[22:23], v[142:143], v[114:115]
	global_store_dwordx4 v[18:19], v[10:13], off
	v_pk_fma_f32 v[6:7], v[6:7], v[134:135], v[122:123]
	s_waitcnt vmcnt(13)
	v_pk_fma_f32 v[4:5], v[4:5], v[132:133], v[128:129]
	v_pk_fma_f32 v[12:13], v[16:17], v[140:141], v[120:121]
	v_pk_fma_f32 v[10:11], v[14:15], v[138:139], v[118:119]
	v_pk_fma_f32 v[2:3], v[2:3], v[130:131], v[126:127]
	global_store_dwordx4 v[18:19], v[10:13], off offset:64
	global_store_dwordx4 v[18:19], v[6:9], off offset:512
	global_store_dwordx4 v[18:19], v[2:5], off offset:576
	s_cbranch_vccnz .LBB0_1090
	s_andn2_b64 vcc, exec, s[4:5]
	s_cbranch_vccnz .LBB0_1089
	s_barrier
	s_branch .LBB0_1089

; __device__ __forceinline__ unsigned xb_ld(unsigned* p)              { return __hip_atomic_load(p, __ATOMIC_RELAXED, __HIP_MEMORY_SCOPE_AGENT); }
; __device__ __forceinline__ void xcd_barrier_complete(unsigned* bar, unsigned x, unsigned& nloc, unsigned& nx) {
;     const unsigned G = gridDim.x * gridDim.y * gridDim.z;
;     unsigned sum, cnt, mine, sp = 0u;
;     for (;;) {
;         sum = 0u; cnt = 0u; mine = 0u;
; #pragma unroll
;         for (unsigned j = 0; j < 16; ++j) { const unsigned c = xb_ld(&bar[XB_XCNT(j)]); sum += c; cnt += (c > 0u) ? 1u : 0u; mine = (j == x) ? c : mine; }
;         if (sum == G) break;
;         __builtin_amdgcn_s_sleep(1);
;         if ((++sp & 255u) == 0u) { if (xb_ld(&bar[XB_TMO])) break; if (sp > XB_SPIN_CAP) { atomicAdd(&bar[XB_TMO], 1u); break; } }
;     }
.LBB0_1110:
	v_mov_b64_e32 v[2:3], s[4:5]
	s_waitcnt lgkmcnt(0)
	global_load_dword v0, v[2:3], off sc1
	v_mov_b64_e32 v[2:3], s[6:7]
	global_load_dword v2, v[2:3], off sc1
	v_mov_b64_e32 v[4:5], s[8:9]
	global_load_dword v3, v[4:5], off sc1
	v_mov_b64_e32 v[4:5], s[10:11]
	global_load_dword v4, v[4:5], off sc1
	v_readlane_b32 s40, v254, 8
	s_or_b64 s[86:87], s[86:87], exec
	s_or_b64 s[84:85], s[84:85], exec
	s_waitcnt vmcnt(0) lgkmcnt(0)
	v_add_u32_e32 v6, v2, v0
	v_add_u32_e32 v6, v6, v3
	v_add_u32_e32 v8, v6, v4
	v_mov_b64_e32 v[6:7], s[12:13]
	global_load_dword v5, v[6:7], off sc1
	v_mov_b64_e32 v[6:7], s[14:15]
	global_load_dword v6, v[6:7], off sc1
	s_waitcnt vmcnt(0) lgkmcnt(0)
	v_add_u32_e32 v8, v8, v5
	v_add_u32_e32 v10, v8, v6
	v_mov_b64_e32 v[8:9], s[16:17]
	global_load_dword v7, v[8:9], off sc1
	v_mov_b64_e32 v[8:9], s[18:19]
	global_load_dword v8, v[8:9], off sc1
	s_waitcnt vmcnt(0) lgkmcnt(0)
	v_add_u32_e32 v10, v10, v7
	v_add_u32_e32 v12, v10, v8
	v_mov_b64_e32 v[10:11], s[20:21]
	global_load_dword v9, v[10:11], off sc1
	v_mov_b64_e32 v[10:11], s[22:23]
	global_load_dword v10, v[10:11], off sc1
	s_waitcnt vmcnt(0) lgkmcnt(0)
	v_add_u32_e32 v12, v12, v9
	v_add_u32_e32 v14, v12, v10
	v_mov_b64_e32 v[12:13], s[24:25]
	global_load_dword v11, v[12:13], off sc1
	v_mov_b64_e32 v[12:13], s[26:27]
	global_load_dword v12, v[12:13], off sc1
	s_waitcnt vmcnt(0) lgkmcnt(0)
	v_add_u32_e32 v14, v14, v11
	v_add_u32_e32 v16, v14, v12
	v_mov_b64_e32 v[14:15], s[28:29]
	global_load_dword v13, v[14:15], off sc1
	v_mov_b64_e32 v[14:15], s[30:31]
	global_load_dword v14, v[14:15], off sc1
	s_waitcnt vmcnt(0) lgkmcnt(0)
	v_add_u32_e32 v16, v16, v13
	v_add_u32_e32 v18, v16, v14
	v_mov_b64_e32 v[16:17], s[56:57]
	global_load_dword v15, v[16:17], off sc1
	v_mov_b64_e32 v[16:17], s[78:79]
	global_load_dword v16, v[16:17], off sc1
	s_waitcnt vmcnt(0) lgkmcnt(0)
	v_add_u32_e32 v18, v18, v15
	v_add_u32_e32 v17, v18, v16
	v_cmp_ne_u32_e32 vcc, s40, v17
	s_and_saveexec_b64 s[88:89], vcc
	s_cbranch_execz .LBB0_1109
	s_and_b32 s40, s90, 0xff
	s_mov_b64 s[64:65], -1
	s_cmp_eq_u32 s40, 0
	s_mov_b64 s[72:73], -1
	s_mov_b64 s[40:41], -1
	s_sleep 1
	s_cbranch_scc1 .LBB0_1113
	s_and_saveexec_b64 s[70:71], s[72:73]
	s_cbranch_execz .LBB0_1108
	s_branch .LBB0_1116
.LBB0_1113:
	v_mov_b64_e32 v[18:19], s[0:1]
	global_load_dword v17, v[18:19], off sc1
	s_mov_b64 s[72:73], 0
	s_waitcnt vmcnt(0) lgkmcnt(0)
	v_cmp_eq_u32_e32 vcc, 0, v17
	s_and_saveexec_b64 s[70:71], vcc
	s_cmp_lt_u32 s90, 0x400001
	s_cselect_b64 s[72:73], -1, 0
	s_xor_b64 s[40:41], exec, -1
	s_and_b64 s[72:73], s[72:73], exec
	s_or_b64 exec, exec, s[70:71]
	v_readlane_b32 s92, v255, 41
	v_readlane_b32 s93, v255, 42
	s_and_saveexec_b64 s[70:71], s[72:73]
	s_cbranch_execz .LBB0_1108

; __device__ __forceinline__ unsigned xb_ld(unsigned* p)              { return __hip_atomic_load(p, __ATOMIC_RELAXED, __HIP_MEMORY_SCOPE_AGENT); }
; __device__ __forceinline__ unsigned xb_add(unsigned* p, unsigned v) { return __hip_atomic_fetch_add(p, v, __ATOMIC_RELAXED, __HIP_MEMORY_SCOPE_AGENT); }
; #define XB_SPIN(cond, bar) do { unsigned _sp = 0; while (cond) {     \
;     if ((++_sp & 255u) == 0u) { if (xb_ld(&(bar)[XB_TMO])) break; if (_sp > XB_SPIN_CAP) { atomicAdd(&(bar)[XB_TMO], 1u); break; } } } } while (0)
; __device__ __forceinline__ void xcd_barrier(const XcdBarrier& b, int wave_s) {
;     ...
;         if (old + 1u == (gen + 1u) * nloc) {
;             __builtin_amdgcn_fence(__ATOMIC_RELEASE, "agent");
;             asm volatile("s_waitcnt vmcnt(0)" ::: "memory");
;             const unsigned og = xb_add(&bar[XB_TOP], 1u);
;             const unsigned tg = og / nx;
;             if (og + 1u == (tg + 1u) * nx) xb_add(&bar[XB_TOPGEN], 1u);
;             else XB_SPIN(xb_ld(&bar[XB_TOPGEN]) == tg, bar);
.LBB0_1134:
	v_mov_b32_e32 v2, s38
	v_add_co_u32_e32 v2, vcc, 0x13000, v2
	v_mov_b32_e32 v3, s39
	buffer_wbl2 sc1
	s_waitcnt vmcnt(0)
	v_addc_co_u32_e32 v3, vcc, 0, v3, vcc
	flat_atomic_add v2, v[2:3], v220 offset:1024 sc0
	v_cvt_f32_u32_e32 v3, v0
	v_sub_u32_e32 v4, 0, v0
	s_mov_b64 s[6:7], -1
	v_rcp_iflag_f32_e32 v3, v3
	s_nop 0
	v_mul_f32_e32 v3, 0x4f7ffffe, v3
	v_cvt_u32_f32_e32 v3, v3
	v_mul_lo_u32 v4, v4, v3
	v_mul_hi_u32 v4, v3, v4
	v_add_u32_e32 v3, v3, v4
	s_waitcnt vmcnt(0) lgkmcnt(0)
	v_mul_hi_u32 v3, v2, v3
	v_mul_lo_u32 v4, v3, v0
	v_sub_u32_e32 v4, v2, v4
	v_cmp_ge_u32_e32 vcc, v4, v0
	v_add_u32_e32 v5, 1, v3
	s_nop 0
	v_cndmask_b32_e32 v3, v3, v5, vcc
	v_sub_u32_e32 v5, v4, v0
	v_cndmask_b32_e32 v4, v4, v5, vcc
	v_cmp_ge_u32_e32 vcc, v4, v0
	v_add_u32_e32 v4, 1, v3
	v_add_u32_e32 v5, 1, v2
	v_cndmask_b32_e32 v4, v3, v4, vcc
	v_mad_u64_u32 v[2:3], s[0:1], v0, v4, v[0:1]
	s_add_u32 s0, s38, 0x13500
	s_addc_u32 s1, s39, 0
	v_cmp_ne_u32_e32 vcc, v5, v2
	v_mov_b64_e32 v[2:3], s[0:1]
	s_and_saveexec_b64 s[4:5], vcc
	s_cbranch_execz .LBB0_1146
	v_mov_b64_e32 v[2:3], s[0:1]
	global_load_dword v0, v[2:3], off sc1
	s_mov_b64 s[10:11], 0
	s_waitcnt vmcnt(0) lgkmcnt(0)
	v_cmp_eq_u32_e32 vcc, v0, v4
	s_and_saveexec_b64 s[8:9], vcc
	s_cbranch_execz .LBB0_1145
	s_add_u32 s6, s38, 0x10200
	s_addc_u32 s7, s39, 0
	s_mov_b32 s22, 1
	s_branch .LBB0_1138

; #define PH unsigned char* ws = a.ws; asm volatile("" : "+s"(ws)); int lq = l; asm volatile("" : "+s"(lq)); (void)lq;
; template <bool FINAL>
; __device__ __forceinline__ void norm_pass(const float* X, const float* g, const float* scale, const float* shift, bf16_t* H, float* OUTF, int vcu_, int NGW_, int wave_s) {
;     ...
;     f32x4 gm[8], sh[8];
; #pragma unroll
;     for (int j = 0; j < 8; ++j) { const f32x4 gv = ((const f32x4*)g)[64 * j + lane];
;         if (!FINAL) { const f32x4 s = ((const f32x4*)scale)[64 * j + lane]; gm[j] = gv * (1.f + s); sh[j] = ((const f32x4*)shift)[64 * j + lane]; } else { gm[j] = gv; sh[j] = (f32x4){0.f, 0.f, 0.f, 0.f}; } }
;     f32x4 nv[8];
;     { const f32x4* xr = (const f32x4*)(X + (size_t)gw * DM) + lane;
; #pragma unroll
;         for (int j = 0; j < 8; ++j) nv[j] = xr[64 * j]; }
; __global__ void __launch_bounds__(NTHR, 2) mega_fwd(Args a) {
;     ...
;     { const int l = 0; PH norm_pass<true>(a.out, SMV + SM_FN, nullptr, nullptr, nullptr, a.out, vcu, NGW, wave_s); }
.LBB0_1148:
	s_mov_b32 s0, 0
	s_nop 0
	v_readlane_b32 s0, v255, 31
	s_lshl_b32 s0, s0, 3
	s_add_i32 s2, s0, s86
	s_cmpk_gt_i32 s2, 0x3fff
	v_mbcnt_lo_u32_b32 v0, -1, 0
	v_mbcnt_hi_u32_b32 v0, -1, v0
	s_cbranch_scc1 .LBB0_1153
	v_and_b32_e32 v0, 63, v0
	v_lshlrev_b32_e32 v96, 4, v0
	v_mov_b32_e32 v97, 0
	v_lshl_add_u64 v[16:17], s[60:61], 0, v[96:97]
	s_mov_b64 s[4:5], 0x28000
	s_ashr_i32 s3, s2, 31
	v_lshl_add_u64 v[18:19], v[16:17], 0, s[4:5]
	v_add_co_u32_e32 v20, vcc, 0x28000, v16
	s_lshl_b64 s[4:5], s[2:3], 13
	s_nop 0
	v_addc_co_u32_e32 v21, vcc, 0, v17, vcc
	s_add_u32 s4, s58, s4
	v_add_co_u32_e32 v40, vcc, 0x29000, v16
	s_addc_u32 s5, s59, s5
	global_load_dwordx4 v[0:3], v[18:19], off offset:1024
	global_load_dwordx4 v[4:7], v[18:19], off offset:2048
	global_load_dwordx4 v[8:11], v[20:21], off
	global_load_dwordx4 v[12:15], v[18:19], off offset:3072
	v_addc_co_u32_e32 v41, vcc, 0, v17, vcc
	v_lshl_add_u64 v[24:25], s[4:5], 0, v[96:97]
	v_add_co_u32_e32 v42, vcc, 0x1000, v24
	global_load_dwordx4 v[16:19], v[40:41], off
	global_load_dwordx4 v[20:23], v[40:41], off offset:1024
	v_addc_co_u32_e32 v43, vcc, 0, v25, vcc
	global_load_dwordx4 v[80:83], v96, s[4:5] offset:3072
	global_load_dwordx4 v[84:87], v96, s[4:5] offset:2048
	global_load_dwordx4 v[88:91], v96, s[4:5] offset:1024
	global_load_dwordx4 v[32:35], v[42:43], off offset:3072
	global_load_dwordx4 v[36:39], v[42:43], off offset:2048
	global_load_dwordx4 v[56:59], v[42:43], off offset:1024
	global_load_dwordx4 v[76:79], v[42:43], off
	global_load_dwordx4 v[92:95], v96, s[4:5]
	global_load_dwordx4 v[24:27], v[40:41], off offset:2048
	global_load_dwordx4 v[28:31], v[40:41], off offset:3072
	s_add_i32 s1, s92, s86
	s_add_i32 s0, s1, s0
	s_ashr_i32 s93, s92, 31
	s_ashr_i32 s1, s0, 31
	s_lshl_b64 s[6:7], s[92:93], 13
	s_lshl_b64 s[0:1], s[0:1], 13
	s_add_u32 s8, s58, s0
	s_movk_i32 s3, 0x1000
	v_mov_b32_e32 v98, 0x358637bd
	s_mov_b32 s12, 0xf800000
	v_mov_b32_e32 v99, 0x260
	s_addc_u32 s9, s59, s1
	s_waitcnt vmcnt(0)
	v_mov_b64_e32 v[40:41], v[80:81]
	v_mov_b64_e32 v[44:45], v[84:85]
	v_mov_b64_e32 v[48:49], v[88:89]
	v_mov_b64_e32 v[62:63], v[34:35]
	v_mov_b64_e32 v[66:67], v[38:39]
	v_mov_b64_e32 v[70:71], v[58:59]
	v_mov_b64_e32 v[72:73], v[76:77]
	v_mov_b64_e32 v[52:53], v[92:93]
	v_mov_b64_e32 v[42:43], v[82:83]
	v_mov_b64_e32 v[46:47], v[86:87]
	v_mov_b64_e32 v[50:51], v[90:91]
	v_mov_b64_e32 v[60:61], v[32:33]
	v_mov_b64_e32 v[64:65], v[36:37]
	v_mov_b64_e32 v[68:69], v[56:57]
	v_mov_b64_e32 v[74:75], v[78:79]
	v_mov_b64_e32 v[54:55], v[94:95]
	s_branch .LBB0_1151

; __global__ void __launch_bounds__(NTHR, 2) mega_fwd(Args a) {
;     ...
;         if (bx == 0) { float* sm = SMV;
;             for (int i = tid; i < 4096; i += NTHR) { sm[SM_N1 + i] = a.norm1[i]; sm[SM_N2 + i] = a.norm2[i]; }
.LBB0_1156:
	global_load_dword v9, v[2:3], off
	v_add_co_u32_e32 v10, vcc, 0xffffc000, v6
	v_add_u32_e32 v8, 0x200, v8
	s_nop 0
	v_addc_co_u32_e32 v11, vcc, -1, v7, vcc
	v_cmp_lt_i32_e32 vcc, s10, v8
	v_lshl_add_u64 v[2:3], v[2:3], 0, s[8:9]
	s_or_b64 s[6:7], vcc, s[6:7]
	s_waitcnt vmcnt(0)
	global_store_dword v[10:11], v9, off
	global_load_dword v9, v[4:5], off
	v_lshl_add_u64 v[4:5], v[4:5], 0, s[8:9]
	s_waitcnt vmcnt(0)
	global_store_dword v[6:7], v9, off
	v_lshl_add_u64 v[6:7], v[6:7], 0, s[8:9]
	s_andn2_b64 exec, exec, s[6:7]
	s_cbranch_execnz .LBB0_1156

; __global__ void __launch_bounds__(NTHR, 2) mega_fwd(Args a) {
;     ...
;             for (int i = tid; i < 2048; i += NTHR) sm[SM_FN + i] = a.final_norm[i];
;             if (tid < 256) { sm[SM_AQ + tid] = a.a_q_norm[tid]; sm[SM_AK + tid] = a.a_k_norm[tid]; sm[SM_DS + tid] = a.d_sub_norm[tid]; sm[SM_RB + tid] = a.rel_bias[tid]; }
;             if (tid < 8) sm[SM_CS + tid] = a.c_sink[tid]; }
.LBB0_1159:
	global_load_dword v7, v[4:5], off
	v_add_u32_e32 v6, 0x200, v6
	v_cmp_lt_i32_e32 vcc, s10, v6
	v_lshl_add_u64 v[4:5], v[4:5], 0, s[8:9]
	s_or_b64 s[6:7], vcc, s[6:7]
	s_waitcnt vmcnt(0)
	global_store_dword v[2:3], v7, off
	v_lshl_add_u64 v[2:3], v[2:3], 0, s[8:9]
	s_andn2_b64 exec, exec, s[6:7]
	s_cbranch_execnz .LBB0_1159
.LBB0_1160:
	s_or_b64 exec, exec, s[4:5]
	s_add_u32 s4, s28, 0x20000
	s_movk_i32 s6, 0x100
	s_addc_u32 s5, s29, 0
	v_cmp_gt_i32_e32 vcc, s6, v66
	s_and_saveexec_b64 s[6:7], vcc
	s_cbranch_execz .LBB0_1162
	v_readlane_b32 s40, v254, 12
	v_lshlrev_b64 v[2:3], 2, v[66:67]
	v_readlane_b32 s52, v254, 24
	v_readlane_b32 s53, v254, 25
	v_readlane_b32 s54, v254, 26
	v_readlane_b32 s55, v254, 27
	v_lshl_add_u64 v[4:5], s[52:53], 0, v[2:3]
	global_load_dword v8, v[4:5], off
	v_lshl_add_u64 v[4:5], s[4:5], 0, v[2:3]
	v_add_co_u32_e32 v4, vcc, 0xa000, v4
	v_lshl_add_u64 v[6:7], s[54:55], 0, v[2:3]
	s_nop 0
	v_addc_co_u32_e32 v5, vcc, 0, v5, vcc
	v_readlane_b32 s41, v254, 13
	v_readlane_b32 s42, v254, 14
	v_readlane_b32 s43, v254, 15
	v_readlane_b32 s44, v254, 16
	v_readlane_b32 s45, v254, 17
	v_readlane_b32 s46, v254, 18
	v_readlane_b32 s47, v254, 19
	v_readlane_b32 s48, v254, 20
	v_readlane_b32 s49, v254, 21
	v_readlane_b32 s50, v254, 22
	v_readlane_b32 s51, v254, 23
	s_waitcnt vmcnt(0)
	global_store_dword v[4:5], v8, off
	global_load_dword v8, v[6:7], off
	v_lshl_add_u64 v[6:7], s[16:17], 0, v[2:3]
	v_readlane_b32 s16, v254, 0
	v_readlane_b32 s22, v254, 6
	v_readlane_b32 s23, v254, 7
	v_readlane_b32 s17, v254, 1
	v_readlane_b32 s18, v254, 2
	v_lshl_add_u64 v[2:3], s[22:23], 0, v[2:3]
	v_readlane_b32 s19, v254, 3
	v_readlane_b32 s20, v254, 4
	v_readlane_b32 s21, v254, 5
	s_waitcnt vmcnt(0)
	global_store_dword v[4:5], v8, off offset:1024
	global_load_dword v6, v[6:7], off
	s_waitcnt vmcnt(0)
	global_store_dword v[4:5], v6, off offset:2048
	global_load_dword v2, v[2:3], off
	s_waitcnt vmcnt(0)
	global_store_dword v[4:5], v2, off offset:3136
.LBB0_1162:
	s_or_b64 exec, exec, s[6:7]
	v_cmp_gt_i32_e32 vcc, 8, v66
	s_and_saveexec_b64 s[6:7], vcc
	s_cbranch_execz .LBB0_1164
	v_lshlrev_b64 v[2:3], 2, v[66:67]
	v_lshl_add_u64 v[4:5], s[12:13], 0, v[2:3]
	global_load_dword v4, v[4:5], off
	v_lshl_add_u64 v[2:3], s[4:5], 0, v[2:3]
	v_add_co_u32_e32 v2, vcc, 0xa000, v2
	s_nop 1
	v_addc_co_u32_e32 v3, vcc, 0, v3, vcc
	s_waitcnt vmcnt(0)
	global_store_dword v[2:3], v4, off offset:3072

; __global__ void __launch_bounds__(NTHR, 2) mega_fwd(Args a) {
;     ...
;         if (bx == 0) for (int i = tid; i < XCD_BAR_WORDS; i += NTHR) ((unsigned*)(ws + WS_BAR))[i] = 0u;
.LBB0_1167:
	v_add_u32_e32 v7, -2, v7
	v_ashrrev_i32_e32 v9, 31, v3
	v_mov_b32_e32 v8, v3
	v_ashrrev_i32_e32 v11, 31, v2
	v_mov_b32_e32 v10, v2
	v_cmp_eq_u32_e32 vcc, 0, v7
	v_add_u32_e32 v3, 0x400, v3
	v_add_u32_e32 v2, 0x400, v2
	v_lshl_add_u64 v[10:11], v[10:11], 2, s[8:9]
	v_lshl_add_u64 v[8:9], v[8:9], 2, s[8:9]
	s_or_b64 s[10:11], vcc, s[10:11]
	global_store_dword v[10:11], v6, off
	global_store_dword v[8:9], v6, off
	s_andn2_b64 exec, exec, s[10:11]
	s_cbranch_execnz .LBB0_1167
	s_or_b64 exec, exec, s[10:11]
	v_cmp_ne_u32_e32 vcc, v4, v5
	v_lshl_add_u32 v2, v5, 9, v66
	s_orn2_b64 s[8:9], vcc, exec

; __global__ void __launch_bounds__(NTHR, 2) mega_fwd(Args a) {
;     ...
;         if (bx == 0) for (int i = tid; i < XCD_BAR_WORDS; i += NTHR) ((unsigned*)(ws + WS_BAR))[i] = 0u;
.LBB0_1171:
	v_add_u32_e32 v4, 0x200, v4
	v_cmp_lt_i32_e32 vcc, s10, v4
	global_store_dword v[2:3], v5, off
	s_or_b64 s[6:7], vcc, s[6:7]
	v_lshl_add_u64 v[2:3], v[2:3], 0, s[8:9]
	s_andn2_b64 exec, exec, s[6:7]
	s_cbranch_execnz .LBB0_1171
